# previous + second pass of the shfl_xor(16|32) -> v_permlane16/32_swap conversion (65 more sites: EpiRes row sums of P3/P5/P10/P12, P9 and P8 q loaders) where the sum is consumed further down or under
# speedup vs baseline: 1.0029x; 1.0029x over previous
; #define GAS __attribute__((address_space(1)))
; __device__ __forceinline__ unsigned pkh(float lo, float hi) { f32x2 v = {lo, hi}; h16x2 h = __builtin_convertvector(v, h16x2); return __builtin_bit_cast(unsigned, h); }
; __device__ __forceinline__ float wave_sum(float v) {
; #pragma unroll
;     for (int o = 1; o < 64; o <<= 1) v += __shfl_xor(v, o);
;     return v;
; }
; __device__ __forceinline__ void p0_prologue(const Frame& F, const Args& a) {
;     ...
;             for (int r = 0; r < 4; ++r) { const int m = m0 + r * NGW; if (m >= M) break; float s = 0.f;
; #pragma unroll
;                 for (int j = 0; j < 4; ++j) s += (v[r][j].x * v[r][j].x + v[r][j].y * v[r][j].y) + (v[r][j].z * v[r][j].z + v[r][j].w * v[r][j].w);
;                 s = wave_sum(s);
;                 if (F.lane == 0) ss0[m] = s;
;                 GAS u32x2* o8 = (GAS u32x2*)(A16 + (size_t)m * DM) + F.lane;
; #pragma unroll
;                 for (int j = 0; j < 4; ++j) { u32x2 w; w.x = pkh(v[r][j].x, v[r][j].y); w.y = pkh(v[r][j].z, v[r][j].w); o8[64 * j] = w; } }
.LBB0_60:
	s_or_b64 exec, exec, s[34:35]
	s_lshl_b64 s[30:31], s[30:31], 11
	v_lshl_add_u64 v[78:79], v[70:71], 0, s[30:31]
	v_cvt_pk_f16_f32 v62, v62, v63
	v_cvt_pk_f16_f32 v63, v64, v65
	v_cvt_pk_f16_f32 v58, v58, v59
	v_cvt_pk_f16_f32 v59, v60, v61
	v_cvt_pk_f16_f32 v54, v54, v55
	v_cvt_pk_f16_f32 v55, v56, v57
	v_cvt_pk_f16_f32 v50, v50, v51
	v_cvt_pk_f16_f32 v51, v52, v53
	s_andn2_b64 vcc, exec, s[28:29]
	global_store_dwordx2 v[78:79], v[62:63], off
	global_store_dwordx2 v[78:79], v[58:59], off offset:512
	global_store_dwordx2 v[78:79], v[54:55], off offset:1024
	global_store_dwordx2 v[78:79], v[50:51], off offset:1536
	s_cbranch_vccnz .LBB0_57
	s_waitcnt vmcnt(15)
	v_mul_f32_e32 v50, v47, v47
	v_mul_f32_e32 v51, v49, v49
	v_fmac_f32_e32 v50, v46, v46
	v_fmac_f32_e32 v51, v48, v48
	v_add_f32_e32 v50, v50, v51
	s_waitcnt vmcnt(14)
	v_mul_f32_e32 v51, v43, v43
	v_mul_f32_e32 v52, v45, v45
	v_fmac_f32_e32 v51, v42, v42
	v_fmac_f32_e32 v52, v44, v44
	v_add_f32_e32 v51, v51, v52
	v_add_f32_e32 v50, v50, v51
	s_waitcnt vmcnt(13)
	v_mul_f32_e32 v51, v39, v39
	v_mul_f32_e32 v52, v41, v41
	v_fmac_f32_e32 v51, v38, v38
	v_fmac_f32_e32 v52, v40, v40
	v_add_f32_e32 v51, v51, v52
	v_add_f32_e32 v50, v50, v51
	s_waitcnt vmcnt(12)
	v_mul_f32_e32 v51, v35, v35
	v_mul_f32_e32 v52, v37, v37
	v_fmac_f32_e32 v51, v34, v34
	v_fmac_f32_e32 v52, v36, v36
	v_add_f32_e32 v51, v51, v52
	v_add_f32_e32 v50, v50, v51
	ds_bpermute_b32 v51, v1, v50
	s_ashr_i32 s5, s4, 31
	s_waitcnt lgkmcnt(0)
	v_add_f32_e32 v50, v50, v51
	ds_bpermute_b32 v51, v72, v50
	s_waitcnt lgkmcnt(0)
	v_add_f32_e32 v50, v50, v51
	ds_bpermute_b32 v51, v73, v50
	s_waitcnt lgkmcnt(0)
	v_add_f32_e32 v50, v50, v51
	ds_bpermute_b32 v51, v74, v50
	s_waitcnt lgkmcnt(0)
	v_add_f32_e32 v50, v50, v51
	v_mov_b32_e32 v51, v50
	s_nop 1
	v_permlane16_swap_b32_e32 v50, v51
	v_add_f32_e32 v50, v50, v51
	v_mov_b32_e32 v51, v50
	s_nop 1
	v_permlane32_swap_b32_e32 v50, v51
	s_and_saveexec_b64 s[28:29], s[0:1]
	s_cbranch_execz .LBB0_63
	s_lshl_b64 s[30:31], s[4:5], 2
	s_add_u32 s30, s20, s30
	s_waitcnt lgkmcnt(0)
	v_add_f32_e32 v50, v50, v51
	s_addc_u32 s31, s21, s31
	global_store_dword v67, v50, s[30:31]
.LBB0_63:
	s_or_b64 exec, exec, s[28:29]
	s_lshl_b64 s[28:29], s[4:5], 11
	s_waitcnt lgkmcnt(0)
	v_lshl_add_u64 v[50:51], v[70:71], 0, s[28:29]
	v_cvt_pk_f16_f32 v46, v46, v47
	v_cvt_pk_f16_f32 v47, v48, v49
	v_cvt_pk_f16_f32 v42, v42, v43
	v_cvt_pk_f16_f32 v43, v44, v45
	v_cvt_pk_f16_f32 v38, v38, v39
	v_cvt_pk_f16_f32 v39, v40, v41
	v_cvt_pk_f16_f32 v34, v34, v35
	v_cvt_pk_f16_f32 v35, v36, v37
	s_andn2_b64 vcc, exec, s[26:27]
	global_store_dwordx2 v[50:51], v[46:47], off
	global_store_dwordx2 v[50:51], v[42:43], off offset:512
	global_store_dwordx2 v[50:51], v[38:39], off offset:1024
	global_store_dwordx2 v[50:51], v[34:35], off offset:1536
	s_cbranch_vccnz .LBB0_57
	s_waitcnt vmcnt(15)
	v_mul_f32_e32 v34, v31, v31
	v_mul_f32_e32 v35, v33, v33
	v_fmac_f32_e32 v34, v30, v30
	v_fmac_f32_e32 v35, v32, v32
	v_add_f32_e32 v34, v34, v35
	s_waitcnt vmcnt(14)
	v_mul_f32_e32 v35, v27, v27
	v_mul_f32_e32 v36, v29, v29
	v_fmac_f32_e32 v35, v26, v26
	v_fmac_f32_e32 v36, v28, v28
	v_add_f32_e32 v35, v35, v36
	v_add_f32_e32 v34, v34, v35
	s_waitcnt vmcnt(13)
	v_mul_f32_e32 v35, v23, v23
	v_mul_f32_e32 v36, v25, v25
	v_fmac_f32_e32 v35, v22, v22
	v_fmac_f32_e32 v36, v24, v24
	v_add_f32_e32 v35, v35, v36
	v_add_f32_e32 v34, v34, v35
	s_waitcnt vmcnt(12)
	v_mul_f32_e32 v35, v19, v19
	v_mul_f32_e32 v36, v21, v21
	v_fmac_f32_e32 v35, v18, v18
	v_fmac_f32_e32 v36, v20, v20
	v_add_f32_e32 v35, v35, v36
	v_add_f32_e32 v34, v34, v35
	ds_bpermute_b32 v35, v1, v34
	s_ashr_i32 s13, s12, 31
	s_waitcnt lgkmcnt(0)
	v_add_f32_e32 v34, v34, v35
	ds_bpermute_b32 v35, v72, v34
	s_waitcnt lgkmcnt(0)
	v_add_f32_e32 v34, v34, v35
	ds_bpermute_b32 v35, v73, v34
	s_waitcnt lgkmcnt(0)
	v_add_f32_e32 v34, v34, v35
	ds_bpermute_b32 v35, v74, v34
	s_waitcnt lgkmcnt(0)
	v_add_f32_e32 v34, v34, v35
	v_mov_b32_e32 v35, v34
	s_nop 1
	v_permlane16_swap_b32_e32 v34, v35
	v_add_f32_e32 v34, v34, v35
	v_mov_b32_e32 v35, v34
	s_nop 1
	v_permlane32_swap_b32_e32 v34, v35
	s_and_saveexec_b64 s[26:27], s[0:1]
	s_cbranch_execz .LBB0_66
	s_lshl_b64 s[28:29], s[12:13], 2
	s_add_u32 s28, s20, s28
	s_waitcnt lgkmcnt(0)
	v_add_f32_e32 v34, v34, v35
	s_addc_u32 s29, s21, s29
	global_store_dword v67, v34, s[28:29]

; __device__ __forceinline__ unsigned pkh(float lo, float hi) { f32x2 v = {lo, hi}; h16x2 h = __builtin_convertvector(v, h16x2); return __builtin_bit_cast(unsigned, h); }
;     __device__ __forceinline__ void operator()(f32x4 (&acc)[2][2][4][2], const Unit& u, const Order& S, int wr, int wc, int fr_, int fq_, LAS unsigned char*, int) const {
;     ...
;                 for (int bj = 0; bj < 2; ++bj) {
;                     f32x4 v0 = acc[ai][bj][m][0] * sc, v1 = acc[ai][bj][m][1] * sc;
;                     if (act) { const f32x2 a0 = gelu_tanh2((f32x2){v0[0], v0[1]}), a1 = gelu_tanh2((f32x2){v0[2], v0[3]}), a2 = gelu_tanh2((f32x2){v1[0], v1[1]}), a3 = gelu_tanh2((f32x2){v1[2], v1[3]});
;                         v0 = (f32x4){a0.x, a0.y, a1.x, a1.y}; v1 = (f32x4){a2.x, a2.y, a3.x, a3.y}; }
;                     sq += (v0[0] * v0[0] + v0[1] * v0[1]) + (v0[2] * v0[2] + v0[3] * v0[3]) + (v1[0] * v1[0] + v1[1] * v1[1]) + (v1[2] * v1[2] + v1[3] * v1[3]);
;                     u32x4 w; w.x = pkh(v0[0], v0[1]); w.y = pkh(v0[2], v0[3]); w.z = pkh(v1[0], v1[1]); w.w = pkh(v1[2], v1[3]);
;                     *(u32x4*)(P + (size_t)row * NA + col0 + bj * HALF) = w;
;                 }
;                 if (stat && !dry) { sq += __shfl_xor(sq, 16); sq += __shfl_xor(sq, 32); if (fq == 0) atomicAdd(ssv + row, sq); }
.LBB0_186:
	s_add_i32 s2, s2, -6
	s_cmp_gt_u32 s2, -4
	s_cselect_b64 s[40:41], -1, 0
	s_cmp_lt_u32 s2, -3
	v_cmp_eq_u32_e64 s[2:3], 0, v158
	v_cvt_pk_f16_f32 v162, v118, v119
	v_cvt_pk_f16_f32 v163, v120, v121
	v_cvt_pk_f16_f32 v164, v114, v115
	v_cvt_pk_f16_f32 v165, v116, v117
	global_store_dwordx4 v[142:143], v[162:165], off offset:256
	s_cbranch_scc1 .LBB0_190
	v_mul_f32_e32 v127, v127, v127
	v_mul_f32_e32 v117, v117, v117
	v_mul_f32_e32 v115, v115, v115
	v_fmac_f32_e32 v127, v126, v126
	v_mul_f32_e32 v126, v129, v129
	v_fmac_f32_e32 v117, v116, v116
	v_fmac_f32_e32 v115, v114, v114
	v_mul_f32_e32 v114, v119, v119
	v_mul_f32_e32 v116, v121, v121
	v_fmac_f32_e32 v126, v128, v128
	v_fmac_f32_e32 v114, v118, v118
	v_fmac_f32_e32 v116, v120, v120
	v_add_f32_e32 v126, v127, v126
	v_mul_f32_e32 v127, v139, v139
	v_add_f32_e32 v114, v114, v116
	v_and_b32_e32 v116, 64, v157
	v_fmac_f32_e32 v127, v138, v138
	v_mul_f32_e32 v125, v125, v125
	v_add_f32_e32 v114, v115, v114
	v_xor_b32_e32 v115, 16, v157
	v_add_u32_e32 v116, 64, v116
	v_add_f32_e32 v126, v127, v126
	v_fmac_f32_e32 v125, v124, v124
	v_cmp_lt_i32_e32 vcc, v115, v116
	v_add_f32_e32 v124, v125, v126
	v_add_f32_e32 v114, v117, v114
	v_cndmask_b32_e32 v115, v157, v115, vcc
	v_add_f32_e32 v114, v124, v114
	v_lshlrev_b32_e32 v115, 2, v115
	v_mov_b32_e32 v115, v114
	s_nop 1
	v_permlane16_swap_b32_e32 v114, v115
	v_add_f32_e32 v114, v114, v115
	v_xor_b32_e32 v115, 32, v157
	v_cmp_lt_i32_e32 vcc, v115, v116
	s_nop 1
	v_cndmask_b32_e32 v115, v157, v115, vcc
	v_lshlrev_b32_e32 v115, 2, v115
	v_mov_b32_e32 v115, v114
	s_nop 1
	v_permlane32_swap_b32_e32 v114, v115
	s_and_saveexec_b64 s[6:7], s[2:3]
	s_cbranch_execz .LBB0_189
	v_lshl_add_u64 v[116:117], v[134:135], 2, s[12:13]
	s_waitcnt lgkmcnt(0)
	v_add_f32_e32 v114, v114, v115
	global_atomic_add_f32 v[116:117], v114, off

; __device__ __forceinline__ unsigned pkh(float lo, float hi) { f32x2 v = {lo, hi}; h16x2 h = __builtin_convertvector(v, h16x2); return __builtin_bit_cast(unsigned, h); }
;     __device__ __forceinline__ void operator()(f32x4 (&acc)[2][2][4][2], const Unit& u, const Order& S, int wr, int wc, int fr_, int fq_, LAS unsigned char*, int) const {
;     ...
;                 for (int bj = 0; bj < 2; ++bj) {
;                     f32x4 v0 = acc[ai][bj][m][0] * sc, v1 = acc[ai][bj][m][1] * sc;
;                     if (act) { const f32x2 a0 = gelu_tanh2((f32x2){v0[0], v0[1]}), a1 = gelu_tanh2((f32x2){v0[2], v0[3]}), a2 = gelu_tanh2((f32x2){v1[0], v1[1]}), a3 = gelu_tanh2((f32x2){v1[2], v1[3]});
;                         v0 = (f32x4){a0.x, a0.y, a1.x, a1.y}; v1 = (f32x4){a2.x, a2.y, a3.x, a3.y}; }
;                     sq += (v0[0] * v0[0] + v0[1] * v0[1]) + (v0[2] * v0[2] + v0[3] * v0[3]) + (v1[0] * v1[0] + v1[1] * v1[1]) + (v1[2] * v1[2] + v1[3] * v1[3]);
;                     u32x4 w; w.x = pkh(v0[0], v0[1]); w.y = pkh(v0[2], v0[3]); w.z = pkh(v1[0], v1[1]); w.w = pkh(v1[2], v1[3]);
;                     *(u32x4*)(P + (size_t)row * NA + col0 + bj * HALF) = w;
;                 }
;                 if (stat && !dry) { sq += __shfl_xor(sq, 16); sq += __shfl_xor(sq, 32); if (fq == 0) atomicAdd(ssv + row, sq); }
.LBB0_194:
	s_waitcnt lgkmcnt(0)
	v_cndmask_b32_e64 v115, 0, 1, s[40:41]
	v_cvt_pk_f16_f32 v124, v102, v103
	v_cvt_pk_f16_f32 v125, v104, v105
	v_cvt_pk_f16_f32 v126, v98, v99
	v_cvt_pk_f16_f32 v127, v100, v101
	v_cmp_ne_u32_e64 s[6:7], 1, v115
	s_andn2_b64 vcc, exec, s[40:41]
	global_store_dwordx4 v[118:119], v[124:127], off offset:256
	s_cbranch_vccnz .LBB0_198
	v_mul_f32_e32 v111, v111, v111
	v_mul_f32_e32 v101, v101, v101
	v_mul_f32_e32 v99, v99, v99
	v_fmac_f32_e32 v111, v110, v110
	v_mul_f32_e32 v110, v113, v113
	v_fmac_f32_e32 v101, v100, v100
	v_fmac_f32_e32 v99, v98, v98
	v_mul_f32_e32 v98, v103, v103
	v_mul_f32_e32 v100, v105, v105
	v_fmac_f32_e32 v110, v112, v112
	v_mul_f32_e32 v107, v107, v107
	v_fmac_f32_e32 v98, v102, v102
	v_fmac_f32_e32 v100, v104, v104
	v_add_f32_e32 v110, v111, v110
	v_fmac_f32_e32 v107, v106, v106
	v_add_f32_e32 v98, v98, v100
	v_and_b32_e32 v100, 64, v157
	v_add_f32_e32 v106, v107, v110
	v_mul_f32_e32 v107, v109, v109
	v_add_f32_e32 v98, v99, v98
	v_xor_b32_e32 v99, 16, v157
	v_add_u32_e32 v100, 64, v100
	v_fmac_f32_e32 v107, v108, v108
	v_cmp_lt_i32_e32 vcc, v99, v100
	v_add_f32_e32 v106, v107, v106
	v_add_f32_e32 v98, v101, v98
	v_cndmask_b32_e32 v99, v157, v99, vcc
	v_add_f32_e32 v98, v106, v98
	v_lshlrev_b32_e32 v99, 2, v99
	v_mov_b32_e32 v99, v98
	s_nop 1
	v_permlane16_swap_b32_e32 v98, v99
	v_add_f32_e32 v98, v98, v99
	v_xor_b32_e32 v99, 32, v157
	v_cmp_lt_i32_e32 vcc, v99, v100
	s_nop 1
	v_cndmask_b32_e32 v99, v157, v99, vcc
	v_lshlrev_b32_e32 v99, 2, v99
	v_mov_b32_e32 v99, v98
	s_nop 1
	v_permlane32_swap_b32_e32 v98, v99
	s_and_saveexec_b64 s[40:41], s[2:3]
	s_cbranch_execz .LBB0_197
	v_ashrrev_i32_e32 v115, 31, v114
	v_lshl_add_u64 v[100:101], v[114:115], 2, s[12:13]
	s_waitcnt lgkmcnt(0)
	v_add_f32_e32 v98, v98, v99
	global_atomic_add_f32 v[100:101], v98, off

; __device__ __forceinline__ unsigned pkh(float lo, float hi) { f32x2 v = {lo, hi}; h16x2 h = __builtin_convertvector(v, h16x2); return __builtin_bit_cast(unsigned, h); }
;     __device__ __forceinline__ void operator()(f32x4 (&acc)[2][2][4][2], const Unit& u, const Order& S, int wr, int wc, int fr_, int fq_, LAS unsigned char*, int) const {
;     ...
;                 for (int bj = 0; bj < 2; ++bj) {
;                     f32x4 v0 = acc[ai][bj][m][0] * sc, v1 = acc[ai][bj][m][1] * sc;
;                     if (act) { const f32x2 a0 = gelu_tanh2((f32x2){v0[0], v0[1]}), a1 = gelu_tanh2((f32x2){v0[2], v0[3]}), a2 = gelu_tanh2((f32x2){v1[0], v1[1]}), a3 = gelu_tanh2((f32x2){v1[2], v1[3]});
;                         v0 = (f32x4){a0.x, a0.y, a1.x, a1.y}; v1 = (f32x4){a2.x, a2.y, a3.x, a3.y}; }
;                     sq += (v0[0] * v0[0] + v0[1] * v0[1]) + (v0[2] * v0[2] + v0[3] * v0[3]) + (v1[0] * v1[0] + v1[1] * v1[1]) + (v1[2] * v1[2] + v1[3] * v1[3]);
;                     u32x4 w; w.x = pkh(v0[0], v0[1]); w.y = pkh(v0[2], v0[3]); w.z = pkh(v1[0], v1[1]); w.w = pkh(v1[2], v1[3]);
;                     *(u32x4*)(P + (size_t)row * NA + col0 + bj * HALF) = w;
;                 }
;                 if (stat && !dry) { sq += __shfl_xor(sq, 16); sq += __shfl_xor(sq, 32); if (fq == 0) atomicAdd(ssv + row, sq); }
.LBB0_202:
	v_cvt_pk_f16_f32 v104, v86, v87
	v_cvt_pk_f16_f32 v105, v88, v89
	v_cvt_pk_f16_f32 v106, v82, v83
	v_cvt_pk_f16_f32 v107, v84, v85
	s_and_b64 vcc, exec, s[6:7]
	global_store_dwordx4 v[102:103], v[104:107], off offset:256
	s_cbranch_vccnz .LBB0_206
	v_mul_f32_e32 v95, v95, v95
	v_mul_f32_e32 v85, v85, v85
	v_mul_f32_e32 v83, v83, v83
	v_fmac_f32_e32 v95, v94, v94
	v_mul_f32_e32 v94, v97, v97
	v_fmac_f32_e32 v85, v84, v84
	v_fmac_f32_e32 v83, v82, v82
	v_mul_f32_e32 v82, v87, v87
	v_mul_f32_e32 v84, v89, v89
	v_fmac_f32_e32 v94, v96, v96
	v_mul_f32_e32 v91, v91, v91
	v_fmac_f32_e32 v82, v86, v86
	v_fmac_f32_e32 v84, v88, v88
	v_add_f32_e32 v94, v95, v94
	v_fmac_f32_e32 v91, v90, v90
	v_add_f32_e32 v82, v82, v84
	v_and_b32_e32 v84, 64, v157
	v_add_f32_e32 v90, v91, v94
	v_mul_f32_e32 v91, v93, v93
	v_add_f32_e32 v82, v83, v82
	v_xor_b32_e32 v83, 16, v157
	v_add_u32_e32 v84, 64, v84
	v_fmac_f32_e32 v91, v92, v92
	v_cmp_lt_i32_e32 vcc, v83, v84
	v_add_f32_e32 v90, v91, v90
	v_add_f32_e32 v82, v85, v82
	v_cndmask_b32_e32 v83, v157, v83, vcc
	v_add_f32_e32 v82, v90, v82
	v_lshlrev_b32_e32 v83, 2, v83
	v_mov_b32_e32 v83, v82
	s_nop 1
	v_permlane16_swap_b32_e32 v82, v83
	v_add_f32_e32 v82, v82, v83
	v_xor_b32_e32 v83, 32, v157
	v_cmp_lt_i32_e32 vcc, v83, v84
	s_nop 1
	v_cndmask_b32_e32 v83, v157, v83, vcc
	v_lshlrev_b32_e32 v83, 2, v83
	v_mov_b32_e32 v83, v82
	s_nop 1
	v_permlane32_swap_b32_e32 v82, v83
	s_and_saveexec_b64 s[40:41], s[2:3]
	s_cbranch_execz .LBB0_205
	v_ashrrev_i32_e32 v99, 31, v98
	v_lshl_add_u64 v[84:85], v[98:99], 2, s[12:13]
	s_waitcnt lgkmcnt(0)
	v_add_f32_e32 v82, v82, v83
	global_atomic_add_f32 v[84:85], v82, off

; __device__ __forceinline__ unsigned pkh(float lo, float hi) { f32x2 v = {lo, hi}; h16x2 h = __builtin_convertvector(v, h16x2); return __builtin_bit_cast(unsigned, h); }
;     __device__ __forceinline__ void operator()(f32x4 (&acc)[2][2][4][2], const Unit& u, const Order& S, int wr, int wc, int fr_, int fq_, LAS unsigned char*, int) const {
;     ...
;                 for (int bj = 0; bj < 2; ++bj) {
;                     f32x4 v0 = acc[ai][bj][m][0] * sc, v1 = acc[ai][bj][m][1] * sc;
;                     if (act) { const f32x2 a0 = gelu_tanh2((f32x2){v0[0], v0[1]}), a1 = gelu_tanh2((f32x2){v0[2], v0[3]}), a2 = gelu_tanh2((f32x2){v1[0], v1[1]}), a3 = gelu_tanh2((f32x2){v1[2], v1[3]});
;                         v0 = (f32x4){a0.x, a0.y, a1.x, a1.y}; v1 = (f32x4){a2.x, a2.y, a3.x, a3.y}; }
;                     sq += (v0[0] * v0[0] + v0[1] * v0[1]) + (v0[2] * v0[2] + v0[3] * v0[3]) + (v1[0] * v1[0] + v1[1] * v1[1]) + (v1[2] * v1[2] + v1[3] * v1[3]);
;                     u32x4 w; w.x = pkh(v0[0], v0[1]); w.y = pkh(v0[2], v0[3]); w.z = pkh(v1[0], v1[1]); w.w = pkh(v1[2], v1[3]);
;                     *(u32x4*)(P + (size_t)row * NA + col0 + bj * HALF) = w;
;                 }
;                 if (stat && !dry) { sq += __shfl_xor(sq, 16); sq += __shfl_xor(sq, 32); if (fq == 0) atomicAdd(ssv + row, sq); }
.LBB0_210:
	v_cvt_pk_f16_f32 v88, v70, v71
	v_cvt_pk_f16_f32 v89, v72, v73
	v_cvt_pk_f16_f32 v90, v66, v67
	v_cvt_pk_f16_f32 v91, v68, v69
	s_and_b64 vcc, exec, s[6:7]
	global_store_dwordx4 v[86:87], v[88:91], off offset:256
	s_cbranch_vccnz .LBB0_214
	v_mul_f32_e32 v79, v79, v79
	v_mul_f32_e32 v69, v69, v69
	v_mul_f32_e32 v67, v67, v67
	v_fmac_f32_e32 v79, v78, v78
	v_mul_f32_e32 v78, v81, v81
	v_fmac_f32_e32 v69, v68, v68
	v_fmac_f32_e32 v67, v66, v66
	v_mul_f32_e32 v66, v71, v71
	v_mul_f32_e32 v68, v73, v73
	v_fmac_f32_e32 v78, v80, v80
	v_mul_f32_e32 v75, v75, v75
	v_fmac_f32_e32 v66, v70, v70
	v_fmac_f32_e32 v68, v72, v72
	v_add_f32_e32 v78, v79, v78
	v_fmac_f32_e32 v75, v74, v74
	v_add_f32_e32 v66, v66, v68
	v_and_b32_e32 v68, 64, v157
	v_add_f32_e32 v74, v75, v78
	v_mul_f32_e32 v75, v77, v77
	v_add_f32_e32 v66, v67, v66
	v_xor_b32_e32 v67, 16, v157
	v_add_u32_e32 v68, 64, v68
	v_fmac_f32_e32 v75, v76, v76
	v_cmp_lt_i32_e32 vcc, v67, v68
	v_add_f32_e32 v74, v75, v74
	v_add_f32_e32 v66, v69, v66
	v_cndmask_b32_e32 v67, v157, v67, vcc
	v_add_f32_e32 v66, v74, v66
	v_lshlrev_b32_e32 v67, 2, v67
	v_mov_b32_e32 v67, v66
	s_nop 1
	v_permlane16_swap_b32_e32 v66, v67
	v_add_f32_e32 v66, v66, v67
	v_xor_b32_e32 v67, 32, v157
	v_cmp_lt_i32_e32 vcc, v67, v68
	s_nop 1
	v_cndmask_b32_e32 v67, v157, v67, vcc
	v_lshlrev_b32_e32 v67, 2, v67
	v_mov_b32_e32 v67, v66
	s_nop 1
	v_permlane32_swap_b32_e32 v66, v67
	s_and_saveexec_b64 s[40:41], s[2:3]
	s_cbranch_execz .LBB0_213
	v_ashrrev_i32_e32 v83, 31, v82
	v_lshl_add_u64 v[68:69], v[82:83], 2, s[12:13]
	s_waitcnt lgkmcnt(0)
	v_add_f32_e32 v66, v66, v67
	global_atomic_add_f32 v[68:69], v66, off

; __device__ __forceinline__ unsigned pkh(float lo, float hi) { f32x2 v = {lo, hi}; h16x2 h = __builtin_convertvector(v, h16x2); return __builtin_bit_cast(unsigned, h); }
;     __device__ __forceinline__ void operator()(f32x4 (&acc)[2][2][4][2], const Unit& u, const Order& S, int wr, int wc, int fr_, int fq_, LAS unsigned char*, int) const {
;     ...
;                 for (int bj = 0; bj < 2; ++bj) {
;                     f32x4 v0 = acc[ai][bj][m][0] * sc, v1 = acc[ai][bj][m][1] * sc;
;                     if (act) { const f32x2 a0 = gelu_tanh2((f32x2){v0[0], v0[1]}), a1 = gelu_tanh2((f32x2){v0[2], v0[3]}), a2 = gelu_tanh2((f32x2){v1[0], v1[1]}), a3 = gelu_tanh2((f32x2){v1[2], v1[3]});
;                         v0 = (f32x4){a0.x, a0.y, a1.x, a1.y}; v1 = (f32x4){a2.x, a2.y, a3.x, a3.y}; }
;                     sq += (v0[0] * v0[0] + v0[1] * v0[1]) + (v0[2] * v0[2] + v0[3] * v0[3]) + (v1[0] * v1[0] + v1[1] * v1[1]) + (v1[2] * v1[2] + v1[3] * v1[3]);
;                     u32x4 w; w.x = pkh(v0[0], v0[1]); w.y = pkh(v0[2], v0[3]); w.z = pkh(v1[0], v1[1]); w.w = pkh(v1[2], v1[3]);
;                     *(u32x4*)(P + (size_t)row * NA + col0 + bj * HALF) = w;
;                 }
;                 if (stat && !dry) { sq += __shfl_xor(sq, 16); sq += __shfl_xor(sq, 32); if (fq == 0) atomicAdd(ssv + row, sq); }
.LBB0_218:
	v_cvt_pk_f16_f32 v72, v54, v55
	v_cvt_pk_f16_f32 v73, v56, v57
	v_cvt_pk_f16_f32 v74, v50, v51
	v_cvt_pk_f16_f32 v75, v52, v53
	s_and_b64 vcc, exec, s[6:7]
	global_store_dwordx4 v[70:71], v[72:75], off offset:256
	s_cbranch_vccnz .LBB0_222
	v_mul_f32_e32 v63, v63, v63
	v_mul_f32_e32 v53, v53, v53
	v_mul_f32_e32 v51, v51, v51
	v_fmac_f32_e32 v63, v62, v62
	v_mul_f32_e32 v62, v65, v65
	v_fmac_f32_e32 v53, v52, v52
	v_fmac_f32_e32 v51, v50, v50
	v_mul_f32_e32 v50, v55, v55
	v_mul_f32_e32 v52, v57, v57
	v_fmac_f32_e32 v62, v64, v64
	v_mul_f32_e32 v59, v59, v59
	v_fmac_f32_e32 v50, v54, v54
	v_fmac_f32_e32 v52, v56, v56
	v_add_f32_e32 v62, v63, v62
	v_fmac_f32_e32 v59, v58, v58
	v_add_f32_e32 v50, v50, v52
	v_and_b32_e32 v52, 64, v157
	v_add_f32_e32 v58, v59, v62
	v_mul_f32_e32 v59, v61, v61
	v_add_f32_e32 v50, v51, v50
	v_xor_b32_e32 v51, 16, v157
	v_add_u32_e32 v52, 64, v52
	v_fmac_f32_e32 v59, v60, v60
	v_cmp_lt_i32_e32 vcc, v51, v52
	v_add_f32_e32 v58, v59, v58
	v_add_f32_e32 v50, v53, v50
	v_cndmask_b32_e32 v51, v157, v51, vcc
	v_add_f32_e32 v50, v58, v50
	v_lshlrev_b32_e32 v51, 2, v51
	v_mov_b32_e32 v51, v50
	s_nop 1
	v_permlane16_swap_b32_e32 v50, v51
	v_add_f32_e32 v50, v50, v51
	v_xor_b32_e32 v51, 32, v157
	v_cmp_lt_i32_e32 vcc, v51, v52
	s_nop 1
	v_cndmask_b32_e32 v51, v157, v51, vcc
	v_lshlrev_b32_e32 v51, 2, v51
	v_mov_b32_e32 v51, v50
	s_nop 1
	v_permlane32_swap_b32_e32 v50, v51
	s_and_saveexec_b64 s[40:41], s[2:3]
	s_cbranch_execz .LBB0_221
	v_ashrrev_i32_e32 v67, 31, v66
	v_lshl_add_u64 v[52:53], v[66:67], 2, s[12:13]
	s_waitcnt lgkmcnt(0)
	v_add_f32_e32 v50, v50, v51
	global_atomic_add_f32 v[52:53], v50, off

; __device__ __forceinline__ unsigned pkh(float lo, float hi) { f32x2 v = {lo, hi}; h16x2 h = __builtin_convertvector(v, h16x2); return __builtin_bit_cast(unsigned, h); }
;     __device__ __forceinline__ void operator()(f32x4 (&acc)[2][2][4][2], const Unit& u, const Order& S, int wr, int wc, int fr_, int fq_, LAS unsigned char*, int) const {
;     ...
;                 for (int bj = 0; bj < 2; ++bj) {
;                     f32x4 v0 = acc[ai][bj][m][0] * sc, v1 = acc[ai][bj][m][1] * sc;
;                     if (act) { const f32x2 a0 = gelu_tanh2((f32x2){v0[0], v0[1]}), a1 = gelu_tanh2((f32x2){v0[2], v0[3]}), a2 = gelu_tanh2((f32x2){v1[0], v1[1]}), a3 = gelu_tanh2((f32x2){v1[2], v1[3]});
;                         v0 = (f32x4){a0.x, a0.y, a1.x, a1.y}; v1 = (f32x4){a2.x, a2.y, a3.x, a3.y}; }
;                     sq += (v0[0] * v0[0] + v0[1] * v0[1]) + (v0[2] * v0[2] + v0[3] * v0[3]) + (v1[0] * v1[0] + v1[1] * v1[1]) + (v1[2] * v1[2] + v1[3] * v1[3]);
;                     u32x4 w; w.x = pkh(v0[0], v0[1]); w.y = pkh(v0[2], v0[3]); w.z = pkh(v1[0], v1[1]); w.w = pkh(v1[2], v1[3]);
;                     *(u32x4*)(P + (size_t)row * NA + col0 + bj * HALF) = w;
;                 }
;                 if (stat && !dry) { sq += __shfl_xor(sq, 16); sq += __shfl_xor(sq, 32); if (fq == 0) atomicAdd(ssv + row, sq); }
.LBB0_226:
	v_cvt_pk_f16_f32 v56, v38, v39
	v_cvt_pk_f16_f32 v57, v40, v41
	v_cvt_pk_f16_f32 v58, v34, v35
	v_cvt_pk_f16_f32 v59, v36, v37
	s_and_b64 vcc, exec, s[6:7]
	global_store_dwordx4 v[54:55], v[56:59], off offset:256
	s_cbranch_vccnz .LBB0_230
	v_mul_f32_e32 v47, v47, v47
	v_mul_f32_e32 v37, v37, v37
	v_mul_f32_e32 v35, v35, v35
	v_fmac_f32_e32 v47, v46, v46
	v_mul_f32_e32 v46, v49, v49
	v_fmac_f32_e32 v37, v36, v36
	v_fmac_f32_e32 v35, v34, v34
	v_mul_f32_e32 v34, v39, v39
	v_mul_f32_e32 v36, v41, v41
	v_fmac_f32_e32 v46, v48, v48
	v_mul_f32_e32 v43, v43, v43
	v_fmac_f32_e32 v34, v38, v38
	v_fmac_f32_e32 v36, v40, v40
	v_add_f32_e32 v46, v47, v46
	v_fmac_f32_e32 v43, v42, v42
	v_add_f32_e32 v34, v34, v36
	v_and_b32_e32 v36, 64, v157
	v_add_f32_e32 v42, v43, v46
	v_mul_f32_e32 v43, v45, v45
	v_add_f32_e32 v34, v35, v34
	v_xor_b32_e32 v35, 16, v157
	v_add_u32_e32 v36, 64, v36
	v_fmac_f32_e32 v43, v44, v44
	v_cmp_lt_i32_e32 vcc, v35, v36
	v_add_f32_e32 v42, v43, v42
	v_add_f32_e32 v34, v37, v34
	v_cndmask_b32_e32 v35, v157, v35, vcc
	v_add_f32_e32 v34, v42, v34
	v_lshlrev_b32_e32 v35, 2, v35
	v_mov_b32_e32 v35, v34
	s_nop 1
	v_permlane16_swap_b32_e32 v34, v35
	v_add_f32_e32 v34, v34, v35
	v_xor_b32_e32 v35, 32, v157
	v_cmp_lt_i32_e32 vcc, v35, v36
	s_nop 1
	v_cndmask_b32_e32 v35, v157, v35, vcc
	v_lshlrev_b32_e32 v35, 2, v35
	v_mov_b32_e32 v35, v34
	s_nop 1
	v_permlane32_swap_b32_e32 v34, v35
	s_and_saveexec_b64 s[40:41], s[2:3]
	s_cbranch_execz .LBB0_229
	v_ashrrev_i32_e32 v51, 31, v50
	v_lshl_add_u64 v[36:37], v[50:51], 2, s[12:13]
	s_waitcnt lgkmcnt(0)
	v_add_f32_e32 v34, v34, v35
	global_atomic_add_f32 v[36:37], v34, off

; __device__ __forceinline__ unsigned pkh(float lo, float hi) { f32x2 v = {lo, hi}; h16x2 h = __builtin_convertvector(v, h16x2); return __builtin_bit_cast(unsigned, h); }
;     __device__ __forceinline__ void operator()(f32x4 (&acc)[2][2][4][2], const Unit& u, const Order& S, int wr, int wc, int fr_, int fq_, LAS unsigned char*, int) const {
;     ...
;                 for (int bj = 0; bj < 2; ++bj) {
;                     f32x4 v0 = acc[ai][bj][m][0] * sc, v1 = acc[ai][bj][m][1] * sc;
;                     if (act) { const f32x2 a0 = gelu_tanh2((f32x2){v0[0], v0[1]}), a1 = gelu_tanh2((f32x2){v0[2], v0[3]}), a2 = gelu_tanh2((f32x2){v1[0], v1[1]}), a3 = gelu_tanh2((f32x2){v1[2], v1[3]});
;                         v0 = (f32x4){a0.x, a0.y, a1.x, a1.y}; v1 = (f32x4){a2.x, a2.y, a3.x, a3.y}; }
;                     sq += (v0[0] * v0[0] + v0[1] * v0[1]) + (v0[2] * v0[2] + v0[3] * v0[3]) + (v1[0] * v1[0] + v1[1] * v1[1]) + (v1[2] * v1[2] + v1[3] * v1[3]);
;                     u32x4 w; w.x = pkh(v0[0], v0[1]); w.y = pkh(v0[2], v0[3]); w.z = pkh(v1[0], v1[1]); w.w = pkh(v1[2], v1[3]);
;                     *(u32x4*)(P + (size_t)row * NA + col0 + bj * HALF) = w;
;                 }
;                 if (stat && !dry) { sq += __shfl_xor(sq, 16); sq += __shfl_xor(sq, 32); if (fq == 0) atomicAdd(ssv + row, sq); }
.LBB0_234:
	v_cvt_pk_f16_f32 v40, v22, v23
	v_cvt_pk_f16_f32 v41, v24, v25
	v_cvt_pk_f16_f32 v42, v18, v19
	v_cvt_pk_f16_f32 v43, v20, v21
	s_and_b64 vcc, exec, s[6:7]
	global_store_dwordx4 v[38:39], v[40:43], off offset:256
	s_cbranch_vccnz .LBB0_238
	v_mul_f32_e32 v31, v31, v31
	v_mul_f32_e32 v21, v21, v21
	v_mul_f32_e32 v19, v19, v19
	v_fmac_f32_e32 v31, v30, v30
	v_mul_f32_e32 v30, v33, v33
	v_fmac_f32_e32 v21, v20, v20
	v_fmac_f32_e32 v19, v18, v18
	v_mul_f32_e32 v18, v23, v23
	v_mul_f32_e32 v20, v25, v25
	v_fmac_f32_e32 v30, v32, v32
	v_mul_f32_e32 v27, v27, v27
	v_fmac_f32_e32 v18, v22, v22
	v_fmac_f32_e32 v20, v24, v24
	v_add_f32_e32 v30, v31, v30
	v_fmac_f32_e32 v27, v26, v26
	v_add_f32_e32 v18, v18, v20
	v_and_b32_e32 v20, 64, v157
	v_add_f32_e32 v26, v27, v30
	v_mul_f32_e32 v27, v29, v29
	v_add_f32_e32 v18, v19, v18
	v_xor_b32_e32 v19, 16, v157
	v_add_u32_e32 v20, 64, v20
	v_fmac_f32_e32 v27, v28, v28
	v_cmp_lt_i32_e32 vcc, v19, v20
	v_add_f32_e32 v26, v27, v26
	v_add_f32_e32 v18, v21, v18
	v_cndmask_b32_e32 v19, v157, v19, vcc
	v_add_f32_e32 v18, v26, v18
	v_lshlrev_b32_e32 v19, 2, v19
	v_mov_b32_e32 v19, v18
	s_nop 1
	v_permlane16_swap_b32_e32 v18, v19
	v_add_f32_e32 v18, v18, v19
	v_xor_b32_e32 v19, 32, v157
	v_cmp_lt_i32_e32 vcc, v19, v20
	s_nop 1
	v_cndmask_b32_e32 v19, v157, v19, vcc
	v_lshlrev_b32_e32 v19, 2, v19
	v_mov_b32_e32 v19, v18
	s_nop 1
	v_permlane32_swap_b32_e32 v18, v19
	s_and_saveexec_b64 s[40:41], s[2:3]
	s_cbranch_execz .LBB0_237
	v_ashrrev_i32_e32 v35, 31, v34
	v_lshl_add_u64 v[20:21], v[34:35], 2, s[12:13]
	s_waitcnt lgkmcnt(0)
	v_add_f32_e32 v18, v18, v19
	global_atomic_add_f32 v[20:21], v18, off

; __device__ __forceinline__ void xattn_load_q(const f16_t* qp  , const float* gqm, int G, float maxgk, h16x8& q0, h16x8& q1, float& mb) {
;     const h16x8 r0v = *(const h16x8*)qp, r1v = *(const h16x8*)(qp + 32);
;     float q[16], ss = 0.f;
; #pragma unroll
;     for (int j = 0; j < 8; ++j) { q[j] = (float)r0v[j]; q[8 + j] = (float)r1v[j]; ss += q[j] * q[j] + q[8 + j] * q[8 + j]; }
;     ss += __shfl_xor(ss, 16); ss += __shfl_xor(ss, 32);
; template <bool Y8>
; __device__ __forceinline__ void xattn_chunk(const Frame& F, const Args& a, int chunk, const f16_t* P, int ldp, int qcol0, const float* gqm, f16_t* Y) {
;     ...
;     for (int hp = 0; hp < 2; ++hp) {
; #pragma unroll
;         for (int k = 0; k < 2; ++k) dma_kv_imgs(F.lds + k * 65536, F.lds + k * 65536 + 32768, KM + (size_t)(b * 4 + 2 * hp + k) * NMEM * HD, VM + (size_t)(b * 4 + 2 * hp + k) * NMEM * HD, F.wave, lane, HD);
;         const int head = 2 * hp + hsel;
;         h16x8 qa0, qa1, qb0, qb1; float mba, mbb;
;         xattn_load_q(P + (size_t)rowa * ldp + qcol0 + head * HD + 8 * G, gqm, G, maxgk, qa0, qa1, mba);
;         xattn_load_q(P + (size_t)rowb * ldp + qcol0 + head * HD + 8 * G, gqm, G, maxgk, qb0, qb1, mbb);
.LBB0_334:
	s_lshl_b32 s2, s14, 1
	s_or_b32 s2, s2, s43
	s_ashr_i32 s3, s2, 31
	s_lshl_b64 s[4:5], s[2:3], 15
	v_lshl_add_u64 v[2:3], v[90:91], 0, s[4:5]
	s_add_i32 s3, s20, 0
	v_lshl_add_u64 v[4:5], v[92:93], 0, s[4:5]
	v_lshl_add_u64 v[6:7], v[2:3], 0, v[100:101]
	s_mov_b32 s4, m0
	s_mov_b32 m0, s3
	s_nop 0
	global_load_lds_dwordx4 v[6:7], off
	s_mov_b32 m0, s4
	s_add_i32 s3, s20, s40
	v_lshl_add_u64 v[6:7], v[4:5], 0, v[100:101]
	s_mov_b32 s4, m0
	s_mov_b32 m0, s3
	s_nop 0
	global_load_lds_dwordx4 v[6:7], off
	s_mov_b32 m0, s4
	s_add_i32 s3, s34, 0
	v_lshl_add_u64 v[6:7], v[2:3], 0, v[102:103]
	s_mov_b32 s4, m0
	s_mov_b32 m0, s3
	s_nop 0
	global_load_lds_dwordx4 v[6:7], off
	s_mov_b32 m0, s4
	s_add_i32 s3, s34, s40
	v_lshl_add_u64 v[6:7], v[4:5], 0, v[102:103]
	s_mov_b32 s4, m0
	s_mov_b32 m0, s3
	s_nop 0
	global_load_lds_dwordx4 v[6:7], off
	s_mov_b32 m0, s4
	s_add_i32 s3, s35, 0
	v_lshl_add_u64 v[6:7], v[2:3], 0, v[104:105]
	s_mov_b32 s4, m0
	s_mov_b32 m0, s3
	s_nop 0
	global_load_lds_dwordx4 v[6:7], off
	s_mov_b32 m0, s4
	s_add_i32 s3, s35, s40
	v_lshl_add_u64 v[6:7], v[4:5], 0, v[104:105]
	s_mov_b32 s4, m0
	s_mov_b32 m0, s3
	s_nop 0
	global_load_lds_dwordx4 v[6:7], off
	s_mov_b32 m0, s4
	s_add_i32 s3, s36, 0
	v_lshl_add_u64 v[2:3], v[2:3], 0, v[106:107]
	s_mov_b32 s4, m0
	s_mov_b32 m0, s3
	s_nop 0
	global_load_lds_dwordx4 v[2:3], off
	s_mov_b32 m0, s4
	s_add_i32 s3, s36, s40
	s_or_b32 s2, s2, 1
	v_lshl_add_u64 v[2:3], v[4:5], 0, v[106:107]
	s_mov_b32 s4, m0
	s_mov_b32 m0, s3
	s_nop 0
	global_load_lds_dwordx4 v[2:3], off
	s_mov_b32 m0, s4
	s_ashr_i32 s3, s2, 31
	s_lshl_b64 s[2:3], s[2:3], 15
	v_lshl_add_u64 v[2:3], v[90:91], 0, s[2:3]
	v_lshl_add_u64 v[4:5], v[92:93], 0, s[2:3]
	s_add_i32 s2, 0, 0x10000
	v_lshl_add_u64 v[6:7], v[2:3], 0, v[100:101]
	s_add_i32 s3, s20, s2
	s_mov_b32 s4, m0
	s_mov_b32 m0, s3
	s_nop 0
	global_load_lds_dwordx4 v[6:7], off
	s_mov_b32 m0, s4
	v_lshl_add_u64 v[6:7], v[4:5], 0, v[100:101]
	s_add_i32 s3, s20, s41
	s_mov_b32 s4, m0
	s_mov_b32 m0, s3
	s_nop 0
	global_load_lds_dwordx4 v[6:7], off
	s_mov_b32 m0, s4
	v_lshl_add_u64 v[6:7], v[2:3], 0, v[102:103]
	s_add_i32 s3, s34, s2
	s_mov_b32 s4, m0
	s_mov_b32 m0, s3
	s_nop 0
	global_load_lds_dwordx4 v[6:7], off
	s_mov_b32 m0, s4
	v_lshl_add_u64 v[6:7], v[4:5], 0, v[102:103]
	s_add_i32 s3, s34, s41
	s_mov_b32 s4, m0
	s_mov_b32 m0, s3
	s_nop 0
	global_load_lds_dwordx4 v[6:7], off
	s_mov_b32 m0, s4
	v_lshl_add_u64 v[6:7], v[2:3], 0, v[104:105]
	s_add_i32 s3, s35, s2
	s_mov_b32 s4, m0
	s_mov_b32 m0, s3
	s_nop 0
	global_load_lds_dwordx4 v[6:7], off
	s_mov_b32 m0, s4
	v_lshl_add_u64 v[6:7], v[4:5], 0, v[104:105]
	s_add_i32 s3, s35, s41
	s_mov_b32 s4, m0
	s_mov_b32 m0, s3
	s_nop 0
	global_load_lds_dwordx4 v[6:7], off
	s_mov_b32 m0, s4
	s_add_i32 s2, s36, s2
	v_lshl_add_u64 v[2:3], v[2:3], 0, v[106:107]
	s_mov_b32 s3, m0
	s_mov_b32 m0, s2
	s_nop 0
	global_load_lds_dwordx4 v[2:3], off
	s_mov_b32 m0, s3
	s_add_i32 s2, s36, s41
	v_lshl_add_u64 v[2:3], v[4:5], 0, v[106:107]
	s_mov_b32 s3, m0
	s_mov_b32 m0, s2
	s_nop 0
	global_load_lds_dwordx4 v[2:3], off
	s_mov_b32 m0, s3
	s_lshl_b32 s2, s14, 7
	s_add_i32 s2, s2, s31
	s_lshl_b32 s14, s2, 1
	v_lshl_add_u64 v[10:11], v[30:31], 0, s[14:15]
	global_load_dwordx4 v[2:5], v[10:11], off offset:3136
	v_lshl_add_u64 v[12:13], v[32:33], 0, s[14:15]
	global_load_dwordx4 v[6:9], v[12:13], off offset:3136
	global_load_dwordx4 v[44:47], v[10:11], off offset:3072
	global_load_dwordx4 v[48:51], v[12:13], off offset:3072
	s_nop 0
	global_load_dwordx4 v[10:13], v[94:95], off offset:144
	global_load_dwordx4 v[14:17], v[94:95], off offset:128
	global_load_dwordx4 v[18:21], v[94:95], off offset:16
	global_load_dwordx4 v[22:25], v[94:95], off
	s_waitcnt vmcnt(0)
	s_barrier
	s_waitcnt vmcnt(6)
	v_cvt_f32_f16_e32 v26, v9
	v_cvt_f32_f16_sdwa v27, v9 dst_sel:DWORD dst_unused:UNUSED_PAD src0_sel:WORD_1
	v_cvt_f32_f16_e32 v28, v8
	v_cvt_f32_f16_sdwa v29, v8 dst_sel:DWORD dst_unused:UNUSED_PAD src0_sel:WORD_1
	v_cvt_f32_f16_e32 v56, v2
	v_cvt_f32_f16_sdwa v57, v2 dst_sel:DWORD dst_unused:UNUSED_PAD src0_sel:WORD_1
	v_cvt_f32_f16_e32 v8, v3
	v_cvt_f32_f16_sdwa v9, v3 dst_sel:DWORD dst_unused:UNUSED_PAD src0_sel:WORD_1
	s_waitcnt vmcnt(5)
	v_cvt_f32_f16_e32 v64, v44
	v_cvt_f32_f16_sdwa v65, v44 dst_sel:DWORD dst_unused:UNUSED_PAD src0_sel:WORD_1
	v_cvt_f32_f16_e32 v60, v47
	v_cvt_f32_f16_sdwa v61, v47 dst_sel:DWORD dst_unused:UNUSED_PAD src0_sel:WORD_1
	v_cvt_f32_f16_e32 v62, v46
	v_cvt_f32_f16_sdwa v63, v46 dst_sel:DWORD dst_unused:UNUSED_PAD src0_sel:WORD_1
	v_cvt_f32_f16_e32 v46, v45
	v_cvt_f32_f16_sdwa v47, v45 dst_sel:DWORD dst_unused:UNUSED_PAD src0_sel:WORD_1
	v_cvt_f32_f16_e32 v54, v4
	v_cvt_f32_f16_sdwa v55, v4 dst_sel:DWORD dst_unused:UNUSED_PAD src0_sel:WORD_1
	v_pk_mul_f32 v[2:3], v[56:57], v[56:57]
	v_cvt_f32_f16_e32 v52, v5
	v_cvt_f32_f16_sdwa v53, v5 dst_sel:DWORD dst_unused:UNUSED_PAD src0_sel:WORD_1
	v_pk_mul_f32 v[66:67], v[8:9], v[8:9]
	v_pk_fma_f32 v[2:3], v[64:65], v[64:65], v[2:3]
	v_pk_fma_f32 v[66:67], v[46:47], v[46:47], v[66:67]
	v_add_f32_e32 v2, v2, v3
	v_pk_mul_f32 v[44:45], v[54:55], v[54:55]
	v_add_f32_e32 v2, v66, v2
	v_pk_fma_f32 v[44:45], v[62:63], v[62:63], v[44:45]
	v_add_f32_e32 v2, v67, v2
	v_pk_mul_f32 v[4:5], v[52:53], v[52:53]
	v_add_f32_e32 v2, v44, v2
	v_pk_fma_f32 v[4:5], v[60:61], v[60:61], v[4:5]
	v_add_f32_e32 v2, v45, v2
	v_add_f32_e32 v2, v4, v2
	v_add_f32_e32 v2, v5, v2
	ds_bpermute_b32 v3, v40, v2
	s_waitcnt vmcnt(4)
	v_cvt_f32_f16_e32 v44, v51
	v_cvt_f32_f16_sdwa v45, v51 dst_sel:DWORD dst_unused:UNUSED_PAD src0_sel:WORD_1
	v_cvt_f32_f16_e32 v66, v50
	v_cvt_f32_f16_sdwa v67, v50 dst_sel:DWORD dst_unused:UNUSED_PAD src0_sel:WORD_1
	s_waitcnt lgkmcnt(0)
; __device__ __forceinline__ void xattn_load_q(const f16_t* qp  , const float* gqm, int G, float maxgk, h16x8& q0, h16x8& q1, float& mb) {
;     ...
;     for (int j = 0; j < 8; ++j) { q[j] = (float)r0v[j]; q[8 + j] = (float)r1v[j]; ss += q[j] * q[j] + q[8 + j] * q[8 + j]; }
;     ss += __shfl_xor(ss, 16); ss += __shfl_xor(ss, 32);
;     const float rn = 1.0f / sqrtf(ss * (1.0f / HD) + EPS);
;     float n2 = 0.f;
; #pragma unroll
;     for (int j = 0; j < 8; ++j) { q[j] *= rn * gqm[8 * G + j]; q[8 + j] *= rn * gqm[32 + 8 * G + j]; n2 += q[j] * q[j] + q[8 + j] * q[8 + j]; }
;     n2 += __shfl_xor(n2, 16); n2 += __shfl_xor(n2, 32);
;     mb = (sqrtf(n2) * maxgk - BOUND_SHIFT) * LOG2E;
	v_add_f32_e32 v2, v2, v3
	v_mov_b32_e32 v3, v2
	s_nop 1
	v_permlane32_swap_b32_e32 v2, v3
	v_cvt_f32_f16_e32 v50, v49
	v_cvt_f32_f16_sdwa v51, v49 dst_sel:DWORD dst_unused:UNUSED_PAD src0_sel:WORD_1
	v_cvt_f32_f16_e32 v38, v7
	v_cvt_f32_f16_sdwa v39, v7 dst_sel:DWORD dst_unused:UNUSED_PAD src0_sel:WORD_1
	s_waitcnt lgkmcnt(0)
	v_add_f32_e32 v2, v2, v3
	v_fmamk_f32 v2, v2, 0x3c800000, v147
	v_mul_f32_e32 v3, 0x4f800000, v2
	v_cmp_gt_f32_e32 vcc, s38, v2
	v_pk_mul_f32 v[4:5], v[28:29], v[28:29]
	v_cvt_f32_f16_e32 v58, v6
	v_cndmask_b32_e32 v43, v2, v3, vcc
	v_sqrt_f32_e32 v49, v43
	v_pk_mul_f32 v[2:3], v[26:27], v[26:27]
	v_cvt_f32_f16_sdwa v59, v6 dst_sel:DWORD dst_unused:UNUSED_PAD src0_sel:WORD_1
	v_pk_fma_f32 v[68:69], v[44:45], v[44:45], v[2:3]
	v_add_u32_e32 v2, -1, v49
	v_add_u32_e32 v3, 1, v49
	v_fma_f32 v70, -v2, v49, v43
	v_fma_f32 v71, -v3, v49, v43
	v_cmp_ge_f32_e64 s[2:3], 0, v70
	v_pk_mul_f32 v[6:7], v[58:59], v[58:59]
	s_nop 0
	v_cndmask_b32_e64 v2, v49, v2, s[2:3]
	v_cmp_lt_f32_e64 s[2:3], 0, v71
	v_pk_fma_f32 v[70:71], v[66:67], v[66:67], v[4:5]
	s_nop 0
	v_cndmask_b32_e64 v2, v2, v3, s[2:3]
	v_mul_f32_e32 v3, 0x37800000, v2
	v_cndmask_b32_e32 v2, v2, v3, vcc
	v_cmp_class_f32_e32 vcc, v43, v148
	s_nop 1
	v_cndmask_b32_e32 v43, v2, v43, vcc
	v_div_scale_f32 v49, s[2:3], v43, v43, 1.0
	v_rcp_f32_e32 v74, v49
	v_pk_mul_f32 v[2:3], v[38:39], v[38:39]
	s_nop 0
	v_pk_fma_f32 v[72:73], v[50:51], v[50:51], v[2:3]
	v_fma_f32 v2, -v49, v74, 1.0
	v_fmac_f32_e32 v74, v2, v74
	v_div_scale_f32 v2, vcc, 1.0, v43, 1.0
	v_mul_f32_e32 v3, v2, v74
	v_fma_f32 v4, -v49, v3, v2
	v_fmac_f32_e32 v3, v4, v74
	v_fma_f32 v2, -v49, v3, v2
	v_div_fmas_f32 v2, v2, v74, v3
	v_div_fixup_f32 v74, v2, v43, 1.0
	s_waitcnt vmcnt(3)
	v_pk_mul_f32 v[2:3], v[12:13], v[74:75] op_sel_hi:[1,0]
	s_nop 0
	v_pk_mul_f32 v[52:53], v[2:3], v[52:53]
	s_nop 0
	v_pk_mul_f32 v[2:3], v[52:53], s[16:17] op_sel_hi:[1,0]
	s_nop 0
	v_cvt_pk_f16_f32 v5, v2, v3
	v_pk_mul_f32 v[2:3], v[10:11], v[74:75] op_sel_hi:[1,0]
	s_nop 0
	v_pk_mul_f32 v[54:55], v[2:3], v[54:55]
	s_nop 0
	v_pk_mul_f32 v[2:3], v[54:55], s[16:17] op_sel_hi:[1,0]
	s_nop 0
	v_cvt_pk_f16_f32 v4, v2, v3
	s_waitcnt vmcnt(2)
	v_pk_mul_f32 v[2:3], v[16:17], v[74:75] op_sel_hi:[1,0]
	s_nop 0
	v_pk_mul_f32 v[76:77], v[2:3], v[8:9]
	v_pk_mul_f32 v[8:9], v[14:15], v[74:75] op_sel_hi:[1,0]
	v_pk_mul_f32 v[2:3], v[76:77], s[16:17] op_sel_hi:[1,0]
	v_pk_mul_f32 v[56:57], v[8:9], v[56:57]
	v_cvt_pk_f16_f32 v3, v2, v3
	v_pk_mul_f32 v[8:9], v[56:57], s[16:17] op_sel_hi:[1,0]
	s_nop 0
	v_cvt_pk_f16_f32 v2, v8, v9
	s_waitcnt vmcnt(1)
	v_pk_mul_f32 v[8:9], v[20:21], v[74:75] op_sel_hi:[1,0]
	s_nop 0
	v_pk_mul_f32 v[60:61], v[8:9], v[60:61]
	s_nop 0
	v_pk_mul_f32 v[8:9], v[60:61], s[16:17] op_sel_hi:[1,0]
	v_pk_mul_f32 v[60:61], v[60:61], v[60:61]
	v_cvt_pk_f16_f32 v9, v8, v9
	v_pk_fma_f32 v[52:53], v[52:53], v[52:53], v[60:61]
	v_pk_mul_f32 v[60:61], v[18:19], v[74:75] op_sel_hi:[1,0]
	s_nop 0
	v_pk_mul_f32 v[60:61], v[60:61], v[62:63]
	s_nop 0
	v_pk_mul_f32 v[62:63], v[60:61], v[60:61]
	s_nop 0
	v_pk_fma_f32 v[54:55], v[54:55], v[54:55], v[62:63]
	s_waitcnt vmcnt(0)
	v_pk_mul_f32 v[62:63], v[24:25], v[74:75] op_sel_hi:[1,0]
	v_pk_mul_f32 v[74:75], v[22:23], v[74:75] op_sel_hi:[1,0]
	v_pk_mul_f32 v[46:47], v[62:63], v[46:47]
	s_nop 0
	v_pk_mul_f32 v[62:63], v[46:47], v[46:47]
	s_nop 0
	v_pk_fma_f32 v[62:63], v[76:77], v[76:77], v[62:63]
	v_cvt_f32_f16_e32 v76, v48
	v_cvt_f32_f16_sdwa v77, v48 dst_sel:DWORD dst_unused:UNUSED_PAD src0_sel:WORD_1
	v_pk_mul_f32 v[48:49], v[74:75], v[64:65]
	v_pk_fma_f32 v[6:7], v[76:77], v[76:77], v[6:7]
	v_pk_mul_f32 v[64:65], v[48:49], v[48:49]
	v_add_f32_e32 v6, v6, v7
	v_pk_fma_f32 v[56:57], v[56:57], v[56:57], v[64:65]
	v_add_f32_e32 v6, v72, v6
	v_add_f32_e32 v8, v56, v57
	v_add_f32_e32 v8, v62, v8
	v_add_f32_e32 v8, v63, v8
	v_add_f32_e32 v6, v73, v6
	v_add_f32_e32 v8, v54, v8
	v_add_f32_e32 v6, v70, v6
	v_add_f32_e32 v8, v55, v8
	v_add_f32_e32 v6, v71, v6
	v_add_f32_e32 v8, v52, v8
	v_add_f32_e32 v6, v68, v6
	v_add_f32_e32 v43, v53, v8
	v_add_f32_e32 v53, v69, v6
	ds_bpermute_b32 v54, v40, v53
	ds_bpermute_b32 v52, v40, v43
	v_pk_mul_f32 v[6:7], v[60:61], s[16:17] op_sel_hi:[1,0]
	s_waitcnt lgkmcnt(1)
	v_add_f32_e32 v53, v53, v54
	v_mov_b32_e32 v54, v53
	s_nop 1
	v_permlane32_swap_b32_e32 v53, v54
	v_cvt_pk_f16_f32 v8, v6, v7
	s_waitcnt lgkmcnt(1)
	v_add_f32_e32 v43, v43, v52
	v_pk_mul_f32 v[6:7], v[46:47], s[16:17] op_sel_hi:[1,0]
	v_mov_b32_e32 v52, v43
	s_nop 1
	v_permlane32_swap_b32_e32 v43, v52
	s_waitcnt lgkmcnt(1)
	v_add_f32_e32 v46, v53, v54
	v_fmamk_f32 v46, v46, 0x3c800000, v147
	v_mul_f32_e32 v47, 0x4f800000, v46
	v_cmp_gt_f32_e32 vcc, s38, v46
	v_cvt_pk_f16_f32 v7, v6, v7
	s_waitcnt lgkmcnt(0)
; template <bool CAUSAL, bool SHARED> ...
;     ...
;     ka[0] = *(LAS const h16x8*)(Ka + kof0); ka[1] = *(LAS const h16x8*)(Ka + kof1); ka[2] = *(LAS const h16x8*)(Ka + 2048 + kof0); ka[3] = *(LAS const h16x8*)(Ka + 2048 + kof1);
;     if (!SHARED) { kb[0] = *(LAS const h16x8*)(Kb + kof0); kb[1] = *(LAS const h16x8*)(Kb + kof1); kb[2] = *(LAS const h16x8*)(Kb + 2048 + kof0); kb[3] = *(LAS const h16x8*)(Kb + 2048 + kof1); }
;     for (int ks = 0; ks < nsteps; ++ks) {
;         LAS const unsigned char* va = Va + ks * 4096 + vrow; LAS const unsigned char* vb = Vb + ks * 4096 + vrow;
;         h16x4 fal[4], fah[4], fbl[4], fbh[4];
; #pragma unroll
;         for (int dt = 0; dt < 4; ++dt) { fal[dt] = vtr(va + ((dt ^ sw) << 5)); fah[dt] = vtr(va + 2048 + ((dt ^ sw) << 5));
;             if (!SHARED) { fbl[dt] = vtr(vb + ((dt ^ sw) << 5)); fbh[dt] = vtr(vb + 2048 + ((dt ^ sw) << 5)); } }
;         __builtin_amdgcn_sched_barrier(0);
;         f32x4 sa0, sa1, sb0, sb1;
;         sa0 = __builtin_amdgcn_mfma_f32_16x16x32_f16(ka[0], qa0, nma, 0, 0, 0); sb0 = __builtin_amdgcn_mfma_f32_16x16x32_f16(SHARED ? ka[0] : kb[0], qb0, nmb, 0, 0, 0);
;         sa1 = __builtin_amdgcn_mfma_f32_16x16x32_f16(ka[2], qa0, nma, 0, 0, 0); sb1 = __builtin_amdgcn_mfma_f32_16x16x32_f16(SHARED ? ka[2] : kb[2], qb0, nmb, 0, 0, 0);
;         sa0 = __builtin_amdgcn_mfma_f32_16x16x32_f16(ka[1], qa1, sa0, 0, 0, 0); sb0 = __builtin_amdgcn_mfma_f32_16x16x32_f16(SHARED ? ka[1] : kb[1], qb1, sb0, 0, 0, 0);
; __device__ __forceinline__ void xattn_load_q(const f16_t* qp  , const float* gqm, int G, float maxgk, h16x8& q0, h16x8& q1, float& mb) {
;     ...
;     const float rn = 1.0f / sqrtf(ss * (1.0f / HD) + EPS);
;     float n2 = 0.f;
; #pragma unroll
;     for (int j = 0; j < 8; ++j) { q[j] *= rn * gqm[8 * G + j]; q[8 + j] *= rn * gqm[32 + 8 * G + j]; n2 += q[j] * q[j] + q[8 + j] * q[8 + j]; }
;     n2 += __shfl_xor(n2, 16); n2 += __shfl_xor(n2, 32);
;     mb = (sqrtf(n2) * maxgk - BOUND_SHIFT) * LOG2E;
;     const float c = 0.125f * LOG2E;
;     u32x4 w0, w1;
;     w0.x = pkh(q[0] * c, q[1] * c); w0.y = pkh(q[2] * c, q[3] * c); w0.z = pkh(q[4] * c, q[5] * c); w0.w = pkh(q[6] * c, q[7] * c);
;     w1.x = pkh(q[8] * c, q[9] * c); w1.y = pkh(q[10] * c, q[11] * c); w1.z = pkh(q[12] * c, q[13] * c); w1.w = pkh(q[14] * c, q[15] * c);
;     q0 = __builtin_bit_cast(h16x8, w0); q1 = __builtin_bit_cast(h16x8, w1);
	v_add_f32_e32 v6, v43, v52
	v_cndmask_b32_e32 v46, v46, v47, vcc
	v_sqrt_f32_e32 v47, v46
	v_mul_f32_e32 v43, 0x4f800000, v6
	v_cmp_gt_f32_e64 s[2:3], s38, v6
	s_nop 1
	v_cndmask_b32_e64 v43, v6, v43, s[2:3]
	v_add_u32_e32 v6, -1, v47
	v_fma_f32 v52, -v6, v47, v46
	v_cmp_ge_f32_e64 s[4:5], 0, v52
	v_add_u32_e32 v52, 1, v47
	v_sqrt_f32_e32 v54, v43
	v_cndmask_b32_e64 v6, v47, v6, s[4:5]
	v_fma_f32 v47, -v52, v47, v46
	v_cmp_lt_f32_e64 s[4:5], 0, v47
	s_nop 1
	v_cndmask_b32_e64 v6, v6, v52, s[4:5]
	v_mul_f32_e32 v47, 0x37800000, v6
	v_cndmask_b32_e32 v6, v6, v47, vcc
	v_cmp_class_f32_e32 vcc, v46, v148
	s_nop 1
	v_cndmask_b32_e32 v52, v6, v46, vcc
	v_div_scale_f32 v53, s[4:5], v52, v52, 1.0
	v_rcp_f32_e32 v55, v53
	v_pk_mul_f32 v[46:47], v[48:49], s[16:17] op_sel_hi:[1,0]
	s_nop 0
	v_cvt_pk_f16_f32 v6, v46, v47
	v_fma_f32 v46, -v53, v55, 1.0
	v_fmac_f32_e32 v55, v46, v55
	v_div_scale_f32 v46, vcc, 1.0, v52, 1.0
	v_mul_f32_e32 v48, v46, v55
	v_fma_f32 v49, -v53, v48, v46
	v_fmac_f32_e32 v48, v49, v55
	v_fma_f32 v46, -v53, v48, v46
	v_div_fmas_f32 v46, v46, v55, v48
	v_add_u32_e32 v47, -1, v54
	v_div_fixup_f32 v46, v46, v52, 1.0
	v_pk_mul_f32 v[22:23], v[22:23], v[46:47] op_sel_hi:[1,0]
	v_pk_mul_f32 v[14:15], v[14:15], v[46:47] op_sel_hi:[1,0]
	v_pk_mul_f32 v[22:23], v[22:23], v[76:77]
	v_pk_mul_f32 v[24:25], v[24:25], v[46:47] op_sel_hi:[1,0]
	v_pk_mul_f32 v[48:49], v[22:23], v[22:23]
	v_pk_mul_f32 v[52:53], v[14:15], v[58:59]
	v_pk_mul_f32 v[24:25], v[24:25], v[50:51]
	v_pk_mul_f32 v[16:17], v[16:17], v[46:47] op_sel_hi:[1,0]
	v_pk_fma_f32 v[14:15], v[52:53], v[52:53], v[48:49]
	v_pk_mul_f32 v[38:39], v[16:17], v[38:39]
	v_pk_mul_f32 v[16:17], v[24:25], v[24:25]
	v_pk_mul_f32 v[18:19], v[18:19], v[46:47] op_sel_hi:[1,0]
	v_pk_fma_f32 v[16:17], v[38:39], v[38:39], v[16:17]
	v_pk_mul_f32 v[18:19], v[18:19], v[66:67]
	v_pk_mul_f32 v[10:11], v[10:11], v[46:47] op_sel_hi:[1,0]
	v_add_f32_e32 v14, v14, v15
	v_pk_mul_f32 v[10:11], v[10:11], v[28:29]
	v_pk_mul_f32 v[28:29], v[18:19], v[18:19]
	v_pk_mul_f32 v[20:21], v[20:21], v[46:47] op_sel_hi:[1,0]
	v_add_f32_e32 v14, v16, v14
	v_pk_fma_f32 v[28:29], v[10:11], v[10:11], v[28:29]
	v_pk_mul_f32 v[20:21], v[20:21], v[44:45]
	v_pk_mul_f32 v[12:13], v[12:13], v[46:47] op_sel_hi:[1,0]
	v_add_f32_e32 v14, v17, v14
	v_pk_mul_f32 v[12:13], v[12:13], v[26:27]
	v_pk_mul_f32 v[26:27], v[20:21], v[20:21]
	v_add_f32_e32 v14, v28, v14
	v_pk_fma_f32 v[26:27], v[12:13], v[12:13], v[26:27]
	v_add_f32_e32 v14, v29, v14
	v_add_f32_e32 v14, v26, v14
	v_add_f32_e32 v14, v27, v14
	ds_bpermute_b32 v15, v40, v14
	v_fma_f32 v16, -v47, v54, v43
	v_add_u32_e32 v17, 1, v54
	v_cmp_ge_f32_e32 vcc, 0, v16
	v_fma_f32 v26, -v17, v54, v43
	s_waitcnt lgkmcnt(0)
	v_add_f32_e32 v14, v14, v15
	v_mov_b32_e32 v15, v14
	s_nop 1
	v_permlane32_swap_b32_e32 v14, v15
	v_cndmask_b32_e32 v16, v54, v47, vcc
	v_cmp_lt_f32_e32 vcc, 0, v26
	v_pk_mul_f32 v[10:11], v[10:11], s[16:17] op_sel_hi:[1,0]
	s_waitcnt lgkmcnt(0)
	v_add_f32_e32 v14, v14, v15
	v_cndmask_b32_e32 v16, v16, v17, vcc
	v_mul_f32_e32 v15, 0x4f800000, v14
	v_cmp_gt_f32_e32 vcc, s38, v14
	v_mul_f32_e32 v17, 0x37800000, v16
	v_cndmask_b32_e64 v16, v16, v17, s[2:3]
	v_cndmask_b32_e32 v14, v14, v15, vcc
	v_sqrt_f32_e32 v15, v14
	v_cmp_class_f32_e64 s[2:3], v43, v148
	s_nop 1
	v_cndmask_b32_e64 v26, v16, v43, s[2:3]
	v_add_u32_e32 v16, -1, v15
	v_fma_f32 v17, -v16, v15, v14
	v_cmp_ge_f32_e64 s[2:3], 0, v17
	v_add_u32_e32 v17, 1, v15
	s_nop 0
	v_cndmask_b32_e64 v16, v15, v16, s[2:3]
	v_fma_f32 v15, -v17, v15, v14
	v_cmp_lt_f32_e64 s[2:3], 0, v15
	s_nop 1
	v_cndmask_b32_e64 v15, v16, v17, s[2:3]
	v_mul_f32_e32 v16, 0x37800000, v15
	v_cndmask_b32_e32 v15, v15, v16, vcc
	v_cmp_class_f32_e32 vcc, v14, v148
	v_pk_mul_f32 v[16:17], v[24:25], s[16:17] op_sel_hi:[1,0]
	s_nop 0
	v_cndmask_b32_e32 v27, v15, v14, vcc
	v_pk_mul_f32 v[14:15], v[22:23], s[16:17] op_sel_hi:[1,0]
	s_nop 0
	v_cvt_pk_f16_f32 v14, v14, v15
	v_cvt_pk_f16_f32 v15, v16, v17
	v_pk_mul_f32 v[16:17], v[18:19], s[16:17] op_sel_hi:[1,0]
	v_pk_mul_f32 v[18:19], v[20:21], s[16:17] op_sel_hi:[1,0]
	v_cvt_pk_f16_f32 v16, v16, v17
	v_cvt_pk_f16_f32 v17, v18, v19
	v_pk_mul_f32 v[18:19], v[52:53], s[16:17] op_sel_hi:[1,0]
	v_pk_mul_f32 v[20:21], v[38:39], s[16:17] op_sel_hi:[1,0]
	v_cvt_pk_f16_f32 v18, v18, v19
	v_cvt_pk_f16_f32 v19, v20, v21
	v_cvt_pk_f16_f32 v20, v10, v11
	v_pk_mul_f32 v[10:11], v[12:13], s[16:17] op_sel_hi:[1,0]
	v_add_u32_e32 v38, v142, v141
	v_cvt_pk_f16_f32 v21, v10, v11
	v_fma_f32 v10, v42, v26, -4.0
	v_mul_f32_e32 v22, 0xbfb8aa3b, v10
	ds_read_b128 v[10:13], v149
	ds_read_b128 v[44:47], v149 offset:2048
	ds_read_b128 v[48:51], v150
	ds_read_b128 v[52:55], v150 offset:2048
	ds_read_b64_tr_b16 v[56:57], v38 offset:32768
	ds_read_b64_tr_b16 v[58:59], v38 offset:34816
	ds_read_b64_tr_b16 v[60:61], v151 offset:32768
	ds_read_b64_tr_b16 v[62:63], v151 offset:34816
	ds_read_b64_tr_b16 v[64:65], v152 offset:32768
	ds_read_b64_tr_b16 v[66:67], v152 offset:34816
	ds_read_b64_tr_b16 v[68:69], v153 offset:32768
	ds_read_b64_tr_b16 v[70:71], v153 offset:34816
	v_fma_f32 v26, v42, v27, -4.0
	v_mul_f32_e32 v26, 0xbfb8aa3b, v26
	v_mov_b32_e32 v23, v22
	v_mov_b32_e32 v24, v22
	v_mov_b32_e32 v25, v22
	v_mov_b32_e32 v27, v26
	v_mov_b32_e32 v28, v26
	v_mov_b32_e32 v29, v26
	s_waitcnt lgkmcnt(11)
	v_mfma_f32_16x16x32_f16 v[72:75], v[10:13], v[6:9], v[22:25]
	v_mfma_f32_16x16x32_f16 v[10:13], v[10:13], v[14:17], v[26:29]
	s_waitcnt lgkmcnt(10)
	v_mfma_f32_16x16x32_f16 v[108:111], v[44:47], v[6:9], v[22:25]
	v_mfma_f32_16x16x32_f16 v[44:47], v[44:47], v[14:17], v[26:29]
	s_waitcnt lgkmcnt(9)
; #define LAS __attribute__((address_space(3)))
; template <bool CAUSAL, bool SHARED> ...
;     ...
;     for (int ks = 0; ks < nsteps; ++ks) {
;         LAS const unsigned char* va = Va + ks * 4096 + vrow; LAS const unsigned char* vb = Vb + ks * 4096 + vrow;
;         h16x4 fal[4], fah[4], fbl[4], fbh[4];
; #pragma unroll
;         for (int dt = 0; dt < 4; ++dt) { fal[dt] = vtr(va + ((dt ^ sw) << 5)); fah[dt] = vtr(va + 2048 + ((dt ^ sw) << 5));
;             if (!SHARED) { fbl[dt] = vtr(vb + ((dt ^ sw) << 5)); fbh[dt] = vtr(vb + 2048 + ((dt ^ sw) << 5)); } }
;         __builtin_amdgcn_sched_barrier(0);
;         f32x4 sa0, sa1, sb0, sb1;
;         sa0 = __builtin_amdgcn_mfma_f32_16x16x32_f16(ka[0], qa0, nma, 0, 0, 0); sb0 = __builtin_amdgcn_mfma_f32_16x16x32_f16(SHARED ? ka[0] : kb[0], qb0, nmb, 0, 0, 0);
;         sa1 = __builtin_amdgcn_mfma_f32_16x16x32_f16(ka[2], qa0, nma, 0, 0, 0); sb1 = __builtin_amdgcn_mfma_f32_16x16x32_f16(SHARED ? ka[2] : kb[2], qb0, nmb, 0, 0, 0);
;         sa0 = __builtin_amdgcn_mfma_f32_16x16x32_f16(ka[1], qa1, sa0, 0, 0, 0); sb0 = __builtin_amdgcn_mfma_f32_16x16x32_f16(SHARED ? ka[1] : kb[1], qb1, sb0, 0, 0, 0);
;         sa1 = __builtin_amdgcn_mfma_f32_16x16x32_f16(ka[3], qa1, sa1, 0, 0, 0); sb1 = __builtin_amdgcn_mfma_f32_16x16x32_f16(SHARED ? ka[3] : kb[3], qb1, sb1, 0, 0, 0);
;         __builtin_amdgcn_sched_barrier(0);
;         if (ks + 1 < nsteps) { LAS const unsigned char* kn = Ka + (ks + 1) * 4096;
;             ka[0] = *(LAS const h16x8*)(kn + kof0); ka[1] = *(LAS const h16x8*)(kn + kof1); ka[2] = *(LAS const h16x8*)(kn + 2048 + kof0); ka[3] = *(LAS const h16x8*)(kn + 2048 + kof1);
;             if (!SHARED) { LAS const unsigned char* kn2 = Kb + (ks + 1) * 4096;
;                 kb[0] = *(LAS const h16x8*)(kn2 + kof0); kb[1] = *(LAS const h16x8*)(kn2 + kof1); kb[2] = *(LAS const h16x8*)(kn2 + 2048 + kof0); kb[3] = *(LAS const h16x8*)(kn2 + 2048 + kof1); } }
;         __builtin_amdgcn_sched_barrier(0);
;         f32x4 pa0, pa1, pb0, pb1;
; #pragma unroll
;         for (int e = 0; e < 4; ++e) { pa0[e] = __builtin_amdgcn_exp2f(sa0[e]); pa1[e] = __builtin_amdgcn_exp2f(sa1[e]);
;                                       pb0[e] = __builtin_amdgcn_exp2f(sb0[e]); pb1[e] = __builtin_amdgcn_exp2f(sb1[e]); }
;         if (CAUSAL) { const int kr = ks * 32 + 4 * G;
; #pragma unroll
	v_mfma_f32_16x16x32_f16 v[72:75], v[48:51], v[2:5], v[72:75]
	v_mfma_f32_16x16x32_f16 v[48:51], v[48:51], v[18:21], v[10:13]
	s_waitcnt lgkmcnt(8)
	v_mfma_f32_16x16x32_f16 v[10:13], v[52:55], v[2:5], v[108:111]
	v_mfma_f32_16x16x32_f16 v[44:47], v[52:55], v[18:21], v[44:47]
	ds_read_b128 v[52:55], v150 offset:6144
	s_nop 0
	ds_read_b128 v[108:111], v150 offset:4096
	ds_read_b128 v[112:115], v149 offset:6144
	ds_read_b128 v[116:119], v149 offset:4096
	ds_read_b64_tr_b16 v[168:169], v38 offset:36864
	ds_read_b64_tr_b16 v[170:171], v38 offset:38912
	ds_read_b64_tr_b16 v[172:173], v151 offset:36864
	ds_read_b64_tr_b16 v[174:175], v151 offset:38912
	ds_read_b64_tr_b16 v[176:177], v152 offset:36864
	ds_read_b64_tr_b16 v[178:179], v152 offset:38912
	ds_read_b64_tr_b16 v[180:181], v153 offset:36864
	ds_read_b64_tr_b16 v[182:183], v153 offset:38912
	v_exp_f32_e32 v39, v72
	v_exp_f32_e32 v43, v10
	v_exp_f32_e32 v76, v44
	v_exp_f32_e32 v44, v73
	v_exp_f32_e32 v77, v11
	v_exp_f32_e32 v155, v12
	v_exp_f32_e32 v160, v50
	v_exp_f32_e32 v50, v13
	v_mov_b64_e32 v[12:13], s[10:11]
	v_exp_f32_e32 v48, v48
	v_exp_f32_e32 v49, v49
	v_exp_f32_e32 v80, v45
	v_exp_f32_e32 v45, v74
	v_exp_f32_e32 v161, v46
	v_exp_f32_e32 v46, v75
	v_mov_b64_e32 v[10:11], s[8:9]
	v_cvt_pk_f16_f32 v72, v39, v44
	v_cvt_pk_f16_f32 v74, v43, v77
	v_exp_f32_e32 v39, v51
	v_exp_f32_e32 v43, v47
	v_cvt_pk_f16_f32 v73, v45, v46
	v_cvt_pk_f16_f32 v75, v155, v50
	v_cvt_pk_f16_f32 v44, v48, v49
	v_cvt_pk_f16_f32 v45, v160, v39
	v_cvt_pk_f16_f32 v46, v76, v80
	v_cvt_pk_f16_f32 v47, v161, v43
	v_mfma_f32_16x16x32_f16 v[156:159], v[10:13], v[72:75], 0
	s_waitcnt lgkmcnt(14)
	v_mfma_f32_16x16x32_f16 v[48:51], v[56:59], v[72:75], 0
	v_mfma_f32_16x16x32_f16 v[56:59], v[56:59], v[44:47], 0
	v_mfma_f32_16x16x32_f16 v[160:163], v[60:63], v[72:75], 0
	v_mfma_f32_16x16x32_f16 v[60:63], v[60:63], v[44:47], 0
	v_mfma_f32_16x16x32_f16 v[164:167], v[64:67], v[72:75], 0
	v_mfma_f32_16x16x32_f16 v[64:67], v[64:67], v[44:47], 0
	s_waitcnt lgkmcnt(12)
	v_mfma_f32_16x16x32_f16 v[72:75], v[68:71], v[72:75], 0
	v_mfma_f32_16x16x32_f16 v[68:71], v[68:71], v[44:47], 0
	v_mfma_f32_16x16x32_f16 v[44:47], v[10:13], v[44:47], 0
	s_waitcnt lgkmcnt(8)
	v_mfma_f32_16x16x32_f16 v[184:187], v[116:119], v[6:9], v[22:25]
	v_mfma_f32_16x16x32_f16 v[116:119], v[116:119], v[14:17], v[26:29]
	v_mfma_f32_16x16x32_f16 v[188:191], v[112:115], v[6:9], v[22:25]
	v_mfma_f32_16x16x32_f16 v[112:115], v[112:115], v[14:17], v[26:29]
	v_mfma_f32_16x16x32_f16 v[184:187], v[108:111], v[2:5], v[184:187]
	v_mfma_f32_16x16x32_f16 v[108:111], v[108:111], v[18:21], v[116:119]
	v_mfma_f32_16x16x32_f16 v[116:119], v[52:55], v[2:5], v[188:191]
	v_mfma_f32_16x16x32_f16 v[52:55], v[52:55], v[18:21], v[112:115]
	s_nop 3
	ds_read_b128 v[112:115], v150 offset:10240
	ds_read_b128 v[188:191], v150 offset:8192
	ds_read_b128 v[192:195], v149 offset:10240
	ds_read_b128 v[196:199], v149 offset:8192
	v_exp_f32_e32 v39, v184
	v_exp_f32_e32 v43, v116
	v_exp_f32_e32 v77, v52
	v_exp_f32_e32 v52, v185
	v_exp_f32_e32 v80, v117
	v_exp_f32_e32 v76, v108
	v_exp_f32_e32 v108, v109
	v_exp_f32_e32 v109, v53
	v_exp_f32_e32 v53, v186
	v_exp_f32_e32 v155, v118
	v_exp_f32_e32 v110, v110
	v_exp_f32_e32 v117, v187
	v_exp_f32_e32 v184, v54
	v_exp_f32_e32 v54, v119
	v_cvt_pk_f16_f32 v116, v39, v52
	v_cvt_pk_f16_f32 v118, v43, v80
	v_exp_f32_e32 v39, v111
	v_exp_f32_e32 v43, v55
	v_cvt_pk_f16_f32 v117, v53, v117
	v_cvt_pk_f16_f32 v119, v155, v54
	v_cvt_pk_f16_f32 v52, v76, v108
	v_cvt_pk_f16_f32 v53, v110, v39
	v_cvt_pk_f16_f32 v54, v77, v109
	v_cvt_pk_f16_f32 v55, v184, v43
	v_mfma_f32_16x16x32_f16 v[156:159], v[10:13], v[116:119], v[156:159]
	s_waitcnt lgkmcnt(10)
	v_mfma_f32_16x16x32_f16 v[48:51], v[168:171], v[116:119], v[48:51]
	v_mfma_f32_16x16x32_f16 v[56:59], v[168:171], v[52:55], v[56:59]
	s_waitcnt lgkmcnt(8)
	v_mfma_f32_16x16x32_f16 v[108:111], v[172:175], v[116:119], v[160:163]
	v_mfma_f32_16x16x32_f16 v[60:63], v[172:175], v[52:55], v[60:63]
	s_waitcnt lgkmcnt(6)
	v_mfma_f32_16x16x32_f16 v[160:163], v[176:179], v[116:119], v[164:167]
	s_waitcnt lgkmcnt(4)
	v_mfma_f32_16x16x32_f16 v[72:75], v[180:183], v[116:119], v[72:75]
	ds_read_b64_tr_b16 v[116:117], v38 offset:40960
	ds_read_b64_tr_b16 v[118:119], v38 offset:43008
	ds_read_b64_tr_b16 v[164:165], v151 offset:40960
	ds_read_b64_tr_b16 v[166:167], v151 offset:43008
	ds_read_b64_tr_b16 v[168:169], v152 offset:40960
	ds_read_b64_tr_b16 v[170:171], v152 offset:43008
	ds_read_b64_tr_b16 v[172:173], v153 offset:40960
	ds_read_b64_tr_b16 v[174:175], v153 offset:43008
	v_mfma_f32_16x16x32_f16 v[64:67], v[176:179], v[52:55], v[64:67]
	v_mfma_f32_16x16x32_f16 v[68:71], v[180:183], v[52:55], v[68:71]
	v_mfma_f32_16x16x32_f16 v[44:47], v[10:13], v[52:55], v[44:47]
	s_waitcnt lgkmcnt(8)
	v_mfma_f32_16x16x32_f16 v[52:55], v[196:199], v[6:9], v[22:25]
	v_mfma_f32_16x16x32_f16 v[176:179], v[196:199], v[14:17], v[26:29]
	v_mfma_f32_16x16x32_f16 v[180:183], v[192:195], v[6:9], v[22:25]
	v_mfma_f32_16x16x32_f16 v[184:187], v[192:195], v[14:17], v[26:29]
	v_mfma_f32_16x16x32_f16 v[52:55], v[188:191], v[2:5], v[52:55]
	v_mfma_f32_16x16x32_f16 v[176:179], v[188:191], v[18:21], v[176:179]
	v_mfma_f32_16x16x32_f16 v[180:183], v[112:115], v[2:5], v[180:183]
	v_mfma_f32_16x16x32_f16 v[112:115], v[112:115], v[18:21], v[184:187]
	s_nop 3
	ds_read_b128 v[184:187], v150 offset:14336
	ds_read_b128 v[188:191], v150 offset:12288
	ds_read_b128 v[192:195], v149 offset:14336
	ds_read_b128 v[196:199], v149 offset:12288
	v_exp_f32_e32 v39, v52
	v_exp_f32_e32 v43, v180
	v_exp_f32_e32 v52, v53
	v_exp_f32_e32 v80, v181
	v_exp_f32_e32 v53, v54
	v_exp_f32_e32 v54, v55
	v_exp_f32_e32 v76, v176
	v_exp_f32_e32 v77, v112
	v_exp_f32_e32 v112, v177
	v_exp_f32_e32 v155, v113
	v_exp_f32_e32 v113, v182
	v_exp_f32_e32 v176, v178
	v_exp_f32_e32 v177, v114
	v_exp_f32_e32 v55, v183
	v_cvt_pk_f16_f32 v52, v39, v52
	v_cvt_pk_f16_f32 v53, v53, v54
	v_cvt_pk_f16_f32 v54, v43, v80
	v_exp_f32_e32 v39, v179
	v_exp_f32_e32 v43, v115
	v_cvt_pk_f16_f32 v55, v113, v55
	v_cvt_pk_f16_f32 v112, v76, v112
	v_cvt_pk_f16_f32 v113, v176, v39
	v_cvt_pk_f16_f32 v114, v77, v155
	v_cvt_pk_f16_f32 v115, v177, v43
	v_mfma_f32_16x16x32_f16 v[156:159], v[10:13], v[52:55], v[156:159]
	s_waitcnt lgkmcnt(10)
; #define LAS __attribute__((address_space(3)))
; template <bool CAUSAL, bool SHARED> ...
;     ...
;     for (int ks = 0; ks < nsteps; ++ks) {
;         LAS const unsigned char* va = Va + ks * 4096 + vrow; LAS const unsigned char* vb = Vb + ks * 4096 + vrow;
;         h16x4 fal[4], fah[4], fbl[4], fbh[4];
; #pragma unroll
;         for (int dt = 0; dt < 4; ++dt) { fal[dt] = vtr(va + ((dt ^ sw) << 5)); fah[dt] = vtr(va + 2048 + ((dt ^ sw) << 5));
;             if (!SHARED) { fbl[dt] = vtr(vb + ((dt ^ sw) << 5)); fbh[dt] = vtr(vb + 2048 + ((dt ^ sw) << 5)); } }
;         __builtin_amdgcn_sched_barrier(0);
;         f32x4 sa0, sa1, sb0, sb1;
;         sa0 = __builtin_amdgcn_mfma_f32_16x16x32_f16(ka[0], qa0, nma, 0, 0, 0); sb0 = __builtin_amdgcn_mfma_f32_16x16x32_f16(SHARED ? ka[0] : kb[0], qb0, nmb, 0, 0, 0);
;         sa1 = __builtin_amdgcn_mfma_f32_16x16x32_f16(ka[2], qa0, nma, 0, 0, 0); sb1 = __builtin_amdgcn_mfma_f32_16x16x32_f16(SHARED ? ka[2] : kb[2], qb0, nmb, 0, 0, 0);
;         sa0 = __builtin_amdgcn_mfma_f32_16x16x32_f16(ka[1], qa1, sa0, 0, 0, 0); sb0 = __builtin_amdgcn_mfma_f32_16x16x32_f16(SHARED ? ka[1] : kb[1], qb1, sb0, 0, 0, 0);
;         sa1 = __builtin_amdgcn_mfma_f32_16x16x32_f16(ka[3], qa1, sa1, 0, 0, 0); sb1 = __builtin_amdgcn_mfma_f32_16x16x32_f16(SHARED ? ka[3] : kb[3], qb1, sb1, 0, 0, 0);
;         __builtin_amdgcn_sched_barrier(0);
;         if (ks + 1 < nsteps) { LAS const unsigned char* kn = Ka + (ks + 1) * 4096;
;             ka[0] = *(LAS const h16x8*)(kn + kof0); ka[1] = *(LAS const h16x8*)(kn + kof1); ka[2] = *(LAS const h16x8*)(kn + 2048 + kof0); ka[3] = *(LAS const h16x8*)(kn + 2048 + kof1);
;             if (!SHARED) { LAS const unsigned char* kn2 = Kb + (ks + 1) * 4096;
;                 kb[0] = *(LAS const h16x8*)(kn2 + kof0); kb[1] = *(LAS const h16x8*)(kn2 + kof1); kb[2] = *(LAS const h16x8*)(kn2 + 2048 + kof0); kb[3] = *(LAS const h16x8*)(kn2 + 2048 + kof1); } }
;         __builtin_amdgcn_sched_barrier(0);
;         f32x4 pa0, pa1, pb0, pb1;
; #pragma unroll
;         for (int e = 0; e < 4; ++e) { pa0[e] = __builtin_amdgcn_exp2f(sa0[e]); pa1[e] = __builtin_amdgcn_exp2f(sa1[e]);
;                                       pb0[e] = __builtin_amdgcn_exp2f(sb0[e]); pb1[e] = __builtin_amdgcn_exp2f(sb1[e]); }
;         if (CAUSAL) { const int kr = ks * 32 + 4 * G;
; #pragma unroll
	v_mfma_f32_16x16x32_f16 v[48:51], v[116:119], v[52:55], v[48:51]
	v_mfma_f32_16x16x32_f16 v[56:59], v[116:119], v[112:115], v[56:59]
	s_waitcnt lgkmcnt(8)
	v_mfma_f32_16x16x32_f16 v[108:111], v[164:167], v[52:55], v[108:111]
	v_mfma_f32_16x16x32_f16 v[60:63], v[164:167], v[112:115], v[60:63]
	s_waitcnt lgkmcnt(6)
	v_mfma_f32_16x16x32_f16 v[116:119], v[168:171], v[52:55], v[160:163]
	v_mfma_f32_16x16x32_f16 v[64:67], v[168:171], v[112:115], v[64:67]
	s_waitcnt lgkmcnt(4)
	v_mfma_f32_16x16x32_f16 v[52:55], v[172:175], v[52:55], v[72:75]
	s_nop 2
	ds_read_b64_tr_b16 v[72:73], v38 offset:45056
	ds_read_b64_tr_b16 v[74:75], v38 offset:47104
	ds_read_b64_tr_b16 v[160:161], v151 offset:45056
	ds_read_b64_tr_b16 v[162:163], v151 offset:47104
	ds_read_b64_tr_b16 v[164:165], v152 offset:45056
	ds_read_b64_tr_b16 v[166:167], v152 offset:47104
	ds_read_b64_tr_b16 v[168:169], v153 offset:45056
	ds_read_b64_tr_b16 v[170:171], v153 offset:47104
	v_mfma_f32_16x16x32_f16 v[68:71], v[172:175], v[112:115], v[68:71]
	v_mfma_f32_16x16x32_f16 v[44:47], v[10:13], v[112:115], v[44:47]
	s_waitcnt lgkmcnt(8)
	v_mfma_f32_16x16x32_f16 v[112:115], v[196:199], v[6:9], v[22:25]
	v_mfma_f32_16x16x32_f16 v[172:175], v[196:199], v[14:17], v[26:29]
	v_mfma_f32_16x16x32_f16 v[176:179], v[192:195], v[6:9], v[22:25]
	v_mfma_f32_16x16x32_f16 v[180:183], v[192:195], v[14:17], v[26:29]
	v_mfma_f32_16x16x32_f16 v[112:115], v[188:191], v[2:5], v[112:115]
	v_mfma_f32_16x16x32_f16 v[172:175], v[188:191], v[18:21], v[172:175]
	v_mfma_f32_16x16x32_f16 v[176:179], v[184:187], v[2:5], v[176:179]
	v_mfma_f32_16x16x32_f16 v[180:183], v[184:187], v[18:21], v[180:183]
	ds_read_b128 v[184:187], v150 offset:18432
	ds_read_b128 v[188:191], v150 offset:16384
	ds_read_b128 v[192:195], v149 offset:18432
	ds_read_b128 v[196:199], v149 offset:16384
	s_nop 0
	v_exp_f32_e32 v39, v112
	s_nop 0
	v_exp_f32_e32 v43, v176
	v_exp_f32_e32 v80, v113
	v_exp_f32_e32 v155, v177
	v_exp_f32_e32 v113, v114
	v_exp_f32_e32 v114, v115
	v_exp_f32_e32 v76, v172
	v_exp_f32_e32 v77, v180
	v_exp_f32_e32 v172, v173
	v_exp_f32_e32 v176, v181
	v_exp_f32_e32 v173, v178
	v_exp_f32_e32 v174, v174
	v_exp_f32_e32 v177, v182
	v_exp_f32_e32 v115, v179
	v_cvt_pk_f16_f32 v112, v39, v80
	v_cvt_pk_f16_f32 v113, v113, v114
	v_cvt_pk_f16_f32 v114, v43, v155
	v_exp_f32_e32 v39, v175
	v_exp_f32_e32 v43, v183
	v_cvt_pk_f16_f32 v115, v173, v115
	v_cvt_pk_f16_f32 v172, v76, v172
	v_cvt_pk_f16_f32 v173, v174, v39
	v_cvt_pk_f16_f32 v174, v77, v176
	v_cvt_pk_f16_f32 v175, v177, v43
	v_mfma_f32_16x16x32_f16 v[156:159], v[10:13], v[112:115], v[156:159]
	s_waitcnt lgkmcnt(10)
	v_mfma_f32_16x16x32_f16 v[48:51], v[72:75], v[112:115], v[48:51]
	v_mfma_f32_16x16x32_f16 v[56:59], v[72:75], v[172:175], v[56:59]
	s_waitcnt lgkmcnt(8)
	v_mfma_f32_16x16x32_f16 v[72:75], v[160:163], v[112:115], v[108:111]
	v_mfma_f32_16x16x32_f16 v[60:63], v[160:163], v[172:175], v[60:63]
	s_waitcnt lgkmcnt(6)
	v_mfma_f32_16x16x32_f16 v[108:111], v[164:167], v[112:115], v[116:119]
	v_mfma_f32_16x16x32_f16 v[64:67], v[164:167], v[172:175], v[64:67]
	s_waitcnt lgkmcnt(4)
	v_mfma_f32_16x16x32_f16 v[52:55], v[168:171], v[112:115], v[52:55]
	ds_read_b64_tr_b16 v[112:113], v38 offset:49152
	ds_read_b64_tr_b16 v[114:115], v38 offset:51200
	ds_read_b64_tr_b16 v[116:117], v151 offset:49152
	ds_read_b64_tr_b16 v[118:119], v151 offset:51200
	ds_read_b64_tr_b16 v[160:161], v152 offset:49152
	ds_read_b64_tr_b16 v[162:163], v152 offset:51200
	ds_read_b64_tr_b16 v[164:165], v153 offset:49152
	ds_read_b64_tr_b16 v[166:167], v153 offset:51200
	v_mfma_f32_16x16x32_f16 v[68:71], v[168:171], v[172:175], v[68:71]
	v_mfma_f32_16x16x32_f16 v[44:47], v[10:13], v[172:175], v[44:47]
	s_waitcnt lgkmcnt(8)
	v_mfma_f32_16x16x32_f16 v[168:171], v[196:199], v[6:9], v[22:25]
	v_mfma_f32_16x16x32_f16 v[172:175], v[196:199], v[14:17], v[26:29]
	v_mfma_f32_16x16x32_f16 v[176:179], v[192:195], v[6:9], v[22:25]
	v_mfma_f32_16x16x32_f16 v[180:183], v[192:195], v[14:17], v[26:29]
	v_mfma_f32_16x16x32_f16 v[168:171], v[188:191], v[2:5], v[168:171]
	v_mfma_f32_16x16x32_f16 v[172:175], v[188:191], v[18:21], v[172:175]
	v_mfma_f32_16x16x32_f16 v[176:179], v[184:187], v[2:5], v[176:179]
	v_mfma_f32_16x16x32_f16 v[180:183], v[184:187], v[18:21], v[180:183]
	ds_read_b128 v[184:187], v150 offset:22528
	ds_read_b128 v[188:191], v150 offset:20480
	ds_read_b128 v[192:195], v149 offset:22528
	ds_read_b128 v[196:199], v149 offset:20480
	s_nop 0
	v_exp_f32_e32 v39, v168
	s_nop 0
	v_exp_f32_e32 v43, v176
	v_exp_f32_e32 v80, v169
	v_exp_f32_e32 v155, v177
	v_exp_f32_e32 v169, v170
	v_exp_f32_e32 v170, v171
	v_exp_f32_e32 v76, v172
	v_exp_f32_e32 v77, v180
	v_exp_f32_e32 v172, v173
	v_exp_f32_e32 v176, v181
	v_exp_f32_e32 v173, v178
	v_exp_f32_e32 v174, v174
	v_exp_f32_e32 v177, v182
	v_exp_f32_e32 v171, v179
	v_cvt_pk_f16_f32 v168, v39, v80
	v_cvt_pk_f16_f32 v169, v169, v170
	v_cvt_pk_f16_f32 v170, v43, v155
	v_exp_f32_e32 v39, v175
	v_exp_f32_e32 v43, v183
	v_cvt_pk_f16_f32 v171, v173, v171
	v_cvt_pk_f16_f32 v172, v76, v172
	v_cvt_pk_f16_f32 v173, v174, v39
	v_cvt_pk_f16_f32 v174, v77, v176
	v_cvt_pk_f16_f32 v175, v177, v43
	s_waitcnt lgkmcnt(10)
	v_mfma_f32_16x16x32_f16 v[48:51], v[112:115], v[168:171], v[48:51]
	v_mfma_f32_16x16x32_f16 v[56:59], v[112:115], v[172:175], v[56:59]
	s_waitcnt lgkmcnt(8)
	v_mfma_f32_16x16x32_f16 v[72:75], v[116:119], v[168:171], v[72:75]
	v_mfma_f32_16x16x32_f16 v[60:63], v[116:119], v[172:175], v[60:63]
	s_waitcnt lgkmcnt(6)
	v_mfma_f32_16x16x32_f16 v[108:111], v[160:163], v[168:171], v[108:111]
	v_mfma_f32_16x16x32_f16 v[64:67], v[160:163], v[172:175], v[64:67]
	s_waitcnt lgkmcnt(4)
; #define LAS __attribute__((address_space(3)))
; template <bool CAUSAL, bool SHARED> ...
;     ...
;     for (int ks = 0; ks < nsteps; ++ks) {
;         LAS const unsigned char* va = Va + ks * 4096 + vrow; LAS const unsigned char* vb = Vb + ks * 4096 + vrow;
;         h16x4 fal[4], fah[4], fbl[4], fbh[4];
; #pragma unroll
;         for (int dt = 0; dt < 4; ++dt) { fal[dt] = vtr(va + ((dt ^ sw) << 5)); fah[dt] = vtr(va + 2048 + ((dt ^ sw) << 5));
;             if (!SHARED) { fbl[dt] = vtr(vb + ((dt ^ sw) << 5)); fbh[dt] = vtr(vb + 2048 + ((dt ^ sw) << 5)); } }
;         __builtin_amdgcn_sched_barrier(0);
;         f32x4 sa0, sa1, sb0, sb1;
;         sa0 = __builtin_amdgcn_mfma_f32_16x16x32_f16(ka[0], qa0, nma, 0, 0, 0); sb0 = __builtin_amdgcn_mfma_f32_16x16x32_f16(SHARED ? ka[0] : kb[0], qb0, nmb, 0, 0, 0);
;         sa1 = __builtin_amdgcn_mfma_f32_16x16x32_f16(ka[2], qa0, nma, 0, 0, 0); sb1 = __builtin_amdgcn_mfma_f32_16x16x32_f16(SHARED ? ka[2] : kb[2], qb0, nmb, 0, 0, 0);
;         sa0 = __builtin_amdgcn_mfma_f32_16x16x32_f16(ka[1], qa1, sa0, 0, 0, 0); sb0 = __builtin_amdgcn_mfma_f32_16x16x32_f16(SHARED ? ka[1] : kb[1], qb1, sb0, 0, 0, 0);
;         sa1 = __builtin_amdgcn_mfma_f32_16x16x32_f16(ka[3], qa1, sa1, 0, 0, 0); sb1 = __builtin_amdgcn_mfma_f32_16x16x32_f16(SHARED ? ka[3] : kb[3], qb1, sb1, 0, 0, 0);
;         __builtin_amdgcn_sched_barrier(0);
;         if (ks + 1 < nsteps) { LAS const unsigned char* kn = Ka + (ks + 1) * 4096;
;             ka[0] = *(LAS const h16x8*)(kn + kof0); ka[1] = *(LAS const h16x8*)(kn + kof1); ka[2] = *(LAS const h16x8*)(kn + 2048 + kof0); ka[3] = *(LAS const h16x8*)(kn + 2048 + kof1);
;             if (!SHARED) { LAS const unsigned char* kn2 = Kb + (ks + 1) * 4096;
;                 kb[0] = *(LAS const h16x8*)(kn2 + kof0); kb[1] = *(LAS const h16x8*)(kn2 + kof1); kb[2] = *(LAS const h16x8*)(kn2 + 2048 + kof0); kb[3] = *(LAS const h16x8*)(kn2 + 2048 + kof1); } }
;         __builtin_amdgcn_sched_barrier(0);
;         f32x4 pa0, pa1, pb0, pb1;
; #pragma unroll
;         for (int e = 0; e < 4; ++e) { pa0[e] = __builtin_amdgcn_exp2f(sa0[e]); pa1[e] = __builtin_amdgcn_exp2f(sa1[e]);
;                                       pb0[e] = __builtin_amdgcn_exp2f(sb0[e]); pb1[e] = __builtin_amdgcn_exp2f(sb1[e]); }
;         if (CAUSAL) { const int kr = ks * 32 + 4 * G;
; #pragma unroll
	v_mfma_f32_16x16x32_f16 v[52:55], v[164:167], v[168:171], v[52:55]
	v_mfma_f32_16x16x32_f16 v[68:71], v[164:167], v[172:175], v[68:71]
	ds_read_b64_tr_b16 v[112:113], v38 offset:53248
	ds_read_b64_tr_b16 v[114:115], v38 offset:55296
	ds_read_b64_tr_b16 v[116:117], v151 offset:53248
	ds_read_b64_tr_b16 v[118:119], v151 offset:55296
	ds_read_b64_tr_b16 v[160:161], v152 offset:53248
	ds_read_b64_tr_b16 v[162:163], v152 offset:55296
	ds_read_b64_tr_b16 v[164:165], v153 offset:53248
	ds_read_b64_tr_b16 v[166:167], v153 offset:55296
	v_mfma_f32_16x16x32_f16 v[156:159], v[10:13], v[168:171], v[156:159]
	v_mfma_f32_16x16x32_f16 v[44:47], v[10:13], v[172:175], v[44:47]
	s_waitcnt lgkmcnt(8)
	v_mfma_f32_16x16x32_f16 v[168:171], v[196:199], v[6:9], v[22:25]
	v_mfma_f32_16x16x32_f16 v[172:175], v[196:199], v[14:17], v[26:29]
	v_mfma_f32_16x16x32_f16 v[176:179], v[192:195], v[6:9], v[22:25]
	v_mfma_f32_16x16x32_f16 v[180:183], v[192:195], v[14:17], v[26:29]
	v_mfma_f32_16x16x32_f16 v[168:171], v[188:191], v[2:5], v[168:171]
	v_mfma_f32_16x16x32_f16 v[172:175], v[188:191], v[18:21], v[172:175]
	v_mfma_f32_16x16x32_f16 v[176:179], v[184:187], v[2:5], v[176:179]
	v_mfma_f32_16x16x32_f16 v[180:183], v[184:187], v[18:21], v[180:183]
	ds_read_b128 v[184:187], v150 offset:26624
	ds_read_b128 v[188:191], v150 offset:24576
	ds_read_b128 v[192:195], v149 offset:26624
	ds_read_b128 v[196:199], v149 offset:24576
	s_nop 0
	v_exp_f32_e32 v39, v168
	s_nop 0
	v_exp_f32_e32 v43, v176
	v_exp_f32_e32 v80, v169
	v_exp_f32_e32 v155, v177
	v_exp_f32_e32 v169, v170
	v_exp_f32_e32 v170, v171
	v_exp_f32_e32 v76, v172
	v_exp_f32_e32 v77, v180
	v_exp_f32_e32 v172, v173
	v_exp_f32_e32 v176, v181
	v_exp_f32_e32 v173, v178
	v_exp_f32_e32 v174, v174
	v_exp_f32_e32 v177, v182
	v_exp_f32_e32 v171, v179
	v_cvt_pk_f16_f32 v168, v39, v80
	v_cvt_pk_f16_f32 v169, v169, v170
	v_cvt_pk_f16_f32 v170, v43, v155
	v_exp_f32_e32 v39, v175
	v_exp_f32_e32 v43, v183
	v_cvt_pk_f16_f32 v171, v173, v171
	v_cvt_pk_f16_f32 v172, v76, v172
	v_cvt_pk_f16_f32 v173, v174, v39
	v_cvt_pk_f16_f32 v174, v77, v176
	v_cvt_pk_f16_f32 v175, v177, v43
	s_waitcnt lgkmcnt(10)
	v_mfma_f32_16x16x32_f16 v[48:51], v[112:115], v[168:171], v[48:51]
	v_mfma_f32_16x16x32_f16 v[56:59], v[112:115], v[172:175], v[56:59]
	s_waitcnt lgkmcnt(8)
	v_mfma_f32_16x16x32_f16 v[72:75], v[116:119], v[168:171], v[72:75]
	v_mfma_f32_16x16x32_f16 v[60:63], v[116:119], v[172:175], v[60:63]
	s_waitcnt lgkmcnt(6)
	v_mfma_f32_16x16x32_f16 v[108:111], v[160:163], v[168:171], v[108:111]
	v_mfma_f32_16x16x32_f16 v[64:67], v[160:163], v[172:175], v[64:67]
	s_waitcnt lgkmcnt(4)
	v_mfma_f32_16x16x32_f16 v[52:55], v[164:167], v[168:171], v[52:55]
	v_mfma_f32_16x16x32_f16 v[68:71], v[164:167], v[172:175], v[68:71]
	ds_read_b64_tr_b16 v[112:113], v38 offset:57344
	ds_read_b64_tr_b16 v[114:115], v38 offset:59392
	ds_read_b64_tr_b16 v[116:117], v151 offset:57344
	ds_read_b64_tr_b16 v[118:119], v151 offset:59392
	ds_read_b64_tr_b16 v[160:161], v152 offset:57344
	ds_read_b64_tr_b16 v[162:163], v152 offset:59392
	ds_read_b64_tr_b16 v[164:165], v153 offset:57344
	ds_read_b64_tr_b16 v[166:167], v153 offset:59392
	v_mfma_f32_16x16x32_f16 v[156:159], v[10:13], v[168:171], v[156:159]
	v_mfma_f32_16x16x32_f16 v[44:47], v[10:13], v[172:175], v[44:47]
	s_waitcnt lgkmcnt(8)
	v_mfma_f32_16x16x32_f16 v[168:171], v[196:199], v[6:9], v[22:25]
	v_mfma_f32_16x16x32_f16 v[172:175], v[196:199], v[14:17], v[26:29]
	v_mfma_f32_16x16x32_f16 v[176:179], v[192:195], v[6:9], v[22:25]
	v_mfma_f32_16x16x32_f16 v[180:183], v[192:195], v[14:17], v[26:29]
	v_mfma_f32_16x16x32_f16 v[168:171], v[188:191], v[2:5], v[168:171]
	v_mfma_f32_16x16x32_f16 v[172:175], v[188:191], v[18:21], v[172:175]
	v_mfma_f32_16x16x32_f16 v[176:179], v[184:187], v[2:5], v[176:179]
	v_mfma_f32_16x16x32_f16 v[180:183], v[184:187], v[18:21], v[180:183]
	ds_read_b128 v[184:187], v150 offset:30720
	ds_read_b128 v[188:191], v150 offset:28672
	ds_read_b128 v[192:195], v149 offset:30720
	ds_read_b128 v[196:199], v149 offset:28672
	s_nop 0
	v_exp_f32_e32 v39, v168
	s_nop 0
	v_exp_f32_e32 v43, v176
	v_exp_f32_e32 v80, v169
	v_exp_f32_e32 v155, v177
	v_exp_f32_e32 v169, v170
	v_exp_f32_e32 v170, v171
	v_exp_f32_e32 v76, v172
	v_exp_f32_e32 v77, v180
	v_exp_f32_e32 v172, v173
	v_exp_f32_e32 v176, v181
	v_exp_f32_e32 v173, v178
	v_exp_f32_e32 v174, v174
	v_exp_f32_e32 v177, v182
	v_exp_f32_e32 v171, v179
	v_cvt_pk_f16_f32 v168, v39, v80
	v_cvt_pk_f16_f32 v169, v169, v170
	v_cvt_pk_f16_f32 v170, v43, v155
	v_exp_f32_e32 v39, v175
	v_exp_f32_e32 v43, v183
	v_cvt_pk_f16_f32 v171, v173, v171
	v_cvt_pk_f16_f32 v172, v76, v172
	v_cvt_pk_f16_f32 v173, v174, v39
	v_cvt_pk_f16_f32 v174, v77, v176
	v_cvt_pk_f16_f32 v175, v177, v43
	s_waitcnt lgkmcnt(10)
	v_mfma_f32_16x16x32_f16 v[48:51], v[112:115], v[168:171], v[48:51]
	v_mfma_f32_16x16x32_f16 v[56:59], v[112:115], v[172:175], v[56:59]
	s_waitcnt lgkmcnt(8)
	v_mfma_f32_16x16x32_f16 v[72:75], v[116:119], v[168:171], v[72:75]
	v_mfma_f32_16x16x32_f16 v[60:63], v[116:119], v[172:175], v[60:63]
	s_waitcnt lgkmcnt(6)
	v_mfma_f32_16x16x32_f16 v[108:111], v[160:163], v[168:171], v[108:111]
	v_mfma_f32_16x16x32_f16 v[64:67], v[160:163], v[172:175], v[64:67]
	s_waitcnt lgkmcnt(4)
; __device__ __forceinline__ h16x8 cat8(h16x4 lo, h16x4 hi) { return (h16x8){lo[0], lo[1], lo[2], lo[3], hi[0], hi[1], hi[2], hi[3]}; }
; template <bool CAUSAL, bool SHARED> ...
;     ...
;         la = __builtin_amdgcn_mfma_f32_16x16x32_f16(ones, pfa, la, 0, 0, 0); lb = __builtin_amdgcn_mfma_f32_16x16x32_f16(ones, pfb, lb, 0, 0, 0);
; #pragma unroll
;         for (int dt = 0; dt < 4; ++dt) {
;             const h16x8 fa = cat8(fal[dt], fah[dt]);
;             const h16x8 fb = SHARED ? fa : cat8(fbl[dt], fbh[dt]);
;             oa[dt] = __builtin_amdgcn_mfma_f32_16x16x32_f16(fa, pfa, oa[dt], 0, 0, 0);
;             ob[dt] = __builtin_amdgcn_mfma_f32_16x16x32_f16(fb, pfb, ob[dt], 0, 0, 0);
;         }
;     }
;     lsa_out = la[0]; lsb_out = lb[0];
; template <bool Y8>
; __device__ __forceinline__ void xattn_chunk(const Frame& F, const Args& a, int chunk, const f16_t* P, int ldp, int qcol0, const float* gqm, f16_t* Y) {
;     ...
;         const float ila = 1.0f / lsa, ilb = 1.0f / lsb;
;         if constexpr (Y8) { unsigned char* yp = (unsigned char*)Y + MIXW + head * HD; store_o8(yp + (size_t)rowa * DM, oa, ila, G); store_o8(yp + (size_t)rowb * DM, ob, ilb, G); }
;         else { f16_t* yp = Y + MIXW + head * HD; store_o16(yp + (size_t)rowa * DM, oa, ila, G); store_o16(yp + (size_t)rowb * DM, ob, ilb, G); }
	v_mfma_f32_16x16x32_f16 v[52:55], v[164:167], v[168:171], v[52:55]
	v_mfma_f32_16x16x32_f16 v[68:71], v[164:167], v[172:175], v[68:71]
	ds_read_b64_tr_b16 v[112:113], v38 offset:61440
	ds_read_b64_tr_b16 v[114:115], v38 offset:63488
	ds_read_b64_tr_b16 v[116:117], v151 offset:61440
	ds_read_b64_tr_b16 v[118:119], v151 offset:63488
	ds_read_b64_tr_b16 v[160:161], v152 offset:61440
	ds_read_b64_tr_b16 v[162:163], v152 offset:63488
	ds_read_b64_tr_b16 v[164:165], v153 offset:61440
	ds_read_b64_tr_b16 v[166:167], v153 offset:63488
	v_mfma_f32_16x16x32_f16 v[156:159], v[10:13], v[168:171], v[156:159]
	v_mfma_f32_16x16x32_f16 v[44:47], v[10:13], v[172:175], v[44:47]
	s_waitcnt lgkmcnt(8)
	v_mfma_f32_16x16x32_f16 v[168:171], v[196:199], v[6:9], v[22:25]
	v_mfma_f32_16x16x32_f16 v[172:175], v[196:199], v[14:17], v[26:29]
	v_mfma_f32_16x16x32_f16 v[6:9], v[192:195], v[6:9], v[22:25]
	v_mfma_f32_16x16x32_f16 v[14:17], v[192:195], v[14:17], v[26:29]
	v_mfma_f32_16x16x32_f16 v[22:25], v[188:191], v[2:5], v[168:171]
	v_mfma_f32_16x16x32_f16 v[26:29], v[188:191], v[18:21], v[172:175]
	v_mfma_f32_16x16x32_f16 v[2:5], v[184:187], v[2:5], v[6:9]
	v_mfma_f32_16x16x32_f16 v[6:9], v[184:187], v[18:21], v[14:17]
	s_nop 7
	v_exp_f32_e32 v21, v7
	v_exp_f32_e32 v7, v4
	v_exp_f32_e32 v5, v5
	v_exp_f32_e32 v14, v22
	v_exp_f32_e32 v15, v2
	v_exp_f32_e32 v20, v6
	v_exp_f32_e32 v2, v23
	v_exp_f32_e32 v6, v3
	v_exp_f32_e32 v3, v24
	v_exp_f32_e32 v4, v25
	v_exp_f32_e32 v18, v26
	v_exp_f32_e32 v19, v27
	v_exp_f32_e32 v22, v28
	v_exp_f32_e32 v23, v8
	v_cvt_pk_f16_f32 v5, v7, v5
	v_exp_f32_e32 v7, v29
	v_exp_f32_e32 v9, v9
	v_cvt_pk_f16_f32 v2, v14, v2
	v_cvt_pk_f16_f32 v3, v3, v4
	v_cvt_pk_f16_f32 v4, v15, v6
	v_cvt_pk_f16_f32 v6, v18, v19
	v_cvt_pk_f16_f32 v7, v22, v7
	v_mfma_f32_16x16x32_f16 v[14:17], v[10:13], v[2:5], v[156:159]
	v_cvt_pk_f16_f32 v8, v20, v21
	v_cvt_pk_f16_f32 v9, v23, v9
	s_add_u32 s4, s21, s14
	s_waitcnt lgkmcnt(6)
	v_mfma_f32_16x16x32_f16 v[16:19], v[112:115], v[2:5], v[48:51]
	s_addc_u32 s5, s22, 0
	v_lshl_add_u64 v[28:29], s[4:5], 0, v[34:35]
	v_lshl_add_u64 v[38:39], s[4:5], 0, v[36:37]
	v_mfma_f32_16x16x32_f16 v[20:23], v[112:115], v[6:9], v[56:59]
	v_lshlrev_b32_e32 v80, 1, v82
	s_and_b64 s[2:3], exec, s[18:19]
	s_mov_b32 s14, 1
	s_waitcnt lgkmcnt(4)
	v_mfma_f32_16x16x32_f16 v[24:27], v[116:119], v[2:5], v[72:75]
	s_mov_b64 s[18:19], 0
	v_lshl_add_u64 v[28:29], v[28:29], 0, v[80:81]
	v_lshl_add_u64 v[38:39], v[38:39], 0, v[80:81]
	v_mfma_f32_16x16x32_f16 v[48:51], v[116:119], v[6:9], v[60:63]
	s_waitcnt lgkmcnt(2)
	v_mfma_f32_16x16x32_f16 v[56:59], v[160:163], v[2:5], v[108:111]
	v_mfma_f32_16x16x32_f16 v[60:63], v[160:163], v[6:9], v[64:67]
	s_waitcnt lgkmcnt(0)
	v_mfma_f32_16x16x32_f16 v[2:5], v[164:167], v[2:5], v[52:55]
	v_mfma_f32_16x16x32_f16 v[52:55], v[164:167], v[6:9], v[68:71]
	v_mfma_f32_16x16x32_f16 v[6:9], v[10:13], v[6:9], v[44:47]
	s_nop 7
	v_div_scale_f32 v7, s[4:5], v14, v14, 1.0
	v_div_scale_f32 v9, s[4:5], v6, v6, 1.0
	v_rcp_f32_e32 v11, v7
	v_rcp_f32_e32 v12, v9
	v_div_scale_f32 v8, vcc, 1.0, v14, 1.0
	v_fma_f32 v13, -v7, v11, 1.0
	v_fma_f32 v15, -v9, v12, 1.0
	v_fmac_f32_e32 v11, v13, v11
	v_div_scale_f32 v10, s[4:5], 1.0, v6, 1.0
	v_fmac_f32_e32 v12, v15, v12
	v_mul_f32_e32 v13, v8, v11
	v_mul_f32_e32 v15, v10, v12
	v_fma_f32 v43, -v7, v13, v8
	v_fma_f32 v44, -v9, v15, v10
	v_fmac_f32_e32 v13, v43, v11
	v_fmac_f32_e32 v15, v44, v12
	v_fma_f32 v7, -v7, v13, v8
	v_fma_f32 v9, -v9, v15, v10
	v_div_fmas_f32 v7, v7, v11, v13
	s_mov_b64 vcc, s[4:5]
	v_div_fixup_f32 v8, v7, v14, 1.0
	v_div_fmas_f32 v7, v9, v12, v15
	v_div_fixup_f32 v10, v7, v6, 1.0
	v_pk_mul_f32 v[6:7], v[8:9], v[16:17] op_sel_hi:[0,1]
	v_pk_mul_f32 v[12:13], v[8:9], v[18:19] op_sel_hi:[0,1]
	v_pk_mul_f32 v[14:15], v[8:9], v[24:25] op_sel_hi:[0,1]
	v_pk_mul_f32 v[16:17], v[8:9], v[26:27] op_sel_hi:[0,1]
	v_pk_mul_f32 v[18:19], v[8:9], v[56:57] op_sel_hi:[0,1]
	v_pk_mul_f32 v[24:25], v[8:9], v[58:59] op_sel_hi:[0,1]
	v_pk_mul_f32 v[26:27], v[8:9], v[2:3] op_sel_hi:[0,1]
	v_pk_mul_f32 v[44:45], v[8:9], v[4:5] op_sel_hi:[0,1]
	v_cvt_pk_f16_f32 v2, v6, v7
	v_cvt_pk_f16_f32 v3, v12, v13
	v_cvt_pk_f16_f32 v4, v14, v15
	v_cvt_pk_f16_f32 v5, v16, v17
	v_cvt_pk_f16_f32 v6, v18, v19
	v_pk_mul_f32 v[12:13], v[20:21], v[10:11] op_sel_hi:[1,0]
	v_pk_mul_f32 v[14:15], v[22:23], v[10:11] op_sel_hi:[1,0]
	v_pk_mul_f32 v[16:17], v[48:49], v[10:11] op_sel_hi:[1,0]
	v_pk_mul_f32 v[18:19], v[50:51], v[10:11] op_sel_hi:[1,0]
	v_cvt_pk_f16_f32 v7, v24, v25
	v_cvt_pk_f16_f32 v8, v26, v27
	v_pk_mul_f32 v[20:21], v[60:61], v[10:11] op_sel_hi:[1,0]
	v_pk_mul_f32 v[22:23], v[62:63], v[10:11] op_sel_hi:[1,0]
	v_pk_mul_f32 v[24:25], v[52:53], v[10:11] op_sel_hi:[1,0]
	v_pk_mul_f32 v[26:27], v[54:55], v[10:11] op_sel_hi:[1,0]
	v_cvt_pk_f16_f32 v10, v12, v13
	v_cvt_pk_f16_f32 v11, v14, v15
	v_cvt_pk_f16_f32 v12, v16, v17
	v_cvt_pk_f16_f32 v13, v18, v19
	v_cvt_pk_f16_f32 v9, v44, v45
	v_permlane16_swap_b32_e32 v2, v4
	v_permlane16_swap_b32_e32 v3, v5
	v_cvt_pk_f16_f32 v14, v20, v21
	v_cvt_pk_f16_f32 v15, v22, v23
	v_cvt_pk_f16_f32 v16, v24, v25
	v_cvt_pk_f16_f32 v17, v26, v27
	v_permlane16_swap_b32_e32 v10, v12
	v_permlane16_swap_b32_e32 v11, v13
	s_mov_b64 vcc, s[2:3]
	v_permlane16_swap_b32_e32 v6, v8
	v_permlane16_swap_b32_e32 v7, v9
	global_store_dwordx4 v[28:29], v[2:5], off
	global_store_dwordx4 v[28:29], v[6:9], off offset:64
	v_permlane16_swap_b32_e32 v14, v16
	v_permlane16_swap_b32_e32 v15, v17
	global_store_dwordx4 v[38:39], v[10:13], off
	global_store_dwordx4 v[38:39], v[14:17], off offset:64
	s_barrier
	s_cbranch_vccnz .LBB0_334
	s_add_i32 s42, s42, s88
	s_cmpk_gt_i32 s42, 0xff
	s_cbranch_scc0 .LBB0_323

; __device__ __forceinline__ unsigned pkh(float lo, float hi) { f32x2 v = {lo, hi}; h16x2 h = __builtin_convertvector(v, h16x2); return __builtin_bit_cast(unsigned, h); }
; __device__ __forceinline__ unsigned pk8(float a, float b, float c, float d) { int w = __builtin_amdgcn_cvt_pk_fp8_f32(a, b, 0, false); w = __builtin_amdgcn_cvt_pk_fp8_f32(c, d, w, true); return (unsigned)w; }
;     __device__ __forceinline__ void operator()(f32x4 (&acc)[2][2][4][2], const Unit& u, const Order& S, int wr, int wc, int fr_, int fq_, LAS unsigned char*, int) const {
;     ...
; #pragma unroll
;         for (int ai = 0; ai < 2; ++ai)
; #pragma unroll
;             for (int m = 0; m < 4; ++m) {
;                 const int row = row0 + ai * HALF + m * 16; const size_t off = (size_t)row * DM + col0;
;                 float sq = 0.f;
; #pragma unroll
;                 for (int bj = 0; bj < 2; ++bj) {
;                     const h16x8 bs = *(const h16x8*)(h16 + off + bj * HALF);
;                     f32x4 o0 = acc[ai][bj][m][0] * pre, o1 = acc[ai][bj][m][1] * pre;
; #pragma unroll
;                     for (int e = 0; e < 4; ++e) { o0[e] += (float)bs[e]; o1[e] += (float)bs[4 + e]; }
;                     if (out32) { if (!dry) { __builtin_nontemporal_store(o0, (f32x4*)(out32 + off + bj * HALF)); __builtin_nontemporal_store(o1, (f32x4*)(out32 + off + bj * HALF + 4)); } }
;                     else if (!dry) {
;                         sq += (o0[0] * o0[0] + o0[1] * o0[1]) + (o0[2] * o0[2] + o0[3] * o0[3]) + (o1[0] * o1[0] + o1[1] * o1[1]) + (o1[2] * o1[2] + o1[3] * o1[3]);
;                         u32x4 w; w.x = pkh(o0[0], o0[1]); w.y = pkh(o0[2], o0[3]); w.z = pkh(o1[0], o1[1]); w.w = pkh(o1[2], o1[3]);
;                         *(u32x4*)(h16 + off + bj * HALF) = w;
;                         if (h8) { u32x2 q; q.x = pk8(o0[0] * F8_SA, o0[1] * F8_SA, o0[2] * F8_SA, o0[3] * F8_SA); q.y = pk8(o1[0] * F8_SA, o1[1] * F8_SA, o1[2] * F8_SA, o1[3] * F8_SA); *(u32x2*)(h8 + off + bj * HALF) = q; } }
;                 }
;                 if (!out32 && !dry) { sq += __shfl_xor(sq, 16); sq += __shfl_xor(sq, 32); if (fq == 0) atomicAdd(ss_out + row, sq); }
.LBB0_403:
	s_lshl_b32 s3, s45, 8
	v_mov_b32_e32 v146, v150
	v_mov_b32_e32 v168, v1
	s_add_i32 s3, s3, s38
	s_lshl_b32 s2, s2, 8
	v_add_u32_e32 v148, s3, v146
	s_or_b32 s2, s2, s39
	v_ashrrev_i32_e32 v149, 31, v148
	v_lshl_add_u32 v146, v168, 3, s2
	v_lshlrev_b64 v[156:157], 11, v[148:149]
	v_ashrrev_i32_e32 v147, 31, v146
	v_lshl_add_u64 v[156:157], s[90:91], 0, v[156:157]
	v_lshl_add_u64 v[166:167], v[146:147], 1, v[156:157]
	global_load_dwordx4 v[158:161], v[166:167], off
	global_load_dwordx4 v[162:165], v[166:167], off offset:256
	v_and_b32_e32 v157, 64, v155
	v_xor_b32_e32 v156, 16, v155
	v_add_u32_e32 v157, 64, v157
	v_xor_b32_e32 v169, 32, v155
	v_cmp_lt_i32_e64 s[2:3], v156, v157
	v_cmp_eq_u32_e32 vcc, 0, v168
	s_waitcnt vmcnt(0)
	v_cvt_f32_f16_e32 v168, v158
	v_cndmask_b32_e64 v156, v155, v156, s[2:3]
	v_cmp_lt_i32_e64 s[2:3], v169, v157
	v_cvt_f32_f16_e32 v172, v162
	v_cvt_f32_f16_sdwa v173, v162 dst_sel:DWORD dst_unused:UNUSED_PAD src0_sel:WORD_1
	v_cndmask_b32_e64 v157, v155, v169, s[2:3]
	v_cvt_f32_f16_sdwa v169, v158 dst_sel:DWORD dst_unused:UNUSED_PAD src0_sel:WORD_1
	v_cvt_f32_f16_e32 v158, v159
	v_cvt_f32_f16_sdwa v159, v159 dst_sel:DWORD dst_unused:UNUSED_PAD src0_sel:WORD_1
	v_cvt_f32_f16_e32 v162, v163
	v_cvt_f32_f16_sdwa v163, v163 dst_sel:DWORD dst_unused:UNUSED_PAD src0_sel:WORD_1
	v_cvt_f32_f16_e32 v170, v160
	v_cvt_f32_f16_sdwa v171, v160 dst_sel:DWORD dst_unused:UNUSED_PAD src0_sel:WORD_1
	v_cvt_f32_f16_e32 v160, v161
	v_cvt_f32_f16_sdwa v161, v161 dst_sel:DWORD dst_unused:UNUSED_PAD src0_sel:WORD_1
	v_cvt_f32_f16_e32 v174, v164
	v_cvt_f32_f16_sdwa v175, v164 dst_sel:DWORD dst_unused:UNUSED_PAD src0_sel:WORD_1
	v_cvt_f32_f16_e32 v164, v165
	v_cvt_f32_f16_sdwa v165, v165 dst_sel:DWORD dst_unused:UNUSED_PAD src0_sel:WORD_1
	v_pk_add_f32 v[126:127], v[126:127], v[168:169]
	v_pk_add_f32 v[128:129], v[128:129], v[158:159]
	v_pk_add_f32 v[118:119], v[118:119], v[172:173]
	v_pk_add_f32 v[120:121], v[120:121], v[162:163]
	v_pk_add_f32 v[122:123], v[122:123], v[170:171]
	v_pk_add_f32 v[124:125], v[124:125], v[160:161]
	v_pk_add_f32 v[158:159], v[114:115], v[174:175]
	v_pk_add_f32 v[160:161], v[116:117], v[164:165]
	v_pk_mul_f32 v[116:117], v[126:127], v[126:127]
	v_pk_mul_f32 v[162:163], v[128:129], v[128:129]
	v_cvt_pk_f16_f32 v114, v126, v127
	v_cvt_pk_f16_f32 v115, v128, v129
	v_pk_mul_f32 v[126:127], v[118:119], v[118:119]
	v_pk_mul_f32 v[128:129], v[120:121], v[120:121]
	v_pk_mul_f32 v[164:165], v[122:123], v[122:123]
	v_pk_mul_f32 v[170:171], v[158:159], v[158:159]
	v_add_f32_e32 v128, v128, v129
	v_add_f32_e32 v126, v126, v127
	v_add_f32_e32 v162, v162, v163
	v_add_f32_e32 v116, v116, v117
	v_pk_mul_f32 v[168:169], v[124:125], v[124:125]
	v_pk_mul_f32 v[172:173], v[160:161], v[160:161]
	v_add_f32_e32 v127, v170, v171
	v_add_f32_e32 v117, v164, v165
	v_add_f32_e32 v126, v126, v128
	v_add_f32_e32 v116, v116, v162
	v_add_f32_e32 v129, v172, v173
	v_add_f32_e32 v163, v168, v169
	v_add_f32_e32 v126, v127, v126
	v_add_f32_e32 v116, v117, v116
	v_add_f32_e32 v117, v129, v126
	v_add_f32_e32 v116, v163, v116
	v_lshlrev_b32_e32 v156, 2, v156
	v_add_f32_e32 v126, v116, v117
	v_mov_b32_e32 v127, v126
	s_nop 1
	v_permlane16_swap_b32_e32 v126, v127
	v_cvt_pk_f16_f32 v116, v122, v123
	v_cvt_pk_f16_f32 v117, v124, v125
	global_store_dwordx4 v[166:167], v[114:117], off
	v_cvt_pk_f16_f32 v118, v118, v119
	v_cvt_pk_f16_f32 v119, v120, v121
	s_waitcnt lgkmcnt(0)
	v_add_f32_e32 v114, v126, v127
	v_lshlrev_b32_e32 v116, 2, v157
	v_mov_b32_e32 v115, v114
	s_nop 1
	v_permlane32_swap_b32_e32 v114, v115
	v_cvt_pk_f16_f32 v120, v158, v159
	v_cvt_pk_f16_f32 v121, v160, v161
	global_store_dwordx4 v[166:167], v[118:121], off offset:256
	s_and_saveexec_b64 s[2:3], vcc
	s_cbranch_execz .LBB0_405
	v_lshl_add_u64 v[118:119], v[148:149], 2, s[18:19]
	s_waitcnt lgkmcnt(0)
	v_add_f32_e32 v114, v114, v115
	global_atomic_add_f32 v[118:119], v114, off
.LBB0_405:
	s_or_b64 exec, exec, s[2:3]
	v_add_u32_e32 v114, 16, v148
	s_waitcnt lgkmcnt(0)
	v_ashrrev_i32_e32 v115, 31, v114
	v_lshlrev_b64 v[118:119], 11, v[114:115]
	v_lshl_add_u64 v[118:119], s[90:91], 0, v[118:119]
	v_lshl_add_u64 v[126:127], v[146:147], 1, v[118:119]
	global_load_dwordx4 v[118:121], v[126:127], off
	global_load_dwordx4 v[122:125], v[126:127], off offset:256
	s_waitcnt vmcnt(1)
	v_cvt_f32_f16_e32 v128, v118
	v_cvt_f32_f16_sdwa v129, v118 dst_sel:DWORD dst_unused:UNUSED_PAD src0_sel:WORD_1
	v_cvt_f32_f16_e32 v118, v119
	v_cvt_f32_f16_sdwa v119, v119 dst_sel:DWORD dst_unused:UNUSED_PAD src0_sel:WORD_1
	s_waitcnt vmcnt(0)
; __device__ __forceinline__ unsigned pkh(float lo, float hi) { f32x2 v = {lo, hi}; h16x2 h = __builtin_convertvector(v, h16x2); return __builtin_bit_cast(unsigned, h); }
; __device__ __forceinline__ unsigned pk8(float a, float b, float c, float d) { int w = __builtin_amdgcn_cvt_pk_fp8_f32(a, b, 0, false); w = __builtin_amdgcn_cvt_pk_fp8_f32(c, d, w, true); return (unsigned)w; }
;     __device__ __forceinline__ void operator()(f32x4 (&acc)[2][2][4][2], const Unit& u, const Order& S, int wr, int wc, int fr_, int fq_, LAS unsigned char*, int) const {
;     ...
; #pragma unroll
;         for (int ai = 0; ai < 2; ++ai)
; #pragma unroll
;             for (int m = 0; m < 4; ++m) {
;                 const int row = row0 + ai * HALF + m * 16; const size_t off = (size_t)row * DM + col0;
;                 float sq = 0.f;
; #pragma unroll
;                 for (int bj = 0; bj < 2; ++bj) {
;                     const h16x8 bs = *(const h16x8*)(h16 + off + bj * HALF);
;                     f32x4 o0 = acc[ai][bj][m][0] * pre, o1 = acc[ai][bj][m][1] * pre;
; #pragma unroll
;                     for (int e = 0; e < 4; ++e) { o0[e] += (float)bs[e]; o1[e] += (float)bs[4 + e]; }
;                     if (out32) { if (!dry) { __builtin_nontemporal_store(o0, (f32x4*)(out32 + off + bj * HALF)); __builtin_nontemporal_store(o1, (f32x4*)(out32 + off + bj * HALF + 4)); } }
;                     else if (!dry) {
;                         sq += (o0[0] * o0[0] + o0[1] * o0[1]) + (o0[2] * o0[2] + o0[3] * o0[3]) + (o1[0] * o1[0] + o1[1] * o1[1]) + (o1[2] * o1[2] + o1[3] * o1[3]);
;                         u32x4 w; w.x = pkh(o0[0], o0[1]); w.y = pkh(o0[2], o0[3]); w.z = pkh(o1[0], o1[1]); w.w = pkh(o1[2], o1[3]);
;                         *(u32x4*)(h16 + off + bj * HALF) = w;
;                         if (h8) { u32x2 q; q.x = pk8(o0[0] * F8_SA, o0[1] * F8_SA, o0[2] * F8_SA, o0[3] * F8_SA); q.y = pk8(o1[0] * F8_SA, o1[1] * F8_SA, o1[2] * F8_SA, o1[3] * F8_SA); *(u32x2*)(h8 + off + bj * HALF) = q; } }
;                 }
;                 if (!out32 && !dry) { sq += __shfl_xor(sq, 16); sq += __shfl_xor(sq, 32); if (fq == 0) atomicAdd(ss_out + row, sq); }
	v_cvt_f32_f16_e32 v160, v122
	v_cvt_f32_f16_sdwa v161, v122 dst_sel:DWORD dst_unused:UNUSED_PAD src0_sel:WORD_1
	v_cvt_f32_f16_e32 v122, v123
	v_cvt_f32_f16_sdwa v123, v123 dst_sel:DWORD dst_unused:UNUSED_PAD src0_sel:WORD_1
	v_cvt_f32_f16_e32 v158, v120
	v_cvt_f32_f16_sdwa v159, v120 dst_sel:DWORD dst_unused:UNUSED_PAD src0_sel:WORD_1
	v_cvt_f32_f16_e32 v120, v121
	v_cvt_f32_f16_sdwa v121, v121 dst_sel:DWORD dst_unused:UNUSED_PAD src0_sel:WORD_1
	v_cvt_f32_f16_e32 v162, v124
	v_cvt_f32_f16_sdwa v163, v124 dst_sel:DWORD dst_unused:UNUSED_PAD src0_sel:WORD_1
	v_cvt_f32_f16_e32 v124, v125
	v_cvt_f32_f16_sdwa v125, v125 dst_sel:DWORD dst_unused:UNUSED_PAD src0_sel:WORD_1
	v_pk_add_f32 v[110:111], v[110:111], v[128:129]
	v_pk_add_f32 v[112:113], v[112:113], v[118:119]
	v_pk_add_f32 v[102:103], v[102:103], v[160:161]
	v_pk_add_f32 v[104:105], v[104:105], v[122:123]
	v_pk_add_f32 v[106:107], v[106:107], v[158:159]
	v_pk_add_f32 v[108:109], v[108:109], v[120:121]
	v_pk_add_f32 v[118:119], v[98:99], v[162:163]
	v_pk_add_f32 v[120:121], v[100:101], v[124:125]
	v_pk_mul_f32 v[100:101], v[110:111], v[110:111]
	v_pk_mul_f32 v[122:123], v[112:113], v[112:113]
	v_cvt_pk_f16_f32 v98, v110, v111
	v_cvt_pk_f16_f32 v99, v112, v113
	v_pk_mul_f32 v[110:111], v[102:103], v[102:103]
	v_pk_mul_f32 v[112:113], v[104:105], v[104:105]
	v_pk_mul_f32 v[124:125], v[106:107], v[106:107]
	v_pk_mul_f32 v[158:159], v[118:119], v[118:119]
	v_add_f32_e32 v112, v112, v113
	v_add_f32_e32 v110, v110, v111
	v_add_f32_e32 v117, v122, v123
	v_add_f32_e32 v100, v100, v101
	v_pk_mul_f32 v[128:129], v[108:109], v[108:109]
	v_pk_mul_f32 v[160:161], v[120:121], v[120:121]
	v_add_f32_e32 v111, v158, v159
	v_add_f32_e32 v101, v124, v125
	v_add_f32_e32 v110, v110, v112
	v_add_f32_e32 v100, v100, v117
	v_add_f32_e32 v113, v160, v161
	v_add_f32_e32 v122, v128, v129
	v_add_f32_e32 v110, v111, v110
	v_add_f32_e32 v100, v101, v100
	v_add_f32_e32 v101, v113, v110
	v_add_f32_e32 v100, v122, v100
	v_add_f32_e32 v110, v100, v101
	ds_bpermute_b32 v111, v156, v110
	v_cvt_pk_f16_f32 v100, v106, v107
	v_cvt_pk_f16_f32 v101, v108, v109
	global_store_dwordx4 v[126:127], v[98:101], off
	s_waitcnt lgkmcnt(0)
	s_nop 0
	v_add_f32_e32 v98, v110, v111
	v_mov_b32_e32 v99, v98
	s_nop 1
	v_permlane32_swap_b32_e32 v98, v99
	v_cvt_pk_f16_f32 v100, v102, v103
	v_cvt_pk_f16_f32 v101, v104, v105
	v_cvt_pk_f16_f32 v102, v118, v119
	v_cvt_pk_f16_f32 v103, v120, v121
	global_store_dwordx4 v[126:127], v[100:103], off offset:256
	s_and_saveexec_b64 s[2:3], vcc
	s_cbranch_execz .LBB0_407
	v_lshl_add_u64 v[100:101], v[114:115], 2, s[18:19]
	s_waitcnt lgkmcnt(0)
	v_add_f32_e32 v98, v98, v99
	global_atomic_add_f32 v[100:101], v98, off
.LBB0_407:
	s_or_b64 exec, exec, s[2:3]
	v_add_u32_e32 v98, 32, v148
	s_waitcnt lgkmcnt(0)
	v_ashrrev_i32_e32 v99, 31, v98
	v_lshlrev_b64 v[100:101], 11, v[98:99]
	v_lshl_add_u64 v[100:101], s[90:91], 0, v[100:101]
	v_lshl_add_u64 v[108:109], v[146:147], 1, v[100:101]
	global_load_dwordx4 v[100:103], v[108:109], off
	global_load_dwordx4 v[104:107], v[108:109], off offset:256
	s_waitcnt vmcnt(1)
	v_cvt_f32_f16_e32 v110, v100
	v_cvt_f32_f16_sdwa v111, v100 dst_sel:DWORD dst_unused:UNUSED_PAD src0_sel:WORD_1
	v_cvt_f32_f16_e32 v100, v101
	v_cvt_f32_f16_sdwa v101, v101 dst_sel:DWORD dst_unused:UNUSED_PAD src0_sel:WORD_1
	s_waitcnt vmcnt(0)
	v_cvt_f32_f16_e32 v114, v104
	v_cvt_f32_f16_sdwa v115, v104 dst_sel:DWORD dst_unused:UNUSED_PAD src0_sel:WORD_1
	v_cvt_f32_f16_e32 v104, v105
	v_cvt_f32_f16_sdwa v105, v105 dst_sel:DWORD dst_unused:UNUSED_PAD src0_sel:WORD_1
	v_cvt_f32_f16_e32 v112, v102
	v_cvt_f32_f16_sdwa v113, v102 dst_sel:DWORD dst_unused:UNUSED_PAD src0_sel:WORD_1
	v_cvt_f32_f16_e32 v102, v103
	v_cvt_f32_f16_sdwa v103, v103 dst_sel:DWORD dst_unused:UNUSED_PAD src0_sel:WORD_1
	v_cvt_f32_f16_e32 v118, v106
	v_cvt_f32_f16_sdwa v119, v106 dst_sel:DWORD dst_unused:UNUSED_PAD src0_sel:WORD_1
	v_cvt_f32_f16_e32 v106, v107
	v_cvt_f32_f16_sdwa v107, v107 dst_sel:DWORD dst_unused:UNUSED_PAD src0_sel:WORD_1
	v_pk_add_f32 v[94:95], v[94:95], v[110:111]
	v_pk_add_f32 v[96:97], v[96:97], v[100:101]
	v_pk_add_f32 v[86:87], v[86:87], v[114:115]
	v_pk_add_f32 v[88:89], v[88:89], v[104:105]
	v_pk_add_f32 v[90:91], v[90:91], v[112:113]
	v_pk_add_f32 v[92:93], v[92:93], v[102:103]
	v_pk_add_f32 v[100:101], v[82:83], v[118:119]
	v_pk_add_f32 v[102:103], v[84:85], v[106:107]
	v_pk_mul_f32 v[84:85], v[94:95], v[94:95]
	v_pk_mul_f32 v[104:105], v[96:97], v[96:97]
	v_cvt_pk_f16_f32 v82, v94, v95
	v_cvt_pk_f16_f32 v83, v96, v97
	v_pk_mul_f32 v[94:95], v[86:87], v[86:87]
	v_pk_mul_f32 v[96:97], v[88:89], v[88:89]
	v_pk_mul_f32 v[106:107], v[90:91], v[90:91]
	v_pk_mul_f32 v[112:113], v[100:101], v[100:101]
	v_add_f32_e32 v96, v96, v97
	v_add_f32_e32 v94, v94, v95
	v_add_f32_e32 v104, v104, v105
	v_add_f32_e32 v84, v84, v85
	v_pk_mul_f32 v[110:111], v[92:93], v[92:93]
	v_pk_mul_f32 v[114:115], v[102:103], v[102:103]
	v_add_f32_e32 v95, v112, v113
	v_add_f32_e32 v85, v106, v107
	v_add_f32_e32 v94, v94, v96
	v_add_f32_e32 v84, v84, v104
	v_add_f32_e32 v97, v114, v115
	v_add_f32_e32 v105, v110, v111
	v_add_f32_e32 v94, v95, v94
	v_add_f32_e32 v84, v85, v84
	v_add_f32_e32 v85, v97, v94
	v_add_f32_e32 v84, v105, v84
	v_add_f32_e32 v94, v84, v85
	ds_bpermute_b32 v95, v156, v94
	v_cvt_pk_f16_f32 v84, v90, v91
	v_cvt_pk_f16_f32 v85, v92, v93
	global_store_dwordx4 v[108:109], v[82:85], off
	s_waitcnt lgkmcnt(0)
	s_nop 0
	v_add_f32_e32 v82, v94, v95
	v_mov_b32_e32 v83, v82
	s_nop 1
	v_permlane32_swap_b32_e32 v82, v83
	v_cvt_pk_f16_f32 v84, v86, v87
	v_cvt_pk_f16_f32 v85, v88, v89
	v_cvt_pk_f16_f32 v86, v100, v101
	v_cvt_pk_f16_f32 v87, v102, v103
	global_store_dwordx4 v[108:109], v[84:87], off offset:256
	s_and_saveexec_b64 s[2:3], vcc
	s_cbranch_execz .LBB0_409
	v_lshl_add_u64 v[84:85], v[98:99], 2, s[18:19]
	s_waitcnt lgkmcnt(0)
	v_add_f32_e32 v82, v82, v83
	global_atomic_add_f32 v[84:85], v82, off
; __device__ __forceinline__ unsigned pkh(float lo, float hi) { f32x2 v = {lo, hi}; h16x2 h = __builtin_convertvector(v, h16x2); return __builtin_bit_cast(unsigned, h); }
; __device__ __forceinline__ unsigned pk8(float a, float b, float c, float d) { int w = __builtin_amdgcn_cvt_pk_fp8_f32(a, b, 0, false); w = __builtin_amdgcn_cvt_pk_fp8_f32(c, d, w, true); return (unsigned)w; }
;     __device__ __forceinline__ void operator()(f32x4 (&acc)[2][2][4][2], const Unit& u, const Order& S, int wr, int wc, int fr_, int fq_, LAS unsigned char*, int) const {
;     ...
; #pragma unroll
;         for (int ai = 0; ai < 2; ++ai)
; #pragma unroll
;             for (int m = 0; m < 4; ++m) {
;                 const int row = row0 + ai * HALF + m * 16; const size_t off = (size_t)row * DM + col0;
;                 float sq = 0.f;
; #pragma unroll
;                 for (int bj = 0; bj < 2; ++bj) {
;                     const h16x8 bs = *(const h16x8*)(h16 + off + bj * HALF);
;                     f32x4 o0 = acc[ai][bj][m][0] * pre, o1 = acc[ai][bj][m][1] * pre;
; #pragma unroll
;                     for (int e = 0; e < 4; ++e) { o0[e] += (float)bs[e]; o1[e] += (float)bs[4 + e]; }
;                     if (out32) { if (!dry) { __builtin_nontemporal_store(o0, (f32x4*)(out32 + off + bj * HALF)); __builtin_nontemporal_store(o1, (f32x4*)(out32 + off + bj * HALF + 4)); } }
;                     else if (!dry) {
;                         sq += (o0[0] * o0[0] + o0[1] * o0[1]) + (o0[2] * o0[2] + o0[3] * o0[3]) + (o1[0] * o1[0] + o1[1] * o1[1]) + (o1[2] * o1[2] + o1[3] * o1[3]);
;                         u32x4 w; w.x = pkh(o0[0], o0[1]); w.y = pkh(o0[2], o0[3]); w.z = pkh(o1[0], o1[1]); w.w = pkh(o1[2], o1[3]);
;                         *(u32x4*)(h16 + off + bj * HALF) = w;
;                         if (h8) { u32x2 q; q.x = pk8(o0[0] * F8_SA, o0[1] * F8_SA, o0[2] * F8_SA, o0[3] * F8_SA); q.y = pk8(o1[0] * F8_SA, o1[1] * F8_SA, o1[2] * F8_SA, o1[3] * F8_SA); *(u32x2*)(h8 + off + bj * HALF) = q; } }
;                 }
;                 if (!out32 && !dry) { sq += __shfl_xor(sq, 16); sq += __shfl_xor(sq, 32); if (fq == 0) atomicAdd(ss_out + row, sq); }
.LBB0_409:
	s_or_b64 exec, exec, s[2:3]
	v_add_u32_e32 v82, 48, v148
	s_waitcnt lgkmcnt(0)
	v_ashrrev_i32_e32 v83, 31, v82
	v_lshlrev_b64 v[84:85], 11, v[82:83]
	v_lshl_add_u64 v[84:85], s[90:91], 0, v[84:85]
	v_lshl_add_u64 v[92:93], v[146:147], 1, v[84:85]
	global_load_dwordx4 v[84:87], v[92:93], off
	global_load_dwordx4 v[88:91], v[92:93], off offset:256
	s_waitcnt vmcnt(1)
	v_cvt_f32_f16_e32 v94, v84
	v_cvt_f32_f16_sdwa v95, v84 dst_sel:DWORD dst_unused:UNUSED_PAD src0_sel:WORD_1
	v_cvt_f32_f16_e32 v84, v85
	v_cvt_f32_f16_sdwa v85, v85 dst_sel:DWORD dst_unused:UNUSED_PAD src0_sel:WORD_1
	s_waitcnt vmcnt(0)
	v_cvt_f32_f16_e32 v98, v88
	v_cvt_f32_f16_sdwa v99, v88 dst_sel:DWORD dst_unused:UNUSED_PAD src0_sel:WORD_1
	v_cvt_f32_f16_e32 v88, v89
	v_cvt_f32_f16_sdwa v89, v89 dst_sel:DWORD dst_unused:UNUSED_PAD src0_sel:WORD_1
	v_cvt_f32_f16_e32 v96, v86
	v_cvt_f32_f16_sdwa v97, v86 dst_sel:DWORD dst_unused:UNUSED_PAD src0_sel:WORD_1
	v_cvt_f32_f16_e32 v86, v87
	v_cvt_f32_f16_sdwa v87, v87 dst_sel:DWORD dst_unused:UNUSED_PAD src0_sel:WORD_1
	v_cvt_f32_f16_e32 v100, v90
	v_cvt_f32_f16_sdwa v101, v90 dst_sel:DWORD dst_unused:UNUSED_PAD src0_sel:WORD_1
	v_cvt_f32_f16_e32 v90, v91
	v_cvt_f32_f16_sdwa v91, v91 dst_sel:DWORD dst_unused:UNUSED_PAD src0_sel:WORD_1
	v_pk_add_f32 v[78:79], v[78:79], v[94:95]
	v_pk_add_f32 v[80:81], v[80:81], v[84:85]
	v_pk_add_f32 v[70:71], v[70:71], v[98:99]
	v_pk_add_f32 v[72:73], v[72:73], v[88:89]
	v_pk_add_f32 v[74:75], v[74:75], v[96:97]
	v_pk_add_f32 v[76:77], v[76:77], v[86:87]
	v_pk_add_f32 v[84:85], v[66:67], v[100:101]
	v_pk_add_f32 v[86:87], v[68:69], v[90:91]
	v_pk_mul_f32 v[68:69], v[78:79], v[78:79]
	v_pk_mul_f32 v[88:89], v[80:81], v[80:81]
	v_cvt_pk_f16_f32 v66, v78, v79
	v_cvt_pk_f16_f32 v67, v80, v81
	v_pk_mul_f32 v[78:79], v[70:71], v[70:71]
	v_pk_mul_f32 v[80:81], v[72:73], v[72:73]
	v_pk_mul_f32 v[90:91], v[74:75], v[74:75]
	v_pk_mul_f32 v[96:97], v[84:85], v[84:85]
	v_add_f32_e32 v80, v80, v81
	v_add_f32_e32 v78, v78, v79
	v_add_f32_e32 v88, v88, v89
	v_add_f32_e32 v68, v68, v69
	v_pk_mul_f32 v[94:95], v[76:77], v[76:77]
	v_pk_mul_f32 v[98:99], v[86:87], v[86:87]
	v_add_f32_e32 v79, v96, v97
	v_add_f32_e32 v69, v90, v91
	v_add_f32_e32 v78, v78, v80
	v_add_f32_e32 v68, v68, v88
	v_add_f32_e32 v81, v98, v99
	v_add_f32_e32 v89, v94, v95
	v_add_f32_e32 v78, v79, v78
	v_add_f32_e32 v68, v69, v68
	v_add_f32_e32 v69, v81, v78
	v_add_f32_e32 v68, v89, v68
	v_add_f32_e32 v78, v68, v69
	ds_bpermute_b32 v79, v156, v78
	v_cvt_pk_f16_f32 v68, v74, v75
	v_cvt_pk_f16_f32 v69, v76, v77
	global_store_dwordx4 v[92:93], v[66:69], off
	s_waitcnt lgkmcnt(0)
	s_nop 0
	v_add_f32_e32 v66, v78, v79
	v_mov_b32_e32 v67, v66
	s_nop 1
	v_permlane32_swap_b32_e32 v66, v67
	v_cvt_pk_f16_f32 v68, v70, v71
	v_cvt_pk_f16_f32 v69, v72, v73
	v_cvt_pk_f16_f32 v70, v84, v85
	v_cvt_pk_f16_f32 v71, v86, v87
	global_store_dwordx4 v[92:93], v[68:71], off offset:256
	s_and_saveexec_b64 s[2:3], vcc
	s_cbranch_execz .LBB0_411
	v_lshl_add_u64 v[68:69], v[82:83], 2, s[18:19]
	s_waitcnt lgkmcnt(0)
	v_add_f32_e32 v66, v66, v67
	global_atomic_add_f32 v[68:69], v66, off
.LBB0_411:
	s_or_b64 exec, exec, s[2:3]
	v_add_u32_e32 v66, 0x80, v148
	s_waitcnt lgkmcnt(0)
	v_ashrrev_i32_e32 v67, 31, v66
	v_lshlrev_b64 v[68:69], 11, v[66:67]
	v_lshl_add_u64 v[68:69], s[90:91], 0, v[68:69]
	v_lshl_add_u64 v[76:77], v[146:147], 1, v[68:69]
	global_load_dwordx4 v[68:71], v[76:77], off
	global_load_dwordx4 v[72:75], v[76:77], off offset:256
	s_waitcnt vmcnt(1)
	v_cvt_f32_f16_e32 v78, v68
	v_cvt_f32_f16_sdwa v79, v68 dst_sel:DWORD dst_unused:UNUSED_PAD src0_sel:WORD_1
	v_cvt_f32_f16_e32 v68, v69
	v_cvt_f32_f16_sdwa v69, v69 dst_sel:DWORD dst_unused:UNUSED_PAD src0_sel:WORD_1
	s_waitcnt vmcnt(0)
	v_cvt_f32_f16_e32 v82, v72
	v_cvt_f32_f16_sdwa v83, v72 dst_sel:DWORD dst_unused:UNUSED_PAD src0_sel:WORD_1
	v_cvt_f32_f16_e32 v72, v73
	v_cvt_f32_f16_sdwa v73, v73 dst_sel:DWORD dst_unused:UNUSED_PAD src0_sel:WORD_1
	v_cvt_f32_f16_e32 v80, v70
	v_cvt_f32_f16_sdwa v81, v70 dst_sel:DWORD dst_unused:UNUSED_PAD src0_sel:WORD_1
	v_cvt_f32_f16_e32 v70, v71
	v_cvt_f32_f16_sdwa v71, v71 dst_sel:DWORD dst_unused:UNUSED_PAD src0_sel:WORD_1
	v_cvt_f32_f16_e32 v84, v74
	v_cvt_f32_f16_sdwa v85, v74 dst_sel:DWORD dst_unused:UNUSED_PAD src0_sel:WORD_1
	v_cvt_f32_f16_e32 v74, v75
	v_cvt_f32_f16_sdwa v75, v75 dst_sel:DWORD dst_unused:UNUSED_PAD src0_sel:WORD_1
	v_pk_add_f32 v[62:63], v[62:63], v[78:79]
	v_pk_add_f32 v[64:65], v[64:65], v[68:69]
	v_pk_add_f32 v[54:55], v[54:55], v[82:83]
	v_pk_add_f32 v[56:57], v[56:57], v[72:73]
	v_pk_add_f32 v[58:59], v[58:59], v[80:81]
	v_pk_add_f32 v[60:61], v[60:61], v[70:71]
	v_pk_add_f32 v[68:69], v[50:51], v[84:85]
	v_pk_add_f32 v[70:71], v[52:53], v[74:75]
	v_pk_mul_f32 v[52:53], v[62:63], v[62:63]
	v_pk_mul_f32 v[72:73], v[64:65], v[64:65]
	v_cvt_pk_f16_f32 v50, v62, v63
	v_cvt_pk_f16_f32 v51, v64, v65
	v_pk_mul_f32 v[62:63], v[54:55], v[54:55]
	v_pk_mul_f32 v[64:65], v[56:57], v[56:57]
	v_pk_mul_f32 v[74:75], v[58:59], v[58:59]
	v_pk_mul_f32 v[80:81], v[68:69], v[68:69]
	v_add_f32_e32 v64, v64, v65
	v_add_f32_e32 v62, v62, v63
	v_add_f32_e32 v72, v72, v73
	v_add_f32_e32 v52, v52, v53
	v_pk_mul_f32 v[78:79], v[60:61], v[60:61]
	v_pk_mul_f32 v[82:83], v[70:71], v[70:71]
	v_add_f32_e32 v63, v80, v81
	v_add_f32_e32 v53, v74, v75
	v_add_f32_e32 v62, v62, v64
	v_add_f32_e32 v52, v52, v72
	v_add_f32_e32 v65, v82, v83
	v_add_f32_e32 v73, v78, v79
	v_add_f32_e32 v62, v63, v62
	v_add_f32_e32 v52, v53, v52
	v_add_f32_e32 v53, v65, v62
	v_add_f32_e32 v52, v73, v52
	v_add_f32_e32 v62, v52, v53
	ds_bpermute_b32 v63, v156, v62
	v_cvt_pk_f16_f32 v52, v58, v59
	v_cvt_pk_f16_f32 v53, v60, v61
	global_store_dwordx4 v[76:77], v[50:53], off
	s_waitcnt lgkmcnt(0)
	s_nop 0
	v_add_f32_e32 v50, v62, v63
	v_mov_b32_e32 v51, v50
	s_nop 1
	v_permlane32_swap_b32_e32 v50, v51
	v_cvt_pk_f16_f32 v52, v54, v55
	v_cvt_pk_f16_f32 v53, v56, v57
	v_cvt_pk_f16_f32 v54, v68, v69
	v_cvt_pk_f16_f32 v55, v70, v71
	global_store_dwordx4 v[76:77], v[52:55], off offset:256
	s_and_saveexec_b64 s[2:3], vcc
	s_cbranch_execz .LBB0_413
	v_lshl_add_u64 v[52:53], v[66:67], 2, s[18:19]
	s_waitcnt lgkmcnt(0)
	v_add_f32_e32 v50, v50, v51
	global_atomic_add_f32 v[52:53], v50, off
; __device__ __forceinline__ unsigned pkh(float lo, float hi) { f32x2 v = {lo, hi}; h16x2 h = __builtin_convertvector(v, h16x2); return __builtin_bit_cast(unsigned, h); }
; __device__ __forceinline__ unsigned pk8(float a, float b, float c, float d) { int w = __builtin_amdgcn_cvt_pk_fp8_f32(a, b, 0, false); w = __builtin_amdgcn_cvt_pk_fp8_f32(c, d, w, true); return (unsigned)w; }
;     __device__ __forceinline__ void operator()(f32x4 (&acc)[2][2][4][2], const Unit& u, const Order& S, int wr, int wc, int fr_, int fq_, LAS unsigned char*, int) const {
;     ...
;                 const int row = row0 + ai * HALF + m * 16; const size_t off = (size_t)row * DM + col0;
;                 float sq = 0.f;
; #pragma unroll
;                 for (int bj = 0; bj < 2; ++bj) {
;                     const h16x8 bs = *(const h16x8*)(h16 + off + bj * HALF);
;                     f32x4 o0 = acc[ai][bj][m][0] * pre, o1 = acc[ai][bj][m][1] * pre;
; #pragma unroll
;                     for (int e = 0; e < 4; ++e) { o0[e] += (float)bs[e]; o1[e] += (float)bs[4 + e]; }
;                     if (out32) { if (!dry) { __builtin_nontemporal_store(o0, (f32x4*)(out32 + off + bj * HALF)); __builtin_nontemporal_store(o1, (f32x4*)(out32 + off + bj * HALF + 4)); } }
;                     else if (!dry) {
;                         sq += (o0[0] * o0[0] + o0[1] * o0[1]) + (o0[2] * o0[2] + o0[3] * o0[3]) + (o1[0] * o1[0] + o1[1] * o1[1]) + (o1[2] * o1[2] + o1[3] * o1[3]);
;                         u32x4 w; w.x = pkh(o0[0], o0[1]); w.y = pkh(o0[2], o0[3]); w.z = pkh(o1[0], o1[1]); w.w = pkh(o1[2], o1[3]);
;                         *(u32x4*)(h16 + off + bj * HALF) = w;
;                         if (h8) { u32x2 q; q.x = pk8(o0[0] * F8_SA, o0[1] * F8_SA, o0[2] * F8_SA, o0[3] * F8_SA); q.y = pk8(o1[0] * F8_SA, o1[1] * F8_SA, o1[2] * F8_SA, o1[3] * F8_SA); *(u32x2*)(h8 + off + bj * HALF) = q; } }
;                 }
;                 if (!out32 && !dry) { sq += __shfl_xor(sq, 16); sq += __shfl_xor(sq, 32); if (fq == 0) atomicAdd(ss_out + row, sq); }
.LBB0_413:
	s_or_b64 exec, exec, s[2:3]
	v_add_u32_e32 v50, 0x90, v148
	s_waitcnt lgkmcnt(0)
	v_ashrrev_i32_e32 v51, 31, v50
	v_lshlrev_b64 v[52:53], 11, v[50:51]
	v_lshl_add_u64 v[52:53], s[90:91], 0, v[52:53]
	v_lshl_add_u64 v[60:61], v[146:147], 1, v[52:53]
	global_load_dwordx4 v[52:55], v[60:61], off
	global_load_dwordx4 v[56:59], v[60:61], off offset:256
	s_waitcnt vmcnt(1)
	v_cvt_f32_f16_e32 v62, v52
	v_cvt_f32_f16_sdwa v63, v52 dst_sel:DWORD dst_unused:UNUSED_PAD src0_sel:WORD_1
	v_cvt_f32_f16_e32 v52, v53
	v_cvt_f32_f16_sdwa v53, v53 dst_sel:DWORD dst_unused:UNUSED_PAD src0_sel:WORD_1
	s_waitcnt vmcnt(0)
	v_cvt_f32_f16_e32 v66, v56
	v_cvt_f32_f16_sdwa v67, v56 dst_sel:DWORD dst_unused:UNUSED_PAD src0_sel:WORD_1
	v_cvt_f32_f16_e32 v56, v57
	v_cvt_f32_f16_sdwa v57, v57 dst_sel:DWORD dst_unused:UNUSED_PAD src0_sel:WORD_1
	v_cvt_f32_f16_e32 v64, v54
	v_cvt_f32_f16_sdwa v65, v54 dst_sel:DWORD dst_unused:UNUSED_PAD src0_sel:WORD_1
	v_cvt_f32_f16_e32 v54, v55
	v_cvt_f32_f16_sdwa v55, v55 dst_sel:DWORD dst_unused:UNUSED_PAD src0_sel:WORD_1
	v_cvt_f32_f16_e32 v68, v58
	v_cvt_f32_f16_sdwa v69, v58 dst_sel:DWORD dst_unused:UNUSED_PAD src0_sel:WORD_1
	v_cvt_f32_f16_e32 v58, v59
	v_cvt_f32_f16_sdwa v59, v59 dst_sel:DWORD dst_unused:UNUSED_PAD src0_sel:WORD_1
	v_pk_add_f32 v[46:47], v[46:47], v[62:63]
	v_pk_add_f32 v[48:49], v[48:49], v[52:53]
	v_pk_add_f32 v[38:39], v[38:39], v[66:67]
	v_pk_add_f32 v[40:41], v[40:41], v[56:57]
	v_pk_add_f32 v[42:43], v[42:43], v[64:65]
	v_pk_add_f32 v[44:45], v[44:45], v[54:55]
	v_pk_add_f32 v[52:53], v[34:35], v[68:69]
	v_pk_add_f32 v[54:55], v[36:37], v[58:59]
	v_pk_mul_f32 v[36:37], v[46:47], v[46:47]
	v_pk_mul_f32 v[56:57], v[48:49], v[48:49]
	v_cvt_pk_f16_f32 v34, v46, v47
	v_cvt_pk_f16_f32 v35, v48, v49
	v_pk_mul_f32 v[46:47], v[38:39], v[38:39]
	v_pk_mul_f32 v[48:49], v[40:41], v[40:41]
	v_pk_mul_f32 v[58:59], v[42:43], v[42:43]
	v_pk_mul_f32 v[64:65], v[52:53], v[52:53]
	v_add_f32_e32 v48, v48, v49
	v_add_f32_e32 v46, v46, v47
	v_add_f32_e32 v56, v56, v57
	v_add_f32_e32 v36, v36, v37
	v_pk_mul_f32 v[62:63], v[44:45], v[44:45]
	v_pk_mul_f32 v[66:67], v[54:55], v[54:55]
	v_add_f32_e32 v47, v64, v65
	v_add_f32_e32 v37, v58, v59
	v_add_f32_e32 v46, v46, v48
	v_add_f32_e32 v36, v36, v56
	v_add_f32_e32 v49, v66, v67
	v_add_f32_e32 v57, v62, v63
	v_add_f32_e32 v46, v47, v46
	v_add_f32_e32 v36, v37, v36
	v_add_f32_e32 v37, v49, v46
	v_add_f32_e32 v36, v57, v36
	v_add_f32_e32 v46, v36, v37
	ds_bpermute_b32 v47, v156, v46
	v_cvt_pk_f16_f32 v36, v42, v43
	v_cvt_pk_f16_f32 v37, v44, v45
	global_store_dwordx4 v[60:61], v[34:37], off
	s_waitcnt lgkmcnt(0)
	s_nop 0
	v_add_f32_e32 v34, v46, v47
	v_mov_b32_e32 v35, v34
	s_nop 1
	v_permlane32_swap_b32_e32 v34, v35
	v_cvt_pk_f16_f32 v36, v38, v39
	v_cvt_pk_f16_f32 v37, v40, v41
	v_cvt_pk_f16_f32 v38, v52, v53
	v_cvt_pk_f16_f32 v39, v54, v55
	global_store_dwordx4 v[60:61], v[36:39], off offset:256
	s_and_saveexec_b64 s[2:3], vcc
	s_cbranch_execz .LBB0_415
	v_lshl_add_u64 v[36:37], v[50:51], 2, s[18:19]
	s_waitcnt lgkmcnt(0)
	v_add_f32_e32 v34, v34, v35
	global_atomic_add_f32 v[36:37], v34, off
.LBB0_415:
	s_or_b64 exec, exec, s[2:3]
	v_add_u32_e32 v34, 0xa0, v148
	s_waitcnt lgkmcnt(0)
	v_ashrrev_i32_e32 v35, 31, v34
	v_lshlrev_b64 v[36:37], 11, v[34:35]
	v_lshl_add_u64 v[36:37], s[90:91], 0, v[36:37]
	v_lshl_add_u64 v[44:45], v[146:147], 1, v[36:37]
	global_load_dwordx4 v[36:39], v[44:45], off
	global_load_dwordx4 v[40:43], v[44:45], off offset:256
	s_waitcnt vmcnt(1)
	v_cvt_f32_f16_e32 v46, v36
	v_cvt_f32_f16_sdwa v47, v36 dst_sel:DWORD dst_unused:UNUSED_PAD src0_sel:WORD_1
	v_cvt_f32_f16_e32 v36, v37
	v_cvt_f32_f16_sdwa v37, v37 dst_sel:DWORD dst_unused:UNUSED_PAD src0_sel:WORD_1
	s_waitcnt vmcnt(0)
	v_cvt_f32_f16_e32 v50, v40
	v_cvt_f32_f16_sdwa v51, v40 dst_sel:DWORD dst_unused:UNUSED_PAD src0_sel:WORD_1
	v_cvt_f32_f16_e32 v40, v41
	v_cvt_f32_f16_sdwa v41, v41 dst_sel:DWORD dst_unused:UNUSED_PAD src0_sel:WORD_1
	v_cvt_f32_f16_e32 v48, v38
	v_cvt_f32_f16_sdwa v49, v38 dst_sel:DWORD dst_unused:UNUSED_PAD src0_sel:WORD_1
	v_cvt_f32_f16_e32 v38, v39
	v_cvt_f32_f16_sdwa v39, v39 dst_sel:DWORD dst_unused:UNUSED_PAD src0_sel:WORD_1
	v_cvt_f32_f16_e32 v52, v42
	v_cvt_f32_f16_sdwa v53, v42 dst_sel:DWORD dst_unused:UNUSED_PAD src0_sel:WORD_1
	v_cvt_f32_f16_e32 v42, v43
	v_cvt_f32_f16_sdwa v43, v43 dst_sel:DWORD dst_unused:UNUSED_PAD src0_sel:WORD_1
	v_pk_add_f32 v[30:31], v[30:31], v[46:47]
	v_pk_add_f32 v[32:33], v[32:33], v[36:37]
	v_pk_add_f32 v[22:23], v[22:23], v[50:51]
	v_pk_add_f32 v[24:25], v[24:25], v[40:41]
	v_pk_add_f32 v[26:27], v[26:27], v[48:49]
	v_pk_add_f32 v[28:29], v[28:29], v[38:39]
	v_pk_add_f32 v[36:37], v[18:19], v[52:53]
	v_pk_add_f32 v[38:39], v[20:21], v[42:43]
	v_pk_mul_f32 v[20:21], v[30:31], v[30:31]
	v_pk_mul_f32 v[40:41], v[32:33], v[32:33]
	v_cvt_pk_f16_f32 v18, v30, v31
	v_cvt_pk_f16_f32 v19, v32, v33
	v_pk_mul_f32 v[30:31], v[22:23], v[22:23]
	v_pk_mul_f32 v[32:33], v[24:25], v[24:25]
	v_pk_mul_f32 v[42:43], v[26:27], v[26:27]
	v_pk_mul_f32 v[48:49], v[36:37], v[36:37]
	v_add_f32_e32 v32, v32, v33
	v_add_f32_e32 v30, v30, v31
	v_add_f32_e32 v40, v40, v41
	v_add_f32_e32 v20, v20, v21
	v_pk_mul_f32 v[46:47], v[28:29], v[28:29]
	v_pk_mul_f32 v[50:51], v[38:39], v[38:39]
	v_add_f32_e32 v31, v48, v49
	v_add_f32_e32 v21, v42, v43
	v_add_f32_e32 v30, v30, v32
	v_add_f32_e32 v20, v20, v40
	v_add_f32_e32 v33, v50, v51
	v_add_f32_e32 v41, v46, v47
	v_add_f32_e32 v30, v31, v30
	v_add_f32_e32 v20, v21, v20
	v_add_f32_e32 v21, v33, v30
	v_add_f32_e32 v20, v41, v20
	v_add_f32_e32 v30, v20, v21
	ds_bpermute_b32 v31, v156, v30
	v_cvt_pk_f16_f32 v20, v26, v27
	v_cvt_pk_f16_f32 v21, v28, v29
	global_store_dwordx4 v[44:45], v[18:21], off
	s_waitcnt lgkmcnt(0)
	s_nop 0
	v_add_f32_e32 v18, v30, v31
	v_mov_b32_e32 v19, v18
	s_nop 1
	v_permlane32_swap_b32_e32 v18, v19
	v_cvt_pk_f16_f32 v20, v22, v23
	v_cvt_pk_f16_f32 v21, v24, v25
	v_cvt_pk_f16_f32 v22, v36, v37
	v_cvt_pk_f16_f32 v23, v38, v39
	global_store_dwordx4 v[44:45], v[20:23], off offset:256
	s_and_saveexec_b64 s[2:3], vcc
	s_cbranch_execz .LBB0_417
	v_lshl_add_u64 v[20:21], v[34:35], 2, s[18:19]
	s_waitcnt lgkmcnt(0)
	v_add_f32_e32 v18, v18, v19
	global_atomic_add_f32 v[20:21], v18, off

; __device__ __forceinline__ unsigned pkh(float lo, float hi) { f32x2 v = {lo, hi}; h16x2 h = __builtin_convertvector(v, h16x2); return __builtin_bit_cast(unsigned, h); }
; __device__ __forceinline__ unsigned pk8(float a, float b, float c, float d) { int w = __builtin_amdgcn_cvt_pk_fp8_f32(a, b, 0, false); w = __builtin_amdgcn_cvt_pk_fp8_f32(c, d, w, true); return (unsigned)w; }
;     __device__ __forceinline__ void operator()(f32x4 (&acc)[2][2][4][2], const Unit& u, const Order& S, int wr, int wc, int fr_, int fq_, LAS unsigned char*, int) const {
;     ...
;                 const int row = row0 + ai * HALF + m * 16; const size_t off = (size_t)row * DM + col0;
;                 float sq = 0.f;
; #pragma unroll
;                 for (int bj = 0; bj < 2; ++bj) {
;                     const h16x8 bs = *(const h16x8*)(h16 + off + bj * HALF);
;                     f32x4 o0 = acc[ai][bj][m][0] * pre, o1 = acc[ai][bj][m][1] * pre;
; #pragma unroll
;                     for (int e = 0; e < 4; ++e) { o0[e] += (float)bs[e]; o1[e] += (float)bs[4 + e]; }
;                     if (out32) { if (!dry) { __builtin_nontemporal_store(o0, (f32x4*)(out32 + off + bj * HALF)); __builtin_nontemporal_store(o1, (f32x4*)(out32 + off + bj * HALF + 4)); } }
;                     else if (!dry) {
;                         sq += (o0[0] * o0[0] + o0[1] * o0[1]) + (o0[2] * o0[2] + o0[3] * o0[3]) + (o1[0] * o1[0] + o1[1] * o1[1]) + (o1[2] * o1[2] + o1[3] * o1[3]);
;                         u32x4 w; w.x = pkh(o0[0], o0[1]); w.y = pkh(o0[2], o0[3]); w.z = pkh(o1[0], o1[1]); w.w = pkh(o1[2], o1[3]);
;                         *(u32x4*)(h16 + off + bj * HALF) = w;
;                         if (h8) { u32x2 q; q.x = pk8(o0[0] * F8_SA, o0[1] * F8_SA, o0[2] * F8_SA, o0[3] * F8_SA); q.y = pk8(o1[0] * F8_SA, o1[1] * F8_SA, o1[2] * F8_SA, o1[3] * F8_SA); *(u32x2*)(h8 + off + bj * HALF) = q; } }
;                 }
;                 if (!out32 && !dry) { sq += __shfl_xor(sq, 16); sq += __shfl_xor(sq, 32); if (fq == 0) atomicAdd(ss_out + row, sq); }
.LBB0_670:
	s_lshl_b32 s2, s45, 8
	v_mov_b32_e32 v146, v150
	v_mov_b32_e32 v170, v1
	s_add_i32 s2, s2, s36
	v_mov_b32_e32 v164, 0
	v_add_u32_e32 v148, s2, v146
	s_lshl_b32 s2, s44, 8
	s_or_b32 s2, s2, s37
	v_lshl_add_u32 v146, v170, 3, s2
	v_ashrrev_i32_e32 v149, 31, v148
	v_ashrrev_i32_e32 v147, 31, v146
	v_lshlrev_b64 v[156:157], 10, v[148:149]
	v_lshl_add_u64 v[160:161], v[156:157], 0, v[146:147]
	v_lshl_add_u64 v[162:163], v[160:161], 1, s[90:91]
	global_load_dwordx4 v[156:159], v[162:163], off
	v_mov_b32_e32 v165, 0
	v_lshl_add_u64 v[160:161], s[10:11], 0, v[160:161]
	v_cmp_eq_u32_e32 vcc, 0, v170
	s_waitcnt vmcnt(0)
	v_cvt_f32_f16_e32 v166, v156
	v_cvt_f32_f16_sdwa v167, v156 dst_sel:DWORD dst_unused:UNUSED_PAD src0_sel:WORD_1
	v_cvt_f32_f16_e32 v168, v158
	v_cvt_f32_f16_sdwa v169, v158 dst_sel:DWORD dst_unused:UNUSED_PAD src0_sel:WORD_1
	v_cvt_f32_f16_e32 v156, v157
	v_cvt_f32_f16_sdwa v157, v157 dst_sel:DWORD dst_unused:UNUSED_PAD src0_sel:WORD_1
	v_cvt_f32_f16_e32 v158, v159
	v_cvt_f32_f16_sdwa v159, v159 dst_sel:DWORD dst_unused:UNUSED_PAD src0_sel:WORD_1
	v_pk_add_f32 v[166:167], v[126:127], v[166:167]
	v_pk_add_f32 v[168:169], v[122:123], v[168:169]
	v_pk_add_f32 v[128:129], v[128:129], v[156:157]
	v_pk_add_f32 v[156:157], v[124:125], v[158:159]
	v_mul_f32_e32 v124, 0x41000000, v166
	v_mul_f32_e32 v125, 0x41000000, v167
	v_mul_f32_e32 v158, 0x41000000, v168
	v_mul_f32_e32 v159, 0x41000000, v169
	v_cvt_pk_fp8_f32 v164, v124, v125
	v_cvt_pk_fp8_f32 v165, v158, v159
	v_mul_f32_e32 v126, 0x41000000, v128
	v_mul_f32_e32 v127, 0x41000000, v129
	v_mul_f32_e32 v124, 0x41000000, v156
	v_mul_f32_e32 v125, 0x41000000, v157
	v_cvt_pk_fp8_f32 v164, v126, v127 op_sel:[0,0,1]
	v_cvt_pk_fp8_f32 v165, v124, v125 op_sel:[0,0,1]
	v_cvt_pk_f16_f32 v122, v166, v167
	v_cvt_pk_f16_f32 v123, v128, v129
	v_cvt_pk_f16_f32 v124, v168, v169
	v_cvt_pk_f16_f32 v125, v156, v157
	global_store_dwordx4 v[162:163], v[122:125], off
	global_store_dwordx2 v[160:161], v[164:165], off
	global_load_dwordx4 v[124:127], v[162:163], off offset:256
	v_and_b32_e32 v123, 64, v155
	v_xor_b32_e32 v122, 16, v155
	v_add_u32_e32 v123, 64, v123
	v_xor_b32_e32 v164, 32, v155
	v_cmp_lt_i32_e64 s[2:3], v122, v123
	v_pk_mul_f32 v[128:129], v[128:129], v[128:129]
	v_pk_mul_f32 v[156:157], v[156:157], v[156:157]
	v_cndmask_b32_e64 v122, v155, v122, s[2:3]
	v_cmp_lt_i32_e64 s[2:3], v164, v123
	v_add_f32_e32 v128, v128, v129
	v_add_f32_e32 v156, v156, v157
	v_cndmask_b32_e64 v123, v155, v164, s[2:3]
	v_pk_mul_f32 v[164:165], v[166:167], v[166:167]
	v_pk_mul_f32 v[166:167], v[168:169], v[168:169]
	v_add_f32_e32 v129, v164, v165
	v_add_f32_e32 v164, v166, v167
	v_add_f32_e32 v128, v129, v128
	v_add_f32_e32 v128, v164, v128
	v_add_f32_e32 v166, v156, v128
	v_lshlrev_b32_e32 v122, 2, v122
	v_mov_b32_e32 v158, 0
	v_mov_b32_e32 v159, 0
	s_waitcnt vmcnt(0)
	v_cvt_f32_f16_e32 v128, v124
	v_cvt_f32_f16_sdwa v129, v124 dst_sel:DWORD dst_unused:UNUSED_PAD src0_sel:WORD_1
	v_cvt_f32_f16_e32 v156, v126
	v_cvt_f32_f16_sdwa v157, v126 dst_sel:DWORD dst_unused:UNUSED_PAD src0_sel:WORD_1
	v_cvt_f32_f16_e32 v124, v125
	v_cvt_f32_f16_sdwa v125, v125 dst_sel:DWORD dst_unused:UNUSED_PAD src0_sel:WORD_1
	v_cvt_f32_f16_e32 v126, v127
	v_cvt_f32_f16_sdwa v127, v127 dst_sel:DWORD dst_unused:UNUSED_PAD src0_sel:WORD_1
	v_pk_add_f32 v[128:129], v[118:119], v[128:129]
	v_pk_add_f32 v[156:157], v[114:115], v[156:157]
	v_pk_add_f32 v[114:115], v[120:121], v[124:125]
	v_pk_add_f32 v[124:125], v[116:117], v[126:127]
	v_pk_mul_f32 v[116:117], v[128:129], v[128:129]
	v_pk_mul_f32 v[120:121], v[114:115], v[114:115]
	v_pk_mul_f32 v[126:127], v[156:157], v[156:157]
	v_add_f32_e32 v120, v120, v121
	v_add_f32_e32 v116, v116, v117
	v_pk_mul_f32 v[164:165], v[124:125], v[124:125]
	v_add_f32_e32 v117, v126, v127
	v_add_f32_e32 v116, v116, v120
	v_add_f32_e32 v121, v164, v165
	v_add_f32_e32 v116, v117, v116
	v_add_f32_e32 v116, v121, v116
	v_add_f32_e32 v116, v166, v116
	v_cvt_pk_f16_f32 v118, v128, v129
	v_mul_f32_e32 v128, 0x41000000, v128
	v_mul_f32_e32 v129, 0x41000000, v129
	v_mov_b32_e32 v117, v116
	s_nop 1
	v_permlane16_swap_b32_e32 v116, v117
	v_cvt_pk_fp8_f32 v158, v128, v129
	v_mul_f32_e32 v167, 0x41000000, v156
	v_mul_f32_e32 v168, 0x41000000, v157
	v_cvt_pk_f16_f32 v119, v114, v115
	v_mul_f32_e32 v114, 0x41000000, v114
	v_mul_f32_e32 v115, 0x41000000, v115
	v_cvt_pk_fp8_f32 v159, v167, v168
	v_cvt_pk_fp8_f32 v158, v114, v115 op_sel:[0,0,1]
	s_waitcnt lgkmcnt(0)
	v_add_f32_e32 v114, v116, v117
	v_lshlrev_b32_e32 v116, 2, v123
	v_mov_b32_e32 v115, v114
	s_nop 1
	v_permlane32_swap_b32_e32 v114, v115
	v_mul_f32_e32 v120, 0x41000000, v124
	v_mul_f32_e32 v121, 0x41000000, v125
	v_cvt_pk_fp8_f32 v159, v120, v121 op_sel:[0,0,1]
	v_cvt_pk_f16_f32 v120, v156, v157
	v_cvt_pk_f16_f32 v121, v124, v125
	global_store_dwordx4 v[162:163], v[118:121], off offset:256
	global_store_dwordx2 v[160:161], v[158:159], off offset:128
	s_and_saveexec_b64 s[2:3], vcc
	s_cbranch_execz .LBB0_672
	v_lshl_add_u64 v[118:119], v[148:149], 2, s[4:5]
	s_waitcnt lgkmcnt(0)
	v_add_f32_e32 v114, v114, v115
	global_atomic_add_f32 v[118:119], v114, off
; __device__ __forceinline__ unsigned pkh(float lo, float hi) { f32x2 v = {lo, hi}; h16x2 h = __builtin_convertvector(v, h16x2); return __builtin_bit_cast(unsigned, h); }
; __device__ __forceinline__ unsigned pk8(float a, float b, float c, float d) { int w = __builtin_amdgcn_cvt_pk_fp8_f32(a, b, 0, false); w = __builtin_amdgcn_cvt_pk_fp8_f32(c, d, w, true); return (unsigned)w; }
;     __device__ __forceinline__ void operator()(f32x4 (&acc)[2][2][4][2], const Unit& u, const Order& S, int wr, int wc, int fr_, int fq_, LAS unsigned char*, int) const {
;     ...
;                 const int row = row0 + ai * HALF + m * 16; const size_t off = (size_t)row * DM + col0;
;                 float sq = 0.f;
; #pragma unroll
;                 for (int bj = 0; bj < 2; ++bj) {
;                     const h16x8 bs = *(const h16x8*)(h16 + off + bj * HALF);
;                     f32x4 o0 = acc[ai][bj][m][0] * pre, o1 = acc[ai][bj][m][1] * pre;
; #pragma unroll
;                     for (int e = 0; e < 4; ++e) { o0[e] += (float)bs[e]; o1[e] += (float)bs[4 + e]; }
;                     if (out32) { if (!dry) { __builtin_nontemporal_store(o0, (f32x4*)(out32 + off + bj * HALF)); __builtin_nontemporal_store(o1, (f32x4*)(out32 + off + bj * HALF + 4)); } }
;                     else if (!dry) {
;                         sq += (o0[0] * o0[0] + o0[1] * o0[1]) + (o0[2] * o0[2] + o0[3] * o0[3]) + (o1[0] * o1[0] + o1[1] * o1[1]) + (o1[2] * o1[2] + o1[3] * o1[3]);
;                         u32x4 w; w.x = pkh(o0[0], o0[1]); w.y = pkh(o0[2], o0[3]); w.z = pkh(o1[0], o1[1]); w.w = pkh(o1[2], o1[3]);
;                         *(u32x4*)(h16 + off + bj * HALF) = w;
;                         if (h8) { u32x2 q; q.x = pk8(o0[0] * F8_SA, o0[1] * F8_SA, o0[2] * F8_SA, o0[3] * F8_SA); q.y = pk8(o1[0] * F8_SA, o1[1] * F8_SA, o1[2] * F8_SA, o1[3] * F8_SA); *(u32x2*)(h8 + off + bj * HALF) = q; } }
;                 }
;                 if (!out32 && !dry) { sq += __shfl_xor(sq, 16); sq += __shfl_xor(sq, 32); if (fq == 0) atomicAdd(ss_out + row, sq); }
.LBB0_672:
	s_or_b64 exec, exec, s[2:3]
	v_add_u32_e32 v114, 16, v148
	s_waitcnt lgkmcnt(0)
	v_ashrrev_i32_e32 v115, 31, v114
	v_lshlrev_b64 v[118:119], 10, v[114:115]
	v_lshl_add_u64 v[124:125], v[118:119], 0, v[146:147]
	v_lshl_add_u64 v[126:127], v[124:125], 1, s[90:91]
	global_load_dwordx4 v[118:121], v[126:127], off
	v_mov_b32_e32 v128, 0
	v_mov_b32_e32 v129, 0
	v_lshl_add_u64 v[124:125], s[10:11], 0, v[124:125]
	s_waitcnt vmcnt(0)
	v_cvt_f32_f16_e32 v156, v118
	v_cvt_f32_f16_sdwa v157, v118 dst_sel:DWORD dst_unused:UNUSED_PAD src0_sel:WORD_1
	v_cvt_f32_f16_e32 v158, v120
	v_cvt_f32_f16_sdwa v159, v120 dst_sel:DWORD dst_unused:UNUSED_PAD src0_sel:WORD_1
	v_cvt_f32_f16_e32 v118, v119
	v_cvt_f32_f16_sdwa v119, v119 dst_sel:DWORD dst_unused:UNUSED_PAD src0_sel:WORD_1
	v_cvt_f32_f16_e32 v120, v121
	v_cvt_f32_f16_sdwa v121, v121 dst_sel:DWORD dst_unused:UNUSED_PAD src0_sel:WORD_1
	v_pk_add_f32 v[110:111], v[110:111], v[156:157]
	v_pk_add_f32 v[156:157], v[106:107], v[158:159]
	v_pk_add_f32 v[112:113], v[112:113], v[118:119]
	v_pk_add_f32 v[118:119], v[108:109], v[120:121]
	v_mul_f32_e32 v108, 0x41000000, v110
	v_mul_f32_e32 v109, 0x41000000, v111
	v_mul_f32_e32 v121, 0x41000000, v156
	v_mul_f32_e32 v123, 0x41000000, v157
	v_cvt_pk_fp8_f32 v128, v108, v109
	v_cvt_pk_fp8_f32 v129, v121, v123
	v_mul_f32_e32 v117, 0x41000000, v112
	v_mul_f32_e32 v120, 0x41000000, v113
	v_mul_f32_e32 v108, 0x41000000, v118
	v_mul_f32_e32 v109, 0x41000000, v119
	v_cvt_pk_fp8_f32 v128, v117, v120 op_sel:[0,0,1]
	v_cvt_pk_fp8_f32 v129, v108, v109 op_sel:[0,0,1]
	v_cvt_pk_f16_f32 v106, v110, v111
	v_cvt_pk_f16_f32 v107, v112, v113
	v_cvt_pk_f16_f32 v108, v156, v157
	v_cvt_pk_f16_f32 v109, v118, v119
	global_store_dwordx4 v[126:127], v[106:109], off
	global_store_dwordx2 v[124:125], v[128:129], off
	global_load_dwordx4 v[106:109], v[126:127], off offset:256
	v_pk_mul_f32 v[110:111], v[110:111], v[110:111]
	v_pk_mul_f32 v[112:113], v[112:113], v[112:113]
	v_pk_mul_f32 v[128:129], v[156:157], v[156:157]
	v_add_f32_e32 v112, v112, v113
	v_add_f32_e32 v110, v110, v111
	v_pk_mul_f32 v[118:119], v[118:119], v[118:119]
	v_add_f32_e32 v111, v128, v129
	v_add_f32_e32 v110, v110, v112
	v_add_f32_e32 v113, v118, v119
	v_add_f32_e32 v110, v111, v110
	v_add_f32_e32 v117, v113, v110
	v_mov_b32_e32 v120, 0
	v_mov_b32_e32 v121, 0
	s_waitcnt vmcnt(0)
	v_cvt_f32_f16_e32 v110, v106
	v_cvt_f32_f16_sdwa v111, v106 dst_sel:DWORD dst_unused:UNUSED_PAD src0_sel:WORD_1
	v_cvt_f32_f16_e32 v112, v108
	v_cvt_f32_f16_sdwa v113, v108 dst_sel:DWORD dst_unused:UNUSED_PAD src0_sel:WORD_1
	v_cvt_f32_f16_e32 v106, v107
	v_cvt_f32_f16_sdwa v107, v107 dst_sel:DWORD dst_unused:UNUSED_PAD src0_sel:WORD_1
	v_cvt_f32_f16_e32 v108, v109
	v_cvt_f32_f16_sdwa v109, v109 dst_sel:DWORD dst_unused:UNUSED_PAD src0_sel:WORD_1
	v_pk_add_f32 v[102:103], v[102:103], v[110:111]
	v_pk_add_f32 v[110:111], v[98:99], v[112:113]
	v_pk_add_f32 v[98:99], v[104:105], v[106:107]
	v_pk_add_f32 v[104:105], v[100:101], v[108:109]
	v_pk_mul_f32 v[106:107], v[102:103], v[102:103]
	v_pk_mul_f32 v[108:109], v[98:99], v[98:99]
	v_pk_mul_f32 v[112:113], v[110:111], v[110:111]
	v_cvt_pk_f16_f32 v100, v102, v103
	v_mul_f32_e32 v102, 0x41000000, v102
	v_mul_f32_e32 v103, 0x41000000, v103
	v_add_f32_e32 v108, v108, v109
	v_add_f32_e32 v106, v106, v107
	v_pk_mul_f32 v[118:119], v[104:105], v[104:105]
	v_add_f32_e32 v107, v112, v113
	v_cvt_pk_fp8_f32 v120, v102, v103
	v_add_f32_e32 v102, v106, v108
	v_add_f32_e32 v109, v118, v119
	v_add_f32_e32 v102, v107, v102
	v_add_f32_e32 v102, v109, v102
	v_add_f32_e32 v102, v117, v102
	v_mul_f32_e32 v123, 0x41000000, v110
	v_mul_f32_e32 v128, 0x41000000, v111
	v_mov_b32_e32 v103, v102
	s_nop 1
	v_permlane16_swap_b32_e32 v102, v103
	v_cvt_pk_fp8_f32 v121, v123, v128
	v_cvt_pk_f16_f32 v101, v98, v99
	v_mul_f32_e32 v98, 0x41000000, v98
	v_mul_f32_e32 v99, 0x41000000, v99
	v_cvt_pk_fp8_f32 v120, v98, v99 op_sel:[0,0,1]
	v_mul_f32_e32 v98, 0x41000000, v104
	v_mul_f32_e32 v99, 0x41000000, v105
	v_cvt_pk_fp8_f32 v121, v98, v99 op_sel:[0,0,1]
	s_waitcnt lgkmcnt(0)
	v_add_f32_e32 v98, v102, v103
	v_mov_b32_e32 v99, v98
	s_nop 1
	v_permlane32_swap_b32_e32 v98, v99
	v_cvt_pk_f16_f32 v102, v110, v111
	v_cvt_pk_f16_f32 v103, v104, v105
	global_store_dwordx4 v[126:127], v[100:103], off offset:256
	global_store_dwordx2 v[124:125], v[120:121], off offset:128
	s_and_saveexec_b64 s[2:3], vcc
	s_cbranch_execz .LBB0_674
	v_lshl_add_u64 v[100:101], v[114:115], 2, s[4:5]
	s_waitcnt lgkmcnt(0)
	v_add_f32_e32 v98, v98, v99
	global_atomic_add_f32 v[100:101], v98, off
; __device__ __forceinline__ unsigned pkh(float lo, float hi) { f32x2 v = {lo, hi}; h16x2 h = __builtin_convertvector(v, h16x2); return __builtin_bit_cast(unsigned, h); }
; __device__ __forceinline__ unsigned pk8(float a, float b, float c, float d) { int w = __builtin_amdgcn_cvt_pk_fp8_f32(a, b, 0, false); w = __builtin_amdgcn_cvt_pk_fp8_f32(c, d, w, true); return (unsigned)w; }
;     __device__ __forceinline__ void operator()(f32x4 (&acc)[2][2][4][2], const Unit& u, const Order& S, int wr, int wc, int fr_, int fq_, LAS unsigned char*, int) const {
;     ...
;                 const int row = row0 + ai * HALF + m * 16; const size_t off = (size_t)row * DM + col0;
;                 float sq = 0.f;
; #pragma unroll
;                 for (int bj = 0; bj < 2; ++bj) {
;                     const h16x8 bs = *(const h16x8*)(h16 + off + bj * HALF);
;                     f32x4 o0 = acc[ai][bj][m][0] * pre, o1 = acc[ai][bj][m][1] * pre;
; #pragma unroll
;                     for (int e = 0; e < 4; ++e) { o0[e] += (float)bs[e]; o1[e] += (float)bs[4 + e]; }
;                     if (out32) { if (!dry) { __builtin_nontemporal_store(o0, (f32x4*)(out32 + off + bj * HALF)); __builtin_nontemporal_store(o1, (f32x4*)(out32 + off + bj * HALF + 4)); } }
;                     else if (!dry) {
;                         sq += (o0[0] * o0[0] + o0[1] * o0[1]) + (o0[2] * o0[2] + o0[3] * o0[3]) + (o1[0] * o1[0] + o1[1] * o1[1]) + (o1[2] * o1[2] + o1[3] * o1[3]);
;                         u32x4 w; w.x = pkh(o0[0], o0[1]); w.y = pkh(o0[2], o0[3]); w.z = pkh(o1[0], o1[1]); w.w = pkh(o1[2], o1[3]);
;                         *(u32x4*)(h16 + off + bj * HALF) = w;
;                         if (h8) { u32x2 q; q.x = pk8(o0[0] * F8_SA, o0[1] * F8_SA, o0[2] * F8_SA, o0[3] * F8_SA); q.y = pk8(o1[0] * F8_SA, o1[1] * F8_SA, o1[2] * F8_SA, o1[3] * F8_SA); *(u32x2*)(h8 + off + bj * HALF) = q; } }
;                 }
;                 if (!out32 && !dry) { sq += __shfl_xor(sq, 16); sq += __shfl_xor(sq, 32); if (fq == 0) atomicAdd(ss_out + row, sq); }
.LBB0_674:
	s_or_b64 exec, exec, s[2:3]
	v_add_u32_e32 v98, 32, v148
	s_waitcnt lgkmcnt(0)
	v_ashrrev_i32_e32 v99, 31, v98
	v_lshlrev_b64 v[100:101], 10, v[98:99]
	v_lshl_add_u64 v[104:105], v[100:101], 0, v[146:147]
	v_lshl_add_u64 v[106:107], v[104:105], 1, s[90:91]
	global_load_dwordx4 v[100:103], v[106:107], off
	v_mov_b32_e32 v108, 0
	v_mov_b32_e32 v109, 0
	v_lshl_add_u64 v[104:105], s[10:11], 0, v[104:105]
	s_waitcnt vmcnt(0)
	v_cvt_f32_f16_e32 v110, v100
	v_cvt_f32_f16_sdwa v111, v100 dst_sel:DWORD dst_unused:UNUSED_PAD src0_sel:WORD_1
	v_cvt_f32_f16_e32 v112, v102
	v_cvt_f32_f16_sdwa v113, v102 dst_sel:DWORD dst_unused:UNUSED_PAD src0_sel:WORD_1
	v_cvt_f32_f16_e32 v100, v101
	v_cvt_f32_f16_sdwa v101, v101 dst_sel:DWORD dst_unused:UNUSED_PAD src0_sel:WORD_1
	v_cvt_f32_f16_e32 v102, v103
	v_cvt_f32_f16_sdwa v103, v103 dst_sel:DWORD dst_unused:UNUSED_PAD src0_sel:WORD_1
	v_pk_add_f32 v[94:95], v[94:95], v[110:111]
	v_pk_add_f32 v[110:111], v[90:91], v[112:113]
	v_pk_add_f32 v[96:97], v[96:97], v[100:101]
	v_pk_add_f32 v[100:101], v[92:93], v[102:103]
	v_mul_f32_e32 v92, 0x41000000, v94
	v_mul_f32_e32 v93, 0x41000000, v95
	v_mul_f32_e32 v112, 0x41000000, v110
	v_mul_f32_e32 v113, 0x41000000, v111
	v_cvt_pk_fp8_f32 v108, v92, v93
	v_cvt_pk_fp8_f32 v109, v112, v113
	v_mul_f32_e32 v102, 0x41000000, v96
	v_mul_f32_e32 v103, 0x41000000, v97
	v_mul_f32_e32 v92, 0x41000000, v100
	v_mul_f32_e32 v93, 0x41000000, v101
	v_cvt_pk_fp8_f32 v108, v102, v103 op_sel:[0,0,1]
	v_cvt_pk_fp8_f32 v109, v92, v93 op_sel:[0,0,1]
	v_cvt_pk_f16_f32 v90, v94, v95
	v_cvt_pk_f16_f32 v91, v96, v97
	v_cvt_pk_f16_f32 v92, v110, v111
	v_cvt_pk_f16_f32 v93, v100, v101
	global_store_dwordx4 v[106:107], v[90:93], off
	global_store_dwordx2 v[104:105], v[108:109], off
	global_load_dwordx4 v[90:93], v[106:107], off offset:256
	v_pk_mul_f32 v[94:95], v[94:95], v[94:95]
	v_pk_mul_f32 v[96:97], v[96:97], v[96:97]
	v_pk_mul_f32 v[108:109], v[110:111], v[110:111]
	v_add_f32_e32 v96, v96, v97
	v_add_f32_e32 v94, v94, v95
	v_pk_mul_f32 v[100:101], v[100:101], v[100:101]
	v_add_f32_e32 v95, v108, v109
	v_add_f32_e32 v94, v94, v96
	v_add_f32_e32 v97, v100, v101
	v_add_f32_e32 v94, v95, v94
	v_add_f32_e32 v108, v97, v94
	v_mov_b32_e32 v102, 0
	v_mov_b32_e32 v103, 0
	s_waitcnt vmcnt(0)
	v_cvt_f32_f16_e32 v94, v90
	v_cvt_f32_f16_sdwa v95, v90 dst_sel:DWORD dst_unused:UNUSED_PAD src0_sel:WORD_1
	v_cvt_f32_f16_e32 v96, v92
	v_cvt_f32_f16_sdwa v97, v92 dst_sel:DWORD dst_unused:UNUSED_PAD src0_sel:WORD_1
	v_cvt_f32_f16_e32 v90, v91
	v_cvt_f32_f16_sdwa v91, v91 dst_sel:DWORD dst_unused:UNUSED_PAD src0_sel:WORD_1
	v_cvt_f32_f16_e32 v92, v93
	v_cvt_f32_f16_sdwa v93, v93 dst_sel:DWORD dst_unused:UNUSED_PAD src0_sel:WORD_1
	v_pk_add_f32 v[86:87], v[86:87], v[94:95]
	v_pk_add_f32 v[94:95], v[82:83], v[96:97]
	v_pk_add_f32 v[82:83], v[88:89], v[90:91]
	v_pk_add_f32 v[88:89], v[84:85], v[92:93]
	v_pk_mul_f32 v[90:91], v[86:87], v[86:87]
	v_pk_mul_f32 v[92:93], v[82:83], v[82:83]
	v_pk_mul_f32 v[96:97], v[94:95], v[94:95]
	v_cvt_pk_f16_f32 v84, v86, v87
	v_mul_f32_e32 v86, 0x41000000, v86
	v_mul_f32_e32 v87, 0x41000000, v87
	v_add_f32_e32 v92, v92, v93
	v_add_f32_e32 v90, v90, v91
	v_pk_mul_f32 v[100:101], v[88:89], v[88:89]
	v_add_f32_e32 v91, v96, v97
	v_cvt_pk_fp8_f32 v102, v86, v87
	v_add_f32_e32 v86, v90, v92
	v_add_f32_e32 v93, v100, v101
	v_add_f32_e32 v86, v91, v86
	v_add_f32_e32 v86, v93, v86
	v_add_f32_e32 v86, v108, v86
	v_mul_f32_e32 v109, 0x41000000, v94
	v_mul_f32_e32 v110, 0x41000000, v95
	v_mov_b32_e32 v87, v86
	s_nop 1
	v_permlane16_swap_b32_e32 v86, v87
	v_cvt_pk_fp8_f32 v103, v109, v110
	v_cvt_pk_f16_f32 v85, v82, v83
	v_mul_f32_e32 v82, 0x41000000, v82
	v_mul_f32_e32 v83, 0x41000000, v83
	v_cvt_pk_fp8_f32 v102, v82, v83 op_sel:[0,0,1]
	v_mul_f32_e32 v82, 0x41000000, v88
	v_mul_f32_e32 v83, 0x41000000, v89
	v_cvt_pk_fp8_f32 v103, v82, v83 op_sel:[0,0,1]
	s_waitcnt lgkmcnt(0)
	v_add_f32_e32 v82, v86, v87
	v_mov_b32_e32 v83, v82
	s_nop 1
	v_permlane32_swap_b32_e32 v82, v83
	v_cvt_pk_f16_f32 v86, v94, v95
	v_cvt_pk_f16_f32 v87, v88, v89
	global_store_dwordx4 v[106:107], v[84:87], off offset:256
	global_store_dwordx2 v[104:105], v[102:103], off offset:128
	s_and_saveexec_b64 s[2:3], vcc
	s_cbranch_execz .LBB0_676
	v_lshl_add_u64 v[84:85], v[98:99], 2, s[4:5]
	s_waitcnt lgkmcnt(0)
	v_add_f32_e32 v82, v82, v83
	global_atomic_add_f32 v[84:85], v82, off
; __device__ __forceinline__ unsigned pkh(float lo, float hi) { f32x2 v = {lo, hi}; h16x2 h = __builtin_convertvector(v, h16x2); return __builtin_bit_cast(unsigned, h); }
; __device__ __forceinline__ unsigned pk8(float a, float b, float c, float d) { int w = __builtin_amdgcn_cvt_pk_fp8_f32(a, b, 0, false); w = __builtin_amdgcn_cvt_pk_fp8_f32(c, d, w, true); return (unsigned)w; }
;     __device__ __forceinline__ void operator()(f32x4 (&acc)[2][2][4][2], const Unit& u, const Order& S, int wr, int wc, int fr_, int fq_, LAS unsigned char*, int) const {
;     ...
;                 const int row = row0 + ai * HALF + m * 16; const size_t off = (size_t)row * DM + col0;
;                 float sq = 0.f;
; #pragma unroll
;                 for (int bj = 0; bj < 2; ++bj) {
;                     const h16x8 bs = *(const h16x8*)(h16 + off + bj * HALF);
;                     f32x4 o0 = acc[ai][bj][m][0] * pre, o1 = acc[ai][bj][m][1] * pre;
; #pragma unroll
;                     for (int e = 0; e < 4; ++e) { o0[e] += (float)bs[e]; o1[e] += (float)bs[4 + e]; }
;                     if (out32) { if (!dry) { __builtin_nontemporal_store(o0, (f32x4*)(out32 + off + bj * HALF)); __builtin_nontemporal_store(o1, (f32x4*)(out32 + off + bj * HALF + 4)); } }
;                     else if (!dry) {
;                         sq += (o0[0] * o0[0] + o0[1] * o0[1]) + (o0[2] * o0[2] + o0[3] * o0[3]) + (o1[0] * o1[0] + o1[1] * o1[1]) + (o1[2] * o1[2] + o1[3] * o1[3]);
;                         u32x4 w; w.x = pkh(o0[0], o0[1]); w.y = pkh(o0[2], o0[3]); w.z = pkh(o1[0], o1[1]); w.w = pkh(o1[2], o1[3]);
;                         *(u32x4*)(h16 + off + bj * HALF) = w;
;                         if (h8) { u32x2 q; q.x = pk8(o0[0] * F8_SA, o0[1] * F8_SA, o0[2] * F8_SA, o0[3] * F8_SA); q.y = pk8(o1[0] * F8_SA, o1[1] * F8_SA, o1[2] * F8_SA, o1[3] * F8_SA); *(u32x2*)(h8 + off + bj * HALF) = q; } }
;                 }
;                 if (!out32 && !dry) { sq += __shfl_xor(sq, 16); sq += __shfl_xor(sq, 32); if (fq == 0) atomicAdd(ss_out + row, sq); }
.LBB0_676:
	s_or_b64 exec, exec, s[2:3]
	v_add_u32_e32 v82, 48, v148
	s_waitcnt lgkmcnt(0)
	v_ashrrev_i32_e32 v83, 31, v82
	v_lshlrev_b64 v[84:85], 10, v[82:83]
	v_lshl_add_u64 v[88:89], v[84:85], 0, v[146:147]
	v_lshl_add_u64 v[90:91], v[88:89], 1, s[90:91]
	global_load_dwordx4 v[84:87], v[90:91], off
	v_mov_b32_e32 v92, 0
	v_mov_b32_e32 v93, 0
	v_lshl_add_u64 v[88:89], s[10:11], 0, v[88:89]
	s_waitcnt vmcnt(0)
	v_cvt_f32_f16_e32 v94, v84
	v_cvt_f32_f16_sdwa v95, v84 dst_sel:DWORD dst_unused:UNUSED_PAD src0_sel:WORD_1
	v_cvt_f32_f16_e32 v96, v86
	v_cvt_f32_f16_sdwa v97, v86 dst_sel:DWORD dst_unused:UNUSED_PAD src0_sel:WORD_1
	v_cvt_f32_f16_e32 v84, v85
	v_cvt_f32_f16_sdwa v85, v85 dst_sel:DWORD dst_unused:UNUSED_PAD src0_sel:WORD_1
	v_cvt_f32_f16_e32 v86, v87
	v_cvt_f32_f16_sdwa v87, v87 dst_sel:DWORD dst_unused:UNUSED_PAD src0_sel:WORD_1
	v_pk_add_f32 v[78:79], v[78:79], v[94:95]
	v_pk_add_f32 v[94:95], v[74:75], v[96:97]
	v_pk_add_f32 v[80:81], v[80:81], v[84:85]
	v_pk_add_f32 v[84:85], v[76:77], v[86:87]
	v_mul_f32_e32 v76, 0x41000000, v78
	v_mul_f32_e32 v77, 0x41000000, v79
	v_mul_f32_e32 v96, 0x41000000, v94
	v_mul_f32_e32 v97, 0x41000000, v95
	v_cvt_pk_fp8_f32 v92, v76, v77
	v_cvt_pk_fp8_f32 v93, v96, v97
	v_mul_f32_e32 v86, 0x41000000, v80
	v_mul_f32_e32 v87, 0x41000000, v81
	v_mul_f32_e32 v76, 0x41000000, v84
	v_mul_f32_e32 v77, 0x41000000, v85
	v_cvt_pk_fp8_f32 v92, v86, v87 op_sel:[0,0,1]
	v_cvt_pk_fp8_f32 v93, v76, v77 op_sel:[0,0,1]
	v_cvt_pk_f16_f32 v74, v78, v79
	v_cvt_pk_f16_f32 v75, v80, v81
	v_cvt_pk_f16_f32 v76, v94, v95
	v_cvt_pk_f16_f32 v77, v84, v85
	global_store_dwordx4 v[90:91], v[74:77], off
	global_store_dwordx2 v[88:89], v[92:93], off
	global_load_dwordx4 v[74:77], v[90:91], off offset:256
	v_pk_mul_f32 v[78:79], v[78:79], v[78:79]
	v_pk_mul_f32 v[80:81], v[80:81], v[80:81]
	v_pk_mul_f32 v[92:93], v[94:95], v[94:95]
	v_add_f32_e32 v80, v80, v81
	v_add_f32_e32 v78, v78, v79
	v_pk_mul_f32 v[84:85], v[84:85], v[84:85]
	v_add_f32_e32 v79, v92, v93
	v_add_f32_e32 v78, v78, v80
	v_add_f32_e32 v81, v84, v85
	v_add_f32_e32 v78, v79, v78
	v_add_f32_e32 v92, v81, v78
	v_mov_b32_e32 v86, 0
	v_mov_b32_e32 v87, 0
	s_waitcnt vmcnt(0)
	v_cvt_f32_f16_e32 v78, v74
	v_cvt_f32_f16_sdwa v79, v74 dst_sel:DWORD dst_unused:UNUSED_PAD src0_sel:WORD_1
	v_cvt_f32_f16_e32 v80, v76
	v_cvt_f32_f16_sdwa v81, v76 dst_sel:DWORD dst_unused:UNUSED_PAD src0_sel:WORD_1
	v_cvt_f32_f16_e32 v74, v75
	v_cvt_f32_f16_sdwa v75, v75 dst_sel:DWORD dst_unused:UNUSED_PAD src0_sel:WORD_1
	v_cvt_f32_f16_e32 v76, v77
	v_cvt_f32_f16_sdwa v77, v77 dst_sel:DWORD dst_unused:UNUSED_PAD src0_sel:WORD_1
	v_pk_add_f32 v[70:71], v[70:71], v[78:79]
	v_pk_add_f32 v[78:79], v[66:67], v[80:81]
	v_pk_add_f32 v[66:67], v[72:73], v[74:75]
	v_pk_add_f32 v[72:73], v[68:69], v[76:77]
	v_pk_mul_f32 v[74:75], v[70:71], v[70:71]
	v_pk_mul_f32 v[76:77], v[66:67], v[66:67]
	v_pk_mul_f32 v[80:81], v[78:79], v[78:79]
	v_cvt_pk_f16_f32 v68, v70, v71
	v_mul_f32_e32 v70, 0x41000000, v70
	v_mul_f32_e32 v71, 0x41000000, v71
	v_add_f32_e32 v76, v76, v77
	v_add_f32_e32 v74, v74, v75
	v_pk_mul_f32 v[84:85], v[72:73], v[72:73]
	v_add_f32_e32 v75, v80, v81
	v_cvt_pk_fp8_f32 v86, v70, v71
	v_add_f32_e32 v70, v74, v76
	v_add_f32_e32 v77, v84, v85
	v_add_f32_e32 v70, v75, v70
	v_add_f32_e32 v70, v77, v70
	v_add_f32_e32 v70, v92, v70
	v_mul_f32_e32 v93, 0x41000000, v78
	v_mul_f32_e32 v94, 0x41000000, v79
	v_mov_b32_e32 v71, v70
	s_nop 1
	v_permlane16_swap_b32_e32 v70, v71
	v_cvt_pk_fp8_f32 v87, v93, v94
	v_cvt_pk_f16_f32 v69, v66, v67
	v_mul_f32_e32 v66, 0x41000000, v66
	v_mul_f32_e32 v67, 0x41000000, v67
	v_cvt_pk_fp8_f32 v86, v66, v67 op_sel:[0,0,1]
	v_mul_f32_e32 v66, 0x41000000, v72
	v_mul_f32_e32 v67, 0x41000000, v73
	v_cvt_pk_fp8_f32 v87, v66, v67 op_sel:[0,0,1]
	s_waitcnt lgkmcnt(0)
	v_add_f32_e32 v66, v70, v71
	v_mov_b32_e32 v67, v66
	s_nop 1
	v_permlane32_swap_b32_e32 v66, v67
	v_cvt_pk_f16_f32 v70, v78, v79
	v_cvt_pk_f16_f32 v71, v72, v73
	global_store_dwordx4 v[90:91], v[68:71], off offset:256
	global_store_dwordx2 v[88:89], v[86:87], off offset:128
	s_and_saveexec_b64 s[2:3], vcc
	s_cbranch_execz .LBB0_678
	v_lshl_add_u64 v[68:69], v[82:83], 2, s[4:5]
	s_waitcnt lgkmcnt(0)
	v_add_f32_e32 v66, v66, v67
	global_atomic_add_f32 v[68:69], v66, off
; __device__ __forceinline__ unsigned pkh(float lo, float hi) { f32x2 v = {lo, hi}; h16x2 h = __builtin_convertvector(v, h16x2); return __builtin_bit_cast(unsigned, h); }
; __device__ __forceinline__ unsigned pk8(float a, float b, float c, float d) { int w = __builtin_amdgcn_cvt_pk_fp8_f32(a, b, 0, false); w = __builtin_amdgcn_cvt_pk_fp8_f32(c, d, w, true); return (unsigned)w; }
;     __device__ __forceinline__ void operator()(f32x4 (&acc)[2][2][4][2], const Unit& u, const Order& S, int wr, int wc, int fr_, int fq_, LAS unsigned char*, int) const {
;     ...
;                 const int row = row0 + ai * HALF + m * 16; const size_t off = (size_t)row * DM + col0;
;                 float sq = 0.f;
; #pragma unroll
;                 for (int bj = 0; bj < 2; ++bj) {
;                     const h16x8 bs = *(const h16x8*)(h16 + off + bj * HALF);
;                     f32x4 o0 = acc[ai][bj][m][0] * pre, o1 = acc[ai][bj][m][1] * pre;
; #pragma unroll
;                     for (int e = 0; e < 4; ++e) { o0[e] += (float)bs[e]; o1[e] += (float)bs[4 + e]; }
;                     if (out32) { if (!dry) { __builtin_nontemporal_store(o0, (f32x4*)(out32 + off + bj * HALF)); __builtin_nontemporal_store(o1, (f32x4*)(out32 + off + bj * HALF + 4)); } }
;                     else if (!dry) {
;                         sq += (o0[0] * o0[0] + o0[1] * o0[1]) + (o0[2] * o0[2] + o0[3] * o0[3]) + (o1[0] * o1[0] + o1[1] * o1[1]) + (o1[2] * o1[2] + o1[3] * o1[3]);
;                         u32x4 w; w.x = pkh(o0[0], o0[1]); w.y = pkh(o0[2], o0[3]); w.z = pkh(o1[0], o1[1]); w.w = pkh(o1[2], o1[3]);
;                         *(u32x4*)(h16 + off + bj * HALF) = w;
;                         if (h8) { u32x2 q; q.x = pk8(o0[0] * F8_SA, o0[1] * F8_SA, o0[2] * F8_SA, o0[3] * F8_SA); q.y = pk8(o1[0] * F8_SA, o1[1] * F8_SA, o1[2] * F8_SA, o1[3] * F8_SA); *(u32x2*)(h8 + off + bj * HALF) = q; } }
;                 }
;                 if (!out32 && !dry) { sq += __shfl_xor(sq, 16); sq += __shfl_xor(sq, 32); if (fq == 0) atomicAdd(ss_out + row, sq); }
.LBB0_678:
	s_or_b64 exec, exec, s[2:3]
	v_add_u32_e32 v66, 0x80, v148
	s_waitcnt lgkmcnt(0)
	v_ashrrev_i32_e32 v67, 31, v66
	v_lshlrev_b64 v[68:69], 10, v[66:67]
	v_lshl_add_u64 v[72:73], v[68:69], 0, v[146:147]
	v_lshl_add_u64 v[74:75], v[72:73], 1, s[90:91]
	global_load_dwordx4 v[68:71], v[74:75], off
	v_mov_b32_e32 v76, 0
	v_mov_b32_e32 v77, 0
	v_lshl_add_u64 v[72:73], s[10:11], 0, v[72:73]
	s_waitcnt vmcnt(0)
	v_cvt_f32_f16_e32 v78, v68
	v_cvt_f32_f16_sdwa v79, v68 dst_sel:DWORD dst_unused:UNUSED_PAD src0_sel:WORD_1
	v_cvt_f32_f16_e32 v80, v70
	v_cvt_f32_f16_sdwa v81, v70 dst_sel:DWORD dst_unused:UNUSED_PAD src0_sel:WORD_1
	v_cvt_f32_f16_e32 v68, v69
	v_cvt_f32_f16_sdwa v69, v69 dst_sel:DWORD dst_unused:UNUSED_PAD src0_sel:WORD_1
	v_cvt_f32_f16_e32 v70, v71
	v_cvt_f32_f16_sdwa v71, v71 dst_sel:DWORD dst_unused:UNUSED_PAD src0_sel:WORD_1
	v_pk_add_f32 v[62:63], v[62:63], v[78:79]
	v_pk_add_f32 v[78:79], v[58:59], v[80:81]
	v_pk_add_f32 v[64:65], v[64:65], v[68:69]
	v_pk_add_f32 v[68:69], v[60:61], v[70:71]
	v_mul_f32_e32 v60, 0x41000000, v62
	v_mul_f32_e32 v61, 0x41000000, v63
	v_mul_f32_e32 v80, 0x41000000, v78
	v_mul_f32_e32 v81, 0x41000000, v79
	v_cvt_pk_fp8_f32 v76, v60, v61
	v_cvt_pk_fp8_f32 v77, v80, v81
	v_mul_f32_e32 v70, 0x41000000, v64
	v_mul_f32_e32 v71, 0x41000000, v65
	v_mul_f32_e32 v60, 0x41000000, v68
	v_mul_f32_e32 v61, 0x41000000, v69
	v_cvt_pk_fp8_f32 v76, v70, v71 op_sel:[0,0,1]
	v_cvt_pk_fp8_f32 v77, v60, v61 op_sel:[0,0,1]
	v_cvt_pk_f16_f32 v58, v62, v63
	v_cvt_pk_f16_f32 v59, v64, v65
	v_cvt_pk_f16_f32 v60, v78, v79
	v_cvt_pk_f16_f32 v61, v68, v69
	global_store_dwordx4 v[74:75], v[58:61], off
	global_store_dwordx2 v[72:73], v[76:77], off
	global_load_dwordx4 v[58:61], v[74:75], off offset:256
	v_pk_mul_f32 v[62:63], v[62:63], v[62:63]
	v_pk_mul_f32 v[64:65], v[64:65], v[64:65]
	v_pk_mul_f32 v[76:77], v[78:79], v[78:79]
	v_add_f32_e32 v64, v64, v65
	v_add_f32_e32 v62, v62, v63
	v_pk_mul_f32 v[68:69], v[68:69], v[68:69]
	v_add_f32_e32 v63, v76, v77
	v_add_f32_e32 v62, v62, v64
	v_add_f32_e32 v65, v68, v69
	v_add_f32_e32 v62, v63, v62
	v_add_f32_e32 v76, v65, v62
	v_mov_b32_e32 v70, 0
	v_mov_b32_e32 v71, 0
	s_waitcnt vmcnt(0)
	v_cvt_f32_f16_e32 v62, v58
	v_cvt_f32_f16_sdwa v63, v58 dst_sel:DWORD dst_unused:UNUSED_PAD src0_sel:WORD_1
	v_cvt_f32_f16_e32 v64, v60
	v_cvt_f32_f16_sdwa v65, v60 dst_sel:DWORD dst_unused:UNUSED_PAD src0_sel:WORD_1
	v_cvt_f32_f16_e32 v58, v59
	v_cvt_f32_f16_sdwa v59, v59 dst_sel:DWORD dst_unused:UNUSED_PAD src0_sel:WORD_1
	v_cvt_f32_f16_e32 v60, v61
	v_cvt_f32_f16_sdwa v61, v61 dst_sel:DWORD dst_unused:UNUSED_PAD src0_sel:WORD_1
	v_pk_add_f32 v[54:55], v[54:55], v[62:63]
	v_pk_add_f32 v[62:63], v[50:51], v[64:65]
	v_pk_add_f32 v[50:51], v[56:57], v[58:59]
	v_pk_add_f32 v[56:57], v[52:53], v[60:61]
	v_pk_mul_f32 v[58:59], v[54:55], v[54:55]
	v_pk_mul_f32 v[60:61], v[50:51], v[50:51]
	v_pk_mul_f32 v[64:65], v[62:63], v[62:63]
	v_cvt_pk_f16_f32 v52, v54, v55
	v_mul_f32_e32 v54, 0x41000000, v54
	v_mul_f32_e32 v55, 0x41000000, v55
	v_add_f32_e32 v60, v60, v61
	v_add_f32_e32 v58, v58, v59
	v_pk_mul_f32 v[68:69], v[56:57], v[56:57]
	v_add_f32_e32 v59, v64, v65
	v_cvt_pk_fp8_f32 v70, v54, v55
	v_add_f32_e32 v54, v58, v60
	v_add_f32_e32 v61, v68, v69
	v_add_f32_e32 v54, v59, v54
	v_add_f32_e32 v54, v61, v54
	v_add_f32_e32 v54, v76, v54
	v_mul_f32_e32 v77, 0x41000000, v62
	v_mul_f32_e32 v78, 0x41000000, v63
	v_mov_b32_e32 v55, v54
	s_nop 1
	v_permlane16_swap_b32_e32 v54, v55
	v_cvt_pk_fp8_f32 v71, v77, v78
	v_cvt_pk_f16_f32 v53, v50, v51
	v_mul_f32_e32 v50, 0x41000000, v50
	v_mul_f32_e32 v51, 0x41000000, v51
	v_cvt_pk_fp8_f32 v70, v50, v51 op_sel:[0,0,1]
	v_mul_f32_e32 v50, 0x41000000, v56
	v_mul_f32_e32 v51, 0x41000000, v57
	v_cvt_pk_fp8_f32 v71, v50, v51 op_sel:[0,0,1]
	s_waitcnt lgkmcnt(0)
	v_add_f32_e32 v50, v54, v55
	v_mov_b32_e32 v51, v50
	s_nop 1
	v_permlane32_swap_b32_e32 v50, v51
	v_cvt_pk_f16_f32 v54, v62, v63
	v_cvt_pk_f16_f32 v55, v56, v57
	global_store_dwordx4 v[74:75], v[52:55], off offset:256
	global_store_dwordx2 v[72:73], v[70:71], off offset:128
	s_and_saveexec_b64 s[2:3], vcc
	s_cbranch_execz .LBB0_680
	v_lshl_add_u64 v[52:53], v[66:67], 2, s[4:5]
	s_waitcnt lgkmcnt(0)
	v_add_f32_e32 v50, v50, v51
	global_atomic_add_f32 v[52:53], v50, off
; __device__ __forceinline__ unsigned pkh(float lo, float hi) { f32x2 v = {lo, hi}; h16x2 h = __builtin_convertvector(v, h16x2); return __builtin_bit_cast(unsigned, h); }
; __device__ __forceinline__ unsigned pk8(float a, float b, float c, float d) { int w = __builtin_amdgcn_cvt_pk_fp8_f32(a, b, 0, false); w = __builtin_amdgcn_cvt_pk_fp8_f32(c, d, w, true); return (unsigned)w; }
;     __device__ __forceinline__ void operator()(f32x4 (&acc)[2][2][4][2], const Unit& u, const Order& S, int wr, int wc, int fr_, int fq_, LAS unsigned char*, int) const {
;     ...
;                 const int row = row0 + ai * HALF + m * 16; const size_t off = (size_t)row * DM + col0;
;                 float sq = 0.f;
; #pragma unroll
;                 for (int bj = 0; bj < 2; ++bj) {
;                     const h16x8 bs = *(const h16x8*)(h16 + off + bj * HALF);
;                     f32x4 o0 = acc[ai][bj][m][0] * pre, o1 = acc[ai][bj][m][1] * pre;
; #pragma unroll
;                     for (int e = 0; e < 4; ++e) { o0[e] += (float)bs[e]; o1[e] += (float)bs[4 + e]; }
;                     if (out32) { if (!dry) { __builtin_nontemporal_store(o0, (f32x4*)(out32 + off + bj * HALF)); __builtin_nontemporal_store(o1, (f32x4*)(out32 + off + bj * HALF + 4)); } }
;                     else if (!dry) {
;                         sq += (o0[0] * o0[0] + o0[1] * o0[1]) + (o0[2] * o0[2] + o0[3] * o0[3]) + (o1[0] * o1[0] + o1[1] * o1[1]) + (o1[2] * o1[2] + o1[3] * o1[3]);
;                         u32x4 w; w.x = pkh(o0[0], o0[1]); w.y = pkh(o0[2], o0[3]); w.z = pkh(o1[0], o1[1]); w.w = pkh(o1[2], o1[3]);
;                         *(u32x4*)(h16 + off + bj * HALF) = w;
;                         if (h8) { u32x2 q; q.x = pk8(o0[0] * F8_SA, o0[1] * F8_SA, o0[2] * F8_SA, o0[3] * F8_SA); q.y = pk8(o1[0] * F8_SA, o1[1] * F8_SA, o1[2] * F8_SA, o1[3] * F8_SA); *(u32x2*)(h8 + off + bj * HALF) = q; } }
;                 }
;                 if (!out32 && !dry) { sq += __shfl_xor(sq, 16); sq += __shfl_xor(sq, 32); if (fq == 0) atomicAdd(ss_out + row, sq); }
.LBB0_680:
	s_or_b64 exec, exec, s[2:3]
	v_add_u32_e32 v50, 0x90, v148
	s_waitcnt lgkmcnt(0)
	v_ashrrev_i32_e32 v51, 31, v50
	v_lshlrev_b64 v[52:53], 10, v[50:51]
	v_lshl_add_u64 v[56:57], v[52:53], 0, v[146:147]
	v_lshl_add_u64 v[58:59], v[56:57], 1, s[90:91]
	global_load_dwordx4 v[52:55], v[58:59], off
	v_mov_b32_e32 v60, 0
	v_mov_b32_e32 v61, 0
	v_lshl_add_u64 v[56:57], s[10:11], 0, v[56:57]
	s_waitcnt vmcnt(0)
	v_cvt_f32_f16_e32 v62, v52
	v_cvt_f32_f16_sdwa v63, v52 dst_sel:DWORD dst_unused:UNUSED_PAD src0_sel:WORD_1
	v_cvt_f32_f16_e32 v64, v54
	v_cvt_f32_f16_sdwa v65, v54 dst_sel:DWORD dst_unused:UNUSED_PAD src0_sel:WORD_1
	v_cvt_f32_f16_e32 v52, v53
	v_cvt_f32_f16_sdwa v53, v53 dst_sel:DWORD dst_unused:UNUSED_PAD src0_sel:WORD_1
	v_cvt_f32_f16_e32 v54, v55
	v_cvt_f32_f16_sdwa v55, v55 dst_sel:DWORD dst_unused:UNUSED_PAD src0_sel:WORD_1
	v_pk_add_f32 v[46:47], v[46:47], v[62:63]
	v_pk_add_f32 v[62:63], v[42:43], v[64:65]
	v_pk_add_f32 v[48:49], v[48:49], v[52:53]
	v_pk_add_f32 v[52:53], v[44:45], v[54:55]
	v_mul_f32_e32 v44, 0x41000000, v46
	v_mul_f32_e32 v45, 0x41000000, v47
	v_mul_f32_e32 v64, 0x41000000, v62
	v_mul_f32_e32 v65, 0x41000000, v63
	v_cvt_pk_fp8_f32 v60, v44, v45
	v_cvt_pk_fp8_f32 v61, v64, v65
	v_mul_f32_e32 v54, 0x41000000, v48
	v_mul_f32_e32 v55, 0x41000000, v49
	v_mul_f32_e32 v44, 0x41000000, v52
	v_mul_f32_e32 v45, 0x41000000, v53
	v_cvt_pk_fp8_f32 v60, v54, v55 op_sel:[0,0,1]
	v_cvt_pk_fp8_f32 v61, v44, v45 op_sel:[0,0,1]
	v_cvt_pk_f16_f32 v42, v46, v47
	v_cvt_pk_f16_f32 v43, v48, v49
	v_cvt_pk_f16_f32 v44, v62, v63
	v_cvt_pk_f16_f32 v45, v52, v53
	global_store_dwordx4 v[58:59], v[42:45], off
	global_store_dwordx2 v[56:57], v[60:61], off
	global_load_dwordx4 v[42:45], v[58:59], off offset:256
	v_pk_mul_f32 v[46:47], v[46:47], v[46:47]
	v_pk_mul_f32 v[48:49], v[48:49], v[48:49]
	v_pk_mul_f32 v[60:61], v[62:63], v[62:63]
	v_add_f32_e32 v48, v48, v49
	v_add_f32_e32 v46, v46, v47
	v_pk_mul_f32 v[52:53], v[52:53], v[52:53]
	v_add_f32_e32 v47, v60, v61
	v_add_f32_e32 v46, v46, v48
	v_add_f32_e32 v49, v52, v53
	v_add_f32_e32 v46, v47, v46
	v_add_f32_e32 v60, v49, v46
	v_mov_b32_e32 v54, 0
	v_mov_b32_e32 v55, 0
	s_waitcnt vmcnt(0)
	v_cvt_f32_f16_e32 v46, v42
	v_cvt_f32_f16_sdwa v47, v42 dst_sel:DWORD dst_unused:UNUSED_PAD src0_sel:WORD_1
	v_cvt_f32_f16_e32 v48, v44
	v_cvt_f32_f16_sdwa v49, v44 dst_sel:DWORD dst_unused:UNUSED_PAD src0_sel:WORD_1
	v_cvt_f32_f16_e32 v42, v43
	v_cvt_f32_f16_sdwa v43, v43 dst_sel:DWORD dst_unused:UNUSED_PAD src0_sel:WORD_1
	v_cvt_f32_f16_e32 v44, v45
	v_cvt_f32_f16_sdwa v45, v45 dst_sel:DWORD dst_unused:UNUSED_PAD src0_sel:WORD_1
	v_pk_add_f32 v[38:39], v[38:39], v[46:47]
	v_pk_add_f32 v[46:47], v[34:35], v[48:49]
	v_pk_add_f32 v[34:35], v[40:41], v[42:43]
	v_pk_add_f32 v[40:41], v[36:37], v[44:45]
	v_pk_mul_f32 v[42:43], v[38:39], v[38:39]
	v_pk_mul_f32 v[44:45], v[34:35], v[34:35]
	v_pk_mul_f32 v[48:49], v[46:47], v[46:47]
	v_cvt_pk_f16_f32 v36, v38, v39
	v_mul_f32_e32 v38, 0x41000000, v38
	v_mul_f32_e32 v39, 0x41000000, v39
	v_add_f32_e32 v44, v44, v45
	v_add_f32_e32 v42, v42, v43
	v_pk_mul_f32 v[52:53], v[40:41], v[40:41]
	v_add_f32_e32 v43, v48, v49
	v_cvt_pk_fp8_f32 v54, v38, v39
	v_add_f32_e32 v38, v42, v44
	v_add_f32_e32 v45, v52, v53
	v_add_f32_e32 v38, v43, v38
	v_add_f32_e32 v38, v45, v38
	v_add_f32_e32 v38, v60, v38
	v_mul_f32_e32 v61, 0x41000000, v46
	v_mul_f32_e32 v62, 0x41000000, v47
	v_mov_b32_e32 v39, v38
	s_nop 1
	v_permlane16_swap_b32_e32 v38, v39
	v_cvt_pk_fp8_f32 v55, v61, v62
	v_cvt_pk_f16_f32 v37, v34, v35
	v_mul_f32_e32 v34, 0x41000000, v34
	v_mul_f32_e32 v35, 0x41000000, v35
	v_cvt_pk_fp8_f32 v54, v34, v35 op_sel:[0,0,1]
	v_mul_f32_e32 v34, 0x41000000, v40
	v_mul_f32_e32 v35, 0x41000000, v41
	v_cvt_pk_fp8_f32 v55, v34, v35 op_sel:[0,0,1]
	s_waitcnt lgkmcnt(0)
	v_add_f32_e32 v34, v38, v39
	v_mov_b32_e32 v35, v34
	s_nop 1
	v_permlane32_swap_b32_e32 v34, v35
	v_cvt_pk_f16_f32 v38, v46, v47
	v_cvt_pk_f16_f32 v39, v40, v41
	global_store_dwordx4 v[58:59], v[36:39], off offset:256
	global_store_dwordx2 v[56:57], v[54:55], off offset:128
	s_and_saveexec_b64 s[2:3], vcc
	s_cbranch_execz .LBB0_682
	v_lshl_add_u64 v[36:37], v[50:51], 2, s[4:5]
	s_waitcnt lgkmcnt(0)
	v_add_f32_e32 v34, v34, v35
	global_atomic_add_f32 v[36:37], v34, off
; __device__ __forceinline__ unsigned pkh(float lo, float hi) { f32x2 v = {lo, hi}; h16x2 h = __builtin_convertvector(v, h16x2); return __builtin_bit_cast(unsigned, h); }
; __device__ __forceinline__ unsigned pk8(float a, float b, float c, float d) { int w = __builtin_amdgcn_cvt_pk_fp8_f32(a, b, 0, false); w = __builtin_amdgcn_cvt_pk_fp8_f32(c, d, w, true); return (unsigned)w; }
;     __device__ __forceinline__ void operator()(f32x4 (&acc)[2][2][4][2], const Unit& u, const Order& S, int wr, int wc, int fr_, int fq_, LAS unsigned char*, int) const {
;     ...
;                 const int row = row0 + ai * HALF + m * 16; const size_t off = (size_t)row * DM + col0;
;                 float sq = 0.f;
; #pragma unroll
;                 for (int bj = 0; bj < 2; ++bj) {
;                     const h16x8 bs = *(const h16x8*)(h16 + off + bj * HALF);
;                     f32x4 o0 = acc[ai][bj][m][0] * pre, o1 = acc[ai][bj][m][1] * pre;
; #pragma unroll
;                     for (int e = 0; e < 4; ++e) { o0[e] += (float)bs[e]; o1[e] += (float)bs[4 + e]; }
;                     if (out32) { if (!dry) { __builtin_nontemporal_store(o0, (f32x4*)(out32 + off + bj * HALF)); __builtin_nontemporal_store(o1, (f32x4*)(out32 + off + bj * HALF + 4)); } }
;                     else if (!dry) {
;                         sq += (o0[0] * o0[0] + o0[1] * o0[1]) + (o0[2] * o0[2] + o0[3] * o0[3]) + (o1[0] * o1[0] + o1[1] * o1[1]) + (o1[2] * o1[2] + o1[3] * o1[3]);
;                         u32x4 w; w.x = pkh(o0[0], o0[1]); w.y = pkh(o0[2], o0[3]); w.z = pkh(o1[0], o1[1]); w.w = pkh(o1[2], o1[3]);
;                         *(u32x4*)(h16 + off + bj * HALF) = w;
;                         if (h8) { u32x2 q; q.x = pk8(o0[0] * F8_SA, o0[1] * F8_SA, o0[2] * F8_SA, o0[3] * F8_SA); q.y = pk8(o1[0] * F8_SA, o1[1] * F8_SA, o1[2] * F8_SA, o1[3] * F8_SA); *(u32x2*)(h8 + off + bj * HALF) = q; } }
;                 }
;                 if (!out32 && !dry) { sq += __shfl_xor(sq, 16); sq += __shfl_xor(sq, 32); if (fq == 0) atomicAdd(ss_out + row, sq); }
.LBB0_682:
	s_or_b64 exec, exec, s[2:3]
	v_add_u32_e32 v34, 0xa0, v148
	s_waitcnt lgkmcnt(0)
	v_ashrrev_i32_e32 v35, 31, v34
	v_lshlrev_b64 v[36:37], 10, v[34:35]
	v_lshl_add_u64 v[40:41], v[36:37], 0, v[146:147]
	v_lshl_add_u64 v[42:43], v[40:41], 1, s[90:91]
	global_load_dwordx4 v[36:39], v[42:43], off
	v_mov_b32_e32 v44, 0
	v_mov_b32_e32 v45, 0
	v_lshl_add_u64 v[40:41], s[10:11], 0, v[40:41]
	s_waitcnt vmcnt(0)
	v_cvt_f32_f16_e32 v46, v36
	v_cvt_f32_f16_sdwa v47, v36 dst_sel:DWORD dst_unused:UNUSED_PAD src0_sel:WORD_1
	v_cvt_f32_f16_e32 v48, v38
	v_cvt_f32_f16_sdwa v49, v38 dst_sel:DWORD dst_unused:UNUSED_PAD src0_sel:WORD_1
	v_cvt_f32_f16_e32 v36, v37
	v_cvt_f32_f16_sdwa v37, v37 dst_sel:DWORD dst_unused:UNUSED_PAD src0_sel:WORD_1
	v_cvt_f32_f16_e32 v38, v39
	v_cvt_f32_f16_sdwa v39, v39 dst_sel:DWORD dst_unused:UNUSED_PAD src0_sel:WORD_1
	v_pk_add_f32 v[30:31], v[30:31], v[46:47]
	v_pk_add_f32 v[46:47], v[26:27], v[48:49]
	v_pk_add_f32 v[32:33], v[32:33], v[36:37]
	v_pk_add_f32 v[36:37], v[28:29], v[38:39]
	v_mul_f32_e32 v28, 0x41000000, v30
	v_mul_f32_e32 v29, 0x41000000, v31
	v_mul_f32_e32 v48, 0x41000000, v46
	v_mul_f32_e32 v49, 0x41000000, v47
	v_cvt_pk_fp8_f32 v44, v28, v29
	v_cvt_pk_fp8_f32 v45, v48, v49
	v_mul_f32_e32 v38, 0x41000000, v32
	v_mul_f32_e32 v39, 0x41000000, v33
	v_mul_f32_e32 v28, 0x41000000, v36
	v_mul_f32_e32 v29, 0x41000000, v37
	v_cvt_pk_fp8_f32 v44, v38, v39 op_sel:[0,0,1]
	v_cvt_pk_fp8_f32 v45, v28, v29 op_sel:[0,0,1]
	v_cvt_pk_f16_f32 v26, v30, v31
	v_cvt_pk_f16_f32 v27, v32, v33
	v_cvt_pk_f16_f32 v28, v46, v47
	v_cvt_pk_f16_f32 v29, v36, v37
	global_store_dwordx4 v[42:43], v[26:29], off
	global_store_dwordx2 v[40:41], v[44:45], off
	global_load_dwordx4 v[26:29], v[42:43], off offset:256
	v_pk_mul_f32 v[30:31], v[30:31], v[30:31]
	v_pk_mul_f32 v[32:33], v[32:33], v[32:33]
	v_pk_mul_f32 v[44:45], v[46:47], v[46:47]
	v_add_f32_e32 v32, v32, v33
	v_add_f32_e32 v30, v30, v31
	v_pk_mul_f32 v[36:37], v[36:37], v[36:37]
	v_add_f32_e32 v31, v44, v45
	v_add_f32_e32 v30, v30, v32
	v_add_f32_e32 v33, v36, v37
	v_add_f32_e32 v30, v31, v30
	v_add_f32_e32 v44, v33, v30
	v_mov_b32_e32 v38, 0
	v_mov_b32_e32 v39, 0
	s_waitcnt vmcnt(0)
	v_cvt_f32_f16_e32 v30, v26
	v_cvt_f32_f16_sdwa v31, v26 dst_sel:DWORD dst_unused:UNUSED_PAD src0_sel:WORD_1
	v_cvt_f32_f16_e32 v32, v28
	v_cvt_f32_f16_sdwa v33, v28 dst_sel:DWORD dst_unused:UNUSED_PAD src0_sel:WORD_1
	v_cvt_f32_f16_e32 v26, v27
	v_cvt_f32_f16_sdwa v27, v27 dst_sel:DWORD dst_unused:UNUSED_PAD src0_sel:WORD_1
	v_cvt_f32_f16_e32 v28, v29
	v_cvt_f32_f16_sdwa v29, v29 dst_sel:DWORD dst_unused:UNUSED_PAD src0_sel:WORD_1
	v_pk_add_f32 v[22:23], v[22:23], v[30:31]
	v_pk_add_f32 v[30:31], v[18:19], v[32:33]
	v_pk_add_f32 v[18:19], v[24:25], v[26:27]
	v_pk_add_f32 v[24:25], v[20:21], v[28:29]
	v_pk_mul_f32 v[26:27], v[22:23], v[22:23]
	v_pk_mul_f32 v[28:29], v[18:19], v[18:19]
	v_pk_mul_f32 v[32:33], v[30:31], v[30:31]
	v_cvt_pk_f16_f32 v20, v22, v23
	v_mul_f32_e32 v22, 0x41000000, v22
	v_mul_f32_e32 v23, 0x41000000, v23
	v_add_f32_e32 v28, v28, v29
	v_add_f32_e32 v26, v26, v27
	v_pk_mul_f32 v[36:37], v[24:25], v[24:25]
	v_add_f32_e32 v27, v32, v33
	v_cvt_pk_fp8_f32 v38, v22, v23
	v_add_f32_e32 v22, v26, v28
	v_add_f32_e32 v29, v36, v37
	v_add_f32_e32 v22, v27, v22
	v_add_f32_e32 v22, v29, v22
	v_add_f32_e32 v22, v44, v22
	v_mul_f32_e32 v45, 0x41000000, v30
	v_mul_f32_e32 v46, 0x41000000, v31
	v_mov_b32_e32 v23, v22
	s_nop 1
	v_permlane16_swap_b32_e32 v22, v23
	v_cvt_pk_fp8_f32 v39, v45, v46
	v_cvt_pk_f16_f32 v21, v18, v19
	v_mul_f32_e32 v18, 0x41000000, v18
	v_mul_f32_e32 v19, 0x41000000, v19
	v_cvt_pk_fp8_f32 v38, v18, v19 op_sel:[0,0,1]
	v_mul_f32_e32 v18, 0x41000000, v24
	v_mul_f32_e32 v19, 0x41000000, v25
	v_cvt_pk_fp8_f32 v39, v18, v19 op_sel:[0,0,1]
	s_waitcnt lgkmcnt(0)
	v_add_f32_e32 v18, v22, v23
	v_mov_b32_e32 v19, v18
	s_nop 1
	v_permlane32_swap_b32_e32 v18, v19
	v_cvt_pk_f16_f32 v22, v30, v31
	v_cvt_pk_f16_f32 v23, v24, v25
	global_store_dwordx4 v[42:43], v[20:23], off offset:256
	global_store_dwordx2 v[40:41], v[38:39], off offset:128
	s_and_saveexec_b64 s[2:3], vcc
	s_cbranch_execz .LBB0_684
	v_lshl_add_u64 v[20:21], v[34:35], 2, s[4:5]
	s_waitcnt lgkmcnt(0)
	v_add_f32_e32 v18, v18, v19
	global_atomic_add_f32 v[20:21], v18, off
; __device__ __forceinline__ unsigned pkh(float lo, float hi) { f32x2 v = {lo, hi}; h16x2 h = __builtin_convertvector(v, h16x2); return __builtin_bit_cast(unsigned, h); }
; __device__ __forceinline__ unsigned pk8(float a, float b, float c, float d) { int w = __builtin_amdgcn_cvt_pk_fp8_f32(a, b, 0, false); w = __builtin_amdgcn_cvt_pk_fp8_f32(c, d, w, true); return (unsigned)w; }
;     __device__ __forceinline__ void operator()(f32x4 (&acc)[2][2][4][2], const Unit& u, const Order& S, int wr, int wc, int fr_, int fq_, LAS unsigned char*, int) const {
;     ...
;                 const int row = row0 + ai * HALF + m * 16; const size_t off = (size_t)row * DM + col0;
;                 float sq = 0.f;
; #pragma unroll
;                 for (int bj = 0; bj < 2; ++bj) {
;                     const h16x8 bs = *(const h16x8*)(h16 + off + bj * HALF);
;                     f32x4 o0 = acc[ai][bj][m][0] * pre, o1 = acc[ai][bj][m][1] * pre;
; #pragma unroll
;                     for (int e = 0; e < 4; ++e) { o0[e] += (float)bs[e]; o1[e] += (float)bs[4 + e]; }
;                     if (out32) { if (!dry) { __builtin_nontemporal_store(o0, (f32x4*)(out32 + off + bj * HALF)); __builtin_nontemporal_store(o1, (f32x4*)(out32 + off + bj * HALF + 4)); } }
;                     else if (!dry) {
;                         sq += (o0[0] * o0[0] + o0[1] * o0[1]) + (o0[2] * o0[2] + o0[3] * o0[3]) + (o1[0] * o1[0] + o1[1] * o1[1]) + (o1[2] * o1[2] + o1[3] * o1[3]);
;                         u32x4 w; w.x = pkh(o0[0], o0[1]); w.y = pkh(o0[2], o0[3]); w.z = pkh(o1[0], o1[1]); w.w = pkh(o1[2], o1[3]);
;                         *(u32x4*)(h16 + off + bj * HALF) = w;
;                         if (h8) { u32x2 q; q.x = pk8(o0[0] * F8_SA, o0[1] * F8_SA, o0[2] * F8_SA, o0[3] * F8_SA); q.y = pk8(o1[0] * F8_SA, o1[1] * F8_SA, o1[2] * F8_SA, o1[3] * F8_SA); *(u32x2*)(h8 + off + bj * HALF) = q; } }
;                 }
;                 if (!out32 && !dry) { sq += __shfl_xor(sq, 16); sq += __shfl_xor(sq, 32); if (fq == 0) atomicAdd(ss_out + row, sq); }
.LBB0_684:
	s_or_b64 exec, exec, s[2:3]
	v_add_u32_e32 v18, 0xb0, v148
	s_waitcnt lgkmcnt(0)
	v_ashrrev_i32_e32 v19, 31, v18
	v_lshlrev_b64 v[20:21], 10, v[18:19]
	v_lshl_add_u64 v[24:25], v[20:21], 0, v[146:147]
	v_lshl_add_u64 v[26:27], v[24:25], 1, s[90:91]
	global_load_dwordx4 v[20:23], v[26:27], off
	v_mov_b32_e32 v28, 0
	v_mov_b32_e32 v29, 0
	v_lshl_add_u64 v[24:25], s[10:11], 0, v[24:25]
	s_waitcnt vmcnt(0)
	v_cvt_f32_f16_e32 v30, v20
	v_cvt_f32_f16_sdwa v31, v20 dst_sel:DWORD dst_unused:UNUSED_PAD src0_sel:WORD_1
	v_cvt_f32_f16_e32 v32, v22
	v_cvt_f32_f16_sdwa v33, v22 dst_sel:DWORD dst_unused:UNUSED_PAD src0_sel:WORD_1
	v_cvt_f32_f16_e32 v20, v21
	v_cvt_f32_f16_sdwa v21, v21 dst_sel:DWORD dst_unused:UNUSED_PAD src0_sel:WORD_1
	v_cvt_f32_f16_e32 v22, v23
	v_cvt_f32_f16_sdwa v23, v23 dst_sel:DWORD dst_unused:UNUSED_PAD src0_sel:WORD_1
	v_pk_add_f32 v[14:15], v[14:15], v[30:31]
	v_pk_add_f32 v[30:31], v[10:11], v[32:33]
	v_pk_add_f32 v[16:17], v[16:17], v[20:21]
	v_pk_add_f32 v[20:21], v[12:13], v[22:23]
	v_mul_f32_e32 v12, 0x41000000, v14
	v_mul_f32_e32 v13, 0x41000000, v15
	v_mul_f32_e32 v32, 0x41000000, v30
	v_mul_f32_e32 v33, 0x41000000, v31
	v_cvt_pk_fp8_f32 v28, v12, v13
	v_cvt_pk_fp8_f32 v29, v32, v33
	v_mul_f32_e32 v22, 0x41000000, v16
	v_mul_f32_e32 v23, 0x41000000, v17
	v_mul_f32_e32 v12, 0x41000000, v20
	v_mul_f32_e32 v13, 0x41000000, v21
	v_cvt_pk_fp8_f32 v28, v22, v23 op_sel:[0,0,1]
	v_cvt_pk_fp8_f32 v29, v12, v13 op_sel:[0,0,1]
	v_cvt_pk_f16_f32 v10, v14, v15
	v_cvt_pk_f16_f32 v11, v16, v17
	v_cvt_pk_f16_f32 v12, v30, v31
	v_cvt_pk_f16_f32 v13, v20, v21
	global_store_dwordx4 v[26:27], v[10:13], off
	global_store_dwordx2 v[24:25], v[28:29], off
	global_load_dwordx4 v[10:13], v[26:27], off offset:256
	v_pk_mul_f32 v[14:15], v[14:15], v[14:15]
	v_pk_mul_f32 v[16:17], v[16:17], v[16:17]
	v_pk_mul_f32 v[28:29], v[30:31], v[30:31]
	v_add_f32_e32 v16, v16, v17
	v_add_f32_e32 v14, v14, v15
	v_pk_mul_f32 v[20:21], v[20:21], v[20:21]
	v_add_f32_e32 v15, v28, v29
	v_add_f32_e32 v14, v14, v16
	v_add_f32_e32 v17, v20, v21
	v_add_f32_e32 v14, v15, v14
	v_add_f32_e32 v28, v17, v14
	v_mov_b32_e32 v22, 0
	v_mov_b32_e32 v23, 0
	s_waitcnt vmcnt(0)
	v_cvt_f32_f16_e32 v14, v10
	v_cvt_f32_f16_sdwa v15, v10 dst_sel:DWORD dst_unused:UNUSED_PAD src0_sel:WORD_1
	v_cvt_f32_f16_e32 v16, v12
	v_cvt_f32_f16_sdwa v17, v12 dst_sel:DWORD dst_unused:UNUSED_PAD src0_sel:WORD_1
	v_cvt_f32_f16_e32 v10, v11
	v_cvt_f32_f16_sdwa v11, v11 dst_sel:DWORD dst_unused:UNUSED_PAD src0_sel:WORD_1
	v_cvt_f32_f16_e32 v12, v13
	v_cvt_f32_f16_sdwa v13, v13 dst_sel:DWORD dst_unused:UNUSED_PAD src0_sel:WORD_1
	v_pk_add_f32 v[6:7], v[6:7], v[14:15]
	v_pk_add_f32 v[14:15], v[2:3], v[16:17]
	v_pk_add_f32 v[2:3], v[8:9], v[10:11]
	v_pk_add_f32 v[8:9], v[4:5], v[12:13]
	v_pk_mul_f32 v[10:11], v[6:7], v[6:7]
	v_pk_mul_f32 v[12:13], v[2:3], v[2:3]
	v_pk_mul_f32 v[16:17], v[14:15], v[14:15]
	v_cvt_pk_f16_f32 v4, v6, v7
	v_mul_f32_e32 v6, 0x41000000, v6
	v_mul_f32_e32 v7, 0x41000000, v7
	v_add_f32_e32 v12, v12, v13
	v_add_f32_e32 v10, v10, v11
	v_pk_mul_f32 v[20:21], v[8:9], v[8:9]
	v_add_f32_e32 v11, v16, v17
	v_cvt_pk_fp8_f32 v22, v6, v7
	v_add_f32_e32 v6, v10, v12
	v_add_f32_e32 v13, v20, v21
	v_add_f32_e32 v6, v11, v6
	v_add_f32_e32 v6, v13, v6
	v_add_f32_e32 v6, v28, v6
	v_mul_f32_e32 v29, 0x41000000, v14
	v_mul_f32_e32 v30, 0x41000000, v15
	v_mov_b32_e32 v7, v6
	s_nop 1
	v_permlane16_swap_b32_e32 v6, v7
	v_cvt_pk_fp8_f32 v23, v29, v30
	v_cvt_pk_f16_f32 v5, v2, v3
	v_mul_f32_e32 v2, 0x41000000, v2
	v_mul_f32_e32 v3, 0x41000000, v3
	v_cvt_pk_fp8_f32 v22, v2, v3 op_sel:[0,0,1]
	v_mul_f32_e32 v2, 0x41000000, v8
	v_mul_f32_e32 v3, 0x41000000, v9
	v_cvt_pk_fp8_f32 v23, v2, v3 op_sel:[0,0,1]
	s_waitcnt lgkmcnt(0)
	v_add_f32_e32 v2, v6, v7
	ds_bpermute_b32 v3, v116, v2
	v_cvt_pk_f16_f32 v6, v14, v15
	v_cvt_pk_f16_f32 v7, v8, v9
	global_store_dwordx4 v[26:27], v[4:7], off offset:256
	global_store_dwordx2 v[24:25], v[22:23], off offset:128
	s_and_saveexec_b64 s[2:3], vcc
	s_cbranch_execz .LBB0_686
	v_lshl_add_u64 v[4:5], v[18:19], 2, s[4:5]
	s_waitcnt lgkmcnt(0)
	v_add_f32_e32 v2, v2, v3
	global_atomic_add_f32 v[4:5], v2, off

; #define LAS __attribute__((address_space(3)))
; __device__ __forceinline__ void dma_kv_imgs(LAS unsigned char* Kimg, LAS unsigned char* Vimg, const f16_t* ksrc, const f16_t* vsrc, int wave, int lane, int pitch = NB) {
;     const int rl = lane >> 3, pos = lane & 7;
;     const int kc = pos ^ rl, vc = 2 * ((pos >> 1) ^ ((lane >> 4) & 3)) + (pos & 1);
;     const unsigned kd = (unsigned)__builtin_amdgcn_readfirstlane((int)(unsigned)(uintptr_t)Kimg), vd = (unsigned)__builtin_amdgcn_readfirstlane((int)(unsigned)(uintptr_t)Vimg);
; #pragma unroll
;     for (int i = 0; i < 4; ++i) { const int pc = wave + 8 * i, row = 8 * pc + rl;
;         glds16_asm(ksrc + (size_t)row * pitch + 8 * kc, (unsigned)__builtin_amdgcn_readfirstlane((int)(kd + pc * 1024)));
;         glds16_asm(vsrc + (size_t)row * pitch + 8 * vc, (unsigned)__builtin_amdgcn_readfirstlane((int)(vd + pc * 1024))); }
; __device__ __forceinline__ void xattn_load_q(const f16_t* qp  , const float* gqm, int G, float maxgk, h16x8& q0, h16x8& q1, float& mb) {
;     const h16x8 r0v = *(const h16x8*)qp, r1v = *(const h16x8*)(qp + 32);
;     float q[16], ss = 0.f;
; #pragma unroll
;     for (int j = 0; j < 8; ++j) { q[j] = (float)r0v[j]; q[8 + j] = (float)r1v[j]; ss += q[j] * q[j] + q[8 + j] * q[8 + j]; }
;     ss += __shfl_xor(ss, 16); ss += __shfl_xor(ss, 32);
;     const float rn = 1.0f / sqrtf(ss * (1.0f / HD) + EPS);
.LBB0_921:
	s_lshl_b32 s0, s8, 1
	s_or_b32 s0, s0, s41
	s_ashr_i32 s1, s0, 31
	s_lshl_b64 s[2:3], s[0:1], 15
	v_lshl_add_u64 v[2:3], v[34:35], 0, s[2:3]
	v_lshl_add_u64 v[4:5], v[36:37], 0, s[2:3]
	v_lshl_add_u64 v[6:7], v[2:3], 0, v[44:45]
	s_mov_b32 s1, m0
	s_mov_b32 m0, s20
	s_nop 0
	global_load_lds_dwordx4 v[6:7], off
	s_mov_b32 m0, s1
	v_lshl_add_u64 v[6:7], v[4:5], 0, v[44:45]
	s_mov_b32 s1, m0
	s_mov_b32 m0, s21
	s_nop 0
	global_load_lds_dwordx4 v[6:7], off
	s_mov_b32 m0, s1
	v_lshl_add_u64 v[6:7], v[2:3], 0, v[46:47]
	s_mov_b32 s1, m0
	s_mov_b32 m0, s24
	s_nop 0
	global_load_lds_dwordx4 v[6:7], off
	s_mov_b32 m0, s1
	v_lshl_add_u64 v[6:7], v[4:5], 0, v[46:47]
	s_mov_b32 s1, m0
	s_mov_b32 m0, s25
	s_nop 0
	global_load_lds_dwordx4 v[6:7], off
	s_mov_b32 m0, s1
	v_lshl_add_u64 v[6:7], v[2:3], 0, v[48:49]
	s_mov_b32 s1, m0
	s_mov_b32 m0, s26
	s_nop 0
	global_load_lds_dwordx4 v[6:7], off
	s_mov_b32 m0, s1
	v_lshl_add_u64 v[6:7], v[4:5], 0, v[48:49]
	s_mov_b32 s1, m0
	s_mov_b32 m0, s27
	s_nop 0
	global_load_lds_dwordx4 v[6:7], off
	s_mov_b32 m0, s1
	v_lshl_add_u64 v[2:3], v[2:3], 0, v[50:51]
	s_mov_b32 s1, m0
	s_mov_b32 m0, s28
	s_nop 0
	global_load_lds_dwordx4 v[2:3], off
	s_mov_b32 m0, s1
	v_lshl_add_u64 v[2:3], v[4:5], 0, v[50:51]
	s_mov_b32 s1, m0
	s_mov_b32 m0, s29
	s_nop 0
	global_load_lds_dwordx4 v[2:3], off
	s_mov_b32 m0, s1
	s_or_b32 s0, s0, 1
	s_ashr_i32 s1, s0, 31
	s_lshl_b64 s[0:1], s[0:1], 15
	v_lshl_add_u64 v[2:3], v[34:35], 0, s[0:1]
	v_lshl_add_u64 v[4:5], v[36:37], 0, s[0:1]
	v_lshl_add_u64 v[6:7], v[2:3], 0, v[44:45]
	s_mov_b32 s0, m0
	s_mov_b32 m0, s30
	s_nop 0
	global_load_lds_dwordx4 v[6:7], off
	s_mov_b32 m0, s0
	v_lshl_add_u64 v[6:7], v[4:5], 0, v[44:45]
	s_mov_b32 s0, m0
	s_mov_b32 m0, s31
	s_nop 0
	global_load_lds_dwordx4 v[6:7], off
	s_mov_b32 m0, s0
	v_lshl_add_u64 v[6:7], v[2:3], 0, v[46:47]
	s_mov_b32 s0, m0
	s_mov_b32 m0, s34
	s_nop 0
	global_load_lds_dwordx4 v[6:7], off
	s_mov_b32 m0, s0
	v_lshl_add_u64 v[6:7], v[4:5], 0, v[46:47]
	s_mov_b32 s0, m0
	s_mov_b32 m0, s35
	s_nop 0
	global_load_lds_dwordx4 v[6:7], off
	s_mov_b32 m0, s0
	v_lshl_add_u64 v[6:7], v[2:3], 0, v[48:49]
	s_mov_b32 s0, m0
	s_mov_b32 m0, s36
	s_nop 0
	global_load_lds_dwordx4 v[6:7], off
	s_mov_b32 m0, s0
	s_lshl_b32 s42, s8, 7
	v_lshl_add_u64 v[6:7], v[4:5], 0, v[48:49]
	s_mov_b32 s0, m0
	s_mov_b32 m0, s37
	s_nop 0
	global_load_lds_dwordx4 v[6:7], off
	s_mov_b32 m0, s0
	s_add_i32 s42, s42, s17
	v_lshl_add_u64 v[2:3], v[2:3], 0, v[50:51]
	s_mov_b32 s0, m0
	s_mov_b32 m0, s38
	s_nop 0
	global_load_lds_dwordx4 v[2:3], off
	s_mov_b32 m0, s0
	s_lshl_b32 s8, s42, 1
	v_lshl_add_u64 v[2:3], v[4:5], 0, v[50:51]
	s_mov_b32 s0, m0
	s_mov_b32 m0, s39
	s_nop 0
	global_load_lds_dwordx4 v[2:3], off
	s_mov_b32 m0, s0
	v_lshl_add_u64 v[10:11], v[54:55], 0, s[8:9]
	global_load_dwordx4 v[2:5], v[10:11], off offset:64
	v_lshl_add_u64 v[12:13], v[58:59], 0, s[8:9]
	global_load_dwordx4 v[6:9], v[12:13], off offset:64
	global_load_dwordx4 v[82:85], v[10:11], off
	global_load_dwordx4 v[86:89], v[12:13], off
	s_nop 0
	global_load_dwordx4 v[10:13], v[38:39], off offset:400
	global_load_dwordx4 v[14:17], v[38:39], off offset:384
	global_load_dwordx4 v[18:21], v[38:39], off offset:272
	global_load_dwordx4 v[22:25], v[38:39], off offset:256
	s_waitcnt vmcnt(0)
	s_barrier
	s_waitcnt vmcnt(6)
	v_cvt_f32_f16_e32 v26, v9
	v_cvt_f32_f16_sdwa v27, v9 dst_sel:DWORD dst_unused:UNUSED_PAD src0_sel:WORD_1
	v_cvt_f32_f16_e32 v28, v8
	v_cvt_f32_f16_sdwa v29, v8 dst_sel:DWORD dst_unused:UNUSED_PAD src0_sel:WORD_1
	v_cvt_f32_f16_e32 v8, v2
	v_cvt_f32_f16_sdwa v9, v2 dst_sel:DWORD dst_unused:UNUSED_PAD src0_sel:WORD_1
	v_cvt_f32_f16_e32 v90, v5
	v_cvt_f32_f16_sdwa v91, v5 dst_sel:DWORD dst_unused:UNUSED_PAD src0_sel:WORD_1
	v_cvt_f32_f16_e32 v92, v4
	v_cvt_f32_f16_sdwa v93, v4 dst_sel:DWORD dst_unused:UNUSED_PAD src0_sel:WORD_1
	v_cvt_f32_f16_e32 v4, v3
	v_cvt_f32_f16_sdwa v5, v3 dst_sel:DWORD dst_unused:UNUSED_PAD src0_sel:WORD_1
	s_waitcnt vmcnt(5)
	v_cvt_f32_f16_e32 v96, v82
	v_cvt_f32_f16_sdwa v97, v82 dst_sel:DWORD dst_unused:UNUSED_PAD src0_sel:WORD_1
	v_cvt_f32_f16_e32 v60, v7
	v_cvt_f32_f16_sdwa v61, v7 dst_sel:DWORD dst_unused:UNUSED_PAD src0_sel:WORD_1
	v_cvt_f32_f16_e32 v64, v6
	v_cvt_f32_f16_sdwa v65, v6 dst_sel:DWORD dst_unused:UNUSED_PAD src0_sel:WORD_1
	v_cvt_f32_f16_e32 v6, v85
	v_cvt_f32_f16_sdwa v7, v85 dst_sel:DWORD dst_unused:UNUSED_PAD src0_sel:WORD_1
	v_cvt_f32_f16_e32 v94, v84
	v_cvt_f32_f16_sdwa v95, v84 dst_sel:DWORD dst_unused:UNUSED_PAD src0_sel:WORD_1
	v_cvt_f32_f16_e32 v84, v83
	v_cvt_f32_f16_sdwa v85, v83 dst_sel:DWORD dst_unused:UNUSED_PAD src0_sel:WORD_1
	v_pk_mul_f32 v[2:3], v[8:9], v[8:9]
	v_pk_mul_f32 v[100:101], v[4:5], v[4:5]
	v_pk_fma_f32 v[2:3], v[96:97], v[96:97], v[2:3]
	v_pk_fma_f32 v[100:101], v[84:85], v[84:85], v[100:101]
	v_add_f32_e32 v2, v2, v3
	v_pk_mul_f32 v[98:99], v[92:93], v[92:93]
	v_add_f32_e32 v2, v100, v2
	v_pk_fma_f32 v[98:99], v[94:95], v[94:95], v[98:99]
	v_add_f32_e32 v2, v101, v2
	v_pk_mul_f32 v[82:83], v[90:91], v[90:91]
	v_add_f32_e32 v2, v98, v2
	v_pk_fma_f32 v[82:83], v[6:7], v[6:7], v[82:83]
	v_add_f32_e32 v2, v99, v2
	v_add_f32_e32 v2, v82, v2
	v_add_f32_e32 v2, v83, v2
	v_mov_b32_e32 v3, v2
	s_nop 1
	v_permlane16_swap_b32_e32 v2, v3
	s_waitcnt vmcnt(4)
	v_cvt_f32_f16_e32 v62, v89
	v_cvt_f32_f16_sdwa v63, v89 dst_sel:DWORD dst_unused:UNUSED_PAD src0_sel:WORD_1
	v_cvt_f32_f16_e32 v82, v88
	v_cvt_f32_f16_sdwa v83, v88 dst_sel:DWORD dst_unused:UNUSED_PAD src0_sel:WORD_1
	s_waitcnt lgkmcnt(0)
; __device__ __forceinline__ unsigned pkh(float lo, float hi) { f32x2 v = {lo, hi}; h16x2 h = __builtin_convertvector(v, h16x2); return __builtin_bit_cast(unsigned, h); }
; __device__ __forceinline__ void xattn_load_q(const f16_t* qp  , const float* gqm, int G, float maxgk, h16x8& q0, h16x8& q1, float& mb) {
;     const h16x8 r0v = *(const h16x8*)qp, r1v = *(const h16x8*)(qp + 32);
;     float q[16], ss = 0.f;
; #pragma unroll
;     for (int j = 0; j < 8; ++j) { q[j] = (float)r0v[j]; q[8 + j] = (float)r1v[j]; ss += q[j] * q[j] + q[8 + j] * q[8 + j]; }
;     ss += __shfl_xor(ss, 16); ss += __shfl_xor(ss, 32);
;     const float rn = 1.0f / sqrtf(ss * (1.0f / HD) + EPS);
;     float n2 = 0.f;
; #pragma unroll
;     for (int j = 0; j < 8; ++j) { q[j] *= rn * gqm[8 * G + j]; q[8 + j] *= rn * gqm[32 + 8 * G + j]; n2 += q[j] * q[j] + q[8 + j] * q[8 + j]; }
;     n2 += __shfl_xor(n2, 16); n2 += __shfl_xor(n2, 32);
;     mb = (sqrtf(n2) * maxgk - BOUND_SHIFT) * LOG2E;
;     const float c = 0.125f * LOG2E;
;     u32x4 w0, w1;
;     w0.x = pkh(q[0] * c, q[1] * c); w0.y = pkh(q[2] * c, q[3] * c); w0.z = pkh(q[4] * c, q[5] * c); w0.w = pkh(q[6] * c, q[7] * c);
;     w1.x = pkh(q[8] * c, q[9] * c); w1.y = pkh(q[10] * c, q[11] * c); w1.z = pkh(q[12] * c, q[13] * c); w1.w = pkh(q[14] * c, q[15] * c);
;     q0 = __builtin_bit_cast(h16x8, w0); q1 = __builtin_bit_cast(h16x8, w1);
	v_add_f32_e32 v102, v2, v3
	v_mov_b32_e32 v103, v102
	s_nop 1
	v_permlane32_swap_b32_e32 v102, v103
	v_cvt_f32_f16_e32 v88, v87
	v_cvt_f32_f16_sdwa v89, v87 dst_sel:DWORD dst_unused:UNUSED_PAD src0_sel:WORD_1
	v_pk_mul_f32 v[2:3], v[26:27], v[26:27]
	v_pk_mul_f32 v[98:99], v[64:65], v[64:65]
	s_waitcnt lgkmcnt(0)
	v_add_f32_e32 v87, v102, v103
	v_fmamk_f32 v87, v87, 0x3c800000, v74
	v_mul_f32_e32 v102, 0x4f800000, v87
	v_cmp_gt_f32_e32 vcc, s19, v87
	v_pk_fma_f32 v[104:105], v[62:63], v[62:63], v[2:3]
	v_pk_mul_f32 v[100:101], v[28:29], v[28:29]
	v_cndmask_b32_e32 v87, v87, v102, vcc
	v_sqrt_f32_e32 v106, v87
	v_pk_mul_f32 v[102:103], v[60:61], v[60:61]
	v_pk_fma_f32 v[100:101], v[82:83], v[82:83], v[100:101]
	v_pk_fma_f32 v[102:103], v[88:89], v[88:89], v[102:103]
	v_add_u32_e32 v2, -1, v106
	v_add_u32_e32 v3, 1, v106
	v_fma_f32 v107, -v2, v106, v87
	v_fma_f32 v108, -v3, v106, v87
	v_cmp_ge_f32_e64 s[0:1], 0, v107
	s_nop 1
	v_cndmask_b32_e64 v2, v106, v2, s[0:1]
	v_cmp_lt_f32_e64 s[0:1], 0, v108
	s_nop 1
	v_cndmask_b32_e64 v2, v2, v3, s[0:1]
	v_mul_f32_e32 v3, 0x37800000, v2
	v_cndmask_b32_e32 v2, v2, v3, vcc
	v_cmp_class_f32_e32 vcc, v87, v75
	s_nop 1
	v_cndmask_b32_e32 v2, v2, v87, vcc
	v_div_scale_f32 v3, s[0:1], v2, v2, 1.0
	v_rcp_f32_e32 v87, v3
	v_div_scale_f32 v106, vcc, 1.0, v2, 1.0
	v_fma_f32 v107, -v3, v87, 1.0
	v_fmac_f32_e32 v87, v107, v87
	v_mul_f32_e32 v107, v106, v87
	v_fma_f32 v108, -v3, v107, v106
	v_fmac_f32_e32 v107, v108, v87
	v_fma_f32 v3, -v3, v107, v106
	v_div_fmas_f32 v3, v3, v87, v107
	v_div_fixup_f32 v106, v3, v2, 1.0
	s_waitcnt vmcnt(3)
	v_pk_mul_f32 v[108:109], v[10:11], v[106:107] op_sel_hi:[1,0]
	s_waitcnt vmcnt(2)
	v_pk_mul_f32 v[110:111], v[16:17], v[106:107] op_sel_hi:[1,0]
	v_pk_mul_f32 v[112:113], v[14:15], v[106:107] op_sel_hi:[1,0]
	v_pk_mul_f32 v[92:93], v[108:109], v[92:93]
	v_pk_mul_f32 v[108:109], v[110:111], v[4:5]
	v_pk_mul_f32 v[110:111], v[112:113], v[8:9]
	v_pk_mul_f32 v[8:9], v[92:93], s[12:13] op_sel_hi:[1,0]
	v_pk_mul_f32 v[2:3], v[12:13], v[106:107] op_sel_hi:[1,0]
	v_cvt_pk_f16_f32 v4, v8, v9
	s_waitcnt vmcnt(1)
	v_pk_mul_f32 v[8:9], v[20:21], v[106:107] op_sel_hi:[1,0]
	v_pk_mul_f32 v[90:91], v[2:3], v[90:91]
	v_pk_mul_f32 v[6:7], v[8:9], v[6:7]
	v_pk_mul_f32 v[2:3], v[90:91], s[12:13] op_sel_hi:[1,0]
	v_pk_mul_f32 v[8:9], v[6:7], s[12:13] op_sel_hi:[1,0]
	v_pk_mul_f32 v[6:7], v[6:7], v[6:7]
	v_pk_mul_f32 v[112:113], v[108:109], s[12:13] op_sel_hi:[1,0]
	v_pk_fma_f32 v[6:7], v[90:91], v[90:91], v[6:7]
	v_pk_mul_f32 v[90:91], v[18:19], v[106:107] op_sel_hi:[1,0]
	v_cvt_pk_f16_f32 v9, v8, v9
	v_pk_mul_f32 v[90:91], v[90:91], v[94:95]
	v_pk_mul_f32 v[114:115], v[110:111], s[12:13] op_sel_hi:[1,0]
	v_pk_mul_f32 v[94:95], v[90:91], v[90:91]
	v_cvt_pk_f16_f32 v5, v2, v3
	v_pk_fma_f32 v[92:93], v[92:93], v[92:93], v[94:95]
	s_waitcnt vmcnt(0)
	v_pk_mul_f32 v[94:95], v[24:25], v[106:107] op_sel_hi:[1,0]
	v_pk_mul_f32 v[106:107], v[22:23], v[106:107] op_sel_hi:[1,0]
	v_pk_mul_f32 v[84:85], v[94:95], v[84:85]
	v_cvt_pk_f16_f32 v3, v112, v113
	v_pk_mul_f32 v[94:95], v[84:85], v[84:85]
	v_cvt_pk_f16_f32 v2, v114, v115
	v_pk_fma_f32 v[94:95], v[108:109], v[108:109], v[94:95]
	v_cvt_f32_f16_e32 v108, v86
	v_cvt_f32_f16_sdwa v109, v86 dst_sel:DWORD dst_unused:UNUSED_PAD src0_sel:WORD_1
	v_pk_mul_f32 v[86:87], v[106:107], v[96:97]
	v_pk_fma_f32 v[98:99], v[108:109], v[108:109], v[98:99]
	v_pk_mul_f32 v[96:97], v[86:87], v[86:87]
	s_nop 0
	v_pk_fma_f32 v[96:97], v[110:111], v[110:111], v[96:97]
	s_nop 0
	v_add_f32_e32 v8, v96, v97
	v_add_f32_e32 v8, v94, v8
	v_add_f32_e32 v8, v95, v8
	v_add_f32_e32 v8, v92, v8
	v_add_f32_e32 v8, v93, v8
	v_add_f32_e32 v6, v6, v8
	v_add_f32_e32 v92, v7, v6
	v_add_f32_e32 v6, v98, v99
	v_add_f32_e32 v6, v102, v6
	v_add_f32_e32 v6, v103, v6
	v_add_f32_e32 v6, v100, v6
	v_add_f32_e32 v6, v101, v6
	v_add_f32_e32 v6, v104, v6
	v_add_f32_e32 v94, v105, v6
	ds_bpermute_b32 v93, v69, v92
	ds_bpermute_b32 v95, v69, v94
	v_pk_mul_f32 v[6:7], v[90:91], s[12:13] op_sel_hi:[1,0]
	s_waitcnt lgkmcnt(1)
	v_add_f32_e32 v90, v92, v93
	s_waitcnt lgkmcnt(0)
	v_add_f32_e32 v92, v94, v95
	v_mov_b32_e32 v93, v92
	s_nop 1
	v_permlane32_swap_b32_e32 v92, v93
	v_mov_b32_e32 v91, v90
	s_nop 1
	v_permlane32_swap_b32_e32 v90, v91
	v_cvt_pk_f16_f32 v8, v6, v7
	v_pk_mul_f32 v[6:7], v[84:85], s[12:13] op_sel_hi:[1,0]
	s_waitcnt lgkmcnt(1)
	v_add_f32_e32 v85, v92, v93
	v_fmamk_f32 v85, v85, 0x3c800000, v74
	v_cvt_pk_f16_f32 v7, v6, v7
	s_waitcnt lgkmcnt(0)
; template <bool CAUSAL, bool SHARED> ...
;     ...
;     const int kof0 = fr * 128 + (((0 + G) ^ (fr & 7)) << 4), kof1 = fr * 128 + (((4 + G) ^ (fr & 7)) << 4);
;     const int vrow = (4 * G + qq) * 128 + p * 8, sw = (2 * G + (qq >> 1)) & 3;
;     const h16x8 ones = {(_Float16)1.0f, (_Float16)1.0f, (_Float16)1.0f, (_Float16)1.0f, (_Float16)1.0f, (_Float16)1.0f, (_Float16)1.0f, (_Float16)1.0f};
;     const f32x4 nma = {-mba, -mba, -mba, -mba}, nmb = {-mbb, -mbb, -mbb, -mbb};
;     f32x4 la = {0.f, 0.f, 0.f, 0.f}, lb = la;
;     h16x8 ka[4], kb[4];
;     ka[0] = *(LAS const h16x8*)(Ka + kof0); ka[1] = *(LAS const h16x8*)(Ka + kof1); ka[2] = *(LAS const h16x8*)(Ka + 2048 + kof0); ka[3] = *(LAS const h16x8*)(Ka + 2048 + kof1);
;     if (!SHARED) { kb[0] = *(LAS const h16x8*)(Kb + kof0); kb[1] = *(LAS const h16x8*)(Kb + kof1); kb[2] = *(LAS const h16x8*)(Kb + 2048 + kof0); kb[3] = *(LAS const h16x8*)(Kb + 2048 + kof1); }
;     for (int ks = 0; ks < nsteps; ++ks) {
;         LAS const unsigned char* va = Va + ks * 4096 + vrow; LAS const unsigned char* vb = Vb + ks * 4096 + vrow;
;         h16x4 fal[4], fah[4], fbl[4], fbh[4];
; #pragma unroll
;         for (int dt = 0; dt < 4; ++dt) { fal[dt] = vtr(va + ((dt ^ sw) << 5)); fah[dt] = vtr(va + 2048 + ((dt ^ sw) << 5));
;             if (!SHARED) { fbl[dt] = vtr(vb + ((dt ^ sw) << 5)); fbh[dt] = vtr(vb + 2048 + ((dt ^ sw) << 5)); } }
;         __builtin_amdgcn_sched_barrier(0);
;         f32x4 sa0, sa1, sb0, sb1;
; __device__ __forceinline__ void xattn_load_q(const f16_t* qp  , const float* gqm, int G, float maxgk, h16x8& q0, h16x8& q1, float& mb) {
;     ...
;     const float rn = 1.0f / sqrtf(ss * (1.0f / HD) + EPS);
;     float n2 = 0.f;
; #pragma unroll
;     for (int j = 0; j < 8; ++j) { q[j] *= rn * gqm[8 * G + j]; q[8 + j] *= rn * gqm[32 + 8 * G + j]; n2 += q[j] * q[j] + q[8 + j] * q[8 + j]; }
;     n2 += __shfl_xor(n2, 16); n2 += __shfl_xor(n2, 32);
;     mb = (sqrtf(n2) * maxgk - BOUND_SHIFT) * LOG2E;
;     const float c = 0.125f * LOG2E;
;     u32x4 w0, w1;
;     w0.x = pkh(q[0] * c, q[1] * c); w0.y = pkh(q[2] * c, q[3] * c); w0.z = pkh(q[4] * c, q[5] * c); w0.w = pkh(q[6] * c, q[7] * c);
;     w1.x = pkh(q[8] * c, q[9] * c); w1.y = pkh(q[10] * c, q[11] * c); w1.z = pkh(q[12] * c, q[13] * c); w1.w = pkh(q[14] * c, q[15] * c);
;     q0 = __builtin_bit_cast(h16x8, w0); q1 = __builtin_bit_cast(h16x8, w1);
	v_add_f32_e32 v6, v90, v91
	v_mul_f32_e32 v90, 0x4f800000, v85
	v_cmp_gt_f32_e32 vcc, s19, v85
	v_mul_f32_e32 v84, 0x4f800000, v6
	v_cmp_gt_f32_e64 s[0:1], s19, v6
	v_cndmask_b32_e32 v85, v85, v90, vcc
	v_sqrt_f32_e32 v90, v85
	v_cndmask_b32_e64 v91, v6, v84, s[0:1]
	v_sqrt_f32_e32 v92, v91
	v_add_u32_e32 v6, -1, v90
	v_fma_f32 v84, -v6, v90, v85
	v_cmp_ge_f32_e64 s[2:3], 0, v84
	v_add_u32_e32 v84, 1, v90
	s_nop 0
	v_cndmask_b32_e64 v6, v90, v6, s[2:3]
	v_fma_f32 v90, -v84, v90, v85
	v_cmp_lt_f32_e64 s[2:3], 0, v90
	s_nop 1
	v_cndmask_b32_e64 v6, v6, v84, s[2:3]
	v_mul_f32_e32 v84, 0x37800000, v6
	v_cndmask_b32_e32 v6, v6, v84, vcc
	v_cmp_class_f32_e32 vcc, v85, v75
	s_nop 1
	v_cndmask_b32_e32 v90, v6, v85, vcc
	v_div_scale_f32 v93, s[2:3], v90, v90, 1.0
	v_rcp_f32_e32 v94, v93
	v_pk_mul_f32 v[84:85], v[86:87], s[12:13] op_sel_hi:[1,0]
	s_nop 0
	v_cvt_pk_f16_f32 v6, v84, v85
	v_fma_f32 v84, -v93, v94, 1.0
	v_fmac_f32_e32 v94, v84, v94
	v_div_scale_f32 v84, vcc, 1.0, v90, 1.0
	v_mul_f32_e32 v86, v84, v94
	v_fma_f32 v87, -v93, v86, v84
	v_fmac_f32_e32 v86, v87, v94
	v_fma_f32 v84, -v93, v86, v84
	v_div_fmas_f32 v84, v84, v94, v86
	v_add_u32_e32 v85, -1, v92
	v_div_fixup_f32 v84, v84, v90, 1.0
	v_pk_mul_f32 v[22:23], v[22:23], v[84:85] op_sel_hi:[1,0]
	v_pk_mul_f32 v[14:15], v[14:15], v[84:85] op_sel_hi:[1,0]
	v_pk_mul_f32 v[22:23], v[22:23], v[108:109]
	v_pk_mul_f32 v[24:25], v[24:25], v[84:85] op_sel_hi:[1,0]
	v_pk_mul_f32 v[86:87], v[22:23], v[22:23]
	v_pk_mul_f32 v[64:65], v[14:15], v[64:65]
	v_pk_mul_f32 v[24:25], v[24:25], v[88:89]
	v_pk_mul_f32 v[16:17], v[16:17], v[84:85] op_sel_hi:[1,0]
	v_pk_fma_f32 v[14:15], v[64:65], v[64:65], v[86:87]
	v_pk_mul_f32 v[60:61], v[16:17], v[60:61]
	v_pk_mul_f32 v[16:17], v[24:25], v[24:25]
	v_pk_mul_f32 v[18:19], v[18:19], v[84:85] op_sel_hi:[1,0]
	v_pk_fma_f32 v[16:17], v[60:61], v[60:61], v[16:17]
	v_pk_mul_f32 v[18:19], v[18:19], v[82:83]
	v_pk_mul_f32 v[10:11], v[10:11], v[84:85] op_sel_hi:[1,0]
	v_add_f32_e32 v14, v14, v15
	v_pk_mul_f32 v[10:11], v[10:11], v[28:29]
	v_pk_mul_f32 v[28:29], v[18:19], v[18:19]
	v_pk_mul_f32 v[20:21], v[20:21], v[84:85] op_sel_hi:[1,0]
	v_add_f32_e32 v14, v16, v14
	v_pk_fma_f32 v[28:29], v[10:11], v[10:11], v[28:29]
	v_pk_mul_f32 v[20:21], v[20:21], v[62:63]
	v_pk_mul_f32 v[12:13], v[12:13], v[84:85] op_sel_hi:[1,0]
	v_add_f32_e32 v14, v17, v14
	v_pk_mul_f32 v[12:13], v[12:13], v[26:27]
	v_pk_mul_f32 v[26:27], v[20:21], v[20:21]
	v_add_f32_e32 v14, v28, v14
	v_pk_fma_f32 v[26:27], v[12:13], v[12:13], v[26:27]
	v_add_f32_e32 v14, v29, v14
	v_add_f32_e32 v14, v26, v14
	v_add_f32_e32 v14, v27, v14
	ds_bpermute_b32 v15, v69, v14
	v_fma_f32 v16, -v85, v92, v91
	v_add_u32_e32 v17, 1, v92
	v_cmp_ge_f32_e32 vcc, 0, v16
	v_fma_f32 v26, -v17, v92, v91
	s_waitcnt lgkmcnt(0)
	v_add_f32_e32 v14, v14, v15
	v_mov_b32_e32 v15, v14
	s_nop 1
	v_permlane32_swap_b32_e32 v14, v15
	v_cndmask_b32_e32 v16, v92, v85, vcc
	v_cmp_lt_f32_e32 vcc, 0, v26
	v_pk_mul_f32 v[10:11], v[10:11], s[12:13] op_sel_hi:[1,0]
	s_waitcnt lgkmcnt(0)
	v_add_f32_e32 v14, v14, v15
	v_cndmask_b32_e32 v16, v16, v17, vcc
	v_mul_f32_e32 v15, 0x4f800000, v14
	v_cmp_gt_f32_e32 vcc, s19, v14
	v_mul_f32_e32 v17, 0x37800000, v16
	v_cndmask_b32_e64 v16, v16, v17, s[0:1]
	v_cndmask_b32_e32 v14, v14, v15, vcc
	v_sqrt_f32_e32 v15, v14
	v_cmp_class_f32_e64 s[0:1], v91, v75
	s_nop 1
	v_cndmask_b32_e64 v26, v16, v91, s[0:1]
	v_add_u32_e32 v16, -1, v15
	v_fma_f32 v17, -v16, v15, v14
	v_cmp_ge_f32_e64 s[0:1], 0, v17
	v_add_u32_e32 v17, 1, v15
	s_nop 0
	v_cndmask_b32_e64 v16, v15, v16, s[0:1]
	v_fma_f32 v15, -v17, v15, v14
	v_cmp_lt_f32_e64 s[0:1], 0, v15
	s_nop 1
	v_cndmask_b32_e64 v15, v16, v17, s[0:1]
	v_mul_f32_e32 v16, 0x37800000, v15
	v_cndmask_b32_e32 v15, v15, v16, vcc
	v_cmp_class_f32_e32 vcc, v14, v75
	v_pk_mul_f32 v[16:17], v[24:25], s[12:13] op_sel_hi:[1,0]
	s_nop 0
	v_cndmask_b32_e32 v27, v15, v14, vcc
	v_pk_mul_f32 v[14:15], v[22:23], s[12:13] op_sel_hi:[1,0]
	s_nop 0
	v_cvt_pk_f16_f32 v14, v14, v15
	v_cvt_pk_f16_f32 v15, v16, v17
	v_pk_mul_f32 v[16:17], v[18:19], s[12:13] op_sel_hi:[1,0]
	v_pk_mul_f32 v[18:19], v[20:21], s[12:13] op_sel_hi:[1,0]
	v_cvt_pk_f16_f32 v16, v16, v17
	v_cvt_pk_f16_f32 v17, v18, v19
	v_pk_mul_f32 v[18:19], v[64:65], s[12:13] op_sel_hi:[1,0]
	v_pk_mul_f32 v[20:21], v[60:61], s[12:13] op_sel_hi:[1,0]
	v_cvt_pk_f16_f32 v18, v18, v19
	v_cvt_pk_f16_f32 v19, v20, v21
	v_cvt_pk_f16_f32 v20, v10, v11
	v_pk_mul_f32 v[10:11], v[12:13], s[12:13] op_sel_hi:[1,0]
	v_add_u32_e32 v60, v72, v71
	v_cvt_pk_f16_f32 v21, v10, v11
	v_fma_f32 v10, v81, v26, -4.0
	v_mul_f32_e32 v22, 0xbfb8aa3b, v10
	ds_read_b128 v[10:13], v76
	ds_read_b128 v[62:65], v76 offset:2048
	ds_read_b128 v[82:85], v77
	ds_read_b128 v[86:89], v77 offset:2048
	ds_read_b64_tr_b16 v[90:91], v60 offset:32768
	ds_read_b64_tr_b16 v[92:93], v60 offset:34816
	ds_read_b64_tr_b16 v[94:95], v78 offset:32768
	ds_read_b64_tr_b16 v[96:97], v78 offset:34816
	ds_read_b64_tr_b16 v[98:99], v79 offset:32768
	ds_read_b64_tr_b16 v[100:101], v79 offset:34816
	ds_read_b64_tr_b16 v[102:103], v80 offset:32768
	ds_read_b64_tr_b16 v[104:105], v80 offset:34816
	v_fma_f32 v26, v81, v27, -4.0
	v_mul_f32_e32 v26, 0xbfb8aa3b, v26
	v_mov_b32_e32 v23, v22
	v_mov_b32_e32 v24, v22
	v_mov_b32_e32 v25, v22
	v_mov_b32_e32 v27, v26
	v_mov_b32_e32 v28, v26
	v_mov_b32_e32 v29, v26
	s_waitcnt lgkmcnt(11)
	v_mfma_f32_16x16x32_f16 v[106:109], v[10:13], v[6:9], v[22:25]
	v_mfma_f32_16x16x32_f16 v[10:13], v[10:13], v[14:17], v[26:29]
	s_waitcnt lgkmcnt(10)
	v_mfma_f32_16x16x32_f16 v[110:113], v[62:65], v[6:9], v[22:25]
	v_mfma_f32_16x16x32_f16 v[62:65], v[62:65], v[14:17], v[26:29]
	s_waitcnt lgkmcnt(9)
; #define LAS __attribute__((address_space(3)))
; template <bool CAUSAL, bool SHARED> ...
;     ...
;     for (int ks = 0; ks < nsteps; ++ks) {
;         LAS const unsigned char* va = Va + ks * 4096 + vrow; LAS const unsigned char* vb = Vb + ks * 4096 + vrow;
;         h16x4 fal[4], fah[4], fbl[4], fbh[4];
; #pragma unroll
;         for (int dt = 0; dt < 4; ++dt) { fal[dt] = vtr(va + ((dt ^ sw) << 5)); fah[dt] = vtr(va + 2048 + ((dt ^ sw) << 5));
;             if (!SHARED) { fbl[dt] = vtr(vb + ((dt ^ sw) << 5)); fbh[dt] = vtr(vb + 2048 + ((dt ^ sw) << 5)); } }
;         __builtin_amdgcn_sched_barrier(0);
;         f32x4 sa0, sa1, sb0, sb1;
;         sa0 = __builtin_amdgcn_mfma_f32_16x16x32_f16(ka[0], qa0, nma, 0, 0, 0); sb0 = __builtin_amdgcn_mfma_f32_16x16x32_f16(SHARED ? ka[0] : kb[0], qb0, nmb, 0, 0, 0);
;         sa1 = __builtin_amdgcn_mfma_f32_16x16x32_f16(ka[2], qa0, nma, 0, 0, 0); sb1 = __builtin_amdgcn_mfma_f32_16x16x32_f16(SHARED ? ka[2] : kb[2], qb0, nmb, 0, 0, 0);
;         sa0 = __builtin_amdgcn_mfma_f32_16x16x32_f16(ka[1], qa1, sa0, 0, 0, 0); sb0 = __builtin_amdgcn_mfma_f32_16x16x32_f16(SHARED ? ka[1] : kb[1], qb1, sb0, 0, 0, 0);
;         sa1 = __builtin_amdgcn_mfma_f32_16x16x32_f16(ka[3], qa1, sa1, 0, 0, 0); sb1 = __builtin_amdgcn_mfma_f32_16x16x32_f16(SHARED ? ka[3] : kb[3], qb1, sb1, 0, 0, 0);
;         __builtin_amdgcn_sched_barrier(0);
;         if (ks + 1 < nsteps) { LAS const unsigned char* kn = Ka + (ks + 1) * 4096;
;             ka[0] = *(LAS const h16x8*)(kn + kof0); ka[1] = *(LAS const h16x8*)(kn + kof1); ka[2] = *(LAS const h16x8*)(kn + 2048 + kof0); ka[3] = *(LAS const h16x8*)(kn + 2048 + kof1);
;             if (!SHARED) { LAS const unsigned char* kn2 = Kb + (ks + 1) * 4096;
;                 kb[0] = *(LAS const h16x8*)(kn2 + kof0); kb[1] = *(LAS const h16x8*)(kn2 + kof1); kb[2] = *(LAS const h16x8*)(kn2 + 2048 + kof0); kb[3] = *(LAS const h16x8*)(kn2 + 2048 + kof1); } }
;         __builtin_amdgcn_sched_barrier(0);
;         f32x4 pa0, pa1, pb0, pb1;
; #pragma unroll
;         for (int e = 0; e < 4; ++e) { pa0[e] = __builtin_amdgcn_exp2f(sa0[e]); pa1[e] = __builtin_amdgcn_exp2f(sa1[e]);
;                                       pb0[e] = __builtin_amdgcn_exp2f(sb0[e]); pb1[e] = __builtin_amdgcn_exp2f(sb1[e]); }
;         if (CAUSAL) { const int kr = ks * 32 + 4 * G;
; #pragma unroll
	v_mfma_f32_16x16x32_f16 v[106:109], v[82:85], v[2:5], v[106:109]
	v_mfma_f32_16x16x32_f16 v[82:85], v[82:85], v[18:21], v[10:13]
	s_waitcnt lgkmcnt(8)
	v_mfma_f32_16x16x32_f16 v[10:13], v[86:89], v[2:5], v[110:113]
	v_mfma_f32_16x16x32_f16 v[62:65], v[86:89], v[18:21], v[62:65]
	ds_read_b128 v[86:89], v77 offset:6144
	s_nop 0
	ds_read_b128 v[110:113], v77 offset:4096
	ds_read_b128 v[114:117], v76 offset:6144
	ds_read_b128 v[118:121], v76 offset:4096
	ds_read_b64_tr_b16 v[134:135], v60 offset:36864
	ds_read_b64_tr_b16 v[136:137], v60 offset:38912
	ds_read_b64_tr_b16 v[138:139], v78 offset:36864
	ds_read_b64_tr_b16 v[140:141], v78 offset:38912
	ds_read_b64_tr_b16 v[142:143], v79 offset:36864
	ds_read_b64_tr_b16 v[144:145], v79 offset:38912
	ds_read_b64_tr_b16 v[146:147], v80 offset:36864
	ds_read_b64_tr_b16 v[148:149], v80 offset:38912
	v_exp_f32_e32 v61, v106
	v_exp_f32_e32 v126, v62
	v_exp_f32_e32 v62, v107
	v_exp_f32_e32 v122, v10
	v_exp_f32_e32 v123, v11
	v_exp_f32_e32 v124, v12
	v_exp_f32_e32 v128, v84
	v_exp_f32_e32 v84, v13
	v_mov_b64_e32 v[12:13], s[6:7]
	v_exp_f32_e32 v82, v82
	v_exp_f32_e32 v83, v83
	v_exp_f32_e32 v127, v63
	v_exp_f32_e32 v63, v108
	v_exp_f32_e32 v129, v64
	v_exp_f32_e32 v64, v109
	v_mov_b64_e32 v[10:11], s[4:5]
	v_cvt_pk_f16_f32 v106, v61, v62
	v_exp_f32_e32 v61, v85
	v_exp_f32_e32 v65, v65
	v_cvt_pk_f16_f32 v107, v63, v64
	v_cvt_pk_f16_f32 v108, v122, v123
	v_cvt_pk_f16_f32 v109, v124, v84
	v_cvt_pk_f16_f32 v62, v82, v83
	v_cvt_pk_f16_f32 v63, v128, v61
	v_cvt_pk_f16_f32 v64, v126, v127
	v_cvt_pk_f16_f32 v65, v129, v65
	v_mfma_f32_16x16x32_f16 v[122:125], v[10:13], v[106:109], 0
	s_waitcnt lgkmcnt(14)
	v_mfma_f32_16x16x32_f16 v[82:85], v[90:93], v[106:109], 0
	v_mfma_f32_16x16x32_f16 v[90:93], v[90:93], v[62:65], 0
	v_mfma_f32_16x16x32_f16 v[126:129], v[94:97], v[106:109], 0
	v_mfma_f32_16x16x32_f16 v[94:97], v[94:97], v[62:65], 0
	v_mfma_f32_16x16x32_f16 v[130:133], v[98:101], v[106:109], 0
	v_mfma_f32_16x16x32_f16 v[98:101], v[98:101], v[62:65], 0
	s_waitcnt lgkmcnt(12)
	v_mfma_f32_16x16x32_f16 v[106:109], v[102:105], v[106:109], 0
	v_mfma_f32_16x16x32_f16 v[102:105], v[102:105], v[62:65], 0
	v_mfma_f32_16x16x32_f16 v[62:65], v[10:13], v[62:65], 0
	s_waitcnt lgkmcnt(8)
	v_mfma_f32_16x16x32_f16 v[150:153], v[118:121], v[6:9], v[22:25]
	v_mfma_f32_16x16x32_f16 v[118:121], v[118:121], v[14:17], v[26:29]
	v_mfma_f32_16x16x32_f16 v[154:157], v[114:117], v[6:9], v[22:25]
	v_mfma_f32_16x16x32_f16 v[114:117], v[114:117], v[14:17], v[26:29]
	v_mfma_f32_16x16x32_f16 v[150:153], v[110:113], v[2:5], v[150:153]
	v_mfma_f32_16x16x32_f16 v[110:113], v[110:113], v[18:21], v[118:121]
	v_mfma_f32_16x16x32_f16 v[118:121], v[86:89], v[2:5], v[154:157]
	v_mfma_f32_16x16x32_f16 v[86:89], v[86:89], v[18:21], v[114:117]
	s_nop 3
	ds_read_b128 v[114:117], v77 offset:10240
	ds_read_b128 v[154:157], v77 offset:8192
	ds_read_b128 v[158:161], v76 offset:10240
	ds_read_b128 v[162:165], v76 offset:8192
	v_exp_f32_e32 v61, v150
	v_exp_f32_e32 v166, v86
	v_exp_f32_e32 v86, v151
	v_exp_f32_e32 v150, v118
	v_exp_f32_e32 v110, v110
	v_exp_f32_e32 v151, v119
	v_exp_f32_e32 v111, v111
	v_exp_f32_e32 v167, v87
	v_exp_f32_e32 v87, v152
	v_exp_f32_e32 v152, v120
	v_exp_f32_e32 v112, v112
	v_exp_f32_e32 v119, v153
	v_exp_f32_e32 v153, v88
	v_exp_f32_e32 v88, v121
	v_cvt_pk_f16_f32 v118, v61, v86
	v_exp_f32_e32 v61, v113
	v_exp_f32_e32 v89, v89
	v_cvt_pk_f16_f32 v119, v87, v119
	v_cvt_pk_f16_f32 v120, v150, v151
	v_cvt_pk_f16_f32 v121, v152, v88
	v_cvt_pk_f16_f32 v86, v110, v111
	v_cvt_pk_f16_f32 v87, v112, v61
	v_cvt_pk_f16_f32 v88, v166, v167
	v_cvt_pk_f16_f32 v89, v153, v89
	v_mfma_f32_16x16x32_f16 v[122:125], v[10:13], v[118:121], v[122:125]
	s_waitcnt lgkmcnt(10)
	v_mfma_f32_16x16x32_f16 v[82:85], v[134:137], v[118:121], v[82:85]
	v_mfma_f32_16x16x32_f16 v[90:93], v[134:137], v[86:89], v[90:93]
	s_waitcnt lgkmcnt(8)
	v_mfma_f32_16x16x32_f16 v[110:113], v[138:141], v[118:121], v[126:129]
	v_mfma_f32_16x16x32_f16 v[94:97], v[138:141], v[86:89], v[94:97]
	s_waitcnt lgkmcnt(6)
	v_mfma_f32_16x16x32_f16 v[126:129], v[142:145], v[118:121], v[130:133]
	s_waitcnt lgkmcnt(4)
	v_mfma_f32_16x16x32_f16 v[106:109], v[146:149], v[118:121], v[106:109]
	ds_read_b64_tr_b16 v[118:119], v60 offset:40960
	ds_read_b64_tr_b16 v[120:121], v60 offset:43008
	ds_read_b64_tr_b16 v[130:131], v78 offset:40960
	ds_read_b64_tr_b16 v[132:133], v78 offset:43008
	ds_read_b64_tr_b16 v[134:135], v79 offset:40960
	ds_read_b64_tr_b16 v[136:137], v79 offset:43008
	ds_read_b64_tr_b16 v[138:139], v80 offset:40960
	ds_read_b64_tr_b16 v[140:141], v80 offset:43008
	v_mfma_f32_16x16x32_f16 v[98:101], v[142:145], v[86:89], v[98:101]
	v_mfma_f32_16x16x32_f16 v[102:105], v[146:149], v[86:89], v[102:105]
	v_mfma_f32_16x16x32_f16 v[62:65], v[10:13], v[86:89], v[62:65]
	s_waitcnt lgkmcnt(8)
	v_mfma_f32_16x16x32_f16 v[86:89], v[162:165], v[6:9], v[22:25]
	v_mfma_f32_16x16x32_f16 v[142:145], v[162:165], v[14:17], v[26:29]
	v_mfma_f32_16x16x32_f16 v[146:149], v[158:161], v[6:9], v[22:25]
	v_mfma_f32_16x16x32_f16 v[150:153], v[158:161], v[14:17], v[26:29]
	v_mfma_f32_16x16x32_f16 v[86:89], v[154:157], v[2:5], v[86:89]
	v_mfma_f32_16x16x32_f16 v[142:145], v[154:157], v[18:21], v[142:145]
	v_mfma_f32_16x16x32_f16 v[146:149], v[114:117], v[2:5], v[146:149]
	v_mfma_f32_16x16x32_f16 v[114:117], v[114:117], v[18:21], v[150:153]
	s_nop 3
	ds_read_b128 v[150:153], v77 offset:14336
	ds_read_b128 v[154:157], v77 offset:12288
	ds_read_b128 v[158:161], v76 offset:14336
	ds_read_b128 v[162:165], v76 offset:12288
	v_exp_f32_e32 v61, v86
	v_exp_f32_e32 v86, v87
	v_exp_f32_e32 v146, v146
	v_exp_f32_e32 v142, v142
	v_exp_f32_e32 v166, v114
	v_exp_f32_e32 v114, v147
	v_exp_f32_e32 v143, v143
	v_exp_f32_e32 v147, v115
	v_exp_f32_e32 v87, v88
	v_exp_f32_e32 v115, v148
	v_exp_f32_e32 v144, v144
	v_exp_f32_e32 v88, v89
	v_exp_f32_e32 v148, v116
	v_exp_f32_e32 v89, v149
	v_cvt_pk_f16_f32 v86, v61, v86
	v_exp_f32_e32 v61, v145
	v_exp_f32_e32 v117, v117
	v_cvt_pk_f16_f32 v87, v87, v88
	v_cvt_pk_f16_f32 v88, v146, v114
	v_cvt_pk_f16_f32 v89, v115, v89
	v_cvt_pk_f16_f32 v114, v142, v143
	v_cvt_pk_f16_f32 v115, v144, v61
	v_cvt_pk_f16_f32 v116, v166, v147
	v_cvt_pk_f16_f32 v117, v148, v117
	v_mfma_f32_16x16x32_f16 v[122:125], v[10:13], v[86:89], v[122:125]
	s_waitcnt lgkmcnt(10)
; #define LAS __attribute__((address_space(3)))
; template <bool CAUSAL, bool SHARED> ...
;     ...
;     for (int ks = 0; ks < nsteps; ++ks) {
;         LAS const unsigned char* va = Va + ks * 4096 + vrow; LAS const unsigned char* vb = Vb + ks * 4096 + vrow;
;         h16x4 fal[4], fah[4], fbl[4], fbh[4];
; #pragma unroll
;         for (int dt = 0; dt < 4; ++dt) { fal[dt] = vtr(va + ((dt ^ sw) << 5)); fah[dt] = vtr(va + 2048 + ((dt ^ sw) << 5));
;             if (!SHARED) { fbl[dt] = vtr(vb + ((dt ^ sw) << 5)); fbh[dt] = vtr(vb + 2048 + ((dt ^ sw) << 5)); } }
;         __builtin_amdgcn_sched_barrier(0);
;         f32x4 sa0, sa1, sb0, sb1;
;         sa0 = __builtin_amdgcn_mfma_f32_16x16x32_f16(ka[0], qa0, nma, 0, 0, 0); sb0 = __builtin_amdgcn_mfma_f32_16x16x32_f16(SHARED ? ka[0] : kb[0], qb0, nmb, 0, 0, 0);
;         sa1 = __builtin_amdgcn_mfma_f32_16x16x32_f16(ka[2], qa0, nma, 0, 0, 0); sb1 = __builtin_amdgcn_mfma_f32_16x16x32_f16(SHARED ? ka[2] : kb[2], qb0, nmb, 0, 0, 0);
;         sa0 = __builtin_amdgcn_mfma_f32_16x16x32_f16(ka[1], qa1, sa0, 0, 0, 0); sb0 = __builtin_amdgcn_mfma_f32_16x16x32_f16(SHARED ? ka[1] : kb[1], qb1, sb0, 0, 0, 0);
;         sa1 = __builtin_amdgcn_mfma_f32_16x16x32_f16(ka[3], qa1, sa1, 0, 0, 0); sb1 = __builtin_amdgcn_mfma_f32_16x16x32_f16(SHARED ? ka[3] : kb[3], qb1, sb1, 0, 0, 0);
;         __builtin_amdgcn_sched_barrier(0);
;         if (ks + 1 < nsteps) { LAS const unsigned char* kn = Ka + (ks + 1) * 4096;
;             ka[0] = *(LAS const h16x8*)(kn + kof0); ka[1] = *(LAS const h16x8*)(kn + kof1); ka[2] = *(LAS const h16x8*)(kn + 2048 + kof0); ka[3] = *(LAS const h16x8*)(kn + 2048 + kof1);
;             if (!SHARED) { LAS const unsigned char* kn2 = Kb + (ks + 1) * 4096;
;                 kb[0] = *(LAS const h16x8*)(kn2 + kof0); kb[1] = *(LAS const h16x8*)(kn2 + kof1); kb[2] = *(LAS const h16x8*)(kn2 + 2048 + kof0); kb[3] = *(LAS const h16x8*)(kn2 + 2048 + kof1); } }
;         __builtin_amdgcn_sched_barrier(0);
;         f32x4 pa0, pa1, pb0, pb1;
; #pragma unroll
;         for (int e = 0; e < 4; ++e) { pa0[e] = __builtin_amdgcn_exp2f(sa0[e]); pa1[e] = __builtin_amdgcn_exp2f(sa1[e]);
;                                       pb0[e] = __builtin_amdgcn_exp2f(sb0[e]); pb1[e] = __builtin_amdgcn_exp2f(sb1[e]); }
;         if (CAUSAL) { const int kr = ks * 32 + 4 * G;
; #pragma unroll
	v_mfma_f32_16x16x32_f16 v[82:85], v[118:121], v[86:89], v[82:85]
	v_mfma_f32_16x16x32_f16 v[90:93], v[118:121], v[114:117], v[90:93]
	s_waitcnt lgkmcnt(8)
	v_mfma_f32_16x16x32_f16 v[110:113], v[130:133], v[86:89], v[110:113]
	v_mfma_f32_16x16x32_f16 v[94:97], v[130:133], v[114:117], v[94:97]
	s_waitcnt lgkmcnt(6)
	v_mfma_f32_16x16x32_f16 v[118:121], v[134:137], v[86:89], v[126:129]
	v_mfma_f32_16x16x32_f16 v[98:101], v[134:137], v[114:117], v[98:101]
	s_waitcnt lgkmcnt(4)
	v_mfma_f32_16x16x32_f16 v[86:89], v[138:141], v[86:89], v[106:109]
	s_nop 2
	ds_read_b64_tr_b16 v[106:107], v60 offset:45056
	ds_read_b64_tr_b16 v[108:109], v60 offset:47104
	ds_read_b64_tr_b16 v[126:127], v78 offset:45056
	ds_read_b64_tr_b16 v[128:129], v78 offset:47104
	ds_read_b64_tr_b16 v[130:131], v79 offset:45056
	ds_read_b64_tr_b16 v[132:133], v79 offset:47104
	ds_read_b64_tr_b16 v[134:135], v80 offset:45056
	ds_read_b64_tr_b16 v[136:137], v80 offset:47104
	v_mfma_f32_16x16x32_f16 v[102:105], v[138:141], v[114:117], v[102:105]
	v_mfma_f32_16x16x32_f16 v[62:65], v[10:13], v[114:117], v[62:65]
	s_waitcnt lgkmcnt(8)
	v_mfma_f32_16x16x32_f16 v[114:117], v[162:165], v[6:9], v[22:25]
	v_mfma_f32_16x16x32_f16 v[138:141], v[162:165], v[14:17], v[26:29]
	v_mfma_f32_16x16x32_f16 v[142:145], v[158:161], v[6:9], v[22:25]
	v_mfma_f32_16x16x32_f16 v[146:149], v[158:161], v[14:17], v[26:29]
	v_mfma_f32_16x16x32_f16 v[114:117], v[154:157], v[2:5], v[114:117]
	v_mfma_f32_16x16x32_f16 v[138:141], v[154:157], v[18:21], v[138:141]
	v_mfma_f32_16x16x32_f16 v[142:145], v[150:153], v[2:5], v[142:145]
	v_mfma_f32_16x16x32_f16 v[146:149], v[150:153], v[18:21], v[146:149]
	ds_read_b128 v[150:153], v77 offset:18432
	ds_read_b128 v[154:157], v77 offset:16384
	ds_read_b128 v[158:161], v76 offset:18432
	ds_read_b128 v[162:165], v76 offset:16384
	s_nop 0
	v_exp_f32_e32 v61, v114
	v_exp_f32_e32 v114, v115
	v_exp_f32_e32 v142, v142
	v_exp_f32_e32 v138, v138
	v_exp_f32_e32 v146, v146
	v_exp_f32_e32 v143, v143
	v_exp_f32_e32 v139, v139
	v_exp_f32_e32 v147, v147
	v_exp_f32_e32 v115, v116
	v_exp_f32_e32 v144, v144
	v_exp_f32_e32 v140, v140
	v_exp_f32_e32 v116, v117
	v_exp_f32_e32 v148, v148
	v_exp_f32_e32 v117, v145
	v_cvt_pk_f16_f32 v114, v61, v114
	v_exp_f32_e32 v61, v141
	v_exp_f32_e32 v141, v149
	v_cvt_pk_f16_f32 v115, v115, v116
	v_cvt_pk_f16_f32 v116, v142, v143
	v_cvt_pk_f16_f32 v117, v144, v117
	v_cvt_pk_f16_f32 v138, v138, v139
	v_cvt_pk_f16_f32 v139, v140, v61
	v_cvt_pk_f16_f32 v140, v146, v147
	v_cvt_pk_f16_f32 v141, v148, v141
	v_mfma_f32_16x16x32_f16 v[122:125], v[10:13], v[114:117], v[122:125]
	s_waitcnt lgkmcnt(10)
	v_mfma_f32_16x16x32_f16 v[82:85], v[106:109], v[114:117], v[82:85]
	v_mfma_f32_16x16x32_f16 v[90:93], v[106:109], v[138:141], v[90:93]
	s_waitcnt lgkmcnt(8)
	v_mfma_f32_16x16x32_f16 v[106:109], v[126:129], v[114:117], v[110:113]
	v_mfma_f32_16x16x32_f16 v[94:97], v[126:129], v[138:141], v[94:97]
	s_waitcnt lgkmcnt(6)
	v_mfma_f32_16x16x32_f16 v[110:113], v[130:133], v[114:117], v[118:121]
	v_mfma_f32_16x16x32_f16 v[98:101], v[130:133], v[138:141], v[98:101]
	s_waitcnt lgkmcnt(4)
	v_mfma_f32_16x16x32_f16 v[86:89], v[134:137], v[114:117], v[86:89]
	ds_read_b64_tr_b16 v[114:115], v60 offset:49152
	ds_read_b64_tr_b16 v[116:117], v60 offset:51200
	ds_read_b64_tr_b16 v[118:119], v78 offset:49152
	ds_read_b64_tr_b16 v[120:121], v78 offset:51200
	ds_read_b64_tr_b16 v[126:127], v79 offset:49152
	ds_read_b64_tr_b16 v[128:129], v79 offset:51200
	ds_read_b64_tr_b16 v[130:131], v80 offset:49152
	ds_read_b64_tr_b16 v[132:133], v80 offset:51200
	v_mfma_f32_16x16x32_f16 v[102:105], v[134:137], v[138:141], v[102:105]
	v_mfma_f32_16x16x32_f16 v[62:65], v[10:13], v[138:141], v[62:65]
	s_waitcnt lgkmcnt(8)
	v_mfma_f32_16x16x32_f16 v[134:137], v[162:165], v[6:9], v[22:25]
	v_mfma_f32_16x16x32_f16 v[138:141], v[162:165], v[14:17], v[26:29]
	v_mfma_f32_16x16x32_f16 v[142:145], v[158:161], v[6:9], v[22:25]
	v_mfma_f32_16x16x32_f16 v[146:149], v[158:161], v[14:17], v[26:29]
	v_mfma_f32_16x16x32_f16 v[134:137], v[154:157], v[2:5], v[134:137]
	v_mfma_f32_16x16x32_f16 v[138:141], v[154:157], v[18:21], v[138:141]
	v_mfma_f32_16x16x32_f16 v[142:145], v[150:153], v[2:5], v[142:145]
	v_mfma_f32_16x16x32_f16 v[146:149], v[150:153], v[18:21], v[146:149]
	ds_read_b128 v[150:153], v77 offset:22528
	ds_read_b128 v[154:157], v77 offset:20480
	ds_read_b128 v[158:161], v76 offset:22528
	ds_read_b128 v[162:165], v76 offset:20480
	s_nop 0
	v_exp_f32_e32 v61, v134
	v_exp_f32_e32 v134, v135
	v_exp_f32_e32 v142, v142
	v_exp_f32_e32 v138, v138
	v_exp_f32_e32 v146, v146
	v_exp_f32_e32 v143, v143
	v_exp_f32_e32 v139, v139
	v_exp_f32_e32 v147, v147
	v_exp_f32_e32 v135, v136
	v_exp_f32_e32 v144, v144
	v_exp_f32_e32 v140, v140
	v_exp_f32_e32 v136, v137
	v_exp_f32_e32 v148, v148
	v_exp_f32_e32 v137, v145
	v_cvt_pk_f16_f32 v134, v61, v134
	v_exp_f32_e32 v61, v141
	v_exp_f32_e32 v141, v149
	v_cvt_pk_f16_f32 v135, v135, v136
	v_cvt_pk_f16_f32 v136, v142, v143
	v_cvt_pk_f16_f32 v137, v144, v137
	v_cvt_pk_f16_f32 v138, v138, v139
	v_cvt_pk_f16_f32 v139, v140, v61
	v_cvt_pk_f16_f32 v140, v146, v147
	v_cvt_pk_f16_f32 v141, v148, v141
	s_waitcnt lgkmcnt(10)
	v_mfma_f32_16x16x32_f16 v[82:85], v[114:117], v[134:137], v[82:85]
	v_mfma_f32_16x16x32_f16 v[90:93], v[114:117], v[138:141], v[90:93]
	s_waitcnt lgkmcnt(8)
	v_mfma_f32_16x16x32_f16 v[106:109], v[118:121], v[134:137], v[106:109]
	v_mfma_f32_16x16x32_f16 v[94:97], v[118:121], v[138:141], v[94:97]
	s_waitcnt lgkmcnt(6)
	v_mfma_f32_16x16x32_f16 v[110:113], v[126:129], v[134:137], v[110:113]
	v_mfma_f32_16x16x32_f16 v[98:101], v[126:129], v[138:141], v[98:101]
	s_waitcnt lgkmcnt(4)
; #define LAS __attribute__((address_space(3)))
; template <bool CAUSAL, bool SHARED> ...
;     ...
;     for (int ks = 0; ks < nsteps; ++ks) {
;         LAS const unsigned char* va = Va + ks * 4096 + vrow; LAS const unsigned char* vb = Vb + ks * 4096 + vrow;
;         h16x4 fal[4], fah[4], fbl[4], fbh[4];
; #pragma unroll
;         for (int dt = 0; dt < 4; ++dt) { fal[dt] = vtr(va + ((dt ^ sw) << 5)); fah[dt] = vtr(va + 2048 + ((dt ^ sw) << 5));
;             if (!SHARED) { fbl[dt] = vtr(vb + ((dt ^ sw) << 5)); fbh[dt] = vtr(vb + 2048 + ((dt ^ sw) << 5)); } }
;         __builtin_amdgcn_sched_barrier(0);
;         f32x4 sa0, sa1, sb0, sb1;
;         sa0 = __builtin_amdgcn_mfma_f32_16x16x32_f16(ka[0], qa0, nma, 0, 0, 0); sb0 = __builtin_amdgcn_mfma_f32_16x16x32_f16(SHARED ? ka[0] : kb[0], qb0, nmb, 0, 0, 0);
;         sa1 = __builtin_amdgcn_mfma_f32_16x16x32_f16(ka[2], qa0, nma, 0, 0, 0); sb1 = __builtin_amdgcn_mfma_f32_16x16x32_f16(SHARED ? ka[2] : kb[2], qb0, nmb, 0, 0, 0);
;         sa0 = __builtin_amdgcn_mfma_f32_16x16x32_f16(ka[1], qa1, sa0, 0, 0, 0); sb0 = __builtin_amdgcn_mfma_f32_16x16x32_f16(SHARED ? ka[1] : kb[1], qb1, sb0, 0, 0, 0);
;         sa1 = __builtin_amdgcn_mfma_f32_16x16x32_f16(ka[3], qa1, sa1, 0, 0, 0); sb1 = __builtin_amdgcn_mfma_f32_16x16x32_f16(SHARED ? ka[3] : kb[3], qb1, sb1, 0, 0, 0);
;         __builtin_amdgcn_sched_barrier(0);
;         if (ks + 1 < nsteps) { LAS const unsigned char* kn = Ka + (ks + 1) * 4096;
;             ka[0] = *(LAS const h16x8*)(kn + kof0); ka[1] = *(LAS const h16x8*)(kn + kof1); ka[2] = *(LAS const h16x8*)(kn + 2048 + kof0); ka[3] = *(LAS const h16x8*)(kn + 2048 + kof1);
;             if (!SHARED) { LAS const unsigned char* kn2 = Kb + (ks + 1) * 4096;
;                 kb[0] = *(LAS const h16x8*)(kn2 + kof0); kb[1] = *(LAS const h16x8*)(kn2 + kof1); kb[2] = *(LAS const h16x8*)(kn2 + 2048 + kof0); kb[3] = *(LAS const h16x8*)(kn2 + 2048 + kof1); } }
;         __builtin_amdgcn_sched_barrier(0);
;         f32x4 pa0, pa1, pb0, pb1;
; #pragma unroll
;         for (int e = 0; e < 4; ++e) { pa0[e] = __builtin_amdgcn_exp2f(sa0[e]); pa1[e] = __builtin_amdgcn_exp2f(sa1[e]);
;                                       pb0[e] = __builtin_amdgcn_exp2f(sb0[e]); pb1[e] = __builtin_amdgcn_exp2f(sb1[e]); }
;         if (CAUSAL) { const int kr = ks * 32 + 4 * G;
; #pragma unroll
	v_mfma_f32_16x16x32_f16 v[86:89], v[130:133], v[134:137], v[86:89]
	v_mfma_f32_16x16x32_f16 v[102:105], v[130:133], v[138:141], v[102:105]
	ds_read_b64_tr_b16 v[114:115], v60 offset:53248
	ds_read_b64_tr_b16 v[116:117], v60 offset:55296
	ds_read_b64_tr_b16 v[118:119], v78 offset:53248
	ds_read_b64_tr_b16 v[120:121], v78 offset:55296
	ds_read_b64_tr_b16 v[126:127], v79 offset:53248
	ds_read_b64_tr_b16 v[128:129], v79 offset:55296
	ds_read_b64_tr_b16 v[130:131], v80 offset:53248
	ds_read_b64_tr_b16 v[132:133], v80 offset:55296
	v_mfma_f32_16x16x32_f16 v[122:125], v[10:13], v[134:137], v[122:125]
	v_mfma_f32_16x16x32_f16 v[62:65], v[10:13], v[138:141], v[62:65]
	s_waitcnt lgkmcnt(8)
	v_mfma_f32_16x16x32_f16 v[134:137], v[162:165], v[6:9], v[22:25]
	v_mfma_f32_16x16x32_f16 v[138:141], v[162:165], v[14:17], v[26:29]
	v_mfma_f32_16x16x32_f16 v[142:145], v[158:161], v[6:9], v[22:25]
	v_mfma_f32_16x16x32_f16 v[146:149], v[158:161], v[14:17], v[26:29]
	v_mfma_f32_16x16x32_f16 v[134:137], v[154:157], v[2:5], v[134:137]
	v_mfma_f32_16x16x32_f16 v[138:141], v[154:157], v[18:21], v[138:141]
	v_mfma_f32_16x16x32_f16 v[142:145], v[150:153], v[2:5], v[142:145]
	v_mfma_f32_16x16x32_f16 v[146:149], v[150:153], v[18:21], v[146:149]
	ds_read_b128 v[150:153], v77 offset:26624
	ds_read_b128 v[154:157], v77 offset:24576
	ds_read_b128 v[158:161], v76 offset:26624
	ds_read_b128 v[162:165], v76 offset:24576
	s_nop 0
	v_exp_f32_e32 v61, v134
	v_exp_f32_e32 v134, v135
	v_exp_f32_e32 v142, v142
	v_exp_f32_e32 v138, v138
	v_exp_f32_e32 v146, v146
	v_exp_f32_e32 v143, v143
	v_exp_f32_e32 v139, v139
	v_exp_f32_e32 v147, v147
	v_exp_f32_e32 v135, v136
	v_exp_f32_e32 v144, v144
	v_exp_f32_e32 v140, v140
	v_exp_f32_e32 v136, v137
	v_exp_f32_e32 v148, v148
	v_exp_f32_e32 v137, v145
	v_cvt_pk_f16_f32 v134, v61, v134
	v_exp_f32_e32 v61, v141
	v_exp_f32_e32 v141, v149
	v_cvt_pk_f16_f32 v135, v135, v136
	v_cvt_pk_f16_f32 v136, v142, v143
	v_cvt_pk_f16_f32 v137, v144, v137
	v_cvt_pk_f16_f32 v138, v138, v139
	v_cvt_pk_f16_f32 v139, v140, v61
	v_cvt_pk_f16_f32 v140, v146, v147
	v_cvt_pk_f16_f32 v141, v148, v141
	s_waitcnt lgkmcnt(10)
	v_mfma_f32_16x16x32_f16 v[82:85], v[114:117], v[134:137], v[82:85]
	v_mfma_f32_16x16x32_f16 v[90:93], v[114:117], v[138:141], v[90:93]
	s_waitcnt lgkmcnt(8)
	v_mfma_f32_16x16x32_f16 v[106:109], v[118:121], v[134:137], v[106:109]
	v_mfma_f32_16x16x32_f16 v[94:97], v[118:121], v[138:141], v[94:97]
	s_waitcnt lgkmcnt(6)
	v_mfma_f32_16x16x32_f16 v[110:113], v[126:129], v[134:137], v[110:113]
	v_mfma_f32_16x16x32_f16 v[98:101], v[126:129], v[138:141], v[98:101]
	s_waitcnt lgkmcnt(4)
	v_mfma_f32_16x16x32_f16 v[86:89], v[130:133], v[134:137], v[86:89]
	v_mfma_f32_16x16x32_f16 v[102:105], v[130:133], v[138:141], v[102:105]
	ds_read_b64_tr_b16 v[114:115], v60 offset:57344
	ds_read_b64_tr_b16 v[116:117], v60 offset:59392
	ds_read_b64_tr_b16 v[118:119], v78 offset:57344
	ds_read_b64_tr_b16 v[120:121], v78 offset:59392
	ds_read_b64_tr_b16 v[126:127], v79 offset:57344
	ds_read_b64_tr_b16 v[128:129], v79 offset:59392
	ds_read_b64_tr_b16 v[130:131], v80 offset:57344
	ds_read_b64_tr_b16 v[132:133], v80 offset:59392
	v_mfma_f32_16x16x32_f16 v[122:125], v[10:13], v[134:137], v[122:125]
	v_mfma_f32_16x16x32_f16 v[62:65], v[10:13], v[138:141], v[62:65]
	s_waitcnt lgkmcnt(8)
	v_mfma_f32_16x16x32_f16 v[134:137], v[162:165], v[6:9], v[22:25]
	v_mfma_f32_16x16x32_f16 v[138:141], v[162:165], v[14:17], v[26:29]
	v_mfma_f32_16x16x32_f16 v[142:145], v[158:161], v[6:9], v[22:25]
	v_mfma_f32_16x16x32_f16 v[146:149], v[158:161], v[14:17], v[26:29]
	v_mfma_f32_16x16x32_f16 v[134:137], v[154:157], v[2:5], v[134:137]
	v_mfma_f32_16x16x32_f16 v[138:141], v[154:157], v[18:21], v[138:141]
	v_mfma_f32_16x16x32_f16 v[142:145], v[150:153], v[2:5], v[142:145]
	v_mfma_f32_16x16x32_f16 v[146:149], v[150:153], v[18:21], v[146:149]
	ds_read_b128 v[150:153], v77 offset:30720
	ds_read_b128 v[154:157], v77 offset:28672
	ds_read_b128 v[158:161], v76 offset:30720
	ds_read_b128 v[162:165], v76 offset:28672
	s_nop 0
	v_exp_f32_e32 v61, v134
	v_exp_f32_e32 v134, v135
	v_exp_f32_e32 v142, v142
	v_exp_f32_e32 v138, v138
	v_exp_f32_e32 v146, v146
	v_exp_f32_e32 v143, v143
	v_exp_f32_e32 v139, v139
	v_exp_f32_e32 v147, v147
	v_exp_f32_e32 v135, v136
	v_exp_f32_e32 v144, v144
	v_exp_f32_e32 v140, v140
	v_exp_f32_e32 v136, v137
	v_exp_f32_e32 v148, v148
	v_exp_f32_e32 v137, v145
	v_cvt_pk_f16_f32 v134, v61, v134
	v_exp_f32_e32 v61, v141
	v_exp_f32_e32 v141, v149
	v_cvt_pk_f16_f32 v135, v135, v136
	v_cvt_pk_f16_f32 v136, v142, v143
	v_cvt_pk_f16_f32 v137, v144, v137
	v_cvt_pk_f16_f32 v138, v138, v139
	v_cvt_pk_f16_f32 v139, v140, v61
	v_cvt_pk_f16_f32 v140, v146, v147
	v_cvt_pk_f16_f32 v141, v148, v141
	s_waitcnt lgkmcnt(10)
	v_mfma_f32_16x16x32_f16 v[82:85], v[114:117], v[134:137], v[82:85]
	v_mfma_f32_16x16x32_f16 v[90:93], v[114:117], v[138:141], v[90:93]
	s_waitcnt lgkmcnt(8)
	v_mfma_f32_16x16x32_f16 v[106:109], v[118:121], v[134:137], v[106:109]
	v_mfma_f32_16x16x32_f16 v[94:97], v[118:121], v[138:141], v[94:97]
	s_waitcnt lgkmcnt(6)
	v_mfma_f32_16x16x32_f16 v[110:113], v[126:129], v[134:137], v[110:113]
	v_mfma_f32_16x16x32_f16 v[98:101], v[126:129], v[138:141], v[98:101]
	s_waitcnt lgkmcnt(4)
; __device__ __forceinline__ unsigned pk8(float a, float b, float c, float d) { int w = __builtin_amdgcn_cvt_pk_fp8_f32(a, b, 0, false); w = __builtin_amdgcn_cvt_pk_fp8_f32(c, d, w, true); return (unsigned)w; }
; __device__ __forceinline__ h16x8 cat8(h16x4 lo, h16x4 hi) { return (h16x8){lo[0], lo[1], lo[2], lo[3], hi[0], hi[1], hi[2], hi[3]}; }
; __device__ __forceinline__ int pair16_dim(int G, int dt0) { return (G & 1) ? 16 * (dt0 + 1) + 4 * (G - 1) : 16 * dt0 + 4 * G; }
; __device__ __forceinline__ void store_o8(unsigned char* rowp, const f32x4 (&o)[4], float il, int G) {
;     const float c = il * F8_SY;
; #pragma unroll
;     for (int pr = 0; pr < 2; ++pr) { const int dt0 = 2 * pr;
;         const unsigned a = pk8(o[dt0][0] * c, o[dt0][1] * c, o[dt0][2] * c, o[dt0][3] * c), b = pk8(o[dt0 + 1][0] * c, o[dt0 + 1][1] * c, o[dt0 + 1][2] * c, o[dt0 + 1][3] * c);
;         const auto r = __builtin_amdgcn_permlane16_swap(a, b, false, false);
;         *(u32x2*)(rowp + pair16_dim(G, dt0)) = (u32x2){r[0], r[1]}; }
; }
; template <bool CAUSAL, bool SHARED> ...
;     ...
;         la = __builtin_amdgcn_mfma_f32_16x16x32_f16(ones, pfa, la, 0, 0, 0); lb = __builtin_amdgcn_mfma_f32_16x16x32_f16(ones, pfb, lb, 0, 0, 0);
; #pragma unroll
;         for (int dt = 0; dt < 4; ++dt) {
;             const h16x8 fa = cat8(fal[dt], fah[dt]);
;             const h16x8 fb = SHARED ? fa : cat8(fbl[dt], fbh[dt]);
;             oa[dt] = __builtin_amdgcn_mfma_f32_16x16x32_f16(fa, pfa, oa[dt], 0, 0, 0);
;             ob[dt] = __builtin_amdgcn_mfma_f32_16x16x32_f16(fb, pfb, ob[dt], 0, 0, 0);
;         }
;     }
;     lsa_out = la[0]; lsb_out = lb[0];
	v_mfma_f32_16x16x32_f16 v[86:89], v[130:133], v[134:137], v[86:89]
	v_mfma_f32_16x16x32_f16 v[102:105], v[130:133], v[138:141], v[102:105]
	ds_read_b64_tr_b16 v[114:115], v60 offset:61440
	ds_read_b64_tr_b16 v[116:117], v60 offset:63488
	ds_read_b64_tr_b16 v[118:119], v78 offset:61440
	ds_read_b64_tr_b16 v[120:121], v78 offset:63488
	ds_read_b64_tr_b16 v[126:127], v79 offset:61440
	ds_read_b64_tr_b16 v[128:129], v79 offset:63488
	ds_read_b64_tr_b16 v[130:131], v80 offset:61440
	ds_read_b64_tr_b16 v[132:133], v80 offset:63488
	v_mfma_f32_16x16x32_f16 v[122:125], v[10:13], v[134:137], v[122:125]
	v_mfma_f32_16x16x32_f16 v[60:63], v[10:13], v[138:141], v[62:65]
	s_waitcnt lgkmcnt(8)
	v_mfma_f32_16x16x32_f16 v[134:137], v[162:165], v[6:9], v[22:25]
	v_mfma_f32_16x16x32_f16 v[138:141], v[162:165], v[14:17], v[26:29]
	v_mfma_f32_16x16x32_f16 v[6:9], v[158:161], v[6:9], v[22:25]
	v_mfma_f32_16x16x32_f16 v[14:17], v[158:161], v[14:17], v[26:29]
	v_mfma_f32_16x16x32_f16 v[22:25], v[154:157], v[2:5], v[134:137]
	v_mfma_f32_16x16x32_f16 v[26:29], v[154:157], v[18:21], v[138:141]
	v_mfma_f32_16x16x32_f16 v[2:5], v[150:153], v[2:5], v[6:9]
	v_mfma_f32_16x16x32_f16 v[6:9], v[150:153], v[18:21], v[14:17]
	s_nop 7
	v_exp_f32_e32 v21, v7
	v_exp_f32_e32 v7, v4
	v_exp_f32_e32 v5, v5
	v_exp_f32_e32 v14, v22
	v_exp_f32_e32 v15, v2
	v_exp_f32_e32 v20, v6
	v_exp_f32_e32 v2, v23
	v_exp_f32_e32 v6, v3
	v_exp_f32_e32 v3, v24
	v_exp_f32_e32 v4, v25
	v_exp_f32_e32 v18, v26
	v_exp_f32_e32 v19, v27
	v_exp_f32_e32 v22, v28
	v_exp_f32_e32 v23, v8
	v_cvt_pk_f16_f32 v5, v7, v5
	v_exp_f32_e32 v7, v29
	v_exp_f32_e32 v9, v9
	v_cvt_pk_f16_f32 v2, v14, v2
	v_cvt_pk_f16_f32 v3, v3, v4
	v_cvt_pk_f16_f32 v4, v15, v6
	v_cvt_pk_f16_f32 v6, v18, v19
	v_cvt_pk_f16_f32 v7, v22, v7
	v_mfma_f32_16x16x32_f16 v[14:17], v[10:13], v[2:5], v[122:125]
	v_cvt_pk_f16_f32 v8, v20, v21
	v_cvt_pk_f16_f32 v9, v23, v9
	s_add_u32 s2, s13, s42
	s_waitcnt lgkmcnt(6)
	v_mfma_f32_16x16x32_f16 v[16:19], v[114:117], v[2:5], v[82:85]
	s_addc_u32 s3, s16, 0
	v_mov_b32_e32 v28, 0
	v_mov_b32_e32 v29, 0
	v_mfma_f32_16x16x32_f16 v[20:23], v[114:117], v[6:9], v[90:93]
	v_mov_b32_e32 v65, 0
	v_mov_b32_e32 v64, 0
	s_and_b64 s[0:1], exec, s[14:15]
	s_waitcnt lgkmcnt(4)
	v_mfma_f32_16x16x32_f16 v[24:27], v[118:121], v[2:5], v[106:109]
	s_mov_b32 s8, 1
	s_mov_b64 s[14:15], 0
	v_mfma_f32_16x16x32_f16 v[82:85], v[118:121], v[6:9], v[94:97]
	v_mov_b32_e32 v106, 0
	v_mov_b32_e32 v107, 0
	v_mov_b32_e32 v108, 0
	s_waitcnt lgkmcnt(2)
	v_mfma_f32_16x16x32_f16 v[90:93], v[126:129], v[2:5], v[110:113]
	v_mov_b32_e32 v109, 0
	v_mfma_f32_16x16x32_f16 v[94:97], v[126:129], v[6:9], v[98:101]
	s_waitcnt lgkmcnt(0)
	v_mfma_f32_16x16x32_f16 v[2:5], v[130:133], v[2:5], v[86:89]
	s_nop 0
	v_lshl_add_u64 v[98:99], s[2:3], 0, v[52:53]
	v_lshl_add_u64 v[100:101], s[2:3], 0, v[56:57]
	v_lshl_add_u64 v[98:99], v[98:99], 0, v[30:31]
	v_mfma_f32_16x16x32_f16 v[86:89], v[130:133], v[6:9], v[102:105]
	v_lshl_add_u64 v[100:101], v[100:101], 0, v[30:31]
	v_mfma_f32_16x16x32_f16 v[6:9], v[10:13], v[6:9], v[60:63]
	s_nop 7
	v_div_scale_f32 v7, s[2:3], v14, v14, 1.0
	v_div_scale_f32 v9, s[2:3], v6, v6, 1.0
	v_rcp_f32_e32 v11, v7
	v_rcp_f32_e32 v12, v9
	v_div_scale_f32 v8, vcc, 1.0, v14, 1.0
	v_fma_f32 v13, -v7, v11, 1.0
	v_fma_f32 v15, -v9, v12, 1.0
	v_fmac_f32_e32 v11, v13, v11
	v_div_scale_f32 v10, s[2:3], 1.0, v6, 1.0
	v_fmac_f32_e32 v12, v15, v12
	v_mul_f32_e32 v13, v8, v11
	v_mul_f32_e32 v15, v10, v12
	v_fma_f32 v60, -v7, v13, v8
	v_fma_f32 v61, -v9, v15, v10
	v_fmac_f32_e32 v13, v60, v11
	v_fmac_f32_e32 v15, v61, v12
	v_fma_f32 v7, -v7, v13, v8
	v_fma_f32 v8, -v9, v15, v10
	v_div_fmas_f32 v7, v7, v11, v13
	s_mov_b64 vcc, s[2:3]
	v_div_fixup_f32 v7, v7, v14, 1.0
	v_div_fmas_f32 v8, v8, v12, v15
	v_div_fixup_f32 v6, v8, v6, 1.0
	v_mul_f32_e32 v7, 0x42000000, v7
	v_mul_f32_e32 v8, v16, v7
	v_mul_f32_e32 v9, v17, v7
	v_mul_f32_e32 v12, v7, v24
	v_mul_f32_e32 v13, v7, v25
	v_mul_f32_e32 v2, v7, v2
	v_mul_f32_e32 v3, v7, v3
	v_mul_f32_e32 v6, 0x42000000, v6
	v_mul_f32_e32 v16, v7, v90
	v_mul_f32_e32 v17, v7, v91
	v_cvt_pk_fp8_f32 v28, v8, v9
	v_cvt_pk_fp8_f32 v29, v12, v13
	v_cvt_pk_fp8_f32 v65, v2, v3
	v_mul_f32_e32 v2, v20, v6
	v_mul_f32_e32 v3, v21, v6
	v_mul_f32_e32 v9, v82, v6
	v_mul_f32_e32 v12, v83, v6
	v_cvt_pk_fp8_f32 v64, v16, v17
	v_mul_f32_e32 v8, v23, v6
	v_mul_f32_e32 v17, v94, v6
	v_mul_f32_e32 v20, v95, v6
	v_mul_f32_e32 v23, v86, v6
	v_mul_f32_e32 v24, v87, v6
	v_cvt_pk_fp8_f32 v106, v2, v3
	v_cvt_pk_fp8_f32 v107, v9, v12
	v_cvt_pk_fp8_f32 v108, v17, v20
	v_cvt_pk_fp8_f32 v109, v23, v24
	v_mul_f32_e32 v10, v18, v7
	v_mul_f32_e32 v11, v19, v7
	v_mul_f32_e32 v14, v7, v26
	v_mul_f32_e32 v15, v7, v27
	v_mul_f32_e32 v18, v7, v92
	v_mul_f32_e32 v19, v7, v93
	v_mul_f32_e32 v4, v7, v4
	v_mul_f32_e32 v5, v7, v5
	v_mul_f32_e32 v7, v22, v6
	v_mul_f32_e32 v13, v84, v6
	v_mul_f32_e32 v16, v85, v6
	v_mul_f32_e32 v21, v96, v6
	v_mul_f32_e32 v22, v97, v6
	v_mul_f32_e32 v25, v88, v6
	v_mul_f32_e32 v6, v89, v6
	v_cvt_pk_fp8_f32 v28, v10, v11 op_sel:[0,0,1]
	v_cvt_pk_fp8_f32 v29, v14, v15 op_sel:[0,0,1]
	v_cvt_pk_fp8_f32 v106, v7, v8 op_sel:[0,0,1]
	v_cvt_pk_fp8_f32 v107, v13, v16 op_sel:[0,0,1]
	v_cvt_pk_fp8_f32 v64, v18, v19 op_sel:[0,0,1]
	v_cvt_pk_fp8_f32 v65, v4, v5 op_sel:[0,0,1]
	v_cvt_pk_fp8_f32 v108, v21, v22 op_sel:[0,0,1]
	v_cvt_pk_fp8_f32 v109, v25, v6 op_sel:[0,0,1]
	v_permlane16_swap_b32_e32 v28, v29
	v_permlane16_swap_b32_e32 v106, v107
	s_mov_b64 vcc, s[0:1]
	v_permlane16_swap_b32_e32 v64, v65
	global_store_dwordx2 v[98:99], v[28:29], off
	global_store_dwordx2 v[98:99], v[64:65], off offset:32
	v_permlane16_swap_b32_e32 v108, v109
	global_store_dwordx2 v[100:101], v[106:107], off
	global_store_dwordx2 v[100:101], v[108:109], off offset:32
	s_barrier
	s_cbranch_vccnz .LBB0_921
	s_add_i32 s40, s40, s88
	s_cmpk_lt_i32 s40, 0x100
	s_cbranch_scc1 .LBB0_920

; #define VM_WAIT() asm volatile("s_waitcnt vmcnt(0)" ::: "memory")
; template <bool PR_ENG, bool PR_PART, bool PR_ST>
; __device__ __forceinline__ void moba_own(const Frame& F, const Args& a) {
;     ...
;     for (int up = F.vcu; up < BATCH * MOBA_H * NBLK / 2; up += F.G) {
;         const int bh = up / (NBLK / 2), b = bh / MOBA_H, h = bh % MOBA_H, qb0 = 2 * (up % (NBLK / 2));
;         __syncthreads();
; #pragma unroll
;         for (int k = 0; k < 2; ++k) { const f16_t* kb = P + (size_t)(b * SEQ + (qb0 + k) * MOBA_BLK) * NB + MIXW + h * HD;
;             dma_kv_imgs(F.lds + k * 65536, F.lds + k * 65536 + 32768, kb, kb + MIXW, w, lane); }
;         const int dt0 = w, dt1 = 7 - w;
;         const int tq[2][2] = {{qb0 * MOBA_BLK + 32 * dt0 + fr, qb0 * MOBA_BLK + 32 * dt0 + 16 + fr}, {(qb0 + 1) * MOBA_BLK + 32 * dt1 + fr, (qb0 + 1) * MOBA_BLK + 32 * dt1 + 16 + fr}};
;         VM_WAIT();
;         __syncthreads();
; #pragma unroll
;         for (int k = 0; k < 2; ++k) {
;             const int qb = qb0 + k, nsel = qb < 3 ? qb : 3, dti = k ? dt1 : dt0;
;             const int ta = tq[k][0], tb = tq[k][1];
;             h16x8 q0[2][2], q1[2][2]; float mb[2][2];
; #pragma unroll
;             for (int t = 0; t < 2; ++t) moba_load_q(P + (size_t)(b * SEQ + tq[k][t]) * NB + h * HD, G, maxgk, q0[k][t], q1[k][t], mb[k][t]);
.LBB0_1224:
	s_ashr_i32 s0, s51, 31
	s_lshr_b32 s0, s0, 27
	s_add_i32 s0, s51, s0
	s_mul_hi_i32 s1, s51, 0x2aaaaaab
	s_ashr_i32 s20, s0, 5
	s_lshr_b32 s2, s1, 31
	s_lshr_b32 s1, s1, 6
	s_add_i32 s1, s1, s2
	s_mul_hi_i32 s2, s20, 0x2aaaaaab
	s_lshr_b32 s3, s2, 31
	s_lshr_b32 s2, s2, 1
	s_add_i32 s2, s2, s3
	s_andn2_b32 s0, s0, 31
	s_mul_i32 s2, s2, 12
	s_sub_i32 s52, s51, s0
	s_sub_i32 s2, s20, s2
	s_lshl_b32 s53, s1, 14
	s_lshl_b32 s54, s52, 9
	s_lshl_b32 s22, s2, 6
	s_add_i32 s21, s54, s53
	s_ashr_i32 s23, s22, 31
	s_mul_i32 s1, s21, 0x1400
	s_mul_hi_i32 s0, s21, 0x1400
	s_add_u32 s2, s58, s1
	s_addc_u32 s3, s59, s0
	s_lshl_b64 s[0:1], s[22:23], 1
	s_add_u32 s2, s2, s0
	s_addc_u32 s3, s3, s1
	v_mov_b32_e32 v169, v163
	v_lshl_add_u64 v[2:3], s[2:3], 0, v[168:169]
	v_mov_b32_e32 v171, v163
	v_lshl_add_u64 v[2:3], v[2:3], 0, s[14:15]
	v_lshl_add_u64 v[4:5], s[2:3], 0, v[170:171]
	s_barrier
	v_lshl_add_u64 v[4:5], v[4:5], 0, s[16:17]
	v_lshl_add_u64 v[6:7], v[2:3], 0, v[172:173]
	s_mov_b32 s2, m0
	s_mov_b32 m0, s35
	s_nop 0
	global_load_lds_dwordx4 v[6:7], off
	s_mov_b32 m0, s2
	v_lshl_add_u64 v[6:7], v[4:5], 0, v[172:173]
	s_mov_b32 s2, m0
	s_mov_b32 m0, s36
	s_nop 0
	global_load_lds_dwordx4 v[6:7], off
	s_mov_b32 m0, s2
	v_lshl_add_u64 v[6:7], v[2:3], 0, v[174:175]
	s_mov_b32 s2, m0
	s_mov_b32 m0, s37
	s_nop 0
	global_load_lds_dwordx4 v[6:7], off
	s_mov_b32 m0, s2
	v_lshl_add_u64 v[6:7], v[4:5], 0, v[174:175]
	s_mov_b32 s2, m0
	s_mov_b32 m0, s38
	s_nop 0
	global_load_lds_dwordx4 v[6:7], off
	s_mov_b32 m0, s2
	v_lshl_add_u64 v[6:7], v[2:3], 0, v[176:177]
	s_mov_b32 s2, m0
	s_mov_b32 m0, s39
	s_nop 0
	global_load_lds_dwordx4 v[6:7], off
	s_mov_b32 m0, s2
	v_lshl_add_u64 v[6:7], v[4:5], 0, v[176:177]
	s_mov_b32 s2, m0
	s_mov_b32 m0, s40
	s_nop 0
	global_load_lds_dwordx4 v[6:7], off
	s_mov_b32 m0, s2
	v_lshl_add_u64 v[2:3], v[2:3], 0, v[178:179]
	s_mov_b32 s2, m0
	s_mov_b32 m0, s41
	s_nop 0
	global_load_lds_dwordx4 v[2:3], off
	s_mov_b32 m0, s2
	v_lshl_add_u64 v[2:3], v[4:5], 0, v[178:179]
	s_mov_b32 s2, m0
	s_mov_b32 m0, s42
	s_nop 0
	global_load_lds_dwordx4 v[2:3], off
	s_mov_b32 m0, s2
	s_or_b32 s2, s21, 0x100
	s_mul_hi_i32 s3, s2, 0x1400
	s_mulk_i32 s2, 0x1400
	s_add_u32 s2, s58, s2
	s_addc_u32 s3, s59, s3
	s_add_u32 s2, s2, s0
	s_addc_u32 s3, s3, s1
	v_lshl_add_u64 v[2:3], s[2:3], 0, v[168:169]
	v_lshl_add_u64 v[2:3], v[2:3], 0, s[14:15]
	v_lshl_add_u64 v[4:5], s[2:3], 0, v[170:171]
	v_lshl_add_u64 v[4:5], v[4:5], 0, s[16:17]
	v_lshl_add_u64 v[6:7], v[2:3], 0, v[172:173]
	s_mov_b32 s2, m0
	s_mov_b32 m0, s43
	s_nop 0
	global_load_lds_dwordx4 v[6:7], off
	s_mov_b32 m0, s2
	v_lshl_add_u64 v[6:7], v[4:5], 0, v[172:173]
	s_mov_b32 s2, m0
	s_mov_b32 m0, s44
	s_nop 0
	global_load_lds_dwordx4 v[6:7], off
	s_mov_b32 m0, s2
	v_lshl_add_u64 v[6:7], v[2:3], 0, v[174:175]
	s_mov_b32 s2, m0
	s_mov_b32 m0, s45
	s_nop 0
	global_load_lds_dwordx4 v[6:7], off
	s_mov_b32 m0, s2
	v_lshl_add_u64 v[6:7], v[4:5], 0, v[174:175]
	s_mov_b32 s2, m0
	s_mov_b32 m0, s46
	s_nop 0
	global_load_lds_dwordx4 v[6:7], off
	s_mov_b32 m0, s2
	v_lshl_add_u64 v[6:7], v[2:3], 0, v[176:177]
	s_mov_b32 s2, m0
	s_mov_b32 m0, s47
	s_nop 0
	global_load_lds_dwordx4 v[6:7], off
	s_mov_b32 m0, s2
	v_lshl_add_u64 v[6:7], v[4:5], 0, v[176:177]
	s_mov_b32 s2, m0
	s_mov_b32 m0, s48
	s_nop 0
	global_load_lds_dwordx4 v[6:7], off
	s_mov_b32 m0, s2
	v_lshl_add_u64 v[2:3], v[2:3], 0, v[178:179]
	s_mov_b32 s2, m0
	s_mov_b32 m0, s49
	s_nop 0
	global_load_lds_dwordx4 v[2:3], off
	s_mov_b32 m0, s2
	v_lshl_add_u64 v[2:3], v[4:5], 0, v[178:179]
	s_mov_b32 s2, m0
	s_mov_b32 m0, s50
	s_nop 0
	global_load_lds_dwordx4 v[2:3], off
	s_mov_b32 m0, s2
	s_add_u32 s2, s58, s0
	v_add_u32_e32 v186, s54, v198
	s_addc_u32 s3, s59, s1
	v_add_u32_e32 v188, s53, v186
	v_mov_b64_e32 v[10:11], s[2:3]
	v_mad_i64_i32 v[2:3], s[0:1], v188, s29, v[10:11]
	v_lshl_add_u64 v[6:7], v[2:3], 0, v[162:163]
	s_waitcnt vmcnt(0)
	s_barrier
	global_load_dwordx4 v[2:5], v[6:7], off
	s_nop 0
	global_load_dwordx4 v[6:9], v[6:7], off offset:64
	v_or_b32_e32 v192, 16, v186
	v_add_u32_e32 v190, s53, v192
	v_mad_i64_i32 v[10:11], s[0:1], v190, s29, v[10:11]
	v_lshl_add_u64 v[14:15], v[10:11], 0, v[162:163]
	global_load_dwordx4 v[10:13], v[14:15], off
	v_ashrrev_i32_e32 v189, 31, v188
	global_load_dwordx4 v[14:17], v[14:15], off offset:64
	ds_read_b128 v[118:121], v209 offset:2048
	ds_read_b128 v[122:125], v209
	ds_read_b128 v[126:129], v207 offset:2048
	ds_read_b128 v[114:117], v207
	v_ashrrev_i32_e32 v191, 31, v190
	s_mov_b32 s21, 0
	s_mov_b32 s24, 0
	s_mov_b32 s25, 0
	v_mov_b32_e32 v82, 0
	v_mov_b32_e32 v83, v163
	v_mov_b32_e32 v84, v163
	v_mov_b32_e32 v85, v163
	v_mov_b32_e32 v32, v163
	v_mov_b32_e32 v33, v163
	v_mov_b32_e32 v94, 0
	v_mov_b32_e32 v95, v163
	v_mov_b32_e32 v96, v163
	v_mov_b32_e32 v97, v163
	s_waitcnt vmcnt(3)
	v_cvt_f32_f16_e32 v18, v2
	v_cvt_f32_f16_sdwa v19, v2 dst_sel:DWORD dst_unused:UNUSED_PAD src0_sel:WORD_1
	s_waitcnt vmcnt(2)
; __device__ __forceinline__ unsigned pkh(float lo, float hi) { f32x2 v = {lo, hi}; h16x2 h = __builtin_convertvector(v, h16x2); return __builtin_bit_cast(unsigned, h); }
; __device__ __forceinline__ void moba_load_q(const f16_t* qrow, int G, float maxgk, h16x8& q0, h16x8& q1, float& mb) {
;     const h16x8 r0v = *(const h16x8*)(qrow + 8 * G), r1v = *(const h16x8*)(qrow + 32 + 8 * G);
;     float q[16], n2 = 0.f;
; #pragma unroll
;     for (int j = 0; j < 8; ++j) { q[j] = (float)r0v[j]; q[8 + j] = (float)r1v[j]; n2 += q[j] * q[j] + q[8 + j] * q[8 + j]; }
;     n2 += __shfl_xor(n2, 16); n2 += __shfl_xor(n2, 32);
;     mb = (sqrtf(n2) * maxgk - BOUND_SHIFT) * LOG2E;
;     const float c = 0.125f * LOG2E;
;     u32x4 w0, w1;
;     w0.x = pkh(q[0] * c, q[1] * c); w0.y = pkh(q[2] * c, q[3] * c); w0.z = pkh(q[4] * c, q[5] * c); w0.w = pkh(q[6] * c, q[7] * c);
;     w1.x = pkh(q[8] * c, q[9] * c); w1.y = pkh(q[10] * c, q[11] * c); w1.z = pkh(q[12] * c, q[13] * c); w1.w = pkh(q[14] * c, q[15] * c);
;     q0 = __builtin_bit_cast(h16x8, w0); q1 = __builtin_bit_cast(h16x8, w1);
; }
	v_cvt_f32_f16_e32 v22, v6
	v_cvt_f32_f16_sdwa v23, v6 dst_sel:DWORD dst_unused:UNUSED_PAD src0_sel:WORD_1
	v_cvt_f32_f16_e32 v6, v7
	v_cvt_f32_f16_sdwa v7, v7 dst_sel:DWORD dst_unused:UNUSED_PAD src0_sel:WORD_1
	v_cvt_f32_f16_e32 v2, v3
	v_cvt_f32_f16_sdwa v3, v3 dst_sel:DWORD dst_unused:UNUSED_PAD src0_sel:WORD_1
	v_pk_mul_f32 v[24:25], v[18:19], s[18:19] op_sel_hi:[1,0]
	v_cvt_f32_f16_e32 v20, v4
	v_cvt_pk_f16_f32 v86, v24, v25
	v_cvt_f32_f16_e32 v24, v8
	v_cvt_f32_f16_sdwa v25, v8 dst_sel:DWORD dst_unused:UNUSED_PAD src0_sel:WORD_1
	v_cvt_f32_f16_sdwa v21, v4 dst_sel:DWORD dst_unused:UNUSED_PAD src0_sel:WORD_1
	v_pk_mul_f32 v[28:29], v[22:23], v[22:23]
	v_pk_mul_f32 v[30:31], v[6:7], v[6:7]
	v_pk_fma_f32 v[18:19], v[18:19], v[18:19], v[28:29]
	v_cvt_f32_f16_e32 v8, v9
	v_cvt_f32_f16_sdwa v9, v9 dst_sel:DWORD dst_unused:UNUSED_PAD src0_sel:WORD_1
	v_cvt_f32_f16_e32 v4, v5
	v_cvt_f32_f16_sdwa v5, v5 dst_sel:DWORD dst_unused:UNUSED_PAD src0_sel:WORD_1
	v_pk_mul_f32 v[26:27], v[2:3], s[18:19] op_sel_hi:[1,0]
	v_pk_fma_f32 v[2:3], v[2:3], v[2:3], v[30:31]
	v_add_f32_e32 v18, v18, v19
	v_pk_mul_f32 v[28:29], v[24:25], v[24:25]
	v_add_f32_e32 v2, v2, v18
	v_pk_fma_f32 v[28:29], v[20:21], v[20:21], v[28:29]
	v_add_f32_e32 v2, v3, v2
	v_pk_mul_f32 v[30:31], v[8:9], v[8:9]
	v_add_f32_e32 v2, v28, v2
	v_pk_fma_f32 v[30:31], v[4:5], v[4:5], v[30:31]
	v_add_f32_e32 v2, v29, v2
	v_add_f32_e32 v2, v30, v2
	v_add_f32_e32 v18, v31, v2
	ds_bpermute_b32 v19, v1, v18
	v_pk_mul_f32 v[2:3], v[20:21], s[18:19] op_sel_hi:[1,0]
	s_waitcnt vmcnt(0)
	v_cvt_f32_f16_e32 v20, v16
	v_cvt_pk_f16_f32 v88, v2, v3
	v_pk_mul_f32 v[2:3], v[4:5], s[18:19] op_sel_hi:[1,0]
	s_waitcnt lgkmcnt(0)
	v_add_f32_e32 v4, v18, v19
	v_mov_b32_e32 v5, v4
	s_nop 1
	v_permlane32_swap_b32_e32 v4, v5
	v_cvt_pk_f16_f32 v89, v2, v3
	v_pk_mul_f32 v[2:3], v[22:23], s[18:19] op_sel_hi:[1,0]
	v_cvt_f32_f16_e32 v18, v14
	v_cvt_pk_f16_f32 v90, v2, v3
	s_waitcnt lgkmcnt(0)
	v_add_f32_e32 v4, v4, v5
	v_mul_f32_e32 v5, 0x4f800000, v4
	v_cmp_gt_f32_e32 vcc, s31, v4
	v_pk_mul_f32 v[2:3], v[6:7], s[18:19] op_sel_hi:[1,0]
	v_cvt_f32_f16_sdwa v19, v14 dst_sel:DWORD dst_unused:UNUSED_PAD src0_sel:WORD_1
	v_cndmask_b32_e32 v4, v4, v5, vcc
	v_sqrt_f32_e32 v5, v4
	v_cvt_pk_f16_f32 v91, v2, v3
	v_pk_mul_f32 v[2:3], v[24:25], s[18:19] op_sel_hi:[1,0]
	v_cvt_f32_f16_e32 v14, v15
	v_cvt_pk_f16_f32 v92, v2, v3
	v_add_u32_e32 v2, -1, v5
	v_fma_f32 v3, -v2, v5, v4
	v_cmp_ge_f32_e64 s[0:1], 0, v3
	v_add_u32_e32 v3, 1, v5
	v_cvt_f32_f16_sdwa v15, v15 dst_sel:DWORD dst_unused:UNUSED_PAD src0_sel:WORD_1
	v_cndmask_b32_e64 v2, v5, v2, s[0:1]
	v_fma_f32 v5, -v3, v5, v4
	v_cmp_lt_f32_e64 s[0:1], 0, v5
	v_cvt_f32_f16_sdwa v5, v11 dst_sel:DWORD dst_unused:UNUSED_PAD src0_sel:WORD_1
	v_cvt_f32_f16_sdwa v21, v16 dst_sel:DWORD dst_unused:UNUSED_PAD src0_sel:WORD_1
	v_cndmask_b32_e64 v2, v2, v3, s[0:1]
	v_mul_f32_e32 v3, 0x37800000, v2
	v_cndmask_b32_e32 v2, v2, v3, vcc
	v_cmp_class_f32_e32 vcc, v4, v219
	v_cvt_f32_f16_e32 v16, v17
	v_cvt_f32_f16_sdwa v17, v17 dst_sel:DWORD dst_unused:UNUSED_PAD src0_sel:WORD_1
	v_cndmask_b32_e32 v2, v2, v4, vcc
	v_fma_f32 v24, v197, v2, -4.0
	v_pk_mul_f32 v[2:3], v[8:9], s[18:19] op_sel_hi:[1,0]
	v_cvt_f32_f16_e32 v4, v11
	v_cvt_pk_f16_f32 v93, v2, v3
	v_cvt_f32_f16_e32 v2, v10
	v_cvt_f32_f16_sdwa v3, v10 dst_sel:DWORD dst_unused:UNUSED_PAD src0_sel:WORD_1
	v_cvt_f32_f16_e32 v8, v12
	v_cvt_f32_f16_sdwa v9, v12 dst_sel:DWORD dst_unused:UNUSED_PAD src0_sel:WORD_1
	v_cvt_f32_f16_e32 v10, v13
	v_cvt_f32_f16_sdwa v11, v13 dst_sel:DWORD dst_unused:UNUSED_PAD src0_sel:WORD_1
	v_pk_mul_f32 v[12:13], v[18:19], v[18:19]
	v_pk_mul_f32 v[6:7], v[2:3], s[18:19] op_sel_hi:[1,0]
	v_pk_fma_f32 v[2:3], v[2:3], v[2:3], v[12:13]
	v_pk_mul_f32 v[12:13], v[14:15], v[14:15]
	v_cvt_pk_f16_f32 v98, v6, v7
	v_pk_mul_f32 v[6:7], v[4:5], s[18:19] op_sel_hi:[1,0]
	v_pk_fma_f32 v[4:5], v[4:5], v[4:5], v[12:13]
	v_add_f32_e32 v2, v2, v3
	v_pk_mul_f32 v[12:13], v[20:21], v[20:21]
	v_add_f32_e32 v2, v4, v2
	v_pk_fma_f32 v[12:13], v[8:9], v[8:9], v[12:13]
	v_add_f32_e32 v2, v5, v2
	v_pk_mul_f32 v[22:23], v[16:17], v[16:17]
	v_add_f32_e32 v2, v12, v2
	v_pk_fma_f32 v[22:23], v[10:11], v[10:11], v[22:23]
	v_add_f32_e32 v2, v13, v2
	v_add_f32_e32 v2, v22, v2
	v_add_f32_e32 v4, v23, v2
	ds_bpermute_b32 v5, v1, v4
	v_pk_mul_f32 v[2:3], v[8:9], s[18:19] op_sel_hi:[1,0]
	v_mul_f32_e32 v106, 0xbfb8aa3b, v24
	v_cvt_pk_f16_f32 v100, v2, v3
	v_pk_mul_f32 v[2:3], v[10:11], s[18:19] op_sel_hi:[1,0]
	s_waitcnt lgkmcnt(0)
	v_add_f32_e32 v4, v4, v5
	v_mov_b32_e32 v5, v4
	s_nop 1
	v_permlane32_swap_b32_e32 v4, v5
	v_cvt_pk_f16_f32 v101, v2, v3
	v_pk_mul_f32 v[2:3], v[18:19], s[18:19] op_sel_hi:[1,0]
	v_cvt_pk_f16_f32 v87, v26, v27
	v_cvt_pk_f16_f32 v102, v2, v3
	s_waitcnt lgkmcnt(0)
	v_add_f32_e32 v4, v4, v5
	v_mul_f32_e32 v5, 0x4f800000, v4
	v_cmp_gt_f32_e32 vcc, s31, v4
	v_pk_mul_f32 v[2:3], v[14:15], s[18:19] op_sel_hi:[1,0]
	v_cvt_pk_f16_f32 v99, v6, v7
	v_cndmask_b32_e32 v4, v4, v5, vcc
	v_sqrt_f32_e32 v5, v4
	v_cvt_pk_f16_f32 v103, v2, v3
	v_pk_mul_f32 v[2:3], v[20:21], s[18:19] op_sel_hi:[1,0]
	v_mov_b32_e32 v107, v106
	v_cvt_pk_f16_f32 v104, v2, v3
	v_add_u32_e32 v2, -1, v5
	v_fma_f32 v3, -v2, v5, v4
	v_cmp_ge_f32_e64 s[0:1], 0, v3
	v_add_u32_e32 v3, 1, v5
	v_mov_b32_e32 v108, v106
	v_cndmask_b32_e64 v2, v5, v2, s[0:1]
	v_fma_f32 v5, -v3, v5, v4
	v_cmp_lt_f32_e64 s[0:1], 0, v5
	v_mov_b32_e32 v109, v106
	v_mov_b32_e32 v5, v163
	v_cndmask_b32_e64 v2, v2, v3, s[0:1]
	v_mul_f32_e32 v3, 0x37800000, v2
	v_cndmask_b32_e32 v2, v2, v3, vcc
	v_cmp_class_f32_e32 vcc, v4, v219
	v_mov_b32_e32 v14, 0
	v_mov_b32_e32 v15, v163
	v_cndmask_b32_e32 v2, v2, v4, vcc
	v_fma_f32 v4, v197, v2, -4.0
	v_pk_mul_f32 v[2:3], v[16:17], s[18:19] op_sel_hi:[1,0]
	v_mul_f32_e32 v110, 0xbfb8aa3b, v4
	v_cvt_pk_f16_f32 v105, v2, v3
	v_mov_b32_e32 v111, v110
	v_mov_b32_e32 v112, v110
	v_mov_b32_e32 v113, v110
	v_mov_b32_e32 v2, 0
	v_mov_b32_e32 v3, v163
	v_mov_b32_e32 v4, v163
	v_mov_b32_e32 v16, v163
	v_mov_b32_e32 v17, v163
	v_mov_b32_e32 v10, 0
	v_mov_b32_e32 v11, v163
	v_mov_b32_e32 v12, v163
	v_mov_b32_e32 v13, v163
	v_mov_b32_e32 v6, 0
	v_mov_b32_e32 v7, v163
	v_mov_b32_e32 v8, v163
	v_mov_b32_e32 v9, v163
	v_mov_b32_e32 v18, 0
	v_mov_b32_e32 v19, v163
	v_mov_b32_e32 v20, v163
	v_mov_b32_e32 v21, v163
	v_mov_b32_e32 v26, 0
	v_mov_b32_e32 v27, v163
	v_mov_b32_e32 v28, v163
	v_mov_b32_e32 v29, v163
	v_mov_b32_e32 v22, 0
	v_mov_b32_e32 v23, v163
	v_mov_b32_e32 v24, v163
	v_mov_b32_e32 v25, v163
	v_mov_b32_e32 v30, 0
	v_mov_b32_e32 v31, v163
	s_branch .LBB0_1226

; __device__ __forceinline__ unsigned pk8(float a, float b, float c, float d) { int w = __builtin_amdgcn_cvt_pk_fp8_f32(a, b, 0, false); w = __builtin_amdgcn_cvt_pk_fp8_f32(c, d, w, true); return (unsigned)w; }
; __device__ __forceinline__ int pair16_dim(int G, int dt0) { return (G & 1) ? 16 * (dt0 + 1) + 4 * (G - 1) : 16 * dt0 + 4 * G; }
; __device__ __forceinline__ void store_o8(unsigned char* rowp, const f32x4 (&o)[4], float il, int G) {
;     const float c = il * F8_SY;
; #pragma unroll
;     for (int pr = 0; pr < 2; ++pr) { const int dt0 = 2 * pr;
;         const unsigned a = pk8(o[dt0][0] * c, o[dt0][1] * c, o[dt0][2] * c, o[dt0][3] * c), b = pk8(o[dt0 + 1][0] * c, o[dt0 + 1][1] * c, o[dt0 + 1][2] * c, o[dt0 + 1][3] * c);
;         const auto r = __builtin_amdgcn_permlane16_swap(a, b, false, false);
;         *(u32x2*)(rowp + pair16_dim(G, dt0)) = (u32x2){r[0], r[1]}; }
; }
; __device__ __forceinline__ void moba_load_q(const f16_t* qrow, int G, float maxgk, h16x8& q0, h16x8& q1, float& mb) {
;     const h16x8 r0v = *(const h16x8*)(qrow + 8 * G), r1v = *(const h16x8*)(qrow + 32 + 8 * G);
;     float q[16], n2 = 0.f;
; #pragma unroll
;     for (int j = 0; j < 8; ++j) { q[j] = (float)r0v[j]; q[8 + j] = (float)r1v[j]; n2 += q[j] * q[j] + q[8 + j] * q[8 + j]; }
;     n2 += __shfl_xor(n2, 16); n2 += __shfl_xor(n2, 32);
;     mb = (sqrtf(n2) * maxgk - BOUND_SHIFT) * LOG2E;
.LBB0_1240:
	s_nop 0
	v_div_scale_f32 v32, s[24:25], v30, v30, 1.0
	v_rcp_f32_e32 v33, v32
	v_lshl_add_u64 v[186:187], v[164:165], 0, s[22:23]
	v_add_u32_e32 v192, s54, v200
	v_or_b32_e32 v194, 16, v192
	v_fma_f32 v86, -v32, v33, 1.0
	v_fmac_f32_e32 v33, v86, v33
	v_div_scale_f32 v86, vcc, 1.0, v30, 1.0
	v_mul_f32_e32 v87, v86, v33
	v_fma_f32 v88, -v32, v87, v86
	v_fmac_f32_e32 v87, v88, v33
	v_fma_f32 v32, -v32, v87, v86
	v_div_scale_f32 v86, s[22:23], v31, v31, 1.0
	v_rcp_f32_e32 v88, v86
	v_div_fmas_f32 v32, v32, v33, v87
	v_div_fixup_f32 v30, v32, v30, 1.0
	v_mul_f32_e32 v30, 0x42000000, v30
	v_fma_f32 v32, -v86, v88, 1.0
	v_fmac_f32_e32 v88, v32, v88
	v_div_scale_f32 v32, vcc, 1.0, v31, 1.0
	v_mul_f32_e32 v33, v32, v88
	v_fma_f32 v87, -v86, v33, v32
	v_fmac_f32_e32 v33, v87, v88
	v_fma_f32 v32, -v86, v33, v32
	v_div_fmas_f32 v86, v32, v88, v33
	v_mul_f32_e32 v33, v30, v82
	v_mul_f32_e32 v82, v30, v83
	v_mov_b32_e32 v32, 0
	v_cvt_pk_fp8_f32 v32, v33, v82
	v_mul_f32_e32 v26, v30, v26
	v_mul_f32_e32 v27, v30, v27
	v_mov_b32_e32 v33, 0
	v_cvt_pk_fp8_f32 v33, v26, v27
	v_mul_f32_e32 v27, v30, v29
	v_mul_f32_e32 v29, v30, v22
	v_mul_f32_e32 v23, v30, v23
	v_mov_b32_e32 v22, 0
	v_mul_f32_e32 v26, v30, v28
	v_div_fixup_f32 v28, v86, v31, 1.0
	v_cvt_pk_fp8_f32 v22, v29, v23
	v_mul_f32_e32 v18, v30, v18
	v_mul_f32_e32 v19, v30, v19
	v_mov_b32_e32 v23, 0
	v_cvt_pk_fp8_f32 v23, v18, v19
	v_mul_f32_e32 v18, v30, v20
	v_mul_f32_e32 v20, 0x42000000, v28
	v_mul_f32_e32 v19, v30, v21
	v_mul_f32_e32 v21, v20, v14
	v_mul_f32_e32 v15, v20, v15
	v_mov_b32_e32 v14, 0
	v_cvt_pk_fp8_f32 v14, v21, v15
	v_mul_f32_e32 v10, v20, v10
	v_mul_f32_e32 v11, v20, v11
	v_mov_b32_e32 v15, 0
	v_cvt_pk_fp8_f32 v15, v10, v11
	v_mul_f32_e32 v10, v20, v12
	v_mul_f32_e32 v12, v20, v6
	v_mul_f32_e32 v7, v20, v7
	v_mov_b32_e32 v6, 0
	v_cvt_pk_fp8_f32 v6, v12, v7
	v_mul_f32_e32 v2, v20, v2
	v_mul_f32_e32 v3, v20, v3
	v_mov_b32_e32 v7, 0
	v_cvt_pk_fp8_f32 v7, v2, v3
	v_mul_f32_e32 v16, v20, v16
	v_mul_f32_e32 v17, v20, v17
	v_mul_f32_e32 v11, v20, v13
	v_mul_f32_e32 v8, v20, v8
	v_mul_f32_e32 v9, v20, v9
	v_mul_f32_e32 v2, v20, v4
	v_mul_f32_e32 v3, v20, v5
	v_mul_f32_e32 v83, v30, v84
	v_mul_f32_e32 v84, v30, v85
	v_mul_f32_e32 v24, v30, v24
	v_mul_f32_e32 v25, v30, v25
	v_cvt_pk_fp8_f32 v14, v16, v17 op_sel:[0,0,1]
	v_cvt_pk_fp8_f32 v15, v10, v11 op_sel:[0,0,1]
	v_cvt_pk_fp8_f32 v6, v8, v9 op_sel:[0,0,1]
	v_cvt_pk_fp8_f32 v7, v2, v3 op_sel:[0,0,1]
	v_cvt_pk_fp8_f32 v32, v83, v84 op_sel:[0,0,1]
	v_cvt_pk_fp8_f32 v33, v26, v27 op_sel:[0,0,1]
	v_cvt_pk_fp8_f32 v22, v24, v25 op_sel:[0,0,1]
	v_cvt_pk_fp8_f32 v23, v18, v19 op_sel:[0,0,1]
	v_lshlrev_b64 v[10:11], 10, v[190:191]
	v_lshlrev_b64 v[26:27], 10, v[188:189]
	v_permlane16_swap_b32_e32 v14, v15
	v_lshl_add_u64 v[2:3], v[186:187], 0, v[10:11]
	v_permlane16_swap_b32_e32 v6, v7
	v_add_u32_e32 v188, s53, v192
	v_mov_b64_e32 v[10:11], s[2:3]
	v_permlane16_swap_b32_e32 v32, v33
	v_lshl_add_u64 v[18:19], v[186:187], 0, v[26:27]
	v_permlane16_swap_b32_e32 v22, v23
	global_store_dwordx2 v[2:3], v[14:15], off
	global_store_dwordx2 v[2:3], v[6:7], off offset:32
	v_mad_i64_i32 v[2:3], s[2:3], v188, s29, v[10:11]
	global_store_dwordx2 v[18:19], v[32:33], off
	global_store_dwordx2 v[18:19], v[22:23], off offset:32
	v_lshl_add_u64 v[6:7], v[2:3], 0, v[162:163]
	global_load_dwordx4 v[2:5], v[6:7], off
	s_nop 0
	global_load_dwordx4 v[6:9], v[6:7], off offset:64
	v_add_u32_e32 v190, s53, v194
	v_mad_i64_i32 v[10:11], s[2:3], v190, s29, v[10:11]
	v_lshl_add_u64 v[10:11], v[10:11], 0, v[162:163]
	global_load_dwordx4 v[16:19], v[10:11], off
	global_load_dwordx4 v[82:85], v[10:11], off offset:64
	s_andn2_b64 vcc, exec, s[12:13]
	s_mov_b32 s22, 0
	s_waitcnt vmcnt(3)
	v_cvt_f32_f16_e32 v32, v2
	s_waitcnt vmcnt(2)
	v_cvt_f32_f16_e32 v24, v6
	v_cvt_f32_f16_sdwa v25, v6 dst_sel:DWORD dst_unused:UNUSED_PAD src0_sel:WORD_1
	v_cvt_f32_f16_sdwa v33, v2 dst_sel:DWORD dst_unused:UNUSED_PAD src0_sel:WORD_1
	v_cvt_f32_f16_e32 v22, v7
	v_cvt_f32_f16_sdwa v23, v7 dst_sel:DWORD dst_unused:UNUSED_PAD src0_sel:WORD_1
	v_cvt_f32_f16_e32 v30, v3
	v_cvt_f32_f16_sdwa v31, v3 dst_sel:DWORD dst_unused:UNUSED_PAD src0_sel:WORD_1
	v_cvt_f32_f16_e32 v14, v8
	v_cvt_f32_f16_sdwa v15, v8 dst_sel:DWORD dst_unused:UNUSED_PAD src0_sel:WORD_1
	v_cvt_f32_f16_e32 v28, v4
	v_cvt_f32_f16_sdwa v29, v4 dst_sel:DWORD dst_unused:UNUSED_PAD src0_sel:WORD_1
	v_pk_mul_f32 v[2:3], v[24:25], v[24:25]
	v_cvt_f32_f16_e32 v26, v5
	v_cvt_f32_f16_sdwa v27, v5 dst_sel:DWORD dst_unused:UNUSED_PAD src0_sel:WORD_1
	v_pk_fma_f32 v[4:5], v[32:33], v[32:33], v[2:3]
	v_pk_mul_f32 v[6:7], v[22:23], v[22:23]
	v_cvt_f32_f16_e32 v2, v9
	v_cvt_f32_f16_sdwa v3, v9 dst_sel:DWORD dst_unused:UNUSED_PAD src0_sel:WORD_1
	v_pk_fma_f32 v[6:7], v[30:31], v[30:31], v[6:7]
	v_add_f32_e32 v4, v4, v5
	v_pk_mul_f32 v[8:9], v[14:15], v[14:15]
	v_add_f32_e32 v4, v6, v4
	v_pk_fma_f32 v[8:9], v[28:29], v[28:29], v[8:9]
	v_add_f32_e32 v4, v7, v4
	v_pk_mul_f32 v[10:11], v[2:3], v[2:3]
	v_add_f32_e32 v4, v8, v4
	v_pk_fma_f32 v[10:11], v[26:27], v[26:27], v[10:11]
	v_add_f32_e32 v4, v9, v4
	v_add_f32_e32 v4, v10, v4
	v_add_f32_e32 v90, v11, v4
	s_waitcnt vmcnt(0)
	v_cvt_f32_f16_e32 v10, v82
	v_cvt_f32_f16_sdwa v11, v82 dst_sel:DWORD dst_unused:UNUSED_PAD src0_sel:WORD_1
	v_cvt_f32_f16_e32 v6, v16
	v_cvt_f32_f16_sdwa v7, v16 dst_sel:DWORD dst_unused:UNUSED_PAD src0_sel:WORD_1
	v_cvt_f32_f16_e32 v20, v83
	v_cvt_f32_f16_sdwa v21, v83 dst_sel:DWORD dst_unused:UNUSED_PAD src0_sel:WORD_1
	v_cvt_f32_f16_e32 v8, v17
	v_cvt_f32_f16_sdwa v9, v17 dst_sel:DWORD dst_unused:UNUSED_PAD src0_sel:WORD_1
	v_cvt_f32_f16_e32 v16, v84
	v_cvt_f32_f16_sdwa v17, v84 dst_sel:DWORD dst_unused:UNUSED_PAD src0_sel:WORD_1
	v_cvt_f32_f16_e32 v12, v18
	v_cvt_f32_f16_sdwa v13, v18 dst_sel:DWORD dst_unused:UNUSED_PAD src0_sel:WORD_1
	v_pk_mul_f32 v[4:5], v[10:11], v[10:11]
	v_pk_mul_f32 v[86:87], v[20:21], v[20:21]
	v_pk_fma_f32 v[82:83], v[6:7], v[6:7], v[4:5]
	v_cvt_f32_f16_e32 v4, v85
	v_cvt_f32_f16_sdwa v5, v85 dst_sel:DWORD dst_unused:UNUSED_PAD src0_sel:WORD_1
	v_cvt_f32_f16_e32 v18, v19
	v_cvt_f32_f16_sdwa v19, v19 dst_sel:DWORD dst_unused:UNUSED_PAD src0_sel:WORD_1
	v_pk_fma_f32 v[84:85], v[8:9], v[8:9], v[86:87]
	v_add_f32_e32 v82, v82, v83
	v_pk_mul_f32 v[86:87], v[16:17], v[16:17]
	v_add_f32_e32 v82, v84, v82
	v_pk_fma_f32 v[86:87], v[12:13], v[12:13], v[86:87]
	v_add_f32_e32 v82, v85, v82
	v_pk_mul_f32 v[88:89], v[4:5], v[4:5]
	v_add_f32_e32 v82, v86, v82
	v_pk_fma_f32 v[88:89], v[18:19], v[18:19], v[88:89]
	v_add_f32_e32 v82, v87, v82
	v_add_f32_e32 v82, v88, v82
	v_add_f32_e32 v82, v89, v82
	v_mov_b32_e32 v91, v90
	s_nop 1
	v_permlane16_swap_b32_e32 v90, v91
	ds_bpermute_b32 v83, v1, v82
	s_waitcnt lgkmcnt(1)
	v_add_f32_e32 v84, v90, v91
	s_waitcnt lgkmcnt(0)
	v_add_f32_e32 v82, v82, v83
	v_mov_b32_e32 v85, v84
	s_nop 1
	v_permlane32_swap_b32_e32 v84, v85
	v_mov_b32_e32 v83, v82
	s_nop 1
	v_permlane32_swap_b32_e32 v82, v83
	s_cbranch_vccnz .LBB0_1245
; #define LAS __attribute__((address_space(3)))
; __device__ __forceinline__ unsigned pkh(float lo, float hi) { f32x2 v = {lo, hi}; h16x2 h = __builtin_convertvector(v, h16x2); return __builtin_bit_cast(unsigned, h); }
; template <bool CAUSAL, bool SHARED> ...
;     ...
;     const int kof0 = fr * 128 + (((0 + G) ^ (fr & 7)) << 4), kof1 = fr * 128 + (((4 + G) ^ (fr & 7)) << 4);
;     const int vrow = (4 * G + qq) * 128 + p * 8, sw = (2 * G + (qq >> 1)) & 3;
;     const h16x8 ones = {(_Float16)1.0f, (_Float16)1.0f, (_Float16)1.0f, (_Float16)1.0f, (_Float16)1.0f, (_Float16)1.0f, (_Float16)1.0f, (_Float16)1.0f};
;     const f32x4 nma = {-mba, -mba, -mba, -mba}, nmb = {-mbb, -mbb, -mbb, -mbb};
;     f32x4 la = {0.f, 0.f, 0.f, 0.f}, lb = la;
;     h16x8 ka[4], kb[4];
;     ka[0] = *(LAS const h16x8*)(Ka + kof0); ka[1] = *(LAS const h16x8*)(Ka + kof1); ka[2] = *(LAS const h16x8*)(Ka + 2048 + kof0); ka[3] = *(LAS const h16x8*)(Ka + 2048 + kof1);
;     if (!SHARED) { kb[0] = *(LAS const h16x8*)(Kb + kof0); kb[1] = *(LAS const h16x8*)(Kb + kof1); kb[2] = *(LAS const h16x8*)(Kb + 2048 + kof0); kb[3] = *(LAS const h16x8*)(Kb + 2048 + kof1); }
; __device__ __forceinline__ void moba_load_q(const f16_t* qrow, int G, float maxgk, h16x8& q0, h16x8& q1, float& mb) {
;     ...
;     mb = (sqrtf(n2) * maxgk - BOUND_SHIFT) * LOG2E;
;     const float c = 0.125f * LOG2E;
;     u32x4 w0, w1;
;     w0.x = pkh(q[0] * c, q[1] * c); w0.y = pkh(q[2] * c, q[3] * c); w0.z = pkh(q[4] * c, q[5] * c); w0.w = pkh(q[6] * c, q[7] * c);
;     w1.x = pkh(q[8] * c, q[9] * c); w1.y = pkh(q[10] * c, q[11] * c); w1.z = pkh(q[12] * c, q[13] * c); w1.w = pkh(q[14] * c, q[15] * c);
;     q0 = __builtin_bit_cast(h16x8, w0); q1 = __builtin_bit_cast(h16x8, w1);
; }
	v_pk_mul_f32 v[24:25], v[24:25], s[18:19] op_sel_hi:[1,0]
	v_pk_mul_f32 v[14:15], v[14:15], s[18:19] op_sel_hi:[1,0]
	v_cvt_pk_f16_f32 v90, v24, v25
	s_waitcnt lgkmcnt(1)
	v_add_f32_e32 v24, v84, v85
	v_mul_f32_e32 v25, 0x4f800000, v24
	v_cmp_gt_f32_e32 vcc, s31, v24
	v_pk_mul_f32 v[22:23], v[22:23], s[18:19] op_sel_hi:[1,0]
	v_cvt_pk_f16_f32 v92, v14, v15
	v_cndmask_b32_e32 v24, v24, v25, vcc
	v_sqrt_f32_e32 v25, v24
	v_cvt_pk_f16_f32 v91, v22, v23
	v_pk_mul_f32 v[2:3], v[2:3], s[18:19] op_sel_hi:[1,0]
	v_pk_mul_f32 v[32:33], v[32:33], s[18:19] op_sel_hi:[1,0]
	v_add_u32_e32 v15, -1, v25
	v_fma_f32 v22, -v15, v25, v24
	v_cmp_ge_f32_e64 s[2:3], 0, v22
	v_add_u32_e32 v22, 1, v25
	v_fma_f32 v23, -v22, v25, v24
	v_cndmask_b32_e64 v15, v25, v15, s[2:3]
	v_cmp_lt_f32_e64 s[2:3], 0, v23
	v_cvt_pk_f16_f32 v93, v2, v3
	v_pk_mul_f32 v[2:3], v[6:7], s[18:19] op_sel_hi:[1,0]
	v_cndmask_b32_e64 v15, v15, v22, s[2:3]
	v_mul_f32_e32 v22, 0x37800000, v15
	v_cndmask_b32_e32 v15, v15, v22, vcc
	v_cmp_class_f32_e32 vcc, v24, v219
	s_waitcnt lgkmcnt(0)
	v_add_f32_e32 v6, v82, v83
	v_cvt_pk_f16_f32 v94, v2, v3
	v_cndmask_b32_e32 v15, v15, v24, vcc
	v_pk_mul_f32 v[2:3], v[8:9], s[18:19] op_sel_hi:[1,0]
	v_mul_f32_e32 v7, 0x4f800000, v6
	v_cmp_gt_f32_e32 vcc, s31, v6
	v_cvt_pk_f16_f32 v95, v2, v3
	v_pk_mul_f32 v[2:3], v[12:13], s[18:19] op_sel_hi:[1,0]
	v_cndmask_b32_e32 v6, v6, v7, vcc
	v_cvt_pk_f16_f32 v96, v2, v3
	v_pk_mul_f32 v[2:3], v[18:19], s[18:19] op_sel_hi:[1,0]
	v_sqrt_f32_e32 v7, v6
	v_cvt_pk_f16_f32 v97, v2, v3
	v_pk_mul_f32 v[2:3], v[10:11], s[18:19] op_sel_hi:[1,0]
	v_fma_f32 v15, v197, v15, -4.0
	v_cvt_pk_f16_f32 v98, v2, v3
	v_pk_mul_f32 v[2:3], v[20:21], s[18:19] op_sel_hi:[1,0]
	v_pk_mul_f32 v[30:31], v[30:31], s[18:19] op_sel_hi:[1,0]
	v_cvt_pk_f16_f32 v99, v2, v3
	v_pk_mul_f32 v[2:3], v[16:17], s[18:19] op_sel_hi:[1,0]
	v_pk_mul_f32 v[28:29], v[28:29], s[18:19] op_sel_hi:[1,0]
	v_cvt_pk_f16_f32 v100, v2, v3
	v_add_u32_e32 v2, -1, v7
	v_fma_f32 v3, -v2, v7, v6
	v_cmp_ge_f32_e64 s[2:3], 0, v3
	v_add_u32_e32 v3, 1, v7
	v_pk_mul_f32 v[26:27], v[26:27], s[18:19] op_sel_hi:[1,0]
	v_cndmask_b32_e64 v2, v7, v2, s[2:3]
	v_fma_f32 v7, -v3, v7, v6
	v_cmp_lt_f32_e64 s[2:3], 0, v7
	v_mov_b32_e32 v14, 0
	v_mul_f32_e32 v102, 0xbfb8aa3b, v15
	v_cndmask_b32_e64 v2, v2, v3, s[2:3]
	v_mul_f32_e32 v3, 0x37800000, v2
	v_cndmask_b32_e32 v2, v2, v3, vcc
	v_cmp_class_f32_e32 vcc, v6, v219
	v_cvt_pk_f16_f32 v86, v32, v33
	v_cvt_pk_f16_f32 v87, v30, v31
	v_cndmask_b32_e32 v2, v2, v6, vcc
	v_fma_f32 v6, v197, v2, -4.0
	v_pk_mul_f32 v[2:3], v[4:5], s[18:19] op_sel_hi:[1,0]
	v_mul_f32_e32 v106, 0xbfb8aa3b, v6
	v_cvt_pk_f16_f32 v101, v2, v3
	v_add_u32_e32 v2, s34, v202
	v_add_u32_e32 v3, s34, v201
	ds_read_b128 v[114:117], v2
	ds_read_b128 v[110:113], v3
	v_add_u32_e32 v2, s30, v202
	v_add_u32_e32 v3, s30, v201
	ds_read_b128 v[122:125], v2
	ds_read_b128 v[118:121], v3
	v_cvt_pk_f16_f32 v88, v28, v29
	v_cvt_pk_f16_f32 v89, v26, v27
	v_mov_b32_e32 v103, v102
	v_mov_b32_e32 v104, v102
	v_mov_b32_e32 v105, v102
	v_mov_b32_e32 v107, v106
	v_mov_b32_e32 v108, v106
	v_mov_b32_e32 v109, v106
	v_mov_b32_e32 v169, v217
	v_mov_b32_e32 v171, v215
	v_mov_b32_e32 v189, v213
	v_mov_b32_e32 v191, v211
	v_mov_b32_e32 v193, v202
	v_mov_b32_e32 v195, v201
	s_mov_b32 s23, 0
	v_mov_b32_e32 v15, v14
	v_mov_b32_e32 v16, v14
	v_mov_b32_e32 v17, v14
	v_mov_b32_e32 v2, v14
	v_mov_b32_e32 v3, v14
	v_mov_b32_e32 v4, v14
	v_mov_b32_e32 v5, v14
	v_mov_b32_e32 v6, v14
	v_mov_b32_e32 v7, v14
	v_mov_b32_e32 v8, v14
	v_mov_b32_e32 v9, v14
	v_mov_b32_e32 v10, v14
	v_mov_b32_e32 v11, v14
	v_mov_b32_e32 v12, v14
	v_mov_b32_e32 v13, v14
	v_mov_b32_e32 v30, v14
	v_mov_b32_e32 v31, v14
	v_mov_b32_e32 v32, v14
	v_mov_b32_e32 v33, v14
	v_mov_b32_e32 v18, v14
	v_mov_b32_e32 v19, v14
	v_mov_b32_e32 v20, v14
	v_mov_b32_e32 v21, v14
	v_mov_b32_e32 v22, v14
	v_mov_b32_e32 v23, v14
	v_mov_b32_e32 v24, v14
	v_mov_b32_e32 v25, v14
	v_mov_b32_e32 v26, v14
	v_mov_b32_e32 v27, v14
	v_mov_b32_e32 v28, v14
	v_mov_b32_e32 v29, v14
	v_mov_b32_e32 v82, v14
	v_mov_b32_e32 v83, v14
	v_mov_b32_e32 v84, v14
	v_mov_b32_e32 v85, v14
	v_mov_b32_e32 v126, v14
	v_mov_b32_e32 v127, v14
	v_mov_b32_e32 v128, v14
	v_mov_b32_e32 v129, v14
	s_branch .LBB0_1243

; __device__ __forceinline__ unsigned pkh(float lo, float hi) { f32x2 v = {lo, hi}; h16x2 h = __builtin_convertvector(v, h16x2); return __builtin_bit_cast(unsigned, h); }
; __device__ __forceinline__ unsigned pk8(float a, float b, float c, float d) { int w = __builtin_amdgcn_cvt_pk_fp8_f32(a, b, 0, false); w = __builtin_amdgcn_cvt_pk_fp8_f32(c, d, w, true); return (unsigned)w; }
;     __device__ __forceinline__ void operator()(f32x4 (&acc)[2][2][4][2], const Unit& u, const Order& S, int wr, int wc, int fr_, int fq_, LAS unsigned char*, int) const {
;     ...
;                 const int row = row0 + ai * HALF + m * 16; const size_t off = (size_t)row * DM + col0;
;                 float sq = 0.f;
; #pragma unroll
;                 for (int bj = 0; bj < 2; ++bj) {
;                     const h16x8 bs = *(const h16x8*)(h16 + off + bj * HALF);
;                     f32x4 o0 = acc[ai][bj][m][0] * pre, o1 = acc[ai][bj][m][1] * pre;
; #pragma unroll
;                     for (int e = 0; e < 4; ++e) { o0[e] += (float)bs[e]; o1[e] += (float)bs[4 + e]; }
;                     if (out32) { if (!dry) { __builtin_nontemporal_store(o0, (f32x4*)(out32 + off + bj * HALF)); __builtin_nontemporal_store(o1, (f32x4*)(out32 + off + bj * HALF + 4)); } }
;                     else if (!dry) {
;                         sq += (o0[0] * o0[0] + o0[1] * o0[1]) + (o0[2] * o0[2] + o0[3] * o0[3]) + (o1[0] * o1[0] + o1[1] * o1[1]) + (o1[2] * o1[2] + o1[3] * o1[3]);
;                         u32x4 w; w.x = pkh(o0[0], o0[1]); w.y = pkh(o0[2], o0[3]); w.z = pkh(o1[0], o1[1]); w.w = pkh(o1[2], o1[3]);
;                         *(u32x4*)(h16 + off + bj * HALF) = w;
;                         if (h8) { u32x2 q; q.x = pk8(o0[0] * F8_SA, o0[1] * F8_SA, o0[2] * F8_SA, o0[3] * F8_SA); q.y = pk8(o1[0] * F8_SA, o1[1] * F8_SA, o1[2] * F8_SA, o1[3] * F8_SA); *(u32x2*)(h8 + off + bj * HALF) = q; } }
;                 }
;                 if (!out32 && !dry) { sq += __shfl_xor(sq, 16); sq += __shfl_xor(sq, 32); if (fq == 0) atomicAdd(ss_out + row, sq); }
.LBB0_1326:
	s_lshl_b32 s3, s46, 8
	v_mov_b32_e32 v8, v187
	v_mov_b32_e32 v2, v186
	s_add_i32 s3, s3, s39
	s_nop 15
	s_nop 15
	s_lshl_b32 s2, s2, 8
	v_add_u32_e32 v4, s3, v2
	s_or_b32 s2, s2, s40
	v_ashrrev_i32_e32 v5, 31, v4
	v_lshl_add_u32 v2, v8, 3, s2
	v_lshlrev_b64 v[6:7], 11, v[4:5]
	v_ashrrev_i32_e32 v3, 31, v2
	v_lshl_add_u64 v[6:7], s[90:91], 0, v[6:7]
	v_lshl_add_u64 v[18:19], v[2:3], 1, v[6:7]
	global_load_dwordx4 v[10:13], v[18:19], off
	global_load_dwordx4 v[14:17], v[18:19], off offset:256
	v_and_b32_e32 v7, 64, v192
	v_xor_b32_e32 v6, 16, v192
	v_add_u32_e32 v7, 64, v7
	v_cmp_lt_i32_e64 s[2:3], v6, v7
	v_xor_b32_e32 v9, 32, v192
	v_cmp_eq_u32_e32 vcc, 0, v8
	v_cndmask_b32_e64 v6, v192, v6, s[2:3]
	v_cmp_lt_i32_e64 s[2:3], v9, v7
	v_lshlrev_b32_e32 v8, 2, v6
	s_waitcnt vmcnt(0)
	v_cvt_f32_f16_e32 v6, v10
	v_cvt_f32_f16_sdwa v7, v10 dst_sel:DWORD dst_unused:UNUSED_PAD src0_sel:WORD_1
	v_cvt_f32_f16_e32 v10, v11
	v_cvt_f32_f16_sdwa v11, v11 dst_sel:DWORD dst_unused:UNUSED_PAD src0_sel:WORD_1
	v_cvt_f32_f16_e32 v22, v14
	v_cvt_f32_f16_sdwa v23, v14 dst_sel:DWORD dst_unused:UNUSED_PAD src0_sel:WORD_1
	v_cvt_f32_f16_e32 v14, v15
	v_cvt_f32_f16_sdwa v15, v15 dst_sel:DWORD dst_unused:UNUSED_PAD src0_sel:WORD_1
	v_cvt_f32_f16_e32 v20, v12
	v_cvt_f32_f16_sdwa v21, v12 dst_sel:DWORD dst_unused:UNUSED_PAD src0_sel:WORD_1
	v_cvt_f32_f16_e32 v12, v13
	v_cvt_f32_f16_sdwa v13, v13 dst_sel:DWORD dst_unused:UNUSED_PAD src0_sel:WORD_1
	v_cvt_f32_f16_e32 v24, v16
	v_cvt_f32_f16_sdwa v25, v16 dst_sel:DWORD dst_unused:UNUSED_PAD src0_sel:WORD_1
	v_cvt_f32_f16_e32 v16, v17
	v_cvt_f32_f16_sdwa v17, v17 dst_sel:DWORD dst_unused:UNUSED_PAD src0_sel:WORD_1
	v_pk_fma_f32 v[6:7], v[158:159], s[12:13], v[6:7] op_sel_hi:[1,0,1]
	v_pk_fma_f32 v[26:27], v[160:161], s[12:13], v[10:11] op_sel_hi:[1,0,1]
	v_pk_fma_f32 v[22:23], v[150:151], s[12:13], v[22:23] op_sel_hi:[1,0,1]
	v_pk_fma_f32 v[30:31], v[152:153], s[12:13], v[14:15] op_sel_hi:[1,0,1]
	v_pk_fma_f32 v[20:21], v[154:155], s[12:13], v[20:21] op_sel_hi:[1,0,1]
	v_pk_fma_f32 v[28:29], v[156:157], s[12:13], v[12:13] op_sel_hi:[1,0,1]
	v_pk_fma_f32 v[24:25], v[146:147], s[12:13], v[24:25] op_sel_hi:[1,0,1]
	v_pk_mul_f32 v[12:13], v[6:7], v[6:7]
	v_pk_mul_f32 v[14:15], v[26:27], v[26:27]
	v_cvt_pk_f16_f32 v10, v6, v7
	v_cvt_pk_f16_f32 v11, v26, v27
	v_pk_mul_f32 v[6:7], v[22:23], v[22:23]
	v_pk_mul_f32 v[26:27], v[30:31], v[30:31]
	v_pk_fma_f32 v[32:33], v[148:149], s[12:13], v[16:17] op_sel_hi:[1,0,1]
	v_pk_mul_f32 v[16:17], v[20:21], v[20:21]
	v_pk_mul_f32 v[148:149], v[24:25], v[24:25]
	v_add_f32_e32 v26, v26, v27
	v_add_f32_e32 v6, v6, v7
	v_add_f32_e32 v14, v14, v15
	v_add_f32_e32 v12, v12, v13
	v_pk_mul_f32 v[146:147], v[28:29], v[28:29]
	v_pk_mul_f32 v[150:151], v[32:33], v[32:33]
	v_add_f32_e32 v7, v148, v149
	v_add_f32_e32 v13, v16, v17
	v_add_f32_e32 v6, v6, v26
	v_add_f32_e32 v12, v12, v14
	v_add_f32_e32 v27, v150, v151
	v_add_f32_e32 v15, v146, v147
	v_add_f32_e32 v6, v7, v6
	v_add_f32_e32 v7, v13, v12
	v_add_f32_e32 v6, v27, v6
	v_add_f32_e32 v7, v15, v7
	v_add_f32_e32 v6, v7, v6
	ds_bpermute_b32 v7, v8, v6
	v_cndmask_b32_e64 v9, v192, v9, s[2:3]
	v_lshlrev_b32_e32 v9, 2, v9
	v_cvt_pk_f16_f32 v12, v20, v21
	v_cvt_pk_f16_f32 v13, v28, v29
	s_waitcnt lgkmcnt(0)
	v_add_f32_e32 v6, v6, v7
	v_mov_b32_e32 v7, v6
	s_nop 1
	v_permlane32_swap_b32_e32 v6, v7
	v_cvt_pk_f16_f32 v14, v22, v23
	v_cvt_pk_f16_f32 v15, v30, v31
	v_cvt_pk_f16_f32 v16, v24, v25
	v_cvt_pk_f16_f32 v17, v32, v33
	global_store_dwordx4 v[18:19], v[10:13], off
	global_store_dwordx4 v[18:19], v[14:17], off offset:256
	s_and_saveexec_b64 s[2:3], vcc
	s_cbranch_execz .LBB0_1328
	v_lshl_add_u64 v[10:11], v[4:5], 2, s[18:19]
	s_waitcnt lgkmcnt(0)
	v_add_f32_e32 v5, v6, v7
	global_atomic_add_f32 v[10:11], v5, off
.LBB0_1328:
	s_or_b64 exec, exec, s[2:3]
	v_add_u32_e32 v6, 16, v4
	s_waitcnt lgkmcnt(0)
	v_ashrrev_i32_e32 v7, 31, v6
	v_lshlrev_b64 v[10:11], 11, v[6:7]
	v_lshl_add_u64 v[10:11], s[90:91], 0, v[10:11]
	v_lshl_add_u64 v[18:19], v[2:3], 1, v[10:11]
	global_load_dwordx4 v[10:13], v[18:19], off
	global_load_dwordx4 v[14:17], v[18:19], off offset:256
	s_waitcnt vmcnt(1)
	v_cvt_f32_f16_e32 v20, v10
	v_cvt_f32_f16_sdwa v21, v10 dst_sel:DWORD dst_unused:UNUSED_PAD src0_sel:WORD_1
	v_cvt_f32_f16_e32 v10, v11
	v_cvt_f32_f16_sdwa v11, v11 dst_sel:DWORD dst_unused:UNUSED_PAD src0_sel:WORD_1
	s_waitcnt vmcnt(0)
	v_cvt_f32_f16_e32 v24, v14
	v_cvt_f32_f16_sdwa v25, v14 dst_sel:DWORD dst_unused:UNUSED_PAD src0_sel:WORD_1
	v_cvt_f32_f16_e32 v14, v15
	v_cvt_f32_f16_sdwa v15, v15 dst_sel:DWORD dst_unused:UNUSED_PAD src0_sel:WORD_1
	v_cvt_f32_f16_e32 v22, v12
	v_cvt_f32_f16_sdwa v23, v12 dst_sel:DWORD dst_unused:UNUSED_PAD src0_sel:WORD_1
	v_cvt_f32_f16_e32 v12, v13
	v_cvt_f32_f16_sdwa v13, v13 dst_sel:DWORD dst_unused:UNUSED_PAD src0_sel:WORD_1
	v_cvt_f32_f16_e32 v26, v16
	v_cvt_f32_f16_sdwa v27, v16 dst_sel:DWORD dst_unused:UNUSED_PAD src0_sel:WORD_1
	v_cvt_f32_f16_e32 v16, v17
	v_cvt_f32_f16_sdwa v17, v17 dst_sel:DWORD dst_unused:UNUSED_PAD src0_sel:WORD_1
	v_pk_fma_f32 v[20:21], v[142:143], s[12:13], v[20:21] op_sel_hi:[1,0,1]
	v_pk_fma_f32 v[28:29], v[144:145], s[12:13], v[10:11] op_sel_hi:[1,0,1]
	v_pk_fma_f32 v[24:25], v[134:135], s[12:13], v[24:25] op_sel_hi:[1,0,1]
	v_pk_fma_f32 v[14:15], v[136:137], s[12:13], v[14:15] op_sel_hi:[1,0,1]
	v_pk_fma_f32 v[22:23], v[138:139], s[12:13], v[22:23] op_sel_hi:[1,0,1]
	v_pk_fma_f32 v[30:31], v[140:141], s[12:13], v[12:13] op_sel_hi:[1,0,1]
	v_pk_fma_f32 v[26:27], v[130:131], s[12:13], v[26:27] op_sel_hi:[1,0,1]
	v_pk_mul_f32 v[12:13], v[20:21], v[20:21]
	v_pk_mul_f32 v[32:33], v[28:29], v[28:29]
	v_cvt_pk_f16_f32 v10, v20, v21
	v_cvt_pk_f16_f32 v11, v28, v29
	v_pk_mul_f32 v[20:21], v[24:25], v[24:25]
	v_pk_mul_f32 v[28:29], v[14:15], v[14:15]
	v_pk_fma_f32 v[16:17], v[132:133], s[12:13], v[16:17] op_sel_hi:[1,0,1]
	v_pk_mul_f32 v[130:131], v[22:23], v[22:23]
	v_pk_mul_f32 v[134:135], v[26:27], v[26:27]
	v_add_f32_e32 v5, v28, v29
	v_add_f32_e32 v20, v20, v21
	v_add_f32_e32 v29, v32, v33
	v_add_f32_e32 v12, v12, v13
	v_pk_mul_f32 v[132:133], v[30:31], v[30:31]
	v_pk_mul_f32 v[136:137], v[16:17], v[16:17]
	v_add_f32_e32 v21, v134, v135
	v_add_f32_e32 v13, v130, v131
	v_add_f32_e32 v5, v20, v5
	v_add_f32_e32 v12, v12, v29
	v_add_f32_e32 v28, v136, v137
	v_add_f32_e32 v32, v132, v133
	v_add_f32_e32 v5, v21, v5
	v_add_f32_e32 v12, v13, v12
	v_add_f32_e32 v5, v28, v5
	v_add_f32_e32 v12, v32, v12
	v_add_f32_e32 v5, v12, v5
	v_mov_b32_e32 v20, v5
	s_nop 1
	v_permlane16_swap_b32_e32 v5, v20
	v_cvt_pk_f16_f32 v12, v22, v23
	v_cvt_pk_f16_f32 v13, v30, v31
	global_store_dwordx4 v[18:19], v[10:13], off
	s_waitcnt lgkmcnt(0)
	v_add_f32_e32 v5, v5, v20
	v_mov_b32_e32 v10, v5
	s_nop 1
	v_permlane32_swap_b32_e32 v5, v10
	v_cvt_pk_f16_f32 v12, v24, v25
	v_cvt_pk_f16_f32 v13, v14, v15
	v_cvt_pk_f16_f32 v14, v26, v27
	v_cvt_pk_f16_f32 v15, v16, v17
	global_store_dwordx4 v[18:19], v[12:15], off offset:256
	s_and_saveexec_b64 s[2:3], vcc
	s_cbranch_execz .LBB0_1330
; __device__ __forceinline__ unsigned pkh(float lo, float hi) { f32x2 v = {lo, hi}; h16x2 h = __builtin_convertvector(v, h16x2); return __builtin_bit_cast(unsigned, h); }
; __device__ __forceinline__ unsigned pk8(float a, float b, float c, float d) { int w = __builtin_amdgcn_cvt_pk_fp8_f32(a, b, 0, false); w = __builtin_amdgcn_cvt_pk_fp8_f32(c, d, w, true); return (unsigned)w; }
;     __device__ __forceinline__ void operator()(f32x4 (&acc)[2][2][4][2], const Unit& u, const Order& S, int wr, int wc, int fr_, int fq_, LAS unsigned char*, int) const {
;     ...
;                 const int row = row0 + ai * HALF + m * 16; const size_t off = (size_t)row * DM + col0;
;                 float sq = 0.f;
; #pragma unroll
;                 for (int bj = 0; bj < 2; ++bj) {
;                     const h16x8 bs = *(const h16x8*)(h16 + off + bj * HALF);
;                     f32x4 o0 = acc[ai][bj][m][0] * pre, o1 = acc[ai][bj][m][1] * pre;
; #pragma unroll
;                     for (int e = 0; e < 4; ++e) { o0[e] += (float)bs[e]; o1[e] += (float)bs[4 + e]; }
;                     if (out32) { if (!dry) { __builtin_nontemporal_store(o0, (f32x4*)(out32 + off + bj * HALF)); __builtin_nontemporal_store(o1, (f32x4*)(out32 + off + bj * HALF + 4)); } }
;                     else if (!dry) {
;                         sq += (o0[0] * o0[0] + o0[1] * o0[1]) + (o0[2] * o0[2] + o0[3] * o0[3]) + (o1[0] * o1[0] + o1[1] * o1[1]) + (o1[2] * o1[2] + o1[3] * o1[3]);
;                         u32x4 w; w.x = pkh(o0[0], o0[1]); w.y = pkh(o0[2], o0[3]); w.z = pkh(o1[0], o1[1]); w.w = pkh(o1[2], o1[3]);
;                         *(u32x4*)(h16 + off + bj * HALF) = w;
;                         if (h8) { u32x2 q; q.x = pk8(o0[0] * F8_SA, o0[1] * F8_SA, o0[2] * F8_SA, o0[3] * F8_SA); q.y = pk8(o1[0] * F8_SA, o1[1] * F8_SA, o1[2] * F8_SA, o1[3] * F8_SA); *(u32x2*)(h8 + off + bj * HALF) = q; } }
;                 }
;                 if (!out32 && !dry) { sq += __shfl_xor(sq, 16); sq += __shfl_xor(sq, 32); if (fq == 0) atomicAdd(ss_out + row, sq); }
	v_lshl_add_u64 v[6:7], v[6:7], 2, s[18:19]
	s_waitcnt lgkmcnt(0)
	v_add_f32_e32 v5, v5, v10
	global_atomic_add_f32 v[6:7], v5, off
.LBB0_1330:
	s_or_b64 exec, exec, s[2:3]
	v_add_u32_e32 v6, 32, v4
	v_ashrrev_i32_e32 v7, 31, v6
	s_waitcnt lgkmcnt(0)
	v_lshlrev_b64 v[10:11], 11, v[6:7]
	v_lshl_add_u64 v[10:11], s[90:91], 0, v[10:11]
	v_lshl_add_u64 v[18:19], v[2:3], 1, v[10:11]
	global_load_dwordx4 v[10:13], v[18:19], off
	global_load_dwordx4 v[14:17], v[18:19], off offset:256
	s_waitcnt vmcnt(1)
	v_cvt_f32_f16_e32 v20, v10
	v_cvt_f32_f16_sdwa v21, v10 dst_sel:DWORD dst_unused:UNUSED_PAD src0_sel:WORD_1
	v_cvt_f32_f16_e32 v10, v11
	v_cvt_f32_f16_sdwa v11, v11 dst_sel:DWORD dst_unused:UNUSED_PAD src0_sel:WORD_1
	s_waitcnt vmcnt(0)
	v_cvt_f32_f16_e32 v24, v14
	v_cvt_f32_f16_sdwa v25, v14 dst_sel:DWORD dst_unused:UNUSED_PAD src0_sel:WORD_1
	v_cvt_f32_f16_e32 v14, v15
	v_cvt_f32_f16_sdwa v15, v15 dst_sel:DWORD dst_unused:UNUSED_PAD src0_sel:WORD_1
	v_cvt_f32_f16_e32 v22, v12
	v_cvt_f32_f16_sdwa v23, v12 dst_sel:DWORD dst_unused:UNUSED_PAD src0_sel:WORD_1
	v_cvt_f32_f16_e32 v12, v13
	v_cvt_f32_f16_sdwa v13, v13 dst_sel:DWORD dst_unused:UNUSED_PAD src0_sel:WORD_1
	v_cvt_f32_f16_e32 v26, v16
	v_cvt_f32_f16_sdwa v27, v16 dst_sel:DWORD dst_unused:UNUSED_PAD src0_sel:WORD_1
	v_cvt_f32_f16_e32 v16, v17
	v_cvt_f32_f16_sdwa v17, v17 dst_sel:DWORD dst_unused:UNUSED_PAD src0_sel:WORD_1
	v_pk_fma_f32 v[20:21], v[126:127], s[12:13], v[20:21] op_sel_hi:[1,0,1]
	v_pk_fma_f32 v[28:29], v[128:129], s[12:13], v[10:11] op_sel_hi:[1,0,1]
	v_pk_fma_f32 v[24:25], v[118:119], s[12:13], v[24:25] op_sel_hi:[1,0,1]
	v_pk_fma_f32 v[14:15], v[120:121], s[12:13], v[14:15] op_sel_hi:[1,0,1]
	v_pk_fma_f32 v[22:23], v[122:123], s[12:13], v[22:23] op_sel_hi:[1,0,1]
	v_pk_fma_f32 v[30:31], v[124:125], s[12:13], v[12:13] op_sel_hi:[1,0,1]
	v_pk_fma_f32 v[26:27], v[114:115], s[12:13], v[26:27] op_sel_hi:[1,0,1]
	v_pk_mul_f32 v[12:13], v[20:21], v[20:21]
	v_pk_mul_f32 v[32:33], v[28:29], v[28:29]
	v_cvt_pk_f16_f32 v10, v20, v21
	v_cvt_pk_f16_f32 v11, v28, v29
	v_pk_mul_f32 v[20:21], v[24:25], v[24:25]
	v_pk_mul_f32 v[28:29], v[14:15], v[14:15]
	v_pk_fma_f32 v[16:17], v[116:117], s[12:13], v[16:17] op_sel_hi:[1,0,1]
	v_pk_mul_f32 v[114:115], v[22:23], v[22:23]
	v_pk_mul_f32 v[118:119], v[26:27], v[26:27]
	v_add_f32_e32 v5, v28, v29
	v_add_f32_e32 v20, v20, v21
	v_add_f32_e32 v29, v32, v33
	v_add_f32_e32 v12, v12, v13
	v_pk_mul_f32 v[116:117], v[30:31], v[30:31]
	v_pk_mul_f32 v[120:121], v[16:17], v[16:17]
	v_add_f32_e32 v21, v118, v119
	v_add_f32_e32 v13, v114, v115
	v_add_f32_e32 v5, v20, v5
	v_add_f32_e32 v12, v12, v29
	v_add_f32_e32 v28, v120, v121
	v_add_f32_e32 v32, v116, v117
	v_add_f32_e32 v5, v21, v5
	v_add_f32_e32 v12, v13, v12
	v_add_f32_e32 v5, v28, v5
	v_add_f32_e32 v12, v32, v12
	v_add_f32_e32 v5, v12, v5
	v_mov_b32_e32 v20, v5
	s_nop 1
	v_permlane16_swap_b32_e32 v5, v20
	v_cvt_pk_f16_f32 v12, v22, v23
	v_cvt_pk_f16_f32 v13, v30, v31
	global_store_dwordx4 v[18:19], v[10:13], off
	s_waitcnt lgkmcnt(0)
	v_add_f32_e32 v5, v5, v20
	v_mov_b32_e32 v10, v5
	s_nop 1
	v_permlane32_swap_b32_e32 v5, v10
	v_cvt_pk_f16_f32 v12, v24, v25
	v_cvt_pk_f16_f32 v13, v14, v15
	v_cvt_pk_f16_f32 v14, v26, v27
	v_cvt_pk_f16_f32 v15, v16, v17
	global_store_dwordx4 v[18:19], v[12:15], off offset:256
	s_and_saveexec_b64 s[2:3], vcc
	s_cbranch_execz .LBB0_1332
	v_lshl_add_u64 v[6:7], v[6:7], 2, s[18:19]
	s_waitcnt lgkmcnt(0)
	v_add_f32_e32 v5, v5, v10
	global_atomic_add_f32 v[6:7], v5, off
.LBB0_1332:
	s_or_b64 exec, exec, s[2:3]
	v_add_u32_e32 v6, 48, v4
	v_ashrrev_i32_e32 v7, 31, v6
	s_waitcnt lgkmcnt(0)
	v_lshlrev_b64 v[10:11], 11, v[6:7]
	v_lshl_add_u64 v[10:11], s[90:91], 0, v[10:11]
	v_lshl_add_u64 v[18:19], v[2:3], 1, v[10:11]
	global_load_dwordx4 v[10:13], v[18:19], off
	global_load_dwordx4 v[14:17], v[18:19], off offset:256
	s_waitcnt vmcnt(1)
	v_cvt_f32_f16_e32 v20, v10
	v_cvt_f32_f16_sdwa v21, v10 dst_sel:DWORD dst_unused:UNUSED_PAD src0_sel:WORD_1
	v_cvt_f32_f16_e32 v10, v11
	v_cvt_f32_f16_sdwa v11, v11 dst_sel:DWORD dst_unused:UNUSED_PAD src0_sel:WORD_1
	s_waitcnt vmcnt(0)
	v_cvt_f32_f16_e32 v24, v14
	v_cvt_f32_f16_sdwa v25, v14 dst_sel:DWORD dst_unused:UNUSED_PAD src0_sel:WORD_1
	v_cvt_f32_f16_e32 v14, v15
	v_cvt_f32_f16_sdwa v15, v15 dst_sel:DWORD dst_unused:UNUSED_PAD src0_sel:WORD_1
	v_cvt_f32_f16_e32 v22, v12
	v_cvt_f32_f16_sdwa v23, v12 dst_sel:DWORD dst_unused:UNUSED_PAD src0_sel:WORD_1
	v_cvt_f32_f16_e32 v12, v13
	v_cvt_f32_f16_sdwa v13, v13 dst_sel:DWORD dst_unused:UNUSED_PAD src0_sel:WORD_1
	v_cvt_f32_f16_e32 v26, v16
	v_cvt_f32_f16_sdwa v27, v16 dst_sel:DWORD dst_unused:UNUSED_PAD src0_sel:WORD_1
	v_cvt_f32_f16_e32 v16, v17
	v_cvt_f32_f16_sdwa v17, v17 dst_sel:DWORD dst_unused:UNUSED_PAD src0_sel:WORD_1
	v_pk_fma_f32 v[20:21], v[110:111], s[12:13], v[20:21] op_sel_hi:[1,0,1]
	v_pk_fma_f32 v[28:29], v[112:113], s[12:13], v[10:11] op_sel_hi:[1,0,1]
	v_pk_fma_f32 v[24:25], v[102:103], s[12:13], v[24:25] op_sel_hi:[1,0,1]
	v_pk_fma_f32 v[14:15], v[104:105], s[12:13], v[14:15] op_sel_hi:[1,0,1]
	v_pk_fma_f32 v[22:23], v[106:107], s[12:13], v[22:23] op_sel_hi:[1,0,1]
	v_pk_fma_f32 v[30:31], v[108:109], s[12:13], v[12:13] op_sel_hi:[1,0,1]
	v_pk_fma_f32 v[26:27], v[98:99], s[12:13], v[26:27] op_sel_hi:[1,0,1]
	v_pk_mul_f32 v[12:13], v[20:21], v[20:21]
	v_pk_mul_f32 v[32:33], v[28:29], v[28:29]
	v_cvt_pk_f16_f32 v10, v20, v21
	v_cvt_pk_f16_f32 v11, v28, v29
	v_pk_mul_f32 v[20:21], v[24:25], v[24:25]
	v_pk_mul_f32 v[28:29], v[14:15], v[14:15]
	v_pk_fma_f32 v[16:17], v[100:101], s[12:13], v[16:17] op_sel_hi:[1,0,1]
	v_pk_mul_f32 v[98:99], v[22:23], v[22:23]
	v_pk_mul_f32 v[102:103], v[26:27], v[26:27]
	v_add_f32_e32 v5, v28, v29
	v_add_f32_e32 v20, v20, v21
	v_add_f32_e32 v29, v32, v33
	v_add_f32_e32 v12, v12, v13
	v_pk_mul_f32 v[100:101], v[30:31], v[30:31]
	v_pk_mul_f32 v[104:105], v[16:17], v[16:17]
	v_add_f32_e32 v21, v102, v103
	v_add_f32_e32 v13, v98, v99
	v_add_f32_e32 v5, v20, v5
	v_add_f32_e32 v12, v12, v29
	v_add_f32_e32 v28, v104, v105
	v_add_f32_e32 v32, v100, v101
	v_add_f32_e32 v5, v21, v5
	v_add_f32_e32 v12, v13, v12
	v_add_f32_e32 v5, v28, v5
	v_add_f32_e32 v12, v32, v12
	v_add_f32_e32 v5, v12, v5
	v_mov_b32_e32 v20, v5
	s_nop 1
	v_permlane16_swap_b32_e32 v5, v20
	v_cvt_pk_f16_f32 v12, v22, v23
	v_cvt_pk_f16_f32 v13, v30, v31
	global_store_dwordx4 v[18:19], v[10:13], off
	s_waitcnt lgkmcnt(0)
	v_add_f32_e32 v5, v5, v20
	v_mov_b32_e32 v10, v5
	s_nop 1
	v_permlane32_swap_b32_e32 v5, v10
	v_cvt_pk_f16_f32 v12, v24, v25
	v_cvt_pk_f16_f32 v13, v14, v15
	v_cvt_pk_f16_f32 v14, v26, v27
	v_cvt_pk_f16_f32 v15, v16, v17
	global_store_dwordx4 v[18:19], v[12:15], off offset:256
	s_and_saveexec_b64 s[2:3], vcc
	s_cbranch_execz .LBB0_1334
	v_lshl_add_u64 v[6:7], v[6:7], 2, s[18:19]
	s_waitcnt lgkmcnt(0)
	v_add_f32_e32 v5, v5, v10
	global_atomic_add_f32 v[6:7], v5, off
; __device__ __forceinline__ unsigned pkh(float lo, float hi) { f32x2 v = {lo, hi}; h16x2 h = __builtin_convertvector(v, h16x2); return __builtin_bit_cast(unsigned, h); }
; __device__ __forceinline__ unsigned pk8(float a, float b, float c, float d) { int w = __builtin_amdgcn_cvt_pk_fp8_f32(a, b, 0, false); w = __builtin_amdgcn_cvt_pk_fp8_f32(c, d, w, true); return (unsigned)w; }
;     __device__ __forceinline__ void operator()(f32x4 (&acc)[2][2][4][2], const Unit& u, const Order& S, int wr, int wc, int fr_, int fq_, LAS unsigned char*, int) const {
;     ...
;                 const int row = row0 + ai * HALF + m * 16; const size_t off = (size_t)row * DM + col0;
;                 float sq = 0.f;
; #pragma unroll
;                 for (int bj = 0; bj < 2; ++bj) {
;                     const h16x8 bs = *(const h16x8*)(h16 + off + bj * HALF);
;                     f32x4 o0 = acc[ai][bj][m][0] * pre, o1 = acc[ai][bj][m][1] * pre;
; #pragma unroll
;                     for (int e = 0; e < 4; ++e) { o0[e] += (float)bs[e]; o1[e] += (float)bs[4 + e]; }
;                     if (out32) { if (!dry) { __builtin_nontemporal_store(o0, (f32x4*)(out32 + off + bj * HALF)); __builtin_nontemporal_store(o1, (f32x4*)(out32 + off + bj * HALF + 4)); } }
;                     else if (!dry) {
;                         sq += (o0[0] * o0[0] + o0[1] * o0[1]) + (o0[2] * o0[2] + o0[3] * o0[3]) + (o1[0] * o1[0] + o1[1] * o1[1]) + (o1[2] * o1[2] + o1[3] * o1[3]);
;                         u32x4 w; w.x = pkh(o0[0], o0[1]); w.y = pkh(o0[2], o0[3]); w.z = pkh(o1[0], o1[1]); w.w = pkh(o1[2], o1[3]);
;                         *(u32x4*)(h16 + off + bj * HALF) = w;
;                         if (h8) { u32x2 q; q.x = pk8(o0[0] * F8_SA, o0[1] * F8_SA, o0[2] * F8_SA, o0[3] * F8_SA); q.y = pk8(o1[0] * F8_SA, o1[1] * F8_SA, o1[2] * F8_SA, o1[3] * F8_SA); *(u32x2*)(h8 + off + bj * HALF) = q; } }
;                 }
;                 if (!out32 && !dry) { sq += __shfl_xor(sq, 16); sq += __shfl_xor(sq, 32); if (fq == 0) atomicAdd(ss_out + row, sq); }
.LBB0_1334:
	s_or_b64 exec, exec, s[2:3]
	v_add_u32_e32 v6, 0x80, v4
	v_ashrrev_i32_e32 v7, 31, v6
	s_waitcnt lgkmcnt(0)
	v_lshlrev_b64 v[10:11], 11, v[6:7]
	v_lshl_add_u64 v[10:11], s[90:91], 0, v[10:11]
	v_lshl_add_u64 v[18:19], v[2:3], 1, v[10:11]
	global_load_dwordx4 v[10:13], v[18:19], off
	global_load_dwordx4 v[14:17], v[18:19], off offset:256
	s_waitcnt vmcnt(1)
	v_cvt_f32_f16_e32 v20, v10
	v_cvt_f32_f16_sdwa v21, v10 dst_sel:DWORD dst_unused:UNUSED_PAD src0_sel:WORD_1
	v_cvt_f32_f16_e32 v10, v11
	v_cvt_f32_f16_sdwa v11, v11 dst_sel:DWORD dst_unused:UNUSED_PAD src0_sel:WORD_1
	s_waitcnt vmcnt(0)
	v_cvt_f32_f16_e32 v24, v14
	v_cvt_f32_f16_sdwa v25, v14 dst_sel:DWORD dst_unused:UNUSED_PAD src0_sel:WORD_1
	v_cvt_f32_f16_e32 v14, v15
	v_cvt_f32_f16_sdwa v15, v15 dst_sel:DWORD dst_unused:UNUSED_PAD src0_sel:WORD_1
	v_cvt_f32_f16_e32 v22, v12
	v_cvt_f32_f16_sdwa v23, v12 dst_sel:DWORD dst_unused:UNUSED_PAD src0_sel:WORD_1
	v_cvt_f32_f16_e32 v12, v13
	v_cvt_f32_f16_sdwa v13, v13 dst_sel:DWORD dst_unused:UNUSED_PAD src0_sel:WORD_1
	v_cvt_f32_f16_e32 v26, v16
	v_cvt_f32_f16_sdwa v27, v16 dst_sel:DWORD dst_unused:UNUSED_PAD src0_sel:WORD_1
	v_cvt_f32_f16_e32 v16, v17
	v_cvt_f32_f16_sdwa v17, v17 dst_sel:DWORD dst_unused:UNUSED_PAD src0_sel:WORD_1
	v_pk_fma_f32 v[20:21], v[94:95], s[12:13], v[20:21] op_sel_hi:[1,0,1]
	v_pk_fma_f32 v[28:29], v[96:97], s[12:13], v[10:11] op_sel_hi:[1,0,1]
	v_pk_fma_f32 v[24:25], v[86:87], s[12:13], v[24:25] op_sel_hi:[1,0,1]
	v_pk_fma_f32 v[14:15], v[88:89], s[12:13], v[14:15] op_sel_hi:[1,0,1]
	v_pk_fma_f32 v[22:23], v[90:91], s[12:13], v[22:23] op_sel_hi:[1,0,1]
	v_pk_fma_f32 v[30:31], v[92:93], s[12:13], v[12:13] op_sel_hi:[1,0,1]
	v_pk_fma_f32 v[26:27], v[82:83], s[12:13], v[26:27] op_sel_hi:[1,0,1]
	v_pk_mul_f32 v[12:13], v[20:21], v[20:21]
	v_pk_mul_f32 v[32:33], v[28:29], v[28:29]
	v_cvt_pk_f16_f32 v10, v20, v21
	v_cvt_pk_f16_f32 v11, v28, v29
	v_pk_mul_f32 v[20:21], v[24:25], v[24:25]
	v_pk_mul_f32 v[28:29], v[14:15], v[14:15]
	v_pk_fma_f32 v[16:17], v[84:85], s[12:13], v[16:17] op_sel_hi:[1,0,1]
	v_pk_mul_f32 v[82:83], v[22:23], v[22:23]
	v_pk_mul_f32 v[86:87], v[26:27], v[26:27]
	v_add_f32_e32 v5, v28, v29
	v_add_f32_e32 v20, v20, v21
	v_add_f32_e32 v29, v32, v33
	v_add_f32_e32 v12, v12, v13
	v_pk_mul_f32 v[84:85], v[30:31], v[30:31]
	v_pk_mul_f32 v[88:89], v[16:17], v[16:17]
	v_add_f32_e32 v21, v86, v87
	v_add_f32_e32 v13, v82, v83
	v_add_f32_e32 v5, v20, v5
	v_add_f32_e32 v12, v12, v29
	v_add_f32_e32 v28, v88, v89
	v_add_f32_e32 v32, v84, v85
	v_add_f32_e32 v5, v21, v5
	v_add_f32_e32 v12, v13, v12
	v_add_f32_e32 v5, v28, v5
	v_add_f32_e32 v12, v32, v12
	v_add_f32_e32 v5, v12, v5
	v_mov_b32_e32 v20, v5
	s_nop 1
	v_permlane16_swap_b32_e32 v5, v20
	v_cvt_pk_f16_f32 v12, v22, v23
	v_cvt_pk_f16_f32 v13, v30, v31
	global_store_dwordx4 v[18:19], v[10:13], off
	s_waitcnt lgkmcnt(0)
	v_add_f32_e32 v5, v5, v20
	v_mov_b32_e32 v10, v5
	s_nop 1
	v_permlane32_swap_b32_e32 v5, v10
	v_cvt_pk_f16_f32 v12, v24, v25
	v_cvt_pk_f16_f32 v13, v14, v15
	v_cvt_pk_f16_f32 v14, v26, v27
	v_cvt_pk_f16_f32 v15, v16, v17
	global_store_dwordx4 v[18:19], v[12:15], off offset:256
	s_and_saveexec_b64 s[2:3], vcc
	s_cbranch_execz .LBB0_1336
	v_lshl_add_u64 v[6:7], v[6:7], 2, s[18:19]
	s_waitcnt lgkmcnt(0)
	v_add_f32_e32 v5, v5, v10
	global_atomic_add_f32 v[6:7], v5, off
; __device__ __forceinline__ unsigned pkh(float lo, float hi) { f32x2 v = {lo, hi}; h16x2 h = __builtin_convertvector(v, h16x2); return __builtin_bit_cast(unsigned, h); }
; __device__ __forceinline__ unsigned pk8(float a, float b, float c, float d) { int w = __builtin_amdgcn_cvt_pk_fp8_f32(a, b, 0, false); w = __builtin_amdgcn_cvt_pk_fp8_f32(c, d, w, true); return (unsigned)w; }
;     __device__ __forceinline__ void operator()(f32x4 (&acc)[2][2][4][2], const Unit& u, const Order& S, int wr, int wc, int fr_, int fq_, LAS unsigned char*, int) const {
;     ...
;                 const int row = row0 + ai * HALF + m * 16; const size_t off = (size_t)row * DM + col0;
;                 float sq = 0.f;
; #pragma unroll
;                 for (int bj = 0; bj < 2; ++bj) {
;                     const h16x8 bs = *(const h16x8*)(h16 + off + bj * HALF);
;                     f32x4 o0 = acc[ai][bj][m][0] * pre, o1 = acc[ai][bj][m][1] * pre;
; #pragma unroll
;                     for (int e = 0; e < 4; ++e) { o0[e] += (float)bs[e]; o1[e] += (float)bs[4 + e]; }
;                     if (out32) { if (!dry) { __builtin_nontemporal_store(o0, (f32x4*)(out32 + off + bj * HALF)); __builtin_nontemporal_store(o1, (f32x4*)(out32 + off + bj * HALF + 4)); } }
;                     else if (!dry) {
;                         sq += (o0[0] * o0[0] + o0[1] * o0[1]) + (o0[2] * o0[2] + o0[3] * o0[3]) + (o1[0] * o1[0] + o1[1] * o1[1]) + (o1[2] * o1[2] + o1[3] * o1[3]);
;                         u32x4 w; w.x = pkh(o0[0], o0[1]); w.y = pkh(o0[2], o0[3]); w.z = pkh(o1[0], o1[1]); w.w = pkh(o1[2], o1[3]);
;                         *(u32x4*)(h16 + off + bj * HALF) = w;
;                         if (h8) { u32x2 q; q.x = pk8(o0[0] * F8_SA, o0[1] * F8_SA, o0[2] * F8_SA, o0[3] * F8_SA); q.y = pk8(o1[0] * F8_SA, o1[1] * F8_SA, o1[2] * F8_SA, o1[3] * F8_SA); *(u32x2*)(h8 + off + bj * HALF) = q; } }
;                 }
;                 if (!out32 && !dry) { sq += __shfl_xor(sq, 16); sq += __shfl_xor(sq, 32); if (fq == 0) atomicAdd(ss_out + row, sq); }
.LBB0_1336:
	s_or_b64 exec, exec, s[2:3]
	v_add_u32_e32 v6, 0x90, v4
	v_ashrrev_i32_e32 v7, 31, v6
	s_waitcnt lgkmcnt(0)
	v_lshlrev_b64 v[10:11], 11, v[6:7]
	v_lshl_add_u64 v[10:11], s[90:91], 0, v[10:11]
	v_lshl_add_u64 v[18:19], v[2:3], 1, v[10:11]
	global_load_dwordx4 v[10:13], v[18:19], off
	global_load_dwordx4 v[14:17], v[18:19], off offset:256
	s_waitcnt vmcnt(1)
	v_cvt_f32_f16_e32 v20, v10
	v_cvt_f32_f16_sdwa v21, v10 dst_sel:DWORD dst_unused:UNUSED_PAD src0_sel:WORD_1
	v_cvt_f32_f16_e32 v10, v11
	v_cvt_f32_f16_sdwa v11, v11 dst_sel:DWORD dst_unused:UNUSED_PAD src0_sel:WORD_1
	s_waitcnt vmcnt(0)
	v_cvt_f32_f16_e32 v24, v14
	v_cvt_f32_f16_sdwa v25, v14 dst_sel:DWORD dst_unused:UNUSED_PAD src0_sel:WORD_1
	v_cvt_f32_f16_e32 v14, v15
	v_cvt_f32_f16_sdwa v15, v15 dst_sel:DWORD dst_unused:UNUSED_PAD src0_sel:WORD_1
	v_cvt_f32_f16_e32 v22, v12
	v_cvt_f32_f16_sdwa v23, v12 dst_sel:DWORD dst_unused:UNUSED_PAD src0_sel:WORD_1
	v_cvt_f32_f16_e32 v12, v13
	v_cvt_f32_f16_sdwa v13, v13 dst_sel:DWORD dst_unused:UNUSED_PAD src0_sel:WORD_1
	v_cvt_f32_f16_e32 v26, v16
	v_cvt_f32_f16_sdwa v27, v16 dst_sel:DWORD dst_unused:UNUSED_PAD src0_sel:WORD_1
	v_cvt_f32_f16_e32 v16, v17
	v_cvt_f32_f16_sdwa v17, v17 dst_sel:DWORD dst_unused:UNUSED_PAD src0_sel:WORD_1
	v_pk_fma_f32 v[20:21], v[78:79], s[12:13], v[20:21] op_sel_hi:[1,0,1]
	v_pk_fma_f32 v[28:29], v[80:81], s[12:13], v[10:11] op_sel_hi:[1,0,1]
	v_pk_fma_f32 v[24:25], v[70:71], s[12:13], v[24:25] op_sel_hi:[1,0,1]
	v_pk_fma_f32 v[14:15], v[72:73], s[12:13], v[14:15] op_sel_hi:[1,0,1]
	v_pk_fma_f32 v[22:23], v[74:75], s[12:13], v[22:23] op_sel_hi:[1,0,1]
	v_pk_fma_f32 v[30:31], v[76:77], s[12:13], v[12:13] op_sel_hi:[1,0,1]
	v_pk_fma_f32 v[26:27], v[66:67], s[12:13], v[26:27] op_sel_hi:[1,0,1]
	v_pk_mul_f32 v[12:13], v[20:21], v[20:21]
	v_pk_mul_f32 v[32:33], v[28:29], v[28:29]
	v_cvt_pk_f16_f32 v10, v20, v21
	v_cvt_pk_f16_f32 v11, v28, v29
	v_pk_mul_f32 v[20:21], v[24:25], v[24:25]
	v_pk_mul_f32 v[28:29], v[14:15], v[14:15]
	v_pk_fma_f32 v[16:17], v[68:69], s[12:13], v[16:17] op_sel_hi:[1,0,1]
	v_pk_mul_f32 v[66:67], v[22:23], v[22:23]
	v_pk_mul_f32 v[70:71], v[26:27], v[26:27]
	v_add_f32_e32 v5, v28, v29
	v_add_f32_e32 v20, v20, v21
	v_add_f32_e32 v29, v32, v33
	v_add_f32_e32 v12, v12, v13
	v_pk_mul_f32 v[68:69], v[30:31], v[30:31]
	v_pk_mul_f32 v[72:73], v[16:17], v[16:17]
	v_add_f32_e32 v21, v70, v71
	v_add_f32_e32 v13, v66, v67
	v_add_f32_e32 v5, v20, v5
	v_add_f32_e32 v12, v12, v29
	v_add_f32_e32 v28, v72, v73
	v_add_f32_e32 v32, v68, v69
	v_add_f32_e32 v5, v21, v5
	v_add_f32_e32 v12, v13, v12
	v_add_f32_e32 v5, v28, v5
	v_add_f32_e32 v12, v32, v12
	v_add_f32_e32 v5, v12, v5
	v_mov_b32_e32 v20, v5
	s_nop 1
	v_permlane16_swap_b32_e32 v5, v20
	v_cvt_pk_f16_f32 v12, v22, v23
	v_cvt_pk_f16_f32 v13, v30, v31
	global_store_dwordx4 v[18:19], v[10:13], off
	s_waitcnt lgkmcnt(0)
	v_add_f32_e32 v5, v5, v20
	v_mov_b32_e32 v10, v5
	s_nop 1
	v_permlane32_swap_b32_e32 v5, v10
	v_cvt_pk_f16_f32 v12, v24, v25
	v_cvt_pk_f16_f32 v13, v14, v15
	v_cvt_pk_f16_f32 v14, v26, v27
	v_cvt_pk_f16_f32 v15, v16, v17
	global_store_dwordx4 v[18:19], v[12:15], off offset:256
	s_and_saveexec_b64 s[2:3], vcc
	s_cbranch_execz .LBB0_1338
	v_lshl_add_u64 v[6:7], v[6:7], 2, s[18:19]
	s_waitcnt lgkmcnt(0)
	v_add_f32_e32 v5, v5, v10
	global_atomic_add_f32 v[6:7], v5, off
.LBB0_1338:
	s_or_b64 exec, exec, s[2:3]
	v_add_u32_e32 v6, 0xa0, v4
	v_ashrrev_i32_e32 v7, 31, v6
	s_waitcnt lgkmcnt(0)
	v_lshlrev_b64 v[10:11], 11, v[6:7]
	v_lshl_add_u64 v[10:11], s[90:91], 0, v[10:11]
	v_lshl_add_u64 v[18:19], v[2:3], 1, v[10:11]
	global_load_dwordx4 v[10:13], v[18:19], off
	global_load_dwordx4 v[14:17], v[18:19], off offset:256
	s_waitcnt vmcnt(1)
	v_cvt_f32_f16_e32 v20, v10
	v_cvt_f32_f16_sdwa v21, v10 dst_sel:DWORD dst_unused:UNUSED_PAD src0_sel:WORD_1
	v_cvt_f32_f16_e32 v10, v11
	v_cvt_f32_f16_sdwa v11, v11 dst_sel:DWORD dst_unused:UNUSED_PAD src0_sel:WORD_1
	s_waitcnt vmcnt(0)
	v_cvt_f32_f16_e32 v24, v14
	v_cvt_f32_f16_sdwa v25, v14 dst_sel:DWORD dst_unused:UNUSED_PAD src0_sel:WORD_1
	v_cvt_f32_f16_e32 v14, v15
	v_cvt_f32_f16_sdwa v15, v15 dst_sel:DWORD dst_unused:UNUSED_PAD src0_sel:WORD_1
	v_cvt_f32_f16_e32 v22, v12
	v_cvt_f32_f16_sdwa v23, v12 dst_sel:DWORD dst_unused:UNUSED_PAD src0_sel:WORD_1
	v_cvt_f32_f16_e32 v12, v13
	v_cvt_f32_f16_sdwa v13, v13 dst_sel:DWORD dst_unused:UNUSED_PAD src0_sel:WORD_1
	v_cvt_f32_f16_e32 v26, v16
	v_cvt_f32_f16_sdwa v27, v16 dst_sel:DWORD dst_unused:UNUSED_PAD src0_sel:WORD_1
	v_cvt_f32_f16_e32 v16, v17
	v_cvt_f32_f16_sdwa v17, v17 dst_sel:DWORD dst_unused:UNUSED_PAD src0_sel:WORD_1
	v_pk_fma_f32 v[20:21], v[62:63], s[12:13], v[20:21] op_sel_hi:[1,0,1]
	v_pk_fma_f32 v[28:29], v[64:65], s[12:13], v[10:11] op_sel_hi:[1,0,1]
	v_pk_fma_f32 v[24:25], v[54:55], s[12:13], v[24:25] op_sel_hi:[1,0,1]
	v_pk_fma_f32 v[14:15], v[56:57], s[12:13], v[14:15] op_sel_hi:[1,0,1]
	v_pk_fma_f32 v[22:23], v[58:59], s[12:13], v[22:23] op_sel_hi:[1,0,1]
	v_pk_fma_f32 v[30:31], v[60:61], s[12:13], v[12:13] op_sel_hi:[1,0,1]
	v_pk_fma_f32 v[26:27], v[50:51], s[12:13], v[26:27] op_sel_hi:[1,0,1]
	v_pk_mul_f32 v[12:13], v[20:21], v[20:21]
	v_pk_mul_f32 v[32:33], v[28:29], v[28:29]
	v_cvt_pk_f16_f32 v10, v20, v21
	v_cvt_pk_f16_f32 v11, v28, v29
	v_pk_mul_f32 v[20:21], v[24:25], v[24:25]
	v_pk_mul_f32 v[28:29], v[14:15], v[14:15]
	v_pk_fma_f32 v[16:17], v[52:53], s[12:13], v[16:17] op_sel_hi:[1,0,1]
	v_pk_mul_f32 v[50:51], v[22:23], v[22:23]
	v_pk_mul_f32 v[54:55], v[26:27], v[26:27]
	v_add_f32_e32 v5, v28, v29
	v_add_f32_e32 v20, v20, v21
	v_add_f32_e32 v29, v32, v33
	v_add_f32_e32 v12, v12, v13
	v_pk_mul_f32 v[52:53], v[30:31], v[30:31]
	v_pk_mul_f32 v[56:57], v[16:17], v[16:17]
	v_add_f32_e32 v21, v54, v55
	v_add_f32_e32 v13, v50, v51
	v_add_f32_e32 v5, v20, v5
	v_add_f32_e32 v12, v12, v29
	v_add_f32_e32 v28, v56, v57
	v_add_f32_e32 v32, v52, v53
	v_add_f32_e32 v5, v21, v5
	v_add_f32_e32 v12, v13, v12
	v_add_f32_e32 v5, v28, v5
	v_add_f32_e32 v12, v32, v12
	v_add_f32_e32 v5, v12, v5
	v_mov_b32_e32 v20, v5
	s_nop 1
	v_permlane16_swap_b32_e32 v5, v20
	v_cvt_pk_f16_f32 v12, v22, v23
	v_cvt_pk_f16_f32 v13, v30, v31
	global_store_dwordx4 v[18:19], v[10:13], off
	s_waitcnt lgkmcnt(0)
	v_add_f32_e32 v5, v5, v20
	ds_bpermute_b32 v10, v9, v5
	v_cvt_pk_f16_f32 v12, v24, v25
	v_cvt_pk_f16_f32 v13, v14, v15
	v_cvt_pk_f16_f32 v14, v26, v27
	v_cvt_pk_f16_f32 v15, v16, v17
	global_store_dwordx4 v[18:19], v[12:15], off offset:256
	s_and_saveexec_b64 s[2:3], vcc
	s_cbranch_execz .LBB0_1340
	v_lshl_add_u64 v[6:7], v[6:7], 2, s[18:19]
	s_waitcnt lgkmcnt(0)
	v_add_f32_e32 v5, v5, v10
	global_atomic_add_f32 v[6:7], v5, off

;     __device__ __forceinline__ void operator()(f32x4 (&acc)[2][2][4][2], const Unit& u, const Order& S, int wr, int wc, int fr_, int fq_, LAS unsigned char*, int) const {
;     ...
;                 if (stat && !dry) { sq += __shfl_xor(sq, 16); sq += __shfl_xor(sq, 32); if (fq == 0) atomicAdd(ssv + row, sq); }
.LBB0_1601:
	v_cndmask_b32_e64 v112, 0, 1, s[10:11]
	v_cmp_ne_u32_e64 s[6:7], 1, v112
	s_andn2_b64 vcc, exec, s[10:11]
	v_cmp_eq_u32_e64 s[4:5], 0, v159
	s_cbranch_vccnz .LBB0_1605
	v_and_b32_e32 v113, 64, v158
	v_xor_b32_e32 v112, 16, v158
	v_add_u32_e32 v113, 64, v113
	v_cmp_lt_i32_e32 vcc, v112, v113
	v_xor_b32_e32 v114, 32, v158
	s_nop 0
	v_cndmask_b32_e32 v112, v158, v112, vcc
	v_lshlrev_b32_e32 v112, 2, v112
	ds_bpermute_b32 v112, v112, v160
	v_cmp_lt_i32_e32 vcc, v114, v113
	s_waitcnt lgkmcnt(0)
	v_add_f32_e32 v112, v160, v112
	v_cndmask_b32_e32 v113, v158, v114, vcc
	v_lshlrev_b32_e32 v113, 2, v113
	v_mov_b32_e32 v113, v112
	s_nop 1
	v_permlane32_swap_b32_e32 v112, v113
	s_and_saveexec_b64 s[38:39], s[4:5]
	s_cbranch_execz .LBB0_1604
	v_lshlrev_b64 v[114:115], 2, v[144:145]
	s_waitcnt lgkmcnt(0)
	v_add_f32_e32 v112, v112, v113
	flat_atomic_add_f32 v[114:115], v112

;     __device__ __forceinline__ void operator()(f32x4 (&acc)[2][2][4][2], const Unit& u, const Order& S, int wr, int wc, int fr_, int fq_, LAS unsigned char*, int) const {
;     ...
;                 if (stat && !dry) { sq += __shfl_xor(sq, 16); sq += __shfl_xor(sq, 32); if (fq == 0) atomicAdd(ssv + row, sq); }
.LBB0_1614:
	v_and_b32_e32 v97, 64, v158
	v_xor_b32_e32 v96, 16, v158
	v_add_u32_e32 v97, 64, v97
	v_cmp_lt_i32_e32 vcc, v96, v97
	v_xor_b32_e32 v98, 32, v158
	s_nop 0
	v_cndmask_b32_e32 v96, v158, v96, vcc
	v_lshlrev_b32_e32 v96, 2, v96
	ds_bpermute_b32 v96, v96, v116
	v_cmp_lt_i32_e32 vcc, v98, v97
	s_waitcnt lgkmcnt(0)
	v_add_f32_e32 v96, v116, v96
	v_cndmask_b32_e32 v97, v158, v98, vcc
	v_lshlrev_b32_e32 v97, 2, v97
	v_mov_b32_e32 v97, v96
	s_nop 1
	v_permlane32_swap_b32_e32 v96, v97
	s_and_saveexec_b64 s[38:39], s[4:5]
	s_cbranch_execz .LBB0_1616
	v_lshlrev_b64 v[98:99], 2, v[144:145]
	s_waitcnt lgkmcnt(0)
	v_add_f32_e32 v96, v96, v97
	flat_atomic_add_f32 v[98:99], v96 offset:64

;     __device__ __forceinline__ void operator()(f32x4 (&acc)[2][2][4][2], const Unit& u, const Order& S, int wr, int wc, int fr_, int fq_, LAS unsigned char*, int) const {
;     ...
;                 if (stat && !dry) { sq += __shfl_xor(sq, 16); sq += __shfl_xor(sq, 32); if (fq == 0) atomicAdd(ssv + row, sq); }
.LBB0_1626:
	v_and_b32_e32 v81, 64, v158
	v_xor_b32_e32 v80, 16, v158
	v_add_u32_e32 v81, 64, v81
	v_cmp_lt_i32_e32 vcc, v80, v81
	v_xor_b32_e32 v82, 32, v158
	s_nop 0
	v_cndmask_b32_e32 v80, v158, v80, vcc
	v_lshlrev_b32_e32 v80, 2, v80
	ds_bpermute_b32 v80, v80, v100
	v_cmp_lt_i32_e32 vcc, v82, v81
	s_waitcnt lgkmcnt(0)
	v_add_f32_e32 v80, v100, v80
	v_cndmask_b32_e32 v81, v158, v82, vcc
	v_lshlrev_b32_e32 v81, 2, v81
	v_mov_b32_e32 v81, v80
	s_nop 1
	v_permlane32_swap_b32_e32 v80, v81
	s_and_saveexec_b64 s[38:39], s[4:5]
	s_cbranch_execz .LBB0_1628
	v_lshlrev_b64 v[82:83], 2, v[144:145]
	s_waitcnt lgkmcnt(0)
	v_add_f32_e32 v80, v80, v81
	flat_atomic_add_f32 v[82:83], v80 offset:128

;     __device__ __forceinline__ void operator()(f32x4 (&acc)[2][2][4][2], const Unit& u, const Order& S, int wr, int wc, int fr_, int fq_, LAS unsigned char*, int) const {
;     ...
;                 if (stat && !dry) { sq += __shfl_xor(sq, 16); sq += __shfl_xor(sq, 32); if (fq == 0) atomicAdd(ssv + row, sq); }
.LBB0_1638:
	v_and_b32_e32 v65, 64, v158
	v_xor_b32_e32 v64, 16, v158
	v_add_u32_e32 v65, 64, v65
	v_cmp_lt_i32_e32 vcc, v64, v65
	v_xor_b32_e32 v66, 32, v158
	s_nop 0
	v_cndmask_b32_e32 v64, v158, v64, vcc
	v_lshlrev_b32_e32 v64, 2, v64
	ds_bpermute_b32 v64, v64, v84
	v_cmp_lt_i32_e32 vcc, v66, v65
	s_waitcnt lgkmcnt(0)
	v_add_f32_e32 v64, v84, v64
	v_cndmask_b32_e32 v65, v158, v66, vcc
	v_lshlrev_b32_e32 v65, 2, v65
	v_mov_b32_e32 v65, v64
	s_nop 1
	v_permlane32_swap_b32_e32 v64, v65
	s_and_saveexec_b64 s[38:39], s[4:5]
	s_cbranch_execz .LBB0_1640
	v_lshlrev_b64 v[66:67], 2, v[144:145]
	s_waitcnt lgkmcnt(0)
	v_add_f32_e32 v64, v64, v65
	flat_atomic_add_f32 v[66:67], v64 offset:192

;     __device__ __forceinline__ void operator()(f32x4 (&acc)[2][2][4][2], const Unit& u, const Order& S, int wr, int wc, int fr_, int fq_, LAS unsigned char*, int) const {
;     ...
;                 if (stat && !dry) { sq += __shfl_xor(sq, 16); sq += __shfl_xor(sq, 32); if (fq == 0) atomicAdd(ssv + row, sq); }
.LBB0_1650:
	v_and_b32_e32 v49, 64, v158
	v_xor_b32_e32 v48, 16, v158
	v_add_u32_e32 v49, 64, v49
	v_cmp_lt_i32_e32 vcc, v48, v49
	v_xor_b32_e32 v50, 32, v158
	s_nop 0
	v_cndmask_b32_e32 v48, v158, v48, vcc
	v_lshlrev_b32_e32 v48, 2, v48
	ds_bpermute_b32 v48, v48, v68
	v_cmp_lt_i32_e32 vcc, v50, v49
	s_waitcnt lgkmcnt(0)
	v_add_f32_e32 v48, v68, v48
	v_cndmask_b32_e32 v49, v158, v50, vcc
	v_lshlrev_b32_e32 v49, 2, v49
	v_mov_b32_e32 v49, v48
	s_nop 1
	v_permlane32_swap_b32_e32 v48, v49
	s_and_saveexec_b64 s[38:39], s[4:5]
	s_cbranch_execz .LBB0_1652
	v_lshlrev_b64 v[50:51], 2, v[144:145]
	s_waitcnt lgkmcnt(0)
	v_add_f32_e32 v48, v48, v49
	flat_atomic_add_f32 v[50:51], v48 offset:512

;     __device__ __forceinline__ void operator()(f32x4 (&acc)[2][2][4][2], const Unit& u, const Order& S, int wr, int wc, int fr_, int fq_, LAS unsigned char*, int) const {
;     ...
;                 if (stat && !dry) { sq += __shfl_xor(sq, 16); sq += __shfl_xor(sq, 32); if (fq == 0) atomicAdd(ssv + row, sq); }
.LBB0_1662:
	v_and_b32_e32 v33, 64, v158
	v_xor_b32_e32 v32, 16, v158
	v_add_u32_e32 v33, 64, v33
	v_cmp_lt_i32_e32 vcc, v32, v33
	v_xor_b32_e32 v34, 32, v158
	s_nop 0
	v_cndmask_b32_e32 v32, v158, v32, vcc
	v_lshlrev_b32_e32 v32, 2, v32
	ds_bpermute_b32 v32, v32, v52
	v_cmp_lt_i32_e32 vcc, v34, v33
	s_waitcnt lgkmcnt(0)
	v_add_f32_e32 v32, v52, v32
	v_cndmask_b32_e32 v33, v158, v34, vcc
	v_lshlrev_b32_e32 v33, 2, v33
	v_mov_b32_e32 v33, v32
	s_nop 1
	v_permlane32_swap_b32_e32 v32, v33
	s_and_saveexec_b64 s[38:39], s[4:5]
	s_cbranch_execz .LBB0_1664
	v_lshlrev_b64 v[34:35], 2, v[144:145]
	s_waitcnt lgkmcnt(0)
	v_add_f32_e32 v32, v32, v33
	flat_atomic_add_f32 v[34:35], v32 offset:576

;     __device__ __forceinline__ void operator()(f32x4 (&acc)[2][2][4][2], const Unit& u, const Order& S, int wr, int wc, int fr_, int fq_, LAS unsigned char*, int) const {
;     ...
;                 if (stat && !dry) { sq += __shfl_xor(sq, 16); sq += __shfl_xor(sq, 32); if (fq == 0) atomicAdd(ssv + row, sq); }
.LBB0_1674:
	v_and_b32_e32 v17, 64, v158
	v_xor_b32_e32 v16, 16, v158
	v_add_u32_e32 v17, 64, v17
	v_cmp_lt_i32_e32 vcc, v16, v17
	v_xor_b32_e32 v18, 32, v158
	s_nop 0
	v_cndmask_b32_e32 v16, v158, v16, vcc
	v_lshlrev_b32_e32 v16, 2, v16
	ds_bpermute_b32 v16, v16, v36
	v_cmp_lt_i32_e32 vcc, v18, v17
	s_waitcnt lgkmcnt(0)
	v_add_f32_e32 v16, v36, v16
	v_cndmask_b32_e32 v17, v158, v18, vcc
	v_lshlrev_b32_e32 v17, 2, v17
	v_mov_b32_e32 v17, v16
	s_nop 1
	v_permlane32_swap_b32_e32 v16, v17
	s_and_saveexec_b64 s[38:39], s[4:5]
	s_cbranch_execz .LBB0_1676
	v_lshlrev_b64 v[18:19], 2, v[144:145]
	s_waitcnt lgkmcnt(0)
	v_add_f32_e32 v16, v16, v17
	flat_atomic_add_f32 v[18:19], v16 offset:640
